# S5 scan: dropped broadcast v_movs (use op_sel hi-element select) + removed pk-producer pads file-wide
# baseline (speedup 1.0000x reference)
; DI float wave_sum(float v) {
; #pragma unroll
;     for (int o = 1; o < 64; o <<= 1) v += __shfl_xor(v, o);
;     return v;
; }
; DI void rms_rows_bf16(const Ctx& C, const float* x, const float* g, bf16* out) {
;     for (int m = C.gw; m < T; m += C.ngw) {
;         const f32x4* xr = (const f32x4*)(x + (size_t)m * D) + C.lane; f32x4 v[8]; float s = 0.f;
; #pragma unroll
;         for (int j = 0; j < 8; ++j) { v[j] = xr[64 * j]; s += (v[j].x * v[j].x + v[j].y * v[j].y) + (v[j].z * v[j].z + v[j].w * v[j].w); }
;         const float rstd = 1.0f / sqrtf(wave_sum(s) * (1.0f / D) + EPS);
.LBB0_48:
	v_add_co_u32_e32 v18, vcc, 0xfffff000, v52
	global_load_dwordx4 v[10:13], v[52:53], off offset:-3072
	global_load_dwordx4 v[14:17], v[52:53], off offset:-2048
	global_load_dwordx4 v[6:9], v[52:53], off
	v_addc_co_u32_e32 v19, vcc, -1, v53, vcc
	global_load_dwordx4 v[34:37], v[18:19], off offset:-3072
	global_load_dwordx4 v[30:33], v[18:19], off offset:-2048
	global_load_dwordx4 v[26:29], v[18:19], off offset:-1024
	global_load_dwordx4 v[22:25], v[52:53], off offset:-4096
	s_nop 0
	global_load_dwordx4 v[18:21], v[52:53], off offset:-1024
	global_load_dwordx4 v[38:41], v[0:1], off
	s_add_i32 s8, s8, s16
	s_cmpk_lt_i32 s8, 0x4000
	v_lshl_add_u64 v[52:53], v[52:53], 0, s[20:21]
	s_waitcnt vmcnt(0)
	v_mov_b32_e32 v70, v35
	v_pk_mul_f32 v[60:61], v[16:17], v[16:17]
	v_pk_mul_f32 v[62:63], v[14:15], v[14:15]
	v_mul_f32_e32 v81, v8, v8
	v_mul_f32_e32 v2, v19, v19
	v_mul_f32_e32 v64, v21, v21
	v_mul_f32_e32 v87, v9, v9
	v_pk_mov_b32 v[66:67], v[62:63], v[60:61] op_sel:[1,0]
	v_mov_b32_e32 v63, v61
	v_pk_fma_f32 v[60:61], v[18:19], v[18:19], v[2:3] op_sel_hi:[1,1,0]
	v_pk_fma_f32 v[64:65], v[20:21], v[20:21], v[64:65] op_sel_hi:[1,1,0]
	v_mov_b32_e32 v71, v31
	v_mov_b32_e32 v74, v37
	v_mov_b32_e32 v75, v33
	v_mov_b32_e32 v68, v34
	v_mov_b32_e32 v69, v30
	v_mov_b32_e32 v72, v36
	v_mov_b32_e32 v73, v32
	v_pk_mul_f32 v[76:77], v[28:29], v[28:29]
	v_pk_mul_f32 v[78:79], v[26:27], v[26:27]
	v_pk_add_f32 v[62:63], v[66:67], v[62:63]
	v_mov_b32_e32 v61, v81
	v_mov_b32_e32 v65, v87
	v_pk_mul_f32 v[66:67], v[70:71], v[70:71]
	v_pk_mul_f32 v[70:71], v[74:75], v[74:75]
	v_pk_mov_b32 v[74:75], v[78:79], v[76:77] op_sel:[1,0]
	v_mov_b32_e32 v79, v77
	v_pk_add_f32 v[60:61], v[60:61], v[64:65]
	v_pk_fma_f32 v[64:65], v[68:69], v[68:69], v[66:67]
	v_pk_fma_f32 v[66:67], v[72:73], v[72:73], v[70:71]
	v_mul_f32_e32 v2, v23, v23
	v_mul_f32_e32 v80, v25, v25
	v_pk_add_f32 v[68:69], v[74:75], v[78:79]
	v_pk_add_f32 v[64:65], v[64:65], v[66:67]
	v_mul_f32_e32 v59, v10, v10
	v_mul_f32_e32 v82, v11, v11
	v_mul_f32_e32 v83, v12, v12
	v_mul_f32_e32 v84, v13, v13
	v_pk_fma_f32 v[76:77], v[22:23], v[22:23], v[2:3] op_sel_hi:[1,1,0]
	v_pk_fma_f32 v[80:81], v[24:25], v[24:25], v[80:81] op_sel_hi:[1,1,0]
	v_pk_add_f32 v[66:67], v[68:69], v[68:69] op_sel:[0,1] op_sel_hi:[1,0]
	v_pk_add_f32 v[64:65], v[64:65], v[64:65] op_sel:[0,1] op_sel_hi:[1,0]
	v_mov_b32_e32 v77, v83
	v_mov_b32_e32 v81, v84
	v_mov_b32_e32 v67, v82
	v_mov_b32_e32 v65, v59
	v_pk_add_f32 v[68:69], v[76:77], v[80:81]
	v_pk_add_f32 v[64:65], v[64:65], v[66:67]
	v_mul_f32_e32 v85, v6, v6
	v_pk_add_f32 v[64:65], v[64:65], v[68:69]
	v_mul_f32_e32 v86, v7, v7
	v_pk_add_f32 v[62:63], v[62:63], v[62:63] op_sel:[0,1] op_sel_hi:[1,0]
	v_pk_add_f32 v[64:65], v[64:65], v[64:65] op_sel:[0,1] op_sel_hi:[1,0]
	v_mov_b32_e32 v63, v86
	v_mov_b32_e32 v65, v85
	v_pk_add_f32 v[62:63], v[64:65], v[62:63]
	v_pk_add_f32 v[60:61], v[62:63], v[60:61]
	v_add_f32_e32 v2, v60, v61
	ds_bpermute_b32 v59, v5, v2
	s_waitcnt lgkmcnt(0)
	v_add_f32_e32 v2, v2, v59
	ds_bpermute_b32 v59, v54, v2
	s_waitcnt lgkmcnt(0)
	v_add_f32_e32 v2, v2, v59
	ds_bpermute_b32 v59, v55, v2
	s_waitcnt lgkmcnt(0)
	v_add_f32_e32 v2, v2, v59
	ds_bpermute_b32 v59, v56, v2
	s_waitcnt lgkmcnt(0)
	v_add_f32_e32 v2, v2, v59
	ds_bpermute_b32 v59, v57, v2
	s_waitcnt lgkmcnt(0)
	v_add_f32_e32 v2, v2, v59
	ds_bpermute_b32 v59, v58, v2
	s_waitcnt lgkmcnt(0)
; DI unsigned pk2(float lo, float hi) { return pg8::cvt_pk_bf16(lo, hi); }
; DI void rms_rows_bf16(const Ctx& C, const float* x, const float* g, bf16* out) {
;     ...
;         const float rstd = 1.0f / sqrtf(wave_sum(s) * (1.0f / D) + EPS);
;         const f32x4* gr = (const f32x4*)g + C.lane; v2u* o = (v2u*)(out + (size_t)m * D) + C.lane;
; #pragma unroll
;         for (int j = 0; j < 8; ++j) { const f32x4 gv = gr[64 * j]; v2u w; w.x = pk2(v[j].x * rstd * gv.x, v[j].y * rstd * gv.y); w.y = pk2(v[j].z * rstd * gv.z, v[j].w * rstd * gv.w); o[64 * j] = w; }
	v_add_f32_e32 v2, v2, v59
	v_fmamk_f32 v2, v2, 0x3a000000, v209
	v_mul_f32_e32 v59, 0x4f800000, v2
	v_cmp_gt_f32_e32 vcc, s89, v2
	s_nop 1
	v_cndmask_b32_e32 v2, v2, v59, vcc
	v_sqrt_f32_e32 v59, v2
	s_nop 0
	v_add_u32_e32 v60, -1, v59
	v_add_u32_e32 v61, 1, v59
	v_fma_f32 v62, -v60, v59, v2
	v_fma_f32 v63, -v61, v59, v2
	v_cmp_ge_f32_e64 s[0:1], 0, v62
	s_nop 1
	v_cndmask_b32_e64 v59, v59, v60, s[0:1]
	v_cmp_lt_f32_e64 s[0:1], 0, v63
	s_nop 1
	v_cndmask_b32_e64 v59, v59, v61, s[0:1]
	v_mul_f32_e32 v60, 0x37800000, v59
	v_cndmask_b32_e32 v59, v59, v60, vcc
	v_cmp_class_f32_e32 vcc, v2, v210
	s_nop 1
	v_cndmask_b32_e32 v2, v59, v2, vcc
	v_div_scale_f32 v59, s[0:1], v2, v2, 1.0
	v_rcp_f32_e32 v61, v59
	v_div_scale_f32 v60, vcc, 1.0, v2, 1.0
	v_fma_f32 v62, -v59, v61, 1.0
	v_fmac_f32_e32 v61, v62, v61
	v_mul_f32_e32 v62, v60, v61
	v_fma_f32 v63, -v59, v62, v60
	v_fmac_f32_e32 v62, v63, v61
	v_fma_f32 v59, -v59, v62, v60
	v_div_fmas_f32 v59, v59, v61, v62
	v_div_fixup_f32 v2, v59, v2, 1.0
	v_pk_mul_f32 v[34:35], v[34:35], v[2:3] op_sel_hi:[1,0]
	v_pk_mul_f32 v[36:37], v[36:37], v[2:3] op_sel_hi:[1,0]
	v_pk_mul_f32 v[34:35], v[38:39], v[34:35]
	v_pk_mul_f32 v[36:37], v[40:41], v[36:37]
	v_cvt_pk_bf16_f32 v34, v34, v35
	v_cvt_pk_bf16_f32 v35, v36, v37
	global_load_dwordx4 v[100:103], v[0:1], off offset:1024
	global_load_dwordx4 v[104:107], v[0:1], off offset:2048
	global_load_dwordx4 v[108:111], v[0:1], off offset:3072
	global_load_dwordx4 v[112:115], v[42:43], off
	global_load_dwordx4 v[116:119], v[44:45], off
	global_load_dwordx4 v[120:123], v[46:47], off
	global_load_dwordx4 v[124:127], v[48:49], off
	global_store_dwordx2 v[50:51], v[34:35], off
	v_pk_mul_f32 v[30:31], v[30:31], v[2:3] op_sel_hi:[1,0]
	v_pk_mul_f32 v[32:33], v[32:33], v[2:3] op_sel_hi:[1,0]
	v_pk_mul_f32 v[26:27], v[26:27], v[2:3] op_sel_hi:[1,0]
	v_pk_mul_f32 v[28:29], v[28:29], v[2:3] op_sel_hi:[1,0]
	v_pk_mul_f32 v[22:23], v[22:23], v[2:3] op_sel_hi:[1,0]
	v_pk_mul_f32 v[24:25], v[24:25], v[2:3] op_sel_hi:[1,0]
	v_pk_mul_f32 v[10:11], v[10:11], v[2:3] op_sel_hi:[1,0]
	v_pk_mul_f32 v[12:13], v[12:13], v[2:3] op_sel_hi:[1,0]
	v_pk_mul_f32 v[14:15], v[14:15], v[2:3] op_sel_hi:[1,0]
	v_pk_mul_f32 v[16:17], v[16:17], v[2:3] op_sel_hi:[1,0]
	v_pk_mul_f32 v[6:7], v[6:7], v[2:3] op_sel_hi:[1,0]
	v_pk_mul_f32 v[8:9], v[8:9], v[2:3] op_sel_hi:[1,0]
	s_waitcnt vmcnt(7)
	v_pk_mul_f32 v[30:31], v[100:101], v[30:31]
	v_pk_mul_f32 v[32:33], v[102:103], v[32:33]
	v_cvt_pk_bf16_f32 v30, v30, v31
	v_cvt_pk_bf16_f32 v31, v32, v33
	global_store_dwordx2 v[50:51], v[30:31], off offset:512
	s_waitcnt vmcnt(7)
	v_pk_mul_f32 v[26:27], v[104:105], v[26:27]
	v_pk_mul_f32 v[28:29], v[106:107], v[28:29]
	v_cvt_pk_bf16_f32 v26, v26, v27
	v_cvt_pk_bf16_f32 v27, v28, v29
	global_store_dwordx2 v[50:51], v[26:27], off offset:1024
	s_waitcnt vmcnt(7)
	v_pk_mul_f32 v[22:23], v[108:109], v[22:23]
	v_pk_mul_f32 v[24:25], v[110:111], v[24:25]
	v_cvt_pk_bf16_f32 v22, v22, v23
	v_cvt_pk_bf16_f32 v23, v24, v25
	global_store_dwordx2 v[50:51], v[22:23], off offset:1536
	s_waitcnt vmcnt(7)
	v_pk_mul_f32 v[10:11], v[10:11], v[112:113]
	v_pk_mul_f32 v[12:13], v[12:13], v[114:115]
	v_cvt_pk_bf16_f32 v10, v10, v11
	v_cvt_pk_bf16_f32 v11, v12, v13
	global_store_dwordx2 v[50:51], v[10:11], off offset:2048
	s_waitcnt vmcnt(7)
	v_pk_mul_f32 v[10:11], v[14:15], v[116:117]
	v_pk_mul_f32 v[12:13], v[16:17], v[118:119]
	v_cvt_pk_bf16_f32 v10, v10, v11
	v_cvt_pk_bf16_f32 v11, v12, v13
	global_store_dwordx2 v[50:51], v[10:11], off offset:2560
	v_pk_mul_f32 v[14:15], v[18:19], v[2:3] op_sel_hi:[1,0]
	v_pk_mul_f32 v[16:17], v[20:21], v[2:3] op_sel_hi:[1,0]
	s_waitcnt vmcnt(7)
	v_pk_mul_f32 v[10:11], v[14:15], v[120:121]
	v_pk_mul_f32 v[12:13], v[16:17], v[122:123]
	v_cvt_pk_bf16_f32 v10, v10, v11
	v_cvt_pk_bf16_f32 v11, v12, v13
	global_store_dwordx2 v[50:51], v[10:11], off offset:3072
	s_waitcnt vmcnt(7)
	v_pk_mul_f32 v[6:7], v[6:7], v[124:125]
	v_pk_mul_f32 v[8:9], v[8:9], v[126:127]
	v_cvt_pk_bf16_f32 v6, v6, v7
	v_cvt_pk_bf16_f32 v7, v8, v9
	global_store_dwordx2 v[50:51], v[6:7], off offset:3584
	v_lshl_add_u64 v[50:51], v[50:51], 0, s[18:19]
	s_cbranch_scc1 .LBB0_48

; __device__ __forceinline__ float ep_sigmoid(float x) { return __builtin_amdgcn_rcpf(1.0f + __expf(-x)); }
; __device__ __forceinline__ float ep_rstd(const rowss_t* rowss, int row) { return __builtin_amdgcn_rsqf((float)rowss[row] * (1.0f / 16777216.0f) * (1.0f / 2048.0f) + 1e-6f); }
;     __device__ __forceinline__ void operator()(const f32x4 (&acc)[2][2][4][2], const Unit& u, int wr, int wc, int fr, int fq) const {
;         const int row0 = u.pm * BM + wr * 64 + fr; const int col0 = u.pn * HALF + wc * 32 + 8 * fq;
; #pragma unroll
;         for (int ai = 0; ai < 2; ++ai)
; #pragma unroll
;             for (int m = 0; m < 4; ++m) { bf16_t* rowp = O + (size_t)(row0 + ai * HALF + m * 16) * ldo + col0;
;                 float o[8]; const float rs = rowss ? ep_rstd(rowss, row0 + ai * HALF + m * 16) : 1.0f;
; #pragma unroll
;                 for (int n = 0; n < 2; ++n)
; #pragma unroll
;                     for (int j = 0; j < 4; ++j) { const float g = acc[ai][0][m][n][j] * rs, uu = acc[ai][1][m][n][j] * rs; o[4 * n + j] = g * ep_sigmoid(g) * uu; }
;                 u32x4 w; w.x = cvt_pk_bf16(o[0], o[1]); w.y = cvt_pk_bf16(o[2], o[3]); w.z = cvt_pk_bf16(o[4], o[5]); w.w = cvt_pk_bf16(o[6], o[7]);
;                 *(u32x4*)rowp = w; }
.LBB0_133:
	s_nop 0
	v_pk_mul_f32 v[130:131], v[130:131], v[148:149] op_sel_hi:[1,0]
	v_pk_mul_f32 v[126:127], v[126:127], v[148:149] op_sel_hi:[1,0]
	v_mul_f32_e32 v160, 0xbfb8aa3b, v130
	v_exp_f32_e32 v160, v160
	v_pk_mul_f32 v[128:129], v[128:129], v[148:149] op_sel_hi:[1,0]
	v_pk_mul_f32 v[122:123], v[122:123], v[148:149] op_sel_hi:[1,0]
	v_pk_mul_f32 v[118:119], v[118:119], v[148:149] op_sel_hi:[1,0]
	v_add_f32_e32 v160, 1.0, v160
	v_rcp_f32_e32 v162, v160
	v_mul_f32_e32 v160, 0xbfb8aa3b, v131
	v_exp_f32_e32 v160, v160
	v_lshl_or_b32 v144, s70, 7, v149
	v_mov_b64_e32 v[158:159], s[18:19]
	v_pk_mul_f32 v[120:121], v[120:121], v[148:149] op_sel_hi:[1,0]
	v_add_f32_e32 v160, 1.0, v160
	v_rcp_f32_e32 v163, v160
	v_ashrrev_i32_e32 v145, 31, v144
	v_mad_i64_i32 v[158:159], s[34:35], v142, s25, v[158:159]
	v_pk_mul_f32 v[130:131], v[130:131], v[162:163]
	v_lshl_add_u64 v[158:159], v[144:145], 1, v[158:159]
	v_pk_mul_f32 v[126:127], v[126:127], v[130:131]
	v_pk_mul_f32 v[130:131], v[132:133], v[148:149] op_sel_hi:[1,0]
	v_cvt_pk_bf16_f32 v126, v126, v127
	v_mul_f32_e32 v127, 0xbfb8aa3b, v130
	v_exp_f32_e32 v127, v127
	s_and_b64 vcc, exec, s[8:9]
	v_add_f32_e32 v127, 1.0, v127
	v_rcp_f32_e32 v132, v127
	v_mul_f32_e32 v127, 0xbfb8aa3b, v131
	v_exp_f32_e32 v127, v127
	s_nop 0
	v_add_f32_e32 v127, 1.0, v127
	v_rcp_f32_e32 v133, v127
	s_nop 0
	v_pk_mul_f32 v[130:131], v[130:131], v[132:133]
	v_pk_mul_f32 v[128:129], v[128:129], v[130:131]
	v_cvt_pk_bf16_f32 v127, v128, v129
	v_mul_f32_e32 v128, 0xbfb8aa3b, v122
	v_mul_f32_e32 v129, 0xbfb8aa3b, v123
	v_exp_f32_e32 v128, v128
	v_exp_f32_e32 v129, v129
	v_add_f32_e32 v128, 1.0, v128
	v_add_f32_e32 v129, 1.0, v129
	v_rcp_f32_e32 v128, v128
	v_rcp_f32_e32 v129, v129
	s_nop 0
	v_pk_mul_f32 v[122:123], v[122:123], v[128:129]
	v_pk_mul_f32 v[118:119], v[118:119], v[122:123]
	v_cvt_pk_bf16_f32 v128, v118, v119
	v_pk_mul_f32 v[118:119], v[124:125], v[148:149] op_sel_hi:[1,0]
	v_mul_f32_e32 v122, 0xbfb8aa3b, v118
	v_mul_f32_e32 v123, 0xbfb8aa3b, v119
	v_exp_f32_e32 v122, v122
	v_exp_f32_e32 v123, v123
	v_add_f32_e32 v122, 1.0, v122
	v_add_f32_e32 v123, 1.0, v123
	v_rcp_f32_e32 v122, v122
	v_rcp_f32_e32 v123, v123
	s_nop 0
	v_pk_mul_f32 v[118:119], v[118:119], v[122:123]
	v_pk_mul_f32 v[118:119], v[120:121], v[118:119]
	v_cvt_pk_bf16_f32 v129, v118, v119
	global_store_dwordx4 v[158:159], v[126:129], off
	s_cbranch_vccnz .LBB0_135
	s_waitcnt vmcnt(7) lgkmcnt(0)
	v_ffbh_u32_e32 v120, v169
	v_min_u32_e32 v120, 32, v120
	v_lshlrev_b64 v[118:119], v120, v[168:169]
	v_min_u32_e32 v118, 1, v118
	v_or_b32_e32 v118, v119, v118
	v_cvt_f32_u32_e32 v118, v118
	v_sub_u32_e32 v119, 32, v120
	v_ldexp_f32 v118, v118, v119
	v_mul_f32_e32 v118, 0x33800000, v118
	v_fmamk_f32 v118, v118, 0x3a000000, v209
	v_rsq_f32_e32 v146, v118
.LBB0_135:
	v_or_b32_e32 v120, 16, v142
	v_mov_b64_e32 v[118:119], s[18:19]
	v_mad_i64_i32 v[118:119], s[34:35], v120, s25, v[118:119]
	v_pk_mul_f32 v[120:121], v[114:115], v[146:147] op_sel_hi:[1,0]
	v_pk_mul_f32 v[110:111], v[110:111], v[146:147] op_sel_hi:[1,0]
	v_mul_f32_e32 v114, 0xbfb8aa3b, v120
	v_exp_f32_e32 v115, v114
	v_pk_mul_f32 v[116:117], v[116:117], v[146:147] op_sel_hi:[1,0]
	v_pk_mul_f32 v[112:113], v[112:113], v[146:147] op_sel_hi:[1,0]
	v_pk_mul_f32 v[106:107], v[106:107], v[146:147] op_sel_hi:[1,0]
	v_add_f32_e32 v115, 1.0, v115
	v_rcp_f32_e32 v122, v115
	v_mul_f32_e32 v115, 0xbfb8aa3b, v121
	v_exp_f32_e32 v115, v115
	v_pk_mul_f32 v[102:103], v[102:103], v[146:147] op_sel_hi:[1,0]
	v_pk_mul_f32 v[104:105], v[104:105], v[146:147] op_sel_hi:[1,0]
	v_lshl_add_u64 v[118:119], v[144:145], 1, v[118:119]
	v_add_f32_e32 v115, 1.0, v115
	v_rcp_f32_e32 v123, v115
	v_mov_b32_e32 v114, 1.0
	s_and_b64 vcc, exec, s[8:9]
	v_readlane_b32 s84, v253, 20
	v_pk_mul_f32 v[120:121], v[120:121], v[122:123]
	s_mov_b32 s86, 0x800000
	v_pk_mul_f32 v[110:111], v[110:111], v[120:121]
	v_readlane_b32 s83, v253, 8
	v_cvt_pk_bf16_f32 v110, v110, v111
	v_mul_f32_e32 v111, 0xbfb8aa3b, v116
	v_exp_f32_e32 v111, v111
	s_nop 0
	v_add_f32_e32 v111, 1.0, v111
	v_rcp_f32_e32 v120, v111
	v_mul_f32_e32 v111, 0xbfb8aa3b, v117
	v_exp_f32_e32 v111, v111
	s_nop 0
	v_add_f32_e32 v111, 1.0, v111
	v_rcp_f32_e32 v121, v111
	s_nop 0
	v_pk_mul_f32 v[116:117], v[116:117], v[120:121]
	v_pk_mul_f32 v[112:113], v[112:113], v[116:117]
	v_cvt_pk_bf16_f32 v111, v112, v113
	v_mul_f32_e32 v112, 0xbfb8aa3b, v106
	v_mul_f32_e32 v113, 0xbfb8aa3b, v107
	v_exp_f32_e32 v112, v112
	v_exp_f32_e32 v113, v113
	v_add_f32_e32 v112, 1.0, v112
	v_add_f32_e32 v113, 1.0, v113
	v_rcp_f32_e32 v112, v112
	v_rcp_f32_e32 v113, v113
	s_nop 0
	v_pk_mul_f32 v[106:107], v[106:107], v[112:113]
	v_pk_mul_f32 v[102:103], v[102:103], v[106:107]
	v_cvt_pk_bf16_f32 v112, v102, v103
	v_pk_mul_f32 v[102:103], v[108:109], v[146:147] op_sel_hi:[1,0]
	v_mul_f32_e32 v106, 0xbfb8aa3b, v102
	v_mul_f32_e32 v107, 0xbfb8aa3b, v103
	v_exp_f32_e32 v106, v106
	v_exp_f32_e32 v107, v107
	v_add_f32_e32 v106, 1.0, v106
	v_add_f32_e32 v107, 1.0, v107
	v_rcp_f32_e32 v106, v106
	v_rcp_f32_e32 v107, v107
	s_nop 0
	v_pk_mul_f32 v[102:103], v[102:103], v[106:107]
	v_pk_mul_f32 v[102:103], v[104:105], v[102:103]
	v_cvt_pk_bf16_f32 v113, v102, v103
	v_mov_b32_e32 v102, 1.0
	global_store_dwordx4 v[118:119], v[110:113], off
	s_cbranch_vccnz .LBB0_137
	s_waitcnt vmcnt(7) lgkmcnt(0)
	v_ffbh_u32_e32 v104, v171
	v_min_u32_e32 v104, 32, v104
	v_lshlrev_b64 v[102:103], v104, v[170:171]
	v_min_u32_e32 v102, 1, v102
	v_or_b32_e32 v102, v103, v102
	v_cvt_f32_u32_e32 v102, v102
	v_sub_u32_e32 v103, 32, v104
	v_ldexp_f32 v102, v102, v103
	v_mul_f32_e32 v102, 0x33800000, v102
	v_fmamk_f32 v102, v102, 0x3a000000, v209
	v_rsq_f32_e32 v102, v102
; __device__ __forceinline__ float ep_sigmoid(float x) { return __builtin_amdgcn_rcpf(1.0f + __expf(-x)); }
; __device__ __forceinline__ float ep_rstd(const rowss_t* rowss, int row) { return __builtin_amdgcn_rsqf((float)rowss[row] * (1.0f / 16777216.0f) * (1.0f / 2048.0f) + 1e-6f); }
;     __device__ __forceinline__ void operator()(const f32x4 (&acc)[2][2][4][2], const Unit& u, int wr, int wc, int fr, int fq) const {
;         const int row0 = u.pm * BM + wr * 64 + fr; const int col0 = u.pn * HALF + wc * 32 + 8 * fq;
; #pragma unroll
;         for (int ai = 0; ai < 2; ++ai)
; #pragma unroll
;             for (int m = 0; m < 4; ++m) { bf16_t* rowp = O + (size_t)(row0 + ai * HALF + m * 16) * ldo + col0;
;                 float o[8]; const float rs = rowss ? ep_rstd(rowss, row0 + ai * HALF + m * 16) : 1.0f;
; #pragma unroll
;                 for (int n = 0; n < 2; ++n)
; #pragma unroll
;                     for (int j = 0; j < 4; ++j) { const float g = acc[ai][0][m][n][j] * rs, uu = acc[ai][1][m][n][j] * rs; o[4 * n + j] = g * ep_sigmoid(g) * uu; }
;                 u32x4 w; w.x = cvt_pk_bf16(o[0], o[1]); w.y = cvt_pk_bf16(o[2], o[3]); w.z = cvt_pk_bf16(o[4], o[5]); w.w = cvt_pk_bf16(o[6], o[7]);
;                 *(u32x4*)rowp = w; }
.LBB0_137:
	v_or_b32_e32 v103, 32, v142
	v_mov_b64_e32 v[104:105], s[18:19]
	v_pk_mul_f32 v[98:99], v[98:99], v[102:103] op_sel_hi:[1,0]
	v_mad_i64_i32 v[104:105], s[34:35], v103, s25, v[104:105]
	v_mul_f32_e32 v103, 0xbfb8aa3b, v98
	v_exp_f32_e32 v103, v103
	v_lshl_add_u64 v[104:105], v[144:145], 1, v[104:105]
	s_and_b64 vcc, exec, s[8:9]
	v_add_f32_e32 v103, 1.0, v103
	v_rcp_f32_e32 v106, v103
	v_pk_mul_f32 v[94:95], v[94:95], v[102:103] op_sel_hi:[1,0]
	v_mul_f32_e32 v103, 0xbfb8aa3b, v99
	v_exp_f32_e32 v103, v103
	s_nop 0
	v_add_f32_e32 v103, 1.0, v103
	v_rcp_f32_e32 v107, v103
	v_pk_mul_f32 v[96:97], v[96:97], v[102:103] op_sel_hi:[1,0]
	v_pk_mul_f32 v[90:91], v[90:91], v[102:103] op_sel_hi:[1,0]
	v_pk_mul_f32 v[86:87], v[86:87], v[102:103] op_sel_hi:[1,0]
	v_pk_mul_f32 v[98:99], v[98:99], v[106:107]
	v_pk_mul_f32 v[88:89], v[88:89], v[102:103] op_sel_hi:[1,0]
	v_pk_mul_f32 v[94:95], v[94:95], v[98:99]
	v_pk_mul_f32 v[98:99], v[100:101], v[102:103] op_sel_hi:[1,0]
	v_cvt_pk_bf16_f32 v94, v94, v95
	v_mul_f32_e32 v95, 0xbfb8aa3b, v98
	v_exp_f32_e32 v95, v95
	s_nop 0
	v_add_f32_e32 v95, 1.0, v95
	v_rcp_f32_e32 v100, v95
	v_mul_f32_e32 v95, 0xbfb8aa3b, v99
	v_exp_f32_e32 v95, v95
	s_nop 0
	v_add_f32_e32 v95, 1.0, v95
	v_rcp_f32_e32 v101, v95
	s_nop 0
	v_pk_mul_f32 v[98:99], v[98:99], v[100:101]
	v_pk_mul_f32 v[96:97], v[96:97], v[98:99]
	v_cvt_pk_bf16_f32 v95, v96, v97
	v_mul_f32_e32 v96, 0xbfb8aa3b, v90
	v_mul_f32_e32 v97, 0xbfb8aa3b, v91
	v_exp_f32_e32 v96, v96
	v_exp_f32_e32 v97, v97
	v_add_f32_e32 v96, 1.0, v96
	v_add_f32_e32 v97, 1.0, v97
	v_rcp_f32_e32 v96, v96
	v_rcp_f32_e32 v97, v97
	s_nop 0
	v_pk_mul_f32 v[90:91], v[90:91], v[96:97]
	v_pk_mul_f32 v[86:87], v[86:87], v[90:91]
	v_cvt_pk_bf16_f32 v96, v86, v87
	v_pk_mul_f32 v[86:87], v[92:93], v[102:103] op_sel_hi:[1,0]
	v_mul_f32_e32 v90, 0xbfb8aa3b, v86
	v_mul_f32_e32 v91, 0xbfb8aa3b, v87
	v_exp_f32_e32 v90, v90
	v_exp_f32_e32 v91, v91
	v_add_f32_e32 v90, 1.0, v90
	v_add_f32_e32 v91, 1.0, v91
	v_rcp_f32_e32 v90, v90
	v_rcp_f32_e32 v91, v91
	s_nop 0
	v_pk_mul_f32 v[86:87], v[86:87], v[90:91]
	v_pk_mul_f32 v[86:87], v[88:89], v[86:87]
	v_cvt_pk_bf16_f32 v97, v86, v87
	global_store_dwordx4 v[104:105], v[94:97], off
	s_cbranch_vccnz .LBB0_139
	s_waitcnt vmcnt(7) lgkmcnt(0)
	v_ffbh_u32_e32 v88, v173
	v_min_u32_e32 v88, 32, v88
	v_lshlrev_b64 v[86:87], v88, v[172:173]
	v_min_u32_e32 v86, 1, v86
	v_or_b32_e32 v86, v87, v86
	v_cvt_f32_u32_e32 v86, v86
	v_sub_u32_e32 v87, 32, v88
	v_ldexp_f32 v86, v86, v87
	v_mul_f32_e32 v86, 0x33800000, v86
	v_fmamk_f32 v86, v86, 0x3a000000, v209
	v_rsq_f32_e32 v114, v86
.LBB0_139:
	v_or_b32_e32 v88, 48, v142
	v_mov_b64_e32 v[86:87], s[18:19]
	v_mad_i64_i32 v[86:87], s[34:35], v88, s25, v[86:87]
	v_pk_mul_f32 v[88:89], v[82:83], v[114:115] op_sel_hi:[1,0]
	v_pk_mul_f32 v[78:79], v[78:79], v[114:115] op_sel_hi:[1,0]
	v_mul_f32_e32 v82, 0xbfb8aa3b, v88
	v_exp_f32_e32 v83, v82
	v_pk_mul_f32 v[84:85], v[84:85], v[114:115] op_sel_hi:[1,0]
	v_pk_mul_f32 v[80:81], v[80:81], v[114:115] op_sel_hi:[1,0]
	v_pk_mul_f32 v[74:75], v[74:75], v[114:115] op_sel_hi:[1,0]
	v_add_f32_e32 v83, 1.0, v83
	v_rcp_f32_e32 v90, v83
	v_mul_f32_e32 v83, 0xbfb8aa3b, v89
	v_exp_f32_e32 v83, v83
	v_pk_mul_f32 v[70:71], v[70:71], v[114:115] op_sel_hi:[1,0]
	v_pk_mul_f32 v[72:73], v[72:73], v[114:115] op_sel_hi:[1,0]
	v_lshl_add_u64 v[86:87], v[144:145], 1, v[86:87]
	v_add_f32_e32 v83, 1.0, v83
	v_rcp_f32_e32 v91, v83
	v_mov_b32_e32 v82, 1.0
	s_and_b64 vcc, exec, s[8:9]
	v_pk_mul_f32 v[88:89], v[88:89], v[90:91]
	v_pk_mul_f32 v[78:79], v[78:79], v[88:89]
	v_cvt_pk_bf16_f32 v78, v78, v79
	v_mul_f32_e32 v79, 0xbfb8aa3b, v84
	v_exp_f32_e32 v79, v79
	s_nop 0
	v_add_f32_e32 v79, 1.0, v79
	v_rcp_f32_e32 v88, v79
	v_mul_f32_e32 v79, 0xbfb8aa3b, v85
	v_exp_f32_e32 v79, v79
	s_nop 0
	v_add_f32_e32 v79, 1.0, v79
	v_rcp_f32_e32 v89, v79
	s_nop 0
	v_pk_mul_f32 v[84:85], v[84:85], v[88:89]
	v_pk_mul_f32 v[80:81], v[80:81], v[84:85]
	v_cvt_pk_bf16_f32 v79, v80, v81
	v_mul_f32_e32 v80, 0xbfb8aa3b, v74
	v_mul_f32_e32 v81, 0xbfb8aa3b, v75
	v_exp_f32_e32 v80, v80
	v_exp_f32_e32 v81, v81
	v_add_f32_e32 v80, 1.0, v80
	v_add_f32_e32 v81, 1.0, v81
	v_rcp_f32_e32 v80, v80
	v_rcp_f32_e32 v81, v81
	s_nop 0
	v_pk_mul_f32 v[74:75], v[74:75], v[80:81]
	v_pk_mul_f32 v[70:71], v[70:71], v[74:75]
	v_cvt_pk_bf16_f32 v80, v70, v71
	v_pk_mul_f32 v[70:71], v[76:77], v[114:115] op_sel_hi:[1,0]
	v_mul_f32_e32 v74, 0xbfb8aa3b, v70
	v_mul_f32_e32 v75, 0xbfb8aa3b, v71
	v_exp_f32_e32 v74, v74
	v_exp_f32_e32 v75, v75
	v_add_f32_e32 v74, 1.0, v74
	v_add_f32_e32 v75, 1.0, v75
	v_rcp_f32_e32 v74, v74
	v_rcp_f32_e32 v75, v75
	s_nop 0
	v_pk_mul_f32 v[70:71], v[70:71], v[74:75]
	v_pk_mul_f32 v[70:71], v[72:73], v[70:71]
	v_cvt_pk_bf16_f32 v81, v70, v71
	v_mov_b32_e32 v70, 1.0
	global_store_dwordx4 v[86:87], v[78:81], off
	s_cbranch_vccnz .LBB0_141
	s_waitcnt vmcnt(7) lgkmcnt(0)
	v_ffbh_u32_e32 v72, v175
	v_min_u32_e32 v72, 32, v72
	v_lshlrev_b64 v[70:71], v72, v[174:175]
	v_min_u32_e32 v70, 1, v70
	v_or_b32_e32 v70, v71, v70
	v_cvt_f32_u32_e32 v70, v70
	v_sub_u32_e32 v71, 32, v72
	v_ldexp_f32 v70, v70, v71
	v_mul_f32_e32 v70, 0x33800000, v70
	v_fmamk_f32 v70, v70, 0x3a000000, v209
	v_rsq_f32_e32 v70, v70
; __device__ __forceinline__ float ep_sigmoid(float x) { return __builtin_amdgcn_rcpf(1.0f + __expf(-x)); }
; __device__ __forceinline__ float ep_rstd(const rowss_t* rowss, int row) { return __builtin_amdgcn_rsqf((float)rowss[row] * (1.0f / 16777216.0f) * (1.0f / 2048.0f) + 1e-6f); }
;     __device__ __forceinline__ void operator()(const f32x4 (&acc)[2][2][4][2], const Unit& u, int wr, int wc, int fr, int fq) const {
;         const int row0 = u.pm * BM + wr * 64 + fr; const int col0 = u.pn * HALF + wc * 32 + 8 * fq;
; #pragma unroll
;         for (int ai = 0; ai < 2; ++ai)
; #pragma unroll
;             for (int m = 0; m < 4; ++m) { bf16_t* rowp = O + (size_t)(row0 + ai * HALF + m * 16) * ldo + col0;
;                 float o[8]; const float rs = rowss ? ep_rstd(rowss, row0 + ai * HALF + m * 16) : 1.0f;
; #pragma unroll
;                 for (int n = 0; n < 2; ++n)
; #pragma unroll
;                     for (int j = 0; j < 4; ++j) { const float g = acc[ai][0][m][n][j] * rs, uu = acc[ai][1][m][n][j] * rs; o[4 * n + j] = g * ep_sigmoid(g) * uu; }
;                 u32x4 w; w.x = cvt_pk_bf16(o[0], o[1]); w.y = cvt_pk_bf16(o[2], o[3]); w.z = cvt_pk_bf16(o[4], o[5]); w.w = cvt_pk_bf16(o[6], o[7]);
;                 *(u32x4*)rowp = w; }
.LBB0_141:
	v_add_u32_e32 v71, 0x80, v142
	v_mov_b64_e32 v[72:73], s[18:19]
	v_pk_mul_f32 v[66:67], v[66:67], v[70:71] op_sel_hi:[1,0]
	v_mad_i64_i32 v[72:73], s[34:35], v71, s25, v[72:73]
	v_mul_f32_e32 v71, 0xbfb8aa3b, v66
	v_exp_f32_e32 v71, v71
	v_lshl_add_u64 v[72:73], v[144:145], 1, v[72:73]
	s_and_b64 vcc, exec, s[8:9]
	v_add_f32_e32 v71, 1.0, v71
	v_rcp_f32_e32 v74, v71
	v_pk_mul_f32 v[62:63], v[62:63], v[70:71] op_sel_hi:[1,0]
	v_mul_f32_e32 v71, 0xbfb8aa3b, v67
	v_exp_f32_e32 v71, v71
	s_nop 0
	v_add_f32_e32 v71, 1.0, v71
	v_rcp_f32_e32 v75, v71
	v_pk_mul_f32 v[64:65], v[64:65], v[70:71] op_sel_hi:[1,0]
	v_pk_mul_f32 v[58:59], v[58:59], v[70:71] op_sel_hi:[1,0]
	v_pk_mul_f32 v[54:55], v[54:55], v[70:71] op_sel_hi:[1,0]
	v_pk_mul_f32 v[66:67], v[66:67], v[74:75]
	v_pk_mul_f32 v[56:57], v[56:57], v[70:71] op_sel_hi:[1,0]
	v_pk_mul_f32 v[62:63], v[62:63], v[66:67]
	v_pk_mul_f32 v[66:67], v[68:69], v[70:71] op_sel_hi:[1,0]
	v_cvt_pk_bf16_f32 v62, v62, v63
	v_mul_f32_e32 v63, 0xbfb8aa3b, v66
	v_exp_f32_e32 v63, v63
	s_nop 0
	v_add_f32_e32 v63, 1.0, v63
	v_rcp_f32_e32 v68, v63
	v_mul_f32_e32 v63, 0xbfb8aa3b, v67
	v_exp_f32_e32 v63, v63
	s_nop 0
	v_add_f32_e32 v63, 1.0, v63
	v_rcp_f32_e32 v69, v63
	s_nop 0
	v_pk_mul_f32 v[66:67], v[66:67], v[68:69]
	v_pk_mul_f32 v[64:65], v[64:65], v[66:67]
	v_cvt_pk_bf16_f32 v63, v64, v65
	v_mul_f32_e32 v64, 0xbfb8aa3b, v58
	v_mul_f32_e32 v65, 0xbfb8aa3b, v59
	v_exp_f32_e32 v64, v64
	v_exp_f32_e32 v65, v65
	v_add_f32_e32 v64, 1.0, v64
	v_add_f32_e32 v65, 1.0, v65
	v_rcp_f32_e32 v64, v64
	v_rcp_f32_e32 v65, v65
	s_nop 0
	v_pk_mul_f32 v[58:59], v[58:59], v[64:65]
	v_pk_mul_f32 v[54:55], v[54:55], v[58:59]
	v_cvt_pk_bf16_f32 v64, v54, v55
	v_pk_mul_f32 v[54:55], v[60:61], v[70:71] op_sel_hi:[1,0]
	v_mul_f32_e32 v58, 0xbfb8aa3b, v54
	v_mul_f32_e32 v59, 0xbfb8aa3b, v55
	v_exp_f32_e32 v58, v58
	v_exp_f32_e32 v59, v59
	v_add_f32_e32 v58, 1.0, v58
	v_add_f32_e32 v59, 1.0, v59
	v_rcp_f32_e32 v58, v58
	v_rcp_f32_e32 v59, v59
	s_nop 0
	v_pk_mul_f32 v[54:55], v[54:55], v[58:59]
	v_pk_mul_f32 v[54:55], v[56:57], v[54:55]
	v_cvt_pk_bf16_f32 v65, v54, v55
	global_store_dwordx4 v[72:73], v[62:65], off
	s_cbranch_vccnz .LBB0_143
	s_waitcnt vmcnt(7) lgkmcnt(0)
	v_ffbh_u32_e32 v56, v177
	v_min_u32_e32 v56, 32, v56
	v_lshlrev_b64 v[54:55], v56, v[176:177]
	v_min_u32_e32 v54, 1, v54
	v_or_b32_e32 v54, v55, v54
	v_cvt_f32_u32_e32 v54, v54
	v_sub_u32_e32 v55, 32, v56
	v_ldexp_f32 v54, v54, v55
	v_mul_f32_e32 v54, 0x33800000, v54
	v_fmamk_f32 v54, v54, 0x3a000000, v209
	v_rsq_f32_e32 v82, v54
.LBB0_143:
	v_add_u32_e32 v56, 0x90, v142
	v_mov_b64_e32 v[54:55], s[18:19]
	v_mad_i64_i32 v[54:55], s[34:35], v56, s25, v[54:55]
	v_pk_mul_f32 v[56:57], v[50:51], v[82:83] op_sel_hi:[1,0]
	v_pk_mul_f32 v[46:47], v[46:47], v[82:83] op_sel_hi:[1,0]
	v_mul_f32_e32 v50, 0xbfb8aa3b, v56
	v_exp_f32_e32 v51, v50
	v_pk_mul_f32 v[52:53], v[52:53], v[82:83] op_sel_hi:[1,0]
	v_pk_mul_f32 v[48:49], v[48:49], v[82:83] op_sel_hi:[1,0]
	v_pk_mul_f32 v[42:43], v[42:43], v[82:83] op_sel_hi:[1,0]
	v_add_f32_e32 v51, 1.0, v51
	v_rcp_f32_e32 v58, v51
	v_mul_f32_e32 v51, 0xbfb8aa3b, v57
	v_exp_f32_e32 v51, v51
	v_pk_mul_f32 v[38:39], v[38:39], v[82:83] op_sel_hi:[1,0]
	v_pk_mul_f32 v[40:41], v[40:41], v[82:83] op_sel_hi:[1,0]
	v_lshl_add_u64 v[54:55], v[144:145], 1, v[54:55]
	v_add_f32_e32 v51, 1.0, v51
	v_rcp_f32_e32 v59, v51
	v_mov_b32_e32 v50, 1.0
	s_and_b64 vcc, exec, s[8:9]
	v_pk_mul_f32 v[56:57], v[56:57], v[58:59]
	v_pk_mul_f32 v[46:47], v[46:47], v[56:57]
	v_cvt_pk_bf16_f32 v46, v46, v47
	v_mul_f32_e32 v47, 0xbfb8aa3b, v52
	v_exp_f32_e32 v47, v47
	s_nop 0
	v_add_f32_e32 v47, 1.0, v47
	v_rcp_f32_e32 v56, v47
	v_mul_f32_e32 v47, 0xbfb8aa3b, v53
	v_exp_f32_e32 v47, v47
	s_nop 0
	v_add_f32_e32 v47, 1.0, v47
	v_rcp_f32_e32 v57, v47
	s_nop 0
	v_pk_mul_f32 v[52:53], v[52:53], v[56:57]
	v_pk_mul_f32 v[48:49], v[48:49], v[52:53]
	v_cvt_pk_bf16_f32 v47, v48, v49
	v_mul_f32_e32 v48, 0xbfb8aa3b, v42
	v_mul_f32_e32 v49, 0xbfb8aa3b, v43
	v_exp_f32_e32 v48, v48
	v_exp_f32_e32 v49, v49
	v_add_f32_e32 v48, 1.0, v48
	v_add_f32_e32 v49, 1.0, v49
	v_rcp_f32_e32 v48, v48
	v_rcp_f32_e32 v49, v49
	s_nop 0
	v_pk_mul_f32 v[42:43], v[42:43], v[48:49]
	v_pk_mul_f32 v[38:39], v[38:39], v[42:43]
	v_cvt_pk_bf16_f32 v48, v38, v39
	v_pk_mul_f32 v[38:39], v[44:45], v[82:83] op_sel_hi:[1,0]
	v_mul_f32_e32 v42, 0xbfb8aa3b, v38
	v_mul_f32_e32 v43, 0xbfb8aa3b, v39
	v_exp_f32_e32 v42, v42
	v_exp_f32_e32 v43, v43
	v_add_f32_e32 v42, 1.0, v42
	v_add_f32_e32 v43, 1.0, v43
	v_rcp_f32_e32 v42, v42
	v_rcp_f32_e32 v43, v43
	s_nop 0
	v_pk_mul_f32 v[38:39], v[38:39], v[42:43]
	v_pk_mul_f32 v[38:39], v[40:41], v[38:39]
	v_cvt_pk_bf16_f32 v49, v38, v39
	v_mov_b32_e32 v38, 1.0
	global_store_dwordx4 v[54:55], v[46:49], off
	s_cbranch_vccnz .LBB0_145
	s_waitcnt vmcnt(7) lgkmcnt(0)
	v_ffbh_u32_e32 v40, v179
	v_min_u32_e32 v40, 32, v40
	v_lshlrev_b64 v[38:39], v40, v[178:179]
	v_min_u32_e32 v38, 1, v38
	v_or_b32_e32 v38, v39, v38
	v_cvt_f32_u32_e32 v38, v38
	v_sub_u32_e32 v39, 32, v40
	v_ldexp_f32 v38, v38, v39
	v_mul_f32_e32 v38, 0x33800000, v38
	v_fmamk_f32 v38, v38, 0x3a000000, v209
	v_rsq_f32_e32 v38, v38
; __device__ __forceinline__ float ep_sigmoid(float x) { return __builtin_amdgcn_rcpf(1.0f + __expf(-x)); }
; __device__ __forceinline__ float ep_rstd(const rowss_t* rowss, int row) { return __builtin_amdgcn_rsqf((float)rowss[row] * (1.0f / 16777216.0f) * (1.0f / 2048.0f) + 1e-6f); }
; #define PG8_BAR __builtin_amdgcn_s_barrier()
;     __device__ __forceinline__ void operator()(const f32x4 (&acc)[2][2][4][2], const Unit& u, int wr, int wc, int fr, int fq) const {
;         const int row0 = u.pm * BM + wr * 64 + fr; const int col0 = u.pn * HALF + wc * 32 + 8 * fq;
; #pragma unroll
;         for (int ai = 0; ai < 2; ++ai)
; #pragma unroll
;             for (int m = 0; m < 4; ++m) { bf16_t* rowp = O + (size_t)(row0 + ai * HALF + m * 16) * ldo + col0;
;                 float o[8]; const float rs = rowss ? ep_rstd(rowss, row0 + ai * HALF + m * 16) : 1.0f;
; #pragma unroll
;                 for (int n = 0; n < 2; ++n)
; #pragma unroll
;                     for (int j = 0; j < 4; ++j) { const float g = acc[ai][0][m][n][j] * rs, uu = acc[ai][1][m][n][j] * rs; o[4 * n + j] = g * ep_sigmoid(g) * uu; }
;                 u32x4 w; w.x = cvt_pk_bf16(o[0], o[1]); w.y = cvt_pk_bf16(o[2], o[3]); w.z = cvt_pk_bf16(o[4], o[5]); w.w = cvt_pk_bf16(o[6], o[7]);
;                 *(u32x4*)rowp = w; }
; template <class Epi, class Sched, bool ALIGN_EPI = false, bool SP2 = false>
; __device__ __forceinline__ void gemm_phase(PG8_LAS unsigned char* lds, const Gemm g, const Sched& S, const Epi& E) {
;     ...
;         if constexpr (ALIGN_EPI) { if (wr == 0) PG8_BAR; }
;         if constexpr (!Epi::AFTER_DRAIN) { E(acc, cur, wr, wc, fr, fq); S.done(cur); }
;         if (!has_next) break;
; #pragma unroll
;         for (int a = 0; a < 2; ++a)
; #pragma unroll
;             for (int b = 0; b < 2; ++b)
; #pragma unroll
;                 for (int m = 0; m < 4; ++m)
; #pragma unroll
;                     for (int n = 0; n < 2; ++n) acc[a][b][m][n] = (f32x4){0.f, 0.f, 0.f, 0.f};
;         cur = nxt; cA = nA; cB = nB; ++ui;
;         if constexpr (ALIGN_EPI) { if (wr == 1) PG8_BAR; }
;     }
.LBB0_145:
	v_add_u32_e32 v39, 0xa0, v142
	v_mov_b64_e32 v[40:41], s[18:19]
	v_pk_mul_f32 v[34:35], v[34:35], v[38:39] op_sel_hi:[1,0]
	v_mad_i64_i32 v[40:41], s[34:35], v39, s25, v[40:41]
	v_mul_f32_e32 v39, 0xbfb8aa3b, v34
	v_exp_f32_e32 v39, v39
	v_lshl_add_u64 v[40:41], v[144:145], 1, v[40:41]
	s_and_b64 vcc, exec, s[8:9]
	v_add_f32_e32 v39, 1.0, v39
	v_rcp_f32_e32 v42, v39
	v_pk_mul_f32 v[30:31], v[30:31], v[38:39] op_sel_hi:[1,0]
	v_mul_f32_e32 v39, 0xbfb8aa3b, v35
	v_exp_f32_e32 v39, v39
	s_nop 0
	v_add_f32_e32 v39, 1.0, v39
	v_rcp_f32_e32 v43, v39
	v_pk_mul_f32 v[32:33], v[32:33], v[38:39] op_sel_hi:[1,0]
	v_pk_mul_f32 v[26:27], v[26:27], v[38:39] op_sel_hi:[1,0]
	v_pk_mul_f32 v[22:23], v[22:23], v[38:39] op_sel_hi:[1,0]
	v_pk_mul_f32 v[34:35], v[34:35], v[42:43]
	v_pk_mul_f32 v[24:25], v[24:25], v[38:39] op_sel_hi:[1,0]
	v_pk_mul_f32 v[30:31], v[30:31], v[34:35]
	v_pk_mul_f32 v[34:35], v[36:37], v[38:39] op_sel_hi:[1,0]
	v_cvt_pk_bf16_f32 v30, v30, v31
	v_mul_f32_e32 v31, 0xbfb8aa3b, v34
	v_exp_f32_e32 v31, v31
	s_nop 0
	v_add_f32_e32 v31, 1.0, v31
	v_rcp_f32_e32 v36, v31
	v_mul_f32_e32 v31, 0xbfb8aa3b, v35
	v_exp_f32_e32 v31, v31
	s_nop 0
	v_add_f32_e32 v31, 1.0, v31
	v_rcp_f32_e32 v37, v31
	s_nop 0
	v_pk_mul_f32 v[34:35], v[34:35], v[36:37]
	v_pk_mul_f32 v[32:33], v[32:33], v[34:35]
	v_cvt_pk_bf16_f32 v31, v32, v33
	v_mul_f32_e32 v32, 0xbfb8aa3b, v26
	v_mul_f32_e32 v33, 0xbfb8aa3b, v27
	v_exp_f32_e32 v32, v32
	v_exp_f32_e32 v33, v33
	v_add_f32_e32 v32, 1.0, v32
	v_add_f32_e32 v33, 1.0, v33
	v_rcp_f32_e32 v32, v32
	v_rcp_f32_e32 v33, v33
	s_nop 0
	v_pk_mul_f32 v[26:27], v[26:27], v[32:33]
	v_pk_mul_f32 v[22:23], v[22:23], v[26:27]
	v_cvt_pk_bf16_f32 v32, v22, v23
	v_pk_mul_f32 v[22:23], v[28:29], v[38:39] op_sel_hi:[1,0]
	v_mul_f32_e32 v26, 0xbfb8aa3b, v22
	v_mul_f32_e32 v27, 0xbfb8aa3b, v23
	v_exp_f32_e32 v26, v26
	v_exp_f32_e32 v27, v27
	v_add_f32_e32 v26, 1.0, v26
	v_add_f32_e32 v27, 1.0, v27
	v_rcp_f32_e32 v26, v26
	v_rcp_f32_e32 v27, v27
	s_nop 0
	v_pk_mul_f32 v[22:23], v[22:23], v[26:27]
	v_pk_mul_f32 v[22:23], v[24:25], v[22:23]
	v_cvt_pk_bf16_f32 v33, v22, v23
	global_store_dwordx4 v[40:41], v[30:33], off
	s_cbranch_vccnz .LBB0_147
	s_waitcnt vmcnt(7) lgkmcnt(0)
	v_ffbh_u32_e32 v24, v181
	v_min_u32_e32 v24, 32, v24
	v_lshlrev_b64 v[22:23], v24, v[180:181]
	v_min_u32_e32 v22, 1, v22
	v_or_b32_e32 v22, v23, v22
	v_cvt_f32_u32_e32 v22, v22
	v_sub_u32_e32 v23, 32, v24
	v_ldexp_f32 v22, v22, v23
	v_mul_f32_e32 v22, 0x33800000, v22
	v_fmamk_f32 v22, v22, 0x3a000000, v209
	v_rsq_f32_e32 v50, v22
.LBB0_147:
	v_add_u32_e32 v24, 0xb0, v142
	v_mov_b64_e32 v[22:23], s[18:19]
	v_pk_mul_f32 v[18:19], v[18:19], v[50:51] op_sel_hi:[1,0]
	v_mad_i64_i32 v[22:23], s[8:9], v24, s25, v[22:23]
	v_mul_f32_e32 v24, 0xbfb8aa3b, v18
	v_mul_f32_e32 v25, 0xbfb8aa3b, v19
	v_exp_f32_e32 v24, v24
	v_exp_f32_e32 v25, v25
	v_pk_mul_f32 v[14:15], v[14:15], v[50:51] op_sel_hi:[1,0]
	v_pk_mul_f32 v[16:17], v[16:17], v[50:51] op_sel_hi:[1,0]
	v_add_f32_e32 v24, 1.0, v24
	v_add_f32_e32 v25, 1.0, v25
	v_rcp_f32_e32 v24, v24
	v_rcp_f32_e32 v25, v25
	v_pk_mul_f32 v[10:11], v[10:11], v[50:51] op_sel_hi:[1,0]
	v_pk_mul_f32 v[6:7], v[6:7], v[50:51] op_sel_hi:[1,0]
	v_pk_mul_f32 v[8:9], v[8:9], v[50:51] op_sel_hi:[1,0]
	v_pk_mul_f32 v[18:19], v[18:19], v[24:25]
	v_lshl_add_u64 v[22:23], v[144:145], 1, v[22:23]
	v_pk_mul_f32 v[14:15], v[14:15], v[18:19]
	v_pk_mul_f32 v[18:19], v[20:21], v[50:51] op_sel_hi:[1,0]
	v_cvt_pk_bf16_f32 v14, v14, v15
	v_mul_f32_e32 v15, 0xbfb8aa3b, v18
	v_exp_f32_e32 v15, v15
	s_mov_b64 s[8:9], -1
	s_andn2_b64 vcc, exec, s[6:7]
	v_add_f32_e32 v15, 1.0, v15
	v_rcp_f32_e32 v20, v15
	v_mul_f32_e32 v15, 0xbfb8aa3b, v19
	v_exp_f32_e32 v15, v15
	s_nop 0
	v_add_f32_e32 v15, 1.0, v15
	v_rcp_f32_e32 v21, v15
	s_nop 0
	v_pk_mul_f32 v[18:19], v[18:19], v[20:21]
	v_pk_mul_f32 v[16:17], v[16:17], v[18:19]
	v_cvt_pk_bf16_f32 v15, v16, v17
	v_mul_f32_e32 v16, 0xbfb8aa3b, v10
	v_mul_f32_e32 v17, 0xbfb8aa3b, v11
	v_exp_f32_e32 v16, v16
	v_exp_f32_e32 v17, v17
	v_add_f32_e32 v16, 1.0, v16
	v_add_f32_e32 v17, 1.0, v17
	v_rcp_f32_e32 v16, v16
	v_rcp_f32_e32 v17, v17
	s_nop 0
	v_pk_mul_f32 v[10:11], v[10:11], v[16:17]
	v_pk_mul_f32 v[6:7], v[6:7], v[10:11]
	v_cvt_pk_bf16_f32 v16, v6, v7
	v_pk_mul_f32 v[6:7], v[12:13], v[50:51] op_sel_hi:[1,0]
	v_mul_f32_e32 v10, 0xbfb8aa3b, v6
	v_mul_f32_e32 v11, 0xbfb8aa3b, v7
	v_exp_f32_e32 v10, v10
	v_exp_f32_e32 v11, v11
	v_add_f32_e32 v10, 1.0, v10
	v_add_f32_e32 v11, 1.0, v11
	v_rcp_f32_e32 v10, v10
	v_rcp_f32_e32 v11, v11
	s_nop 0
	v_pk_mul_f32 v[6:7], v[6:7], v[10:11]
	v_pk_mul_f32 v[6:7], v[8:9], v[6:7]
	v_cvt_pk_bf16_f32 v17, v6, v7
	global_store_dwordx4 v[22:23], v[14:17], off
	s_cbranch_vccnz .LBB0_124
	s_andn2_b64 vcc, exec, s[16:17]
	s_cbranch_vccnz .LBB0_123
	s_barrier
	s_branch .LBB0_123

;     __device__ __forceinline__ void operator()(const f32x4 (&acc)[2][2][4][2], const Unit& u, int wr, int wc, int fr, int fq) const {
;     ...
;             for (int m = 0; m < 4; ++m) { const size_t off = (size_t)(row0 + ai * HALF + m * 16) * ldc + col0; float ss = 0.f;
; #pragma unroll
;                 for (int bj = 0; bj < 2; ++bj)
; #pragma unroll
;                     for (int n = 0; n < 2; ++n) { const f32x4 bs = *(const f32x4*)(base + off + bj * HALF + n * 16); const f32x4 o = bs + acc[ai][bj][m][n] * scale;
;                         *(f32x4*)(out + off + bj * HALF + n * 16) = o;
;                         if (xg) { ss += (o[0] * o[0] + o[1] * o[1]) + (o[2] * o[2] + o[3] * o[3]); const f32x4 og = o * gv[bj][n];
;                             typedef unsigned u32x2v __attribute__((ext_vector_type(2))); u32x2v w; w.x = cvt_pk_bf16(og[0], og[1]); w.y = cvt_pk_bf16(og[2], og[3]); *(u32x2v*)(xg + off + bj * HALF + n * 16) = w; } }
;                 if (xg) { ss += __shfl_xor(ss, 16); ss += __shfl_xor(ss, 32); if (fq == 0) atomicAdd(rowss + row0 + ai * HALF + m * 16, (rowss_t)(ss * 16777216.0f)); } }
.LBB0_286:
	s_mov_b64 s[30:31], 0x58000
	v_lshl_add_u64 v[26:27], v[168:169], 0, s[30:31]
	v_lshlrev_b64 v[24:25], 2, v[26:27]
	v_lshl_add_u64 v[22:23], s[18:19], 0, v[24:25]
	global_load_dwordx4 v[28:31], v[22:23], off
	global_load_dwordx4 v[182:185], v[22:23], off offset:64
	global_load_dwordx4 v[186:189], v[22:23], off offset:512
	global_load_dwordx4 v[190:193], v[22:23], off offset:576
	s_and_b64 vcc, exec, s[10:11]
	v_lshl_add_u64 v[24:25], s[16:17], 0, v[24:25]
	s_mov_b64 s[10:11], -1
	s_waitcnt vmcnt(3) lgkmcnt(0)
	v_pk_fma_f32 v[20:21], v[20:21], 0.5, v[30:31] op_sel_hi:[1,0,1]
	v_pk_fma_f32 v[18:19], v[18:19], 0.5, v[28:29] op_sel_hi:[1,0,1]
	global_store_dwordx4 v[24:25], v[18:21], off
	s_cbranch_vccnz .LBB0_290
	v_pk_mul_f32 v[28:29], v[64:65], v[20:21]
	v_pk_mul_f32 v[30:31], v[62:63], v[18:19]
	v_lshl_add_u64 v[38:39], v[26:27], 1, s[22:23]
	v_cvt_pk_bf16_f32 v30, v30, v31
	v_cvt_pk_bf16_f32 v31, v28, v29
	global_store_dwordx2 v[38:39], v[30:31], off
	v_mul_f32_e32 v19, v19, v19
	v_mul_f32_e32 v21, v21, v21
	v_fmac_f32_e32 v19, v18, v18
	v_fmac_f32_e32 v21, v20, v20
	v_add_f32_e32 v19, v19, v21
	v_and_b32_e32 v41, 64, v218
	v_xor_b32_e32 v40, 16, v218
	v_add_u32_e32 v18, 64, v41
	v_cmp_lt_i32_e32 vcc, v40, v18
	v_xor_b32_e32 v42, 32, v218
	s_waitcnt vmcnt(4) lgkmcnt(0)
	v_pk_fma_f32 v[28:29], v[16:17], 0.5, v[184:185] op_sel_hi:[1,0,1]
	v_pk_fma_f32 v[26:27], v[14:15], 0.5, v[182:183] op_sel_hi:[1,0,1]
	v_pk_mul_f32 v[30:31], v[56:57], v[28:29]
	v_pk_mul_f32 v[32:33], v[54:55], v[26:27]
	global_store_dwordx4 v[24:25], v[26:29], off offset:64
	v_cvt_pk_bf16_f32 v32, v32, v33
	v_cvt_pk_bf16_f32 v33, v30, v31
	global_store_dwordx2 v[38:39], v[32:33], off offset:32
	v_mul_f32_e32 v21, v27, v27
	v_mul_f32_e32 v27, v29, v29
	v_fmac_f32_e32 v21, v26, v26
	v_fmac_f32_e32 v27, v28, v28
	v_add_f32_e32 v21, v21, v27
	v_add_f32_e32 v19, v19, v21
	v_cndmask_b32_e32 v20, v218, v40, vcc
	v_lshlrev_b32_e32 v20, 2, v20
	v_cmp_lt_i32_e32 vcc, v42, v18
	s_waitcnt vmcnt(5) lgkmcnt(0)
	v_pk_fma_f32 v[32:33], v[12:13], 0.5, v[188:189] op_sel_hi:[1,0,1]
	v_pk_fma_f32 v[30:31], v[10:11], 0.5, v[186:187] op_sel_hi:[1,0,1]
	v_pk_mul_f32 v[34:35], v[60:61], v[32:33]
	v_pk_mul_f32 v[36:37], v[58:59], v[30:31]
	global_store_dwordx4 v[24:25], v[30:33], off offset:512
	v_cvt_pk_bf16_f32 v36, v36, v37
	v_cvt_pk_bf16_f32 v37, v34, v35
	global_store_dwordx2 v[38:39], v[36:37], off offset:256
	v_mul_f32_e32 v21, v31, v31
	v_mul_f32_e32 v26, v33, v33
	v_fmac_f32_e32 v21, v30, v30
	v_fmac_f32_e32 v26, v32, v32
	v_add_f32_e32 v21, v21, v26
	v_add_f32_e32 v19, v19, v21
	v_cndmask_b32_e32 v31, v218, v42, vcc
	s_waitcnt vmcnt(6) lgkmcnt(0)
	v_pk_fma_f32 v[28:29], v[8:9], 0.5, v[192:193] op_sel_hi:[1,0,1]
	v_pk_fma_f32 v[26:27], v[6:7], 0.5, v[190:191] op_sel_hi:[1,0,1]
	v_mul_f32_e32 v30, v29, v29
	v_mul_f32_e32 v21, v27, v27
	v_fmac_f32_e32 v21, v26, v26
	v_fmac_f32_e32 v30, v28, v28
	v_add_f32_e32 v21, v21, v30
	v_add_f32_e32 v19, v19, v21
	ds_bpermute_b32 v30, v20, v19
	global_store_dwordx4 v[24:25], v[26:29], off offset:576
	v_pk_mul_f32 v[20:21], v[52:53], v[28:29]
	s_waitcnt lgkmcnt(0)
	v_add_f32_e32 v18, v19, v30
	v_lshlrev_b32_e32 v19, 2, v31
	ds_bpermute_b32 v19, v19, v18
	v_pk_mul_f32 v[26:27], v[50:51], v[26:27]
	v_cvt_pk_bf16_f32 v26, v26, v27
	v_cvt_pk_bf16_f32 v27, v20, v21
	global_store_dwordx2 v[38:39], v[26:27], off offset:288
	s_and_saveexec_b64 s[10:11], s[6:7]
	s_cbranch_execz .LBB0_289
	s_waitcnt lgkmcnt(0)
	v_add_f32_e32 v18, v18, v19
	v_mul_f32_e32 v18, 0x4b800000, v18
	v_trunc_f32_e32 v18, v18
	v_mul_f32_e32 v19, 0x2f800000, v18
	v_floor_f32_e32 v19, v19
	v_fmac_f32_e32 v18, 0xcf800000, v19
	v_cvt_u32_f32_e32 v18, v18
	v_cvt_u32_f32_e32 v19, v19
	v_lshl_add_u64 v[20:21], v[166:167], 3, s[26:27]
	global_atomic_add_x2 v[20:21], v[18:19], off offset:1408

; DI void s5_disc(const S5P& P, int dir, int g, int p, float& lr, float& li, f32x2 (&bb)[16]) {
;     const float dt = expf(P.log_dt[dir * 64 + g]); const float are = P.a_re[(dir * 64 + g) * 64 + p], aim = P.a_im[(dir * 64 + g) * 64 + p];
;     const float mag = expf(dt * are); lr = mag * cosf(dt * aim); li = mag * sinf(dt * aim);
;     const float den = are * are + aim * aim, nr = lr - 1.0f; const float cr = (nr * are + li * aim) / den, ci = (li * are - nr * aim) / den;
;     const f32x4* br = (const f32x4*)(P.b_re + (size_t)(g * 64 + p) * 16); const f32x4* bi = (const f32x4*)(P.b_im + (size_t)(g * 64 + p) * 16);
; #pragma unroll
;     for (int q = 0; q < 4; ++q) { const f32x4 r = br[q], i = bi[q];
; #pragma unroll
;         for (int e = 0; e < 4; ++e) bb[4 * q + e] = (f32x2){cr * r[e] - ci * i[e], cr * i[e] + ci * r[e]}; }
; DI void s5_gen_G(const Ctx& C, const S5P& P, bf16* G) {
;     for (int item = blockIdx.x; item < 128; item += gridDim.x) { const int dir = item & 1, g = item >> 1, p = C.lane;
;         float lr, li; f32x2 bb[16]; s5_disc(P, dir, g, p, lr, li, bb);
;         const int j0 = 16 * C.wave; int e0 = dir ? j0 : 127 - (j0 + 15);
;         float pr = 1.f, pi = 0.f; { float br = lr, bi = li; int n = e0;
.LBB0_375:
	s_or_b64 exec, exec, s[0:1]
	v_mul_f32_e32 v8, v8, v40
	v_mul_f32_e32 v11, 0x3fb8aa3b, v8
	s_mov_b32 s0, 0x3fb8aa3b
	v_fma_f32 v12, v8, s0, -v11
	v_rndne_f32_e32 v14, v11
	v_fmac_f32_e32 v12, 0x32a5705f, v8
	v_sub_f32_e32 v11, v11, v14
	v_add_f32_e32 v11, v11, v12
	v_exp_f32_e32 v11, v11
	v_cvt_i32_f32_e32 v12, v14
	s_mov_b32 s0, 0xc2ce8ed0
	v_cmp_ngt_f32_e32 vcc, s0, v8
	s_mov_b32 s0, 0x42b17218
	v_ldexp_f32 v11, v11, v12
	v_cndmask_b32_e32 v11, 0, v11, vcc
	v_cmp_nlt_f32_e32 vcc, s0, v8
	v_mul_f32_e32 v8, v10, v10
	s_brev_b32 s0, 1
	v_cndmask_b32_e32 v39, v219, v11, vcc
	v_fmamk_f32 v11, v8, 0xb94c1982, v214
	v_fmaak_f32 v11, v8, v11, 0xbe2aaa9d
	v_mul_f32_e32 v11, v8, v11
	v_fmac_f32_e32 v10, v10, v11
	v_fmamk_f32 v11, v8, 0x37d75334, v215
	v_fmaak_f32 v11, v8, v11, 0x3d2aabf7
	v_fmaak_f32 v11, v8, v11, 0xbf000004
	v_fma_f32 v8, v8, v11, 1.0
	v_and_b32_e32 v11, 1, v9
	v_cmp_eq_u32_e32 vcc, 0, v11
	v_lshlrev_b32_e32 v9, 30, v9
	v_readlane_b32 s40, v252, 20
	v_cndmask_b32_e64 v8, -v10, v8, vcc
	v_bitop3_b32 v8, v9, v8, s0 bitop3:0x6c
	v_mul_f32_e32 v9, v13, v13
	v_fmamk_f32 v10, v9, 0xb94c1982, v214
	v_fmaak_f32 v10, v9, v10, 0xbe2aaa9d
	v_mul_f32_e32 v10, v9, v10
	v_fmac_f32_e32 v13, v13, v10
	v_fmamk_f32 v10, v9, 0x37d75334, v215
	v_fmaak_f32 v10, v9, v10, 0x3d2aabf7
	v_fmaak_f32 v10, v9, v10, 0xbf000004
	s_movk_i32 s0, 0x1f8
	v_fma_f32 v9, v9, v10, 1.0
	v_and_b32_e32 v10, 1, v2
	v_lshlrev_b32_e32 v2, 30, v2
	v_cmp_class_f32_e64 vcc, v6, s0
	v_and_b32_e32 v2, 0x80000000, v2
	v_xor_b32_e32 v6, v7, v6
	v_xor_b32_e32 v2, v6, v2
	v_lshl_or_b32 v6, s23, 6, v44
	v_ashrrev_i32_e32 v7, 31, v6
	v_cmp_eq_u32_e64 s[0:1], 0, v10
	v_lshlrev_b64 v[6:7], 6, v[6:7]
	v_readlane_b32 s41, v252, 21
	v_readlane_b32 s42, v252, 22
	v_readlane_b32 s43, v252, 23
	v_cndmask_b32_e32 v8, v222, v8, vcc
	v_cndmask_b32_e64 v9, v9, v13, s[0:1]
	v_lshl_add_u64 v[10:11], s[40:41], 0, v[6:7]
	v_lshl_add_u64 v[34:35], s[42:43], 0, v[6:7]
	v_mul_f32_e32 v152, v39, v8
	v_xor_b32_e32 v2, v2, v9
	v_fma_f32 v38, v39, v8, -1.0
	global_load_dwordx4 v[6:9], v[10:11], off offset:48
	global_load_dwordx4 v[14:17], v[10:11], off offset:32
	global_load_dwordx4 v[22:25], v[10:11], off offset:16
	global_load_dwordx4 v[26:29], v[10:11], off
	s_nop 0
	global_load_dwordx4 v[10:13], v[34:35], off offset:48
	s_waitcnt lgkmcnt(0)
	global_load_dwordx4 v[18:21], v[34:35], off offset:32
	global_load_dwordx4 v[30:33], v[34:35], off offset:16
	s_nop 0
	global_load_dwordx4 v[34:37], v[34:35], off
	v_cndmask_b32_e32 v2, v222, v2, vcc
	v_mul_f32_e32 v39, v39, v2
	v_pk_mul_f32 v[46:47], v[40:41], v[38:39]
	v_mov_b32_e32 v2, v41
	v_add_f32_e32 v45, v46, v47
	v_mov_b32_e32 v46, v38
	v_mov_b32_e32 v47, v41
	v_mov_b32_e32 v48, v39
	v_mov_b32_e32 v49, v40
	v_pk_mul_f32 v[46:47], v[2:3], v[46:47] op_sel_hi:[0,1]
	v_pk_mul_f32 v[40:41], v[40:41], v[48:49] op_sel_hi:[0,1]
	v_add_f32_e32 v38, v41, v47
	v_div_scale_f32 v2, s[8:9], v38, v38, v45
	v_rcp_f32_e32 v41, v2
	v_sub_f32_e32 v40, v40, v46
	v_pk_mul_f32 v[42:43], v[152:153], v[152:153] op_sel_hi:[0,1]
	v_mov_b32_e32 v50, v39
	v_fma_f32 v47, -v2, v41, 1.0
	v_fmac_f32_e32 v41, v47, v41
	v_div_scale_f32 v47, vcc, v45, v38, v45
	v_mul_f32_e32 v48, v47, v41
	v_fma_f32 v49, -v2, v48, v47
	v_fmac_f32_e32 v48, v49, v41
	v_fma_f32 v2, -v2, v48, v47
	v_div_fmas_f32 v2, v2, v41, v48
	v_div_scale_f32 v41, s[8:9], v38, v38, v40
	v_div_fixup_f32 v2, v2, v38, v45
	v_rcp_f32_e32 v45, v41
	v_mov_b32_e32 v51, v153
	s_cmp_eq_u32 s15, 0
	s_cselect_b64 s[0:1], -1, 0
	v_fma_f32 v46, -v41, v45, 1.0
	v_fmac_f32_e32 v45, v46, v45
	v_div_scale_f32 v46, vcc, v40, v38, v40
	v_mul_f32_e32 v47, v46, v45
	v_fma_f32 v48, -v41, v47, v46
	v_fmac_f32_e32 v47, v48, v45
	v_fma_f32 v41, -v41, v47, v46
	v_div_fmas_f32 v41, v41, v45, v47
	v_div_fixup_f32 v38, v41, v38, v40
	s_and_b64 s[8:9], s[0:1], exec
	s_cselect_b32 s10, s22, s21
	s_bitcmp0_b32 s10, 0
	s_cselect_b64 s[8:9], -1, 0
	s_bitcmp0_b32 s10, 1
	s_cselect_b64 vcc, -1, 0
	s_bitcmp0_b32 s10, 2
	s_mov_b64 s[6:7], 0x40000
	s_mov_b32 s10, 15
	s_mov_b32 s11, s20
	v_readlane_b32 s44, v252, 24
	v_readlane_b32 s45, v252, 25
	v_readlane_b32 s46, v252, 26
	v_readlane_b32 s47, v252, 27
	v_readlane_b32 s48, v252, 28
	v_readlane_b32 s49, v252, 29
	v_readlane_b32 s50, v252, 30
	v_readlane_b32 s51, v252, 31
	v_readlane_b32 s52, v252, 32
	v_readlane_b32 s53, v252, 33
	v_readlane_b32 s54, v252, 34
	v_readlane_b32 s55, v252, 35
	s_waitcnt vmcnt(4)
	v_pk_mul_f32 v[46:47], v[26:27], v[38:39] op_sel_hi:[1,0]
	s_waitcnt vmcnt(0)
; DI void s5_disc(const S5P& P, int dir, int g, int p, float& lr, float& li, f32x2 (&bb)[16]) {
;     ...
;     const f32x4* br = (const f32x4*)(P.b_re + (size_t)(g * 64 + p) * 16); const f32x4* bi = (const f32x4*)(P.b_im + (size_t)(g * 64 + p) * 16);
; #pragma unroll
;     for (int q = 0; q < 4; ++q) { const f32x4 r = br[q], i = bi[q];
; #pragma unroll
;         for (int e = 0; e < 4; ++e) bb[4 * q + e] = (f32x2){cr * r[e] - ci * i[e], cr * i[e] + ci * r[e]}; }
; DI void s5_gen_G(const Ctx& C, const S5P& P, bf16* G) {
;     ...
;         float pr = 1.f, pi = 0.f; { float br = lr, bi = li; int n = e0;
; #pragma unroll
;             for (int it = 0; it < 7; ++it) { if (n & 1) { const float t = pr * br - pi * bi; pi = pr * bi + pi * br; pr = t; } const float t2 = br * br - bi * bi; bi = 2.f * br * bi; br = t2; n >>= 1; } }
;         bf16* gre = G + ((size_t)item * 128 + p) * 2048; bf16* gim = gre + (size_t)64 * 2048;
	v_pk_mul_f32 v[40:41], v[34:35], v[38:39] op_sel_hi:[1,0]
	v_pk_fma_f32 v[26:27], v[26:27], v[2:3], v[40:41] op_sel_hi:[1,0,1] neg_lo:[0,0,1] neg_hi:[0,0,1]
	v_pk_fma_f32 v[34:35], v[34:35], v[2:3], v[46:47] op_sel_hi:[1,0,1]
	v_pk_mul_f32 v[40:41], v[36:37], v[38:39] op_sel_hi:[1,0]
	v_pk_mul_f32 v[46:47], v[28:29], v[38:39] op_sel_hi:[1,0]
	v_pk_fma_f32 v[28:29], v[28:29], v[2:3], v[40:41] op_sel_hi:[1,0,1] neg_lo:[0,0,1] neg_hi:[0,0,1]
	v_pk_fma_f32 v[36:37], v[36:37], v[2:3], v[46:47] op_sel_hi:[1,0,1]
	v_pk_mul_f32 v[40:41], v[30:31], v[38:39] op_sel_hi:[1,0]
	v_pk_mul_f32 v[46:47], v[22:23], v[38:39] op_sel_hi:[1,0]
	v_pk_fma_f32 v[22:23], v[22:23], v[2:3], v[40:41] op_sel_hi:[1,0,1] neg_lo:[0,0,1] neg_hi:[0,0,1]
	v_pk_fma_f32 v[30:31], v[30:31], v[2:3], v[46:47] op_sel_hi:[1,0,1]
	v_pk_mul_f32 v[40:41], v[32:33], v[38:39] op_sel_hi:[1,0]
	v_pk_mul_f32 v[46:47], v[24:25], v[38:39] op_sel_hi:[1,0]
	v_pk_fma_f32 v[24:25], v[24:25], v[2:3], v[40:41] op_sel_hi:[1,0,1] neg_lo:[0,0,1] neg_hi:[0,0,1]
	v_pk_fma_f32 v[32:33], v[32:33], v[2:3], v[46:47] op_sel_hi:[1,0,1]
	v_pk_mul_f32 v[40:41], v[18:19], v[38:39] op_sel_hi:[1,0]
	v_pk_mul_f32 v[46:47], v[18:19], v[2:3] op_sel_hi:[1,0]
	v_pk_fma_f32 v[18:19], v[14:15], v[2:3], v[40:41] op_sel_hi:[1,0,1] neg_lo:[0,0,1] neg_hi:[0,0,1]
	v_pk_fma_f32 v[14:15], v[14:15], v[38:39], v[46:47] op_sel_hi:[1,0,1]
	v_pk_mul_f32 v[40:41], v[20:21], v[38:39] op_sel_hi:[1,0]
	v_pk_mul_f32 v[46:47], v[20:21], v[2:3] op_sel_hi:[1,0]
	v_pk_fma_f32 v[20:21], v[16:17], v[2:3], v[40:41] op_sel_hi:[1,0,1] neg_lo:[0,0,1] neg_hi:[0,0,1]
	v_pk_fma_f32 v[16:17], v[16:17], v[38:39], v[46:47] op_sel_hi:[1,0,1]
	v_pk_mul_f32 v[40:41], v[10:11], v[38:39] op_sel_hi:[1,0]
	v_pk_mul_f32 v[46:47], v[10:11], v[2:3] op_sel_hi:[1,0]
	v_pk_fma_f32 v[10:11], v[6:7], v[2:3], v[40:41] op_sel_hi:[1,0,1] neg_lo:[0,0,1] neg_hi:[0,0,1]
	v_pk_fma_f32 v[6:7], v[6:7], v[38:39], v[46:47] op_sel_hi:[1,0,1]
	v_pk_mul_f32 v[40:41], v[12:13], v[38:39] op_sel_hi:[1,0]
	v_pk_mul_f32 v[46:47], v[12:13], v[2:3] op_sel_hi:[1,0]
	v_pk_fma_f32 v[12:13], v[8:9], v[2:3], v[40:41] op_sel_hi:[1,0,1] neg_lo:[0,0,1] neg_hi:[0,0,1]
	v_pk_fma_f32 v[8:9], v[8:9], v[38:39], v[46:47] op_sel_hi:[1,0,1]
	v_mul_f32_e32 v38, v39, v39
	v_pk_fma_f32 v[40:41], v[152:153], v[152:153], v[38:39] op_sel_hi:[0,1,1] neg_lo:[0,0,1] neg_hi:[0,0,1]
	v_pk_mul_f32 v[46:47], v[42:43], v[38:39]
	v_pk_mov_b32 v[42:43], v[42:43], v[40:41] op_sel:[1,0]
	v_mov_b32_e32 v48, v40
	v_pk_mul_f32 v[42:43], v[42:43], v[50:51]
	v_mov_b32_e32 v49, v47
	v_mov_b32_e32 v41, v43
	v_pk_mul_f32 v[40:41], v[48:49], v[40:41]
	v_pk_mul_f32 v[48:49], v[46:47], v[42:43] op_sel:[1,0]
	v_pk_fma_f32 v[42:43], v[46:47], v[42:43], v[40:41] op_sel:[1,0,0] neg_lo:[1,0,0] neg_hi:[1,0,0]
	v_pk_mul_f32 v[46:47], v[40:41], v[48:49]
	v_add_f32_e32 v49, v42, v42
	v_mov_b32_e32 v43, v47
	v_pk_fma_f32 v[42:43], v[42:43], v[42:43], v[46:47] op_sel:[0,0,1] op_sel_hi:[1,1,0] neg_lo:[0,0,1] neg_hi:[0,0,1]
	v_mov_b32_e32 v47, v153
	v_mov_b32_e32 v40, v42
	v_mov_b32_e32 v48, v42
	v_pk_mul_f32 v[40:41], v[40:41], v[48:49]
	s_nop 0
	v_pk_mov_b32 v[42:43], v[40:41], v[42:43] op_sel:[1,0]
	v_mov_b32_e32 v46, v41
	v_pk_mul_f32 v[48:49], v[42:43], v[46:47]
	v_pk_fma_f32 v[42:43], v[42:43], v[46:47], v[40:41] neg_lo:[1,0,0] neg_hi:[1,0,0]
	v_pk_mul_f32 v[40:41], v[40:41], v[48:49]
	v_fmamk_f32 v2, v41, 0x80000000, v42
	v_mov_b32_e32 v43, v41
	v_cndmask_b32_e64 v45, v2, 1.0, s[8:9]
	v_mul_f32_e32 v2, v41, v41
	v_pk_fma_f32 v[46:47], v[42:43], v[42:43], v[2:3] op_sel_hi:[1,1,0] neg_lo:[0,0,1] neg_hi:[0,0,1]
	v_fma_f32 v38, 0, v42, v41
	v_add_f32_e32 v40, v42, v42
	v_mov_b32_e32 v42, v41
	v_mov_b32_e32 v43, v153
	v_mov_b32_e32 v41, v46
	v_cndmask_b32_e64 v38, v38, 0, s[8:9]
	v_pk_mul_f32 v[40:41], v[42:43], v[40:41]
	v_mul_f32_e32 v2, v40, v38
	v_mul_f32_e32 v42, v40, v45
	v_fma_f32 v2, v46, v45, -v2
	v_fmac_f32_e32 v42, v46, v38
	v_cndmask_b32_e32 v38, v42, v38, vcc
	v_cndmask_b32_e32 v42, v2, v45, vcc
	v_mul_f32_e32 v2, v46, v46
	v_fma_f32 v2, -v40, v40, v2
	v_mul_f32_e32 v40, v40, v41
	s_cselect_b64 vcc, -1, 0
	v_mul_f32_e32 v41, v40, v38
	v_mul_f32_e32 v40, v40, v42
	s_ashr_i32 s15, s14, 31
	v_fma_f32 v41, v2, v42, -v41
	v_fmac_f32_e32 v40, v2, v38
	s_lshl_b64 s[8:9], s[14:15], 19
	v_cndmask_b32_e32 v2, v40, v38, vcc
	v_cndmask_b32_e32 v38, v41, v42, vcc
	v_lshl_add_u64 v[40:41], v[0:1], 0, s[8:9]
	v_lshl_add_u64 v[42:43], v[40:41], 0, s[6:7]

; #define LAS __attribute__((address_space(3)))
; DI float logsigmoid_(float x) { return fminf(x, 0.f) - __logf(1.0f + __expf(-fabsf(x))); }
; DI void gla_cum_phase(const Ctx& C, const float* GLR  , const float* w2  , const float* gb  , float* CUM, const bf16* PROJ, bf16* PPG, bf16* QH, bf16* KH) {
;     ...
;         for (int l = 0; l < 64; ++l) { float pre = bias;
; #pragma unroll
;             for (int r4 = 0; r4 < 4; ++r4) { const f32x4 lv = *(const LAS f32x4*)(low + l * 16 + 4 * r4); pre += lv.x * wr[4 * r4] + lv.y * wr[4 * r4 + 1] + lv.z * wr[4 * r4 + 2] + lv.w * wr[4 * r4 + 3]; }
;             cum += logsigmoid_(pre) * 0.0625f; const int li = c * 64 + l; const size_t tok = (size_t)b * SEQ + (dir ? SEQ - 1 - li : li);
;             CUM[((size_t)dir * T + tok) * 512 + tid] = cum; }
.LBB0_511:
	v_mov_b32_e32 v23, s83
	ds_read_b128 v[44:47], v23
	ds_read_b128 v[48:51], v23 offset:16
	ds_read_b128 v[52:55], v23 offset:32
	ds_read_b128 v[56:59], v23 offset:48
	s_add_i32 s89, s81, s87
	s_waitcnt lgkmcnt(0)
	v_mov_b32_e32 v24, v44
	s_waitcnt lgkmcnt(2)
	v_mov_b32_e32 v25, v48
	v_mov_b32_e32 v48, v45
	v_pk_mul_f32 v[44:45], v[8:9], v[48:49]
	v_pk_fma_f32 v[24:25], v[6:7], v[24:25], v[44:45]
	v_mov_b32_e32 v44, v46
	v_mov_b32_e32 v45, v50
	v_pk_fma_f32 v[24:25], v[10:11], v[44:45], v[24:25]
	v_mov_b32_e32 v50, v47
	v_pk_fma_f32 v[24:25], v[12:13], v[50:51], v[24:25]
	v_add_f32_e32 v24, v2, v24
	v_add_f32_e32 v46, v24, v25
	s_waitcnt lgkmcnt(0)
	v_mov_b32_e32 v25, v56
	v_mov_b32_e32 v56, v53
	v_mov_b32_e32 v24, v52
	v_pk_mul_f32 v[44:45], v[16:17], v[56:57]
	v_pk_fma_f32 v[24:25], v[14:15], v[24:25], v[44:45]
	v_mov_b32_e32 v44, v54
	v_mov_b32_e32 v45, v58
	v_pk_fma_f32 v[24:25], v[18:19], v[44:45], v[24:25]
	v_mov_b32_e32 v58, v55
	v_pk_fma_f32 v[24:25], v[20:21], v[58:59], v[24:25]
	v_add_f32_e32 v24, v46, v24
	v_add_f32_e32 v24, v24, v25
	v_min_f32_e32 v25, 0, v24
	v_mul_f32_e64 v24, |v24|, s39
	v_exp_f32_e32 v24, v24
	s_nop 0
	v_add_f32_e32 v24, 1.0, v24
	v_cmp_gt_f32_e64 s[0:1], s4, v24
	s_nop 1
	v_cndmask_b32_e64 v44, 0, 32, s[0:1]
	v_ldexp_f32 v24, v24, v44
	v_log_f32_e32 v24, v24
	s_nop 0
	v_mul_f32_e32 v44, 0x3f317217, v24
	v_fma_f32 v44, v24, s88, -v44
	v_fmac_f32_e32 v44, 0x3377d1cf, v24
	v_fmac_f32_e32 v44, 0x3f317217, v24
	v_cmp_lt_f32_e64 s[26:27], |v24|, s33
	s_nop 1
	v_cndmask_b32_e64 v24, v24, v44, s[26:27]
	s_add_i32 s26, s82, 3
	v_cndmask_b32_e64 v44, 0, v223, s[0:1]
	s_and_b64 s[0:1], vcc, exec
	s_cselect_b32 s0, s89, s26
	s_add_u32 s0, s84, s0
	v_sub_f32_e32 v24, v24, v44
	s_addc_u32 s1, s86, 0
	v_sub_f32_e32 v24, v25, v24
	s_lshl_b64 s[0:1], s[0:1], 11
	v_fmac_f32_e32 v22, 0x3d800000, v24
	v_lshl_add_u64 v[24:25], v[28:29], 0, s[0:1]
	global_store_dword v[24:25], v22, off
	ds_read_b128 v[44:47], v23 offset:64
	ds_read_b128 v[48:51], v23 offset:80
	ds_read_b128 v[52:55], v23 offset:96
	ds_read_b128 v[56:59], v23 offset:112
	s_waitcnt lgkmcnt(0)
	v_mov_b32_e32 v24, v44
	v_mov_b32_e32 v25, v48
	v_mov_b32_e32 v48, v45
	v_pk_mul_f32 v[44:45], v[8:9], v[48:49]
	v_pk_fma_f32 v[24:25], v[6:7], v[24:25], v[44:45]
	v_mov_b32_e32 v44, v46
	v_mov_b32_e32 v45, v50
	v_pk_fma_f32 v[24:25], v[10:11], v[44:45], v[24:25]
	v_mov_b32_e32 v50, v47
	v_pk_fma_f32 v[24:25], v[12:13], v[50:51], v[24:25]
	v_add_f32_e32 v24, v2, v24
	v_add_f32_e32 v46, v24, v25
	v_mov_b32_e32 v25, v56
	v_mov_b32_e32 v56, v53
	v_mov_b32_e32 v24, v52
	v_pk_mul_f32 v[44:45], v[16:17], v[56:57]
	v_pk_fma_f32 v[24:25], v[14:15], v[24:25], v[44:45]
	v_mov_b32_e32 v44, v54
	v_mov_b32_e32 v45, v58
	v_pk_fma_f32 v[24:25], v[18:19], v[44:45], v[24:25]
	v_mov_b32_e32 v58, v55
	v_pk_fma_f32 v[24:25], v[20:21], v[58:59], v[24:25]
	v_add_f32_e32 v24, v46, v24
	v_add_f32_e32 v24, v24, v25
	v_min_f32_e32 v25, 0, v24
	v_mul_f32_e64 v24, |v24|, s39
	v_exp_f32_e32 v24, v24
	s_nop 0
	v_add_f32_e32 v24, 1.0, v24
	v_cmp_gt_f32_e64 s[0:1], s4, v24
	s_nop 1
	v_cndmask_b32_e64 v44, 0, 32, s[0:1]
	v_ldexp_f32 v24, v24, v44
	v_log_f32_e32 v24, v24
	s_nop 0
	v_mul_f32_e32 v44, 0x3f317217, v24
	v_fma_f32 v44, v24, s88, -v44
	v_fmac_f32_e32 v44, 0x3377d1cf, v24
	v_fmac_f32_e32 v44, 0x3f317217, v24
	v_cmp_lt_f32_e64 s[26:27], |v24|, s33
	s_nop 1
	v_cndmask_b32_e64 v24, v24, v44, s[26:27]
	s_add_i32 s26, s89, 1
	s_add_i32 s27, s82, 2
	v_cndmask_b32_e64 v44, 0, v223, s[0:1]
	s_and_b64 s[0:1], vcc, exec
	s_cselect_b32 s0, s26, s27
	s_add_u32 s0, s84, s0
	v_sub_f32_e32 v24, v24, v44
	s_addc_u32 s1, s86, 0
	v_sub_f32_e32 v24, v25, v24
	s_lshl_b64 s[0:1], s[0:1], 11
	v_fmac_f32_e32 v22, 0x3d800000, v24
	v_lshl_add_u64 v[24:25], v[28:29], 0, s[0:1]
	global_store_dword v[24:25], v22, off
	ds_read_b128 v[44:47], v23 offset:128
	ds_read_b128 v[48:51], v23 offset:144
	ds_read_b128 v[52:55], v23 offset:160
	ds_read_b128 v[56:59], v23 offset:176
	s_waitcnt lgkmcnt(0)
; #define LAS __attribute__((address_space(3)))
; DI float logsigmoid_(float x) { return fminf(x, 0.f) - __logf(1.0f + __expf(-fabsf(x))); }
; DI void gla_cum_phase(const Ctx& C, const float* GLR  , const float* w2  , const float* gb  , float* CUM, const bf16* PROJ, bf16* PPG, bf16* QH, bf16* KH) {
;     ...
;         for (int l = 0; l < 64; ++l) { float pre = bias;
; #pragma unroll
;             for (int r4 = 0; r4 < 4; ++r4) { const f32x4 lv = *(const LAS f32x4*)(low + l * 16 + 4 * r4); pre += lv.x * wr[4 * r4] + lv.y * wr[4 * r4 + 1] + lv.z * wr[4 * r4 + 2] + lv.w * wr[4 * r4 + 3]; }
;             cum += logsigmoid_(pre) * 0.0625f; const int li = c * 64 + l; const size_t tok = (size_t)b * SEQ + (dir ? SEQ - 1 - li : li);
;             CUM[((size_t)dir * T + tok) * 512 + tid] = cum; }
;         __syncthreads();
;         constexpr int LQ = 136, LT = 72; const float scale = 0.08838834764831845f;
; #pragma unroll 1
;         for (int h = 0; h < 4; ++h) {
;             const float* cref = CUM + ((size_t)dir * T + TOKOF(c, 31)) * 512 + h * 128;
	v_mov_b32_e32 v24, v44
	v_mov_b32_e32 v25, v48
	v_mov_b32_e32 v48, v45
	v_pk_mul_f32 v[44:45], v[8:9], v[48:49]
	v_pk_fma_f32 v[24:25], v[6:7], v[24:25], v[44:45]
	v_mov_b32_e32 v44, v46
	v_mov_b32_e32 v45, v50
	v_pk_fma_f32 v[24:25], v[10:11], v[44:45], v[24:25]
	v_mov_b32_e32 v50, v47
	v_pk_fma_f32 v[24:25], v[12:13], v[50:51], v[24:25]
	v_add_f32_e32 v24, v2, v24
	v_add_f32_e32 v46, v24, v25
	v_mov_b32_e32 v25, v56
	v_mov_b32_e32 v56, v53
	v_mov_b32_e32 v24, v52
	v_pk_mul_f32 v[44:45], v[16:17], v[56:57]
	v_pk_fma_f32 v[24:25], v[14:15], v[24:25], v[44:45]
	v_mov_b32_e32 v44, v54
	v_mov_b32_e32 v45, v58
	v_pk_fma_f32 v[24:25], v[18:19], v[44:45], v[24:25]
	v_mov_b32_e32 v58, v55
	v_pk_fma_f32 v[24:25], v[20:21], v[58:59], v[24:25]
	v_add_f32_e32 v24, v46, v24
	v_add_f32_e32 v24, v24, v25
	v_min_f32_e32 v25, 0, v24
	v_mul_f32_e64 v24, |v24|, s39
	v_exp_f32_e32 v24, v24
	s_nop 0
	v_add_f32_e32 v24, 1.0, v24
	v_cmp_gt_f32_e64 s[0:1], s4, v24
	s_nop 1
	v_cndmask_b32_e64 v44, 0, 32, s[0:1]
	v_ldexp_f32 v24, v24, v44
	v_log_f32_e32 v24, v24
	s_nop 0
	v_mul_f32_e32 v44, 0x3f317217, v24
	v_fma_f32 v44, v24, s88, -v44
	v_fmac_f32_e32 v44, 0x3377d1cf, v24
	v_fmac_f32_e32 v44, 0x3f317217, v24
	v_cmp_lt_f32_e64 s[26:27], |v24|, s33
	s_nop 1
	v_cndmask_b32_e64 v24, v24, v44, s[26:27]
	s_add_i32 s26, s89, 2
	s_add_i32 s27, s82, 1
	v_cndmask_b32_e64 v44, 0, v223, s[0:1]
	s_and_b64 s[0:1], vcc, exec
	s_cselect_b32 s0, s26, s27
	s_add_u32 s0, s84, s0
	v_sub_f32_e32 v24, v24, v44
	s_addc_u32 s1, s86, 0
	v_sub_f32_e32 v24, v25, v24
	s_lshl_b64 s[0:1], s[0:1], 11
	v_fmac_f32_e32 v22, 0x3d800000, v24
	v_lshl_add_u64 v[24:25], v[28:29], 0, s[0:1]
	global_store_dword v[24:25], v22, off
	ds_read_b128 v[44:47], v23 offset:192
	ds_read_b128 v[48:51], v23 offset:208
	ds_read_b128 v[52:55], v23 offset:224
	ds_read_b128 v[56:59], v23 offset:240
	s_add_i32 s89, s89, 3
	s_waitcnt lgkmcnt(0)
	v_mov_b32_e32 v24, v44
	v_mov_b32_e32 v25, v48
	v_mov_b32_e32 v48, v45
	v_pk_mul_f32 v[44:45], v[8:9], v[48:49]
	v_pk_fma_f32 v[24:25], v[6:7], v[24:25], v[44:45]
	v_mov_b32_e32 v44, v46
	v_mov_b32_e32 v45, v50
	v_pk_fma_f32 v[24:25], v[10:11], v[44:45], v[24:25]
	v_mov_b32_e32 v50, v47
	v_pk_fma_f32 v[24:25], v[12:13], v[50:51], v[24:25]
	v_add_f32_e32 v23, v2, v24
	v_add_f32_e32 v23, v23, v25
	v_mov_b32_e32 v25, v56
	v_mov_b32_e32 v56, v53
	v_mov_b32_e32 v24, v52
	v_pk_mul_f32 v[44:45], v[16:17], v[56:57]
	v_pk_fma_f32 v[24:25], v[14:15], v[24:25], v[44:45]
	v_mov_b32_e32 v44, v54
	v_mov_b32_e32 v45, v58
	v_pk_fma_f32 v[24:25], v[18:19], v[44:45], v[24:25]
	v_mov_b32_e32 v58, v55
	v_pk_fma_f32 v[24:25], v[20:21], v[58:59], v[24:25]
	v_add_f32_e32 v23, v23, v24
	v_add_f32_e32 v23, v23, v25
	v_min_f32_e32 v24, 0, v23
	v_mul_f32_e64 v23, |v23|, s39
	v_exp_f32_e32 v23, v23
	s_nop 0
	v_add_f32_e32 v23, 1.0, v23
	v_cmp_gt_f32_e64 s[0:1], s4, v23
	s_nop 1
	v_cndmask_b32_e64 v25, 0, 32, s[0:1]
	v_ldexp_f32 v23, v23, v25
	v_log_f32_e32 v23, v23
	s_nop 0
	v_mul_f32_e32 v25, 0x3f317217, v23
	v_fma_f32 v25, v23, s88, -v25
	v_fmac_f32_e32 v25, 0x3377d1cf, v23
	v_fmac_f32_e32 v25, 0x3f317217, v23
	v_cmp_lt_f32_e64 s[26:27], |v23|, s33
	s_nop 1
	v_cndmask_b32_e64 v23, v23, v25, s[26:27]
	v_cndmask_b32_e64 v25, 0, v223, s[0:1]
	s_and_b64 s[0:1], vcc, exec
	s_cselect_b32 s0, s89, s82
	s_add_u32 s0, s84, s0
	v_sub_f32_e32 v23, v23, v25
	s_addc_u32 s1, s86, 0
	v_sub_f32_e32 v23, v24, v23
	s_lshl_b64 s[0:1], s[0:1], 11
	s_add_i32 s87, s87, 4
	s_addk_i32 s83, 0x100
	s_add_i32 s82, s82, -4
	v_fmac_f32_e32 v22, 0x3d800000, v23
	v_lshl_add_u64 v[24:25], v[28:29], 0, s[0:1]
	s_cmp_lg_u32 s87, 64
	global_store_dword v[24:25], v22, off
	s_cbranch_scc1 .LBB0_511
	v_cndmask_b32_e64 v2, 0, 1, s[44:45]
	s_and_b32 s0, s80, 0x7f
	v_readfirstlane_b32 s26, v2
	s_lshl_b32 s80, s0, 13
	s_lshl_b32 s81, s0, 6
	s_lshl_b32 s82, s26, 14
	s_xor_b32 s27, s79, 0x1fe0
	s_or_b32 s83, s79, 31
	s_and_b64 s[0:1], vcc, exec
	s_cselect_b32 s83, s83, s27
	s_xor_b32 s27, s79, 0x1fc0
	s_or_b32 s84, s79, 63
	s_and_b64 s[0:1], vcc, exec
	s_cselect_b32 s84, s84, s27
	s_lshl_b32 s0, s46, 3
	s_xor_b32 s1, s79, 0x1fff
	v_sub_u32_e32 v2, s1, v30
	v_add_u32_e32 v6, s79, v30
	s_or_b32 s0, s0, s26
	v_cndmask_b32_e32 v6, v2, v6, vcc
	v_sub_u32_e32 v2, s1, v34
	s_ashr_i32 s1, s0, 31
	s_lshl_b64 s[26:27], s[0:1], 20
	s_lshl_b64 s[0:1], s[0:1], 13
	s_or_b32 s0, s0, s81
	v_lshl_add_u64 v[10:11], s[0:1], 0, v[34:35]
	s_or_b32 s26, s26, s80
	v_lshlrev_b64 v[46:47], 8, v[10:11]
	v_lshl_add_u64 v[10:11], s[0:1], 0, v[30:31]
	s_lshl_b64 s[0:1], s[46:47], 26
	v_lshlrev_b64 v[48:49], 8, v[10:11]
	v_or_b32_e32 v10, s0, v40
	s_add_u32 s0, s82, s48
	v_mov_b32_e32 v11, s1
	s_addc_u32 s1, s49, 0
	v_add_u32_e32 v8, s79, v34
	v_lshl_add_u64 v[44:45], s[26:27], 0, v[38:39]
	s_add_u32 s26, s0, s84
	v_cndmask_b32_e32 v8, v2, v8, vcc
	s_addc_u32 s27, s1, 0
	v_ashrrev_i32_e32 v9, 31, v8
	s_lshl_b64 s[26:27], s[26:27], 11
	v_ashrrev_i32_e32 v7, 31, v6
	v_lshlrev_b64 v[12:13], 13, v[8:9]
	v_or_b32_e32 v54, s26, v42
	s_add_u32 s26, s0, s83
	v_lshl_add_u64 v[50:51], v[10:11], 0, v[12:13]
	v_lshlrev_b64 v[12:13], 13, v[6:7]
	v_mov_b32_e32 v55, s27
	s_addc_u32 s27, s1, 0
	v_lshl_add_u64 v[8:9], s[0:1], 0, v[8:9]
	v_lshl_add_u64 v[6:7], s[0:1], 0, v[6:7]
	s_lshl_b64 s[26:27], s[26:27], 11
	v_lshlrev_b64 v[58:59], 11, v[8:9]
	v_lshlrev_b64 v[60:61], 11, v[6:7]
	v_or_b32_e32 v46, v40, v46
	v_or_b32_e32 v48, v40, v48
	v_lshl_add_u64 v[52:53], v[10:11], 0, v[12:13]
	v_mov_b32_e32 v57, s27
	v_or_b32_e32 v56, s26, v42
	v_or_b32_e32 v58, v42, v58
	v_or_b32_e32 v60, v42, v60
	s_mov_b32 s26, 4
	s_mov_b32 s86, 0x800000
	s_mov_b32 s4, 0x1f000000
	s_mov_b32 s5, 0x1b000000
	s_mov_b32 s6, 0x1d000000
	s_mov_b32 s82, 0xf000000
	s_mov_b64 s[8:9], 0x200
	s_mov_b64 s[80:81], 0x2000
	v_readlane_b32 s83, v253, 8
	s_waitcnt lgkmcnt(0)
	s_barrier
	s_branch .LBB0_514

; DI void gla_cum_phase(const Ctx& C, const float* GLR  , const float* w2  , const float* gb  , float* CUM, const bf16* PROJ, bf16* PPG, bf16* QH, bf16* KH) {
;     ...
;             for (int i = 0; i < 2; ++i) { const int idx = tid + NTHR * i, row = idx >> 4, cc = idx & 15, d0 = 8 * cc; const size_t tok = TOKOF(c, row);
;                 const v4u qv = *(const v4u*)(PROJ + tok * CD_N + h * 128 + d0), kv = *(const v4u*)(PROJ + tok * CD_N + 512 + h * 128 + d0);
;                 const float* cp = CUM + ((size_t)dir * T + tok) * 512 + h * 128 + d0;
;                 const f32x4 c0 = *(const f32x4*)cp, c1 = *(const f32x4*)(cp + 4), r0 = *(const f32x4*)(cref + d0), r1 = *(const f32x4*)(cref + d0 + 4);
;                 float q[8] = {bflo(qv.x), bfhi(qv.x), bflo(qv.y), bfhi(qv.y), bflo(qv.z), bfhi(qv.z), bflo(qv.w), bfhi(qv.w)};
;                 float k[8] = {bflo(kv.x), bfhi(kv.x), bflo(kv.y), bfhi(kv.y), bflo(kv.z), bfhi(kv.z), bflo(kv.w), bfhi(kv.w)};
;                 float cu[8] = {c0.x, c0.y, c0.z, c0.w, c1.x, c1.y, c1.z, c1.w}, cr[8] = {r0.x, r0.y, r0.z, r0.w, r1.x, r1.y, r1.z, r1.w};
;                 float qt[8], kt[8];
; #pragma unroll
;                 for (int e = 0; e < 8; ++e) { qt[e] = q[e] * scale * __expf(cu[e] - cr[e]); kt[e] = k[e] * __expf(cr[e] - cu[e]); }
;                 {
;                     const f32x4 t0 = *(const f32x4*)(ctot + d0), t1 = *(const f32x4*)(ctot + d0 + 4); const float ct[8] = {t0.x, t0.y, t0.z, t0.w, t1.x, t1.y, t1.z, t1.w};
;                     float qh[8], kh[8];
; #pragma unroll
;                     for (int e = 0; e < 8; ++e) { qh[e] = q[e] * scale * __expf(cu[e]); kh[e] = k[e] * __expf(ct[e] - cu[e]); }
;                     const size_t go = (((size_t)chain_ * 128 + c) * 64 + row) * 128 + d0;
;                     v4u o2; o2.x = pk2(qh[0], qh[1]); o2.y = pk2(qh[2], qh[3]); o2.z = pk2(qh[4], qh[5]); o2.w = pk2(qh[6], qh[7]); *(v4u*)(QH + go) = o2;
;                     o2.x = pk2(kh[0], kh[1]); o2.y = pk2(kh[2], kh[3]); o2.z = pk2(kh[4], kh[5]); o2.w = pk2(kh[6], kh[7]); *(v4u*)(KH + go) = o2; }
;                 v4u o; o.x = pk2(qt[0], qt[1]); o.y = pk2(qt[2], qt[3]); o.z = pk2(qt[4], qt[5]); o.w = pk2(qt[6], qt[7]); *(LAS v4u*)(Qt + row * LQ + d0) = o;
;                 o.x = pk2(kt[0], kt[1]); o.y = pk2(kt[2], kt[3]); o.z = pk2(kt[4], kt[5]); o.w = pk2(kt[6], kt[7]); *(LAS v4u*)(Kt + row * LQ + d0) = o; }
.LBB0_514:
	s_nop 0
	v_lshl_add_u64 v[6:7], s[34:35], 0, v[52:53]
	v_add_co_u32_e32 v10, vcc, 0x13000000, v6
	v_lshl_add_u64 v[24:25], s[34:35], 0, v[56:57]
	s_nop 0
	v_addc_co_u32_e32 v11, vcc, 0, v7, vcc
	global_load_dwordx4 v[6:9], v[10:11], off
	global_load_dwordx4 v[20:23], v[10:11], off offset:1024
	v_lshl_add_u64 v[10:11], s[34:35], 0, v[60:61]
	v_add_co_u32_e32 v10, vcc, 0x1f000000, v10
	v_lshl_add_u64 v[18:19], s[34:35], 0, v[54:55]
	s_nop 0
	v_addc_co_u32_e32 v11, vcc, 0, v11, vcc
	v_add_co_u32_e32 v64, vcc, 0x1f000000, v24
	global_load_dwordx4 v[14:17], v[10:11], off
	s_nop 0
	global_load_dwordx4 v[10:13], v[10:11], off offset:16
	v_addc_co_u32_e32 v65, vcc, 0, v25, vcc
	global_load_dwordx4 v[68:71], v[64:65], off
	global_load_dwordx4 v[92:95], v[64:65], off offset:16
	v_add_co_u32_e32 v62, vcc, s4, v18
	s_mov_b32 s0, 0x13000000
	s_nop 0
	v_addc_co_u32_e32 v63, vcc, 0, v19, vcc
	s_waitcnt vmcnt(0) lgkmcnt(0)
	v_lshlrev_b32_e32 v90, 16, v20
	v_and_b32_e32 v89, 0xffff0000, v20
	v_lshlrev_b32_e32 v88, 16, v21
	v_and_b32_e32 v87, 0xffff0000, v21
	v_lshlrev_b32_e32 v86, 16, v22
	v_and_b32_e32 v85, 0xffff0000, v22
	v_lshlrev_b32_e32 v84, 16, v23
	v_and_b32_e32 v77, 0xffff0000, v23
	v_mul_f32_e32 v91, 0x3fb8aa3b, v14
	v_sub_f32_e32 v20, v15, v69
	v_mul_f32_e32 v20, 0x3fb8aa3b, v20
	v_exp_f32_e32 v78, v20
	v_sub_f32_e32 v20, v69, v15
	v_mul_f32_e32 v20, 0x3fb8aa3b, v20
	v_exp_f32_e32 v20, v20
	v_sub_f32_e32 v2, v14, v68
	v_mul_f32_e32 v2, 0x3fb8aa3b, v2
	v_exp_f32_e32 v75, v2
	v_sub_f32_e32 v2, v68, v14
	v_mul_f32_e32 v68, v20, v89
	v_sub_f32_e32 v20, v16, v70
	v_mul_f32_e32 v20, 0x3fb8aa3b, v20
	v_exp_f32_e32 v76, v20
	v_sub_f32_e32 v20, v70, v16
	v_mul_f32_e32 v20, 0x3fb8aa3b, v20
	v_exp_f32_e32 v20, v20
	v_mul_f32_e32 v2, 0x3fb8aa3b, v2
	v_exp_f32_e32 v2, v2
	v_mul_f32_e32 v69, v20, v88
	v_sub_f32_e32 v20, v17, v71
	v_mul_f32_e32 v20, 0x3fb8aa3b, v20
	v_exp_f32_e32 v80, v20
	v_sub_f32_e32 v20, v71, v17
	v_mul_f32_e32 v20, 0x3fb8aa3b, v20
	v_exp_f32_e32 v20, v20
	v_mul_f32_e32 v2, v2, v90
	v_mul_f32_e32 v70, v20, v87
	v_sub_f32_e32 v20, v10, v92
	v_mul_f32_e32 v20, 0x3fb8aa3b, v20
	v_exp_f32_e32 v79, v20
	v_sub_f32_e32 v20, v92, v10
	v_mul_f32_e32 v20, 0x3fb8aa3b, v20
	v_exp_f32_e32 v20, v20
	v_exp_f32_e32 v92, v91
	v_mul_f32_e32 v71, v20, v86
	v_sub_f32_e32 v20, v11, v93
	v_mul_f32_e32 v20, 0x3fb8aa3b, v20
	v_exp_f32_e32 v82, v20
	v_sub_f32_e32 v20, v93, v11
	v_mul_f32_e32 v20, 0x3fb8aa3b, v20
	v_exp_f32_e32 v20, v20
	s_nop 0
	v_mul_f32_e32 v72, v20, v85
	v_sub_f32_e32 v20, v12, v94
	v_mul_f32_e32 v20, 0x3fb8aa3b, v20
	v_exp_f32_e32 v81, v20
	v_sub_f32_e32 v20, v94, v12
	v_mul_f32_e32 v20, 0x3fb8aa3b, v20
	v_exp_f32_e32 v20, v20
	s_nop 0
	v_mul_f32_e32 v73, v20, v84
	v_sub_f32_e32 v20, v13, v95
	v_mul_f32_e32 v20, 0x3fb8aa3b, v20
	v_exp_f32_e32 v83, v20
	v_sub_f32_e32 v20, v95, v13
	v_mul_f32_e32 v20, 0x3fb8aa3b, v20
	v_exp_f32_e32 v20, v20
	s_nop 0
	v_mul_f32_e32 v74, v20, v77
	global_load_dwordx4 v[22:25], v[62:63], off
	global_load_dwordx4 v[18:21], v[62:63], off offset:16
	s_waitcnt vmcnt(0) lgkmcnt(0)
	v_sub_f32_e32 v14, v22, v14
	v_mul_f32_e32 v14, 0x3fb8aa3b, v14
	v_exp_f32_e32 v14, v14
	s_nop 0
	v_mul_f32_e32 v22, v14, v90
	v_mul_f32_e32 v14, 0x3fb8aa3b, v15
	v_exp_f32_e32 v93, v14
	v_sub_f32_e32 v14, v23, v15
	v_mul_f32_e32 v14, 0x3fb8aa3b, v14
	v_exp_f32_e32 v14, v14
	v_sub_f32_e32 v15, v24, v16
	v_mul_f32_e32 v15, 0x3fb8aa3b, v15
	v_exp_f32_e32 v15, v15
	v_mul_f32_e32 v23, v14, v89
	v_mul_f32_e32 v14, 0x3fb8aa3b, v16
	v_sub_f32_e32 v16, v25, v17
	v_mul_f32_e32 v16, 0x3fb8aa3b, v16
	v_exp_f32_e32 v16, v16
	v_mul_f32_e32 v24, v15, v88
	v_mul_f32_e32 v15, 0x3fb8aa3b, v17
	v_exp_f32_e32 v14, v14
	v_mul_f32_e32 v25, v16, v87
	v_mul_f32_e32 v16, 0x3fb8aa3b, v10
	v_sub_f32_e32 v10, v18, v10
	v_mul_f32_e32 v10, 0x3fb8aa3b, v10
	v_exp_f32_e32 v10, v10
	v_exp_f32_e32 v15, v15
	v_exp_f32_e32 v16, v16
	v_mul_f32_e32 v18, v10, v86
	v_mul_f32_e32 v10, 0x3fb8aa3b, v11
	v_exp_f32_e32 v17, v10
	v_sub_f32_e32 v10, v19, v11
	v_mul_f32_e32 v10, 0x3fb8aa3b, v10
	v_exp_f32_e32 v10, v10
	v_sub_f32_e32 v11, v20, v12
	v_mul_f32_e32 v11, 0x3fb8aa3b, v11
	v_exp_f32_e32 v11, v11
	v_mul_f32_e32 v19, v10, v85
	v_mul_f32_e32 v10, 0x3fb8aa3b, v12
	v_sub_f32_e32 v12, v21, v13
	v_mul_f32_e32 v12, 0x3fb8aa3b, v12
	v_exp_f32_e32 v12, v12
	v_mul_f32_e32 v20, v11, v84
	v_mul_f32_e32 v11, 0x3fb8aa3b, v13
	v_and_b32_e32 v13, 0xffff0000, v6
	v_mul_f32_e32 v21, v12, v77
	v_lshlrev_b32_e32 v12, 16, v6
	v_pk_mul_f32 v[12:13], v[12:13], s[38:39] op_sel_hi:[1,0]
	v_exp_f32_e32 v10, v10
	v_mul_f32_e32 v75, v12, v75
	v_mul_f32_e32 v77, v13, v78
	v_pk_mul_f32 v[12:13], v[12:13], v[92:93]
	v_exp_f32_e32 v11, v11
	v_cvt_pk_bf16_f32 v6, v12, v13
	v_lshlrev_b32_e32 v12, 16, v7
	v_and_b32_e32 v13, 0xffff0000, v7
	v_pk_mul_f32 v[12:13], v[12:13], s[38:39] op_sel_hi:[1,0]
	v_mul_f32_e32 v76, v12, v76
	v_mul_f32_e32 v78, v13, v80
	v_pk_mul_f32 v[12:13], v[12:13], v[14:15]
	v_cvt_pk_bf16_f32 v7, v12, v13
	v_lshlrev_b32_e32 v12, 16, v8
	v_and_b32_e32 v13, 0xffff0000, v8
	v_pk_mul_f32 v[12:13], v[12:13], s[38:39] op_sel_hi:[1,0]
	v_mul_f32_e32 v14, v12, v79
	v_mul_f32_e32 v15, v13, v82
	v_pk_mul_f32 v[12:13], v[12:13], v[16:17]
	v_cvt_pk_bf16_f32 v8, v12, v13
	v_lshlrev_b32_e32 v12, 16, v9
	v_and_b32_e32 v13, 0xffff0000, v9
	v_pk_mul_f32 v[12:13], v[12:13], s[38:39] op_sel_hi:[1,0]
	v_pk_mul_f32 v[10:11], v[12:13], v[10:11]
	v_mul_f32_e32 v16, v12, v81
	v_cvt_pk_bf16_f32 v9, v10, v11
	v_lshl_add_u64 v[10:11], s[34:35], 0, v[48:49]
	v_add_co_u32_e32 v12, vcc, s5, v10
	v_mul_f32_e32 v17, v13, v83
	s_nop 0
	v_addc_co_u32_e32 v13, vcc, 0, v11, vcc
	v_add_co_u32_e32 v10, vcc, s6, v10
	global_store_dwordx4 v[12:13], v[6:9], off
	s_nop 0
	v_addc_co_u32_e32 v11, vcc, 0, v11, vcc
	v_cvt_pk_bf16_f32 v6, v22, v23
	v_cvt_pk_bf16_f32 v7, v24, v25
	v_cvt_pk_bf16_f32 v8, v18, v19
	v_cvt_pk_bf16_f32 v9, v20, v21
	global_store_dwordx4 v[10:11], v[6:9], off
	s_nop 1
	v_cvt_pk_bf16_f32 v6, v75, v77
	v_cvt_pk_bf16_f32 v7, v76, v78
	v_cvt_pk_bf16_f32 v8, v14, v15
	v_cvt_pk_bf16_f32 v9, v16, v17
	ds_write_b128 v32, v[6:9] offset:4096
	v_cvt_pk_bf16_f32 v6, v2, v68
	v_cvt_pk_bf16_f32 v7, v69, v70
	v_cvt_pk_bf16_f32 v8, v71, v72
	v_cvt_pk_bf16_f32 v9, v73, v74
	ds_write_b128 v32, v[6:9] offset:21504
	v_lshl_add_u64 v[6:7], s[34:35], 0, v[50:51]
	v_add_co_u32_e32 v10, vcc, s0, v6
	s_mov_b64 s[0:1], -1
	s_nop 0
	v_addc_co_u32_e32 v11, vcc, 0, v7, vcc
	global_load_dwordx4 v[6:9], v[10:11], off
	global_load_dwordx4 v[18:21], v[10:11], off offset:1024
	v_lshl_add_u64 v[10:11], s[34:35], 0, v[58:59]
	v_add_co_u32_e32 v10, vcc, s4, v10
	s_waitcnt vmcnt(0) lgkmcnt(0)
; DI void gla_cum_phase(const Ctx& C, const float* GLR  , const float* w2  , const float* gb  , float* CUM, const bf16* PROJ, bf16* PPG, bf16* QH, bf16* KH) {
;     ...
;             for (int i = 0; i < 2; ++i) { const int idx = tid + NTHR * i, row = idx >> 4, cc = idx & 15, d0 = 8 * cc; const size_t tok = TOKOF(c, row);
;                 const v4u qv = *(const v4u*)(PROJ + tok * CD_N + h * 128 + d0), kv = *(const v4u*)(PROJ + tok * CD_N + 512 + h * 128 + d0);
;                 const float* cp = CUM + ((size_t)dir * T + tok) * 512 + h * 128 + d0;
;                 const f32x4 c0 = *(const f32x4*)cp, c1 = *(const f32x4*)(cp + 4), r0 = *(const f32x4*)(cref + d0), r1 = *(const f32x4*)(cref + d0 + 4);
;                 float q[8] = {bflo(qv.x), bfhi(qv.x), bflo(qv.y), bfhi(qv.y), bflo(qv.z), bfhi(qv.z), bflo(qv.w), bfhi(qv.w)};
;                 float k[8] = {bflo(kv.x), bfhi(kv.x), bflo(kv.y), bfhi(kv.y), bflo(kv.z), bfhi(kv.z), bflo(kv.w), bfhi(kv.w)};
;                 float cu[8] = {c0.x, c0.y, c0.z, c0.w, c1.x, c1.y, c1.z, c1.w}, cr[8] = {r0.x, r0.y, r0.z, r0.w, r1.x, r1.y, r1.z, r1.w};
;                 float qt[8], kt[8];
; #pragma unroll
;                 for (int e = 0; e < 8; ++e) { qt[e] = q[e] * scale * __expf(cu[e] - cr[e]); kt[e] = k[e] * __expf(cr[e] - cu[e]); }
;                 {
;                     const f32x4 t0 = *(const f32x4*)(ctot + d0), t1 = *(const f32x4*)(ctot + d0 + 4); const float ct[8] = {t0.x, t0.y, t0.z, t0.w, t1.x, t1.y, t1.z, t1.w};
;                     float qh[8], kh[8];
; #pragma unroll
;                     for (int e = 0; e < 8; ++e) { qh[e] = q[e] * scale * __expf(cu[e]); kh[e] = k[e] * __expf(ct[e] - cu[e]); }
;                     const size_t go = (((size_t)chain_ * 128 + c) * 64 + row) * 128 + d0;
;                     v4u o2; o2.x = pk2(qh[0], qh[1]); o2.y = pk2(qh[2], qh[3]); o2.z = pk2(qh[4], qh[5]); o2.w = pk2(qh[6], qh[7]); *(v4u*)(QH + go) = o2;
;                     o2.x = pk2(kh[0], kh[1]); o2.y = pk2(kh[2], kh[3]); o2.z = pk2(kh[4], kh[5]); o2.w = pk2(kh[6], kh[7]); *(v4u*)(KH + go) = o2; }
;                 v4u o; o.x = pk2(qt[0], qt[1]); o.y = pk2(qt[2], qt[3]); o.z = pk2(qt[4], qt[5]); o.w = pk2(qt[6], qt[7]); *(LAS v4u*)(Qt + row * LQ + d0) = o;
;                 o.x = pk2(kt[0], kt[1]); o.y = pk2(kt[2], kt[3]); o.z = pk2(kt[4], kt[5]); o.w = pk2(kt[6], kt[7]); *(LAS v4u*)(Kt + row * LQ + d0) = o; }
	v_lshlrev_b32_e32 v88, 16, v18
	v_addc_co_u32_e32 v11, vcc, 0, v11, vcc
	global_load_dwordx4 v[14:17], v[10:11], off
	s_nop 0
	global_load_dwordx4 v[10:13], v[10:11], off offset:16
	s_nop 0
	global_load_dwordx4 v[22:25], v[64:65], off
	global_load_dwordx4 v[90:93], v[64:65], off offset:16
	v_and_b32_e32 v87, 0xffff0000, v18
	v_lshlrev_b32_e32 v86, 16, v19
	v_and_b32_e32 v85, 0xffff0000, v19
	v_lshlrev_b32_e32 v84, 16, v20
	v_and_b32_e32 v83, 0xffff0000, v20
	v_lshlrev_b32_e32 v82, 16, v21
	v_and_b32_e32 v74, 0xffff0000, v21
	s_waitcnt vmcnt(0) lgkmcnt(0)
	v_sub_f32_e32 v18, v15, v23
	v_mul_f32_e32 v18, 0x3fb8aa3b, v18
	v_exp_f32_e32 v76, v18
	v_sub_f32_e32 v18, v23, v15
	v_mul_f32_e32 v18, 0x3fb8aa3b, v18
	v_exp_f32_e32 v18, v18
	v_sub_f32_e32 v2, v14, v22
	v_mul_f32_e32 v2, 0x3fb8aa3b, v2
	v_exp_f32_e32 v73, v2
	v_mul_f32_e32 v64, v18, v87
	v_sub_f32_e32 v18, v16, v24
	v_mul_f32_e32 v18, 0x3fb8aa3b, v18
	v_exp_f32_e32 v75, v18
	v_sub_f32_e32 v18, v24, v16
	v_mul_f32_e32 v18, 0x3fb8aa3b, v18
	v_exp_f32_e32 v18, v18
	v_sub_f32_e32 v2, v22, v14
	v_mul_f32_e32 v2, 0x3fb8aa3b, v2
	v_exp_f32_e32 v2, v2
	v_mul_f32_e32 v65, v18, v86
	v_sub_f32_e32 v18, v17, v25
	v_mul_f32_e32 v18, 0x3fb8aa3b, v18
	v_exp_f32_e32 v78, v18
	v_sub_f32_e32 v18, v25, v17
	v_mul_f32_e32 v18, 0x3fb8aa3b, v18
	v_exp_f32_e32 v18, v18
	v_mul_f32_e32 v2, v2, v88
	v_mul_f32_e32 v68, v18, v85
	v_sub_f32_e32 v18, v10, v90
	v_mul_f32_e32 v18, 0x3fb8aa3b, v18
	v_exp_f32_e32 v77, v18
	v_sub_f32_e32 v18, v90, v10
	v_mul_f32_e32 v18, 0x3fb8aa3b, v18
	v_exp_f32_e32 v18, v18
	s_nop 0
	v_mul_f32_e32 v69, v18, v84
	v_sub_f32_e32 v18, v11, v91
	v_mul_f32_e32 v18, 0x3fb8aa3b, v18
	v_exp_f32_e32 v80, v18
	v_sub_f32_e32 v18, v91, v11
	v_mul_f32_e32 v18, 0x3fb8aa3b, v18
	v_exp_f32_e32 v18, v18
	s_nop 0
	v_mul_f32_e32 v70, v18, v83
	v_sub_f32_e32 v18, v12, v92
	v_mul_f32_e32 v18, 0x3fb8aa3b, v18
	v_exp_f32_e32 v79, v18
	v_sub_f32_e32 v18, v92, v12
	v_mul_f32_e32 v18, 0x3fb8aa3b, v18
	v_exp_f32_e32 v18, v18
	s_nop 0
	v_mul_f32_e32 v71, v18, v82
	v_sub_f32_e32 v18, v13, v93
	v_mul_f32_e32 v18, 0x3fb8aa3b, v18
	v_exp_f32_e32 v81, v18
	v_sub_f32_e32 v18, v93, v13
	v_mul_f32_e32 v18, 0x3fb8aa3b, v18
	v_exp_f32_e32 v18, v18
	s_nop 0
	v_mul_f32_e32 v72, v18, v74
	global_load_dwordx4 v[22:25], v[62:63], off
	global_load_dwordx4 v[18:21], v[62:63], off offset:16
	v_mul_f32_e32 v62, 0x3fb8aa3b, v14
	v_exp_f32_e32 v62, v62
	s_waitcnt vmcnt(0) lgkmcnt(0)
	v_sub_f32_e32 v14, v22, v14
	v_mul_f32_e32 v14, 0x3fb8aa3b, v14
	v_exp_f32_e32 v14, v14
	s_nop 0
	v_mul_f32_e32 v22, v14, v88
	v_mul_f32_e32 v14, 0x3fb8aa3b, v15
	v_exp_f32_e32 v63, v14
	v_sub_f32_e32 v14, v23, v15
	v_mul_f32_e32 v14, 0x3fb8aa3b, v14
	v_exp_f32_e32 v14, v14
	v_sub_f32_e32 v15, v24, v16
	v_mul_f32_e32 v15, 0x3fb8aa3b, v15
	v_exp_f32_e32 v15, v15
	v_mul_f32_e32 v23, v14, v87
	v_mul_f32_e32 v14, 0x3fb8aa3b, v16
	v_sub_f32_e32 v16, v25, v17
	v_mul_f32_e32 v16, 0x3fb8aa3b, v16
	v_exp_f32_e32 v16, v16
	v_mul_f32_e32 v24, v15, v86
	v_mul_f32_e32 v15, 0x3fb8aa3b, v17
	v_exp_f32_e32 v14, v14
	v_mul_f32_e32 v25, v16, v85
	v_mul_f32_e32 v16, 0x3fb8aa3b, v10
	v_sub_f32_e32 v10, v18, v10
	v_mul_f32_e32 v10, 0x3fb8aa3b, v10
	v_exp_f32_e32 v10, v10
	v_exp_f32_e32 v15, v15
	v_exp_f32_e32 v16, v16
	v_mul_f32_e32 v18, v10, v84
	v_mul_f32_e32 v10, 0x3fb8aa3b, v11
	v_exp_f32_e32 v17, v10
	v_sub_f32_e32 v10, v19, v11
	v_mul_f32_e32 v10, 0x3fb8aa3b, v10
	v_exp_f32_e32 v10, v10
	v_sub_f32_e32 v11, v20, v12
	v_mul_f32_e32 v11, 0x3fb8aa3b, v11
	v_exp_f32_e32 v11, v11
	v_mul_f32_e32 v19, v10, v83
	v_mul_f32_e32 v10, 0x3fb8aa3b, v12
	v_sub_f32_e32 v12, v21, v13
	v_mul_f32_e32 v12, 0x3fb8aa3b, v12
	v_exp_f32_e32 v12, v12
	v_mul_f32_e32 v20, v11, v82
	v_mul_f32_e32 v11, 0x3fb8aa3b, v13
	v_and_b32_e32 v13, 0xffff0000, v6
	v_mul_f32_e32 v21, v12, v74
	v_lshlrev_b32_e32 v12, 16, v6
	v_pk_mul_f32 v[12:13], v[12:13], s[38:39] op_sel_hi:[1,0]
	v_exp_f32_e32 v10, v10
	v_mul_f32_e32 v73, v12, v73
	v_mul_f32_e32 v74, v13, v76
	v_pk_mul_f32 v[12:13], v[12:13], v[62:63]
	v_exp_f32_e32 v11, v11
	v_cvt_pk_bf16_f32 v6, v12, v13
	v_lshlrev_b32_e32 v12, 16, v7
	v_and_b32_e32 v13, 0xffff0000, v7
	v_pk_mul_f32 v[12:13], v[12:13], s[38:39] op_sel_hi:[1,0]
	v_mul_f32_e32 v62, v12, v75
	v_mul_f32_e32 v63, v13, v78
	v_pk_mul_f32 v[12:13], v[12:13], v[14:15]
	v_cvt_pk_bf16_f32 v7, v12, v13
	v_lshlrev_b32_e32 v12, 16, v8
	v_and_b32_e32 v13, 0xffff0000, v8
	v_pk_mul_f32 v[12:13], v[12:13], s[38:39] op_sel_hi:[1,0]
	v_mul_f32_e32 v14, v12, v77
	v_mul_f32_e32 v15, v13, v80
	v_pk_mul_f32 v[12:13], v[12:13], v[16:17]
	v_cvt_pk_bf16_f32 v8, v12, v13
	v_lshlrev_b32_e32 v12, 16, v9
	v_and_b32_e32 v13, 0xffff0000, v9
	v_pk_mul_f32 v[12:13], v[12:13], s[38:39] op_sel_hi:[1,0]
	v_pk_mul_f32 v[10:11], v[12:13], v[10:11]
	v_mul_f32_e32 v16, v12, v79
	v_cvt_pk_bf16_f32 v9, v10, v11
	v_lshl_add_u64 v[10:11], s[34:35], 0, v[46:47]
	v_add_co_u32_e32 v12, vcc, s5, v10
	v_mul_f32_e32 v17, v13, v81
	s_nop 0
	v_addc_co_u32_e32 v13, vcc, 0, v11, vcc
	v_add_co_u32_e32 v10, vcc, s6, v10
	global_store_dwordx4 v[12:13], v[6:9], off
	s_nop 0
	v_addc_co_u32_e32 v11, vcc, 0, v11, vcc
	v_cvt_pk_bf16_f32 v6, v22, v23
	v_cvt_pk_bf16_f32 v7, v24, v25
	v_cvt_pk_bf16_f32 v8, v18, v19
	v_cvt_pk_bf16_f32 v9, v20, v21
	global_store_dwordx4 v[10:11], v[6:9], off
	s_and_b64 vcc, exec, s[40:41]
	s_nop 0
	v_cvt_pk_bf16_f32 v6, v73, v74
	v_cvt_pk_bf16_f32 v7, v62, v63
	v_cvt_pk_bf16_f32 v8, v14, v15
	v_cvt_pk_bf16_f32 v9, v16, v17
	ds_write_b128 v36, v[6:9] offset:4096
	v_cvt_pk_bf16_f32 v6, v2, v64
	v_cvt_pk_bf16_f32 v7, v65, v68
	v_cvt_pk_bf16_f32 v8, v69, v70
	v_cvt_pk_bf16_f32 v9, v71, v72
	ds_write_b128 v36, v[6:9] offset:21504
	s_waitcnt lgkmcnt(0)
	s_barrier
	s_cbranch_vccz .LBB0_518
	ds_read_b128 v[6:9], v1 offset:4096
	v_add_u32_e32 v2, s70, v27
	ds_read_b128 v[10:13], v2 offset:21504
	s_waitcnt lgkmcnt(0)
	v_mfma_f32_16x16x32_bf16 v[6:9], v[6:9], v[10:13], 0
	ds_read_b128 v[10:13], v1 offset:4160
	ds_read_b128 v[14:17], v2 offset:21568
	s_waitcnt lgkmcnt(0)
	v_mfma_f32_16x16x32_bf16 v[6:9], v[10:13], v[14:17], v[6:9]
	ds_read_b128 v[10:13], v1 offset:4224
	ds_read_b128 v[14:17], v2 offset:21632
	s_waitcnt lgkmcnt(0)
	v_mfma_f32_16x16x32_bf16 v[6:9], v[10:13], v[14:17], v[6:9]
	ds_read_b128 v[10:13], v1 offset:4288
	ds_read_b128 v[14:17], v2 offset:21696
	s_waitcnt lgkmcnt(0)
	v_mfma_f32_16x16x32_bf16 v[6:9], v[10:13], v[14:17], v[6:9]
	s_nop 7
	v_cvt_pk_bf16_f32 v2, v6, s0
	v_cndmask_b32_e64 v2, v2, 0, s[54:55]
	ds_write_b16 v37, v2 offset:38912
	v_cvt_pk_bf16_f32 v2, v7, s0
	v_cndmask_b32_e64 v2, v2, 0, s[72:73]
	ds_write_b16 v37, v2 offset:39056
	v_cvt_pk_bf16_f32 v2, v8, s0
	v_cndmask_b32_e64 v2, v2, 0, s[74:75]
	ds_write_b16 v37, v2 offset:39200
	v_cvt_pk_bf16_f32 v2, v9, s0
	v_cndmask_b32_e64 v2, v2, 0, s[76:77]
	ds_write_b16 v37, v2 offset:39344
	s_cbranch_execz .LBB0_519

; template <int DIRN> DI void s5_dir(const S5P& P, const f32x2* END, const LAS float* UF, LAS bf16* XT, int b, int seg, int g, const bf16x8 (&bfr)[4], f32x4 (&acc)[8], int lane) {
;     ...
; #pragma unroll 8
;         for (int j = 0; j < sl; ++j) { const float* ep = (const float*)END + ((size_t)((b * 2 + DIRN) * SNSEG + j)) * 8192 + g * 128 + lane; const f32x2 e = {ep[0], ep[64]}; const float nr = Lr * xr - Li * xi + e.x, ni = Lr * xi + Li * xr + e.y; xr = nr; xi = ni; } }
.LBB0_617:
	global_load_dword v184, v[80:81], off
	global_load_dword v185, v[80:81], off offset:256
	v_add_co_u32_e32 v80, vcc, 0x8000, v80
	s_nop 1
	v_addc_co_u32_e32 v81, vcc, 0, v81, vcc
	global_load_dword v186, v[80:81], off
	global_load_dword v187, v[80:81], off offset:256
	v_add_co_u32_e32 v80, vcc, 0x8000, v80
	s_nop 1
	v_addc_co_u32_e32 v81, vcc, 0, v81, vcc
	global_load_dword v188, v[80:81], off
	global_load_dword v189, v[80:81], off offset:256
	v_add_co_u32_e32 v80, vcc, 0x8000, v80
	s_nop 1
	v_addc_co_u32_e32 v81, vcc, 0, v81, vcc
	global_load_dword v190, v[80:81], off
	global_load_dword v191, v[80:81], off offset:256
	v_add_co_u32_e32 v80, vcc, 0x8000, v80
	s_nop 1
	v_addc_co_u32_e32 v81, vcc, 0, v81, vcc
	global_load_dword v192, v[80:81], off
	global_load_dword v193, v[80:81], off offset:256
	v_add_co_u32_e32 v80, vcc, 0x8000, v80
	s_nop 1
	v_addc_co_u32_e32 v81, vcc, 0, v81, vcc
	global_load_dword v194, v[80:81], off
	global_load_dword v195, v[80:81], off offset:256
	v_add_co_u32_e32 v80, vcc, 0x8000, v80
	s_nop 1
	v_addc_co_u32_e32 v81, vcc, 0, v81, vcc
	global_load_dword v196, v[80:81], off
	global_load_dword v197, v[80:81], off offset:256
	v_add_co_u32_e32 v80, vcc, 0x8000, v80
	s_nop 1
	v_addc_co_u32_e32 v81, vcc, 0, v81, vcc
	global_load_dword v198, v[80:81], off
	global_load_dword v199, v[80:81], off offset:256
	v_add_co_u32_e32 v80, vcc, 0x8000, v80
	s_nop 1
	v_addc_co_u32_e32 v81, vcc, 0, v81, vcc
	s_add_i32 s1, s1, 8
	v_pk_mul_f32 v[84:85], v[74:75], v[174:175] op_sel:[0,1] op_sel_hi:[1,0]
	v_pk_fma_f32 v[88:89], v[76:77], v[174:175], v[84:85]
	v_pk_fma_f32 v[82:83], v[76:77], v[174:175], v[84:85] neg_lo:[0,0,1] neg_hi:[0,0,1]
	v_mov_b32_e32 v83, v89
	s_waitcnt vmcnt(14) lgkmcnt(0)
	v_pk_add_f32 v[174:175], v[82:83], v[184:185]
	v_pk_mul_f32 v[84:85], v[74:75], v[174:175] op_sel:[0,1] op_sel_hi:[1,0]
	v_pk_fma_f32 v[88:89], v[76:77], v[174:175], v[84:85]
	v_pk_fma_f32 v[82:83], v[76:77], v[174:175], v[84:85] neg_lo:[0,0,1] neg_hi:[0,0,1]
	v_mov_b32_e32 v83, v89
	s_waitcnt vmcnt(12)
	v_pk_add_f32 v[174:175], v[82:83], v[186:187]
	v_pk_mul_f32 v[84:85], v[74:75], v[174:175] op_sel:[0,1] op_sel_hi:[1,0]
	v_pk_fma_f32 v[88:89], v[76:77], v[174:175], v[84:85]
	v_pk_fma_f32 v[82:83], v[76:77], v[174:175], v[84:85] neg_lo:[0,0,1] neg_hi:[0,0,1]
	v_mov_b32_e32 v83, v89
	s_waitcnt vmcnt(10)
	v_pk_add_f32 v[174:175], v[82:83], v[188:189]
	v_pk_mul_f32 v[84:85], v[74:75], v[174:175] op_sel:[0,1] op_sel_hi:[1,0]
	v_pk_fma_f32 v[88:89], v[76:77], v[174:175], v[84:85]
	v_pk_fma_f32 v[82:83], v[76:77], v[174:175], v[84:85] neg_lo:[0,0,1] neg_hi:[0,0,1]
	v_mov_b32_e32 v83, v89
	s_waitcnt vmcnt(8)
	v_pk_add_f32 v[174:175], v[82:83], v[190:191]
	v_pk_mul_f32 v[84:85], v[74:75], v[174:175] op_sel:[0,1] op_sel_hi:[1,0]
	v_pk_fma_f32 v[88:89], v[76:77], v[174:175], v[84:85]
	v_pk_fma_f32 v[82:83], v[76:77], v[174:175], v[84:85] neg_lo:[0,0,1] neg_hi:[0,0,1]
	v_mov_b32_e32 v83, v89
	s_waitcnt vmcnt(6)
	v_pk_add_f32 v[174:175], v[82:83], v[192:193]
	v_pk_mul_f32 v[84:85], v[74:75], v[174:175] op_sel:[0,1] op_sel_hi:[1,0]
	v_pk_fma_f32 v[88:89], v[76:77], v[174:175], v[84:85]
	v_pk_fma_f32 v[82:83], v[76:77], v[174:175], v[84:85] neg_lo:[0,0,1] neg_hi:[0,0,1]
	v_mov_b32_e32 v83, v89
	s_waitcnt vmcnt(4)
	v_pk_add_f32 v[174:175], v[82:83], v[194:195]
	v_pk_mul_f32 v[84:85], v[74:75], v[174:175] op_sel:[0,1] op_sel_hi:[1,0]
	v_pk_fma_f32 v[88:89], v[76:77], v[174:175], v[84:85]
	v_pk_fma_f32 v[82:83], v[76:77], v[174:175], v[84:85] neg_lo:[0,0,1] neg_hi:[0,0,1]
	v_mov_b32_e32 v83, v89
	s_waitcnt vmcnt(2)
	v_pk_add_f32 v[174:175], v[82:83], v[196:197]
	v_pk_mul_f32 v[84:85], v[74:75], v[174:175] op_sel:[0,1] op_sel_hi:[1,0]
	v_pk_fma_f32 v[88:89], v[76:77], v[174:175], v[84:85]
	v_pk_fma_f32 v[82:83], v[76:77], v[174:175], v[84:85] neg_lo:[0,0,1] neg_hi:[0,0,1]
	v_mov_b32_e32 v83, v89
	s_waitcnt vmcnt(0)
	v_pk_add_f32 v[174:175], v[82:83], v[198:199]
	s_cmp_eq_u32 s11, s1
	s_cbranch_scc0 .LBB0_617
	s_bfe_u32 s1, s30, 0x30006
	s_cmp_eq_u32 s1, 0
	s_cbranch_scc0 .LBB0_620
	s_branch .LBB0_622

; #define LAS __attribute__((address_space(3)))
; DI unsigned pk2(float lo, float hi) { return pg8::cvt_pk_bf16(lo, hi); }
; DI f32x4 mfma16(bf16x8 a, bf16x8 b, f32x4 c) { return __builtin_amdgcn_mfma_f32_16x16x32_bf16(a, b, c, 0, 0, 0); }
; template <int DIRN, int SUB> DI void s5_subtile(const LAS float* UF, LAS bf16* XT, float lr, float li, const f32x2 (&bb)[16], f32x2& x,
;                                                 const bf16x8 (&bfr)[4], f32x4& acc0, f32x4& acc1, int lane) {
;     ...
;     for (int i = 0; i < 32; ++i) { const int r = DIRN ? 31 - i : i;
;         x = s5_step((const LAS f32x4*)(UF + (32 * SUB + r) * 16), bb, lr, li, x);
;         const unsigned pkd = pk2(x.x, x.y); XT[r * 136 + lane] = (bf16)(pkd & 0xffffu); XT[r * 136 + 64 + lane] = (bf16)(pkd >> 16); }
; #pragma unroll
;     for (int ks = 0; ks < 4; ++ks) { const bf16x8 a0 = *(const LAS bf16x8*)(XT + (lane & 15) * 136 + 32 * ks + 8 * (lane >> 4)), a1 = *(const LAS bf16x8*)(XT + (16 + (lane & 15)) * 136 + 32 * ks + 8 * (lane >> 4));
;         acc0 = mfma16(a0, bfr[ks], acc0); acc1 = mfma16(a1, bfr[ks], acc1); }
.LBB0_623:
	s_add_i32 s1, s49, s0
	v_mov_b32_e32 v2, s1
	ds_read_b128 v[72:75], v2
	ds_read_b128 v[76:79], v2 offset:16
	ds_read_b128 v[80:83], v2 offset:32
	ds_read_b128 v[84:87], v2 offset:48
	s_waitcnt lgkmcnt(3)
	v_pk_mul_f32 v[88:89], v[180:181], v[72:73] op_sel:[0,1]
	v_pk_fma_f32 v[72:73], v[178:179], v[72:73], v[88:89] op_sel_hi:[1,0,1]
	v_mov_b32_e32 v2, v75
	v_pk_fma_f32 v[72:73], v[182:183], v[74:75], v[72:73] op_sel_hi:[1,0,1]
	s_waitcnt lgkmcnt(1)
	v_pk_mul_f32 v[74:75], v[196:197], v[80:81] op_sel:[0,1]
	v_pk_fma_f32 v[72:73], v[184:185], v[2:3], v[72:73] op_sel_hi:[1,0,1]
	v_pk_fma_f32 v[72:73], v[186:187], v[76:77], v[72:73] op_sel_hi:[1,0,1]
	v_pk_fma_f32 v[74:75], v[194:195], v[80:81], v[74:75] op_sel_hi:[1,0,1]
	v_pk_fma_f32 v[72:73], v[188:189], v[76:77], v[72:73] op_sel:[0,1,0]
	v_pk_fma_f32 v[74:75], v[198:199], v[82:83], v[74:75] op_sel_hi:[1,0,1]
	v_pk_fma_f32 v[72:73], v[190:191], v[78:79], v[72:73] op_sel_hi:[1,0,1]
	v_pk_fma_f32 v[72:73], v[192:193], v[78:79], v[72:73] op_sel:[0,1,0]
	v_pk_fma_f32 v[74:75], v[200:201], v[82:83], v[74:75] op_sel:[0,1,0]
	s_waitcnt lgkmcnt(0)
	v_pk_fma_f32 v[74:75], v[202:203], v[84:85], v[74:75] op_sel_hi:[1,0,1]
	v_pk_fma_f32 v[74:75], v[204:205], v[84:85], v[74:75] op_sel:[0,1,0]
	v_pk_fma_f32 v[74:75], v[206:207], v[86:87], v[74:75] op_sel_hi:[1,0,1]
	v_pk_fma_f32 v[74:75], v[176:177], v[86:87], v[74:75] op_sel:[0,1,0]
	v_pk_add_f32 v[72:73], v[72:73], v[74:75]
	v_pk_fma_f32 v[72:73], v[128:129], v[174:175], v[72:73] op_sel:[0,1,0] op_sel_hi:[1,0,1]
	v_pk_fma_f32 v[174:175], v[126:127], v[174:175], v[72:73]
	v_add_u32_e32 v72, s49, v1
	v_cvt_pk_bf16_f32 v2, v174, s0
	v_cvt_pk_bf16_f32 v71, v175, s0
	s_add_i32 s0, s0, 64
	v_add_u32_e32 v1, 0x110, v1
	s_cmpk_lg_i32 s0, 0x800
	ds_write_b16 v72, v2
	ds_write_b16 v72, v71 offset:128
	s_cbranch_scc1 .LBB0_623
	v_and_b32_e32 v125, 15, v122
	v_mul_u32_u24_e32 v1, 0x110, v125
	v_lshlrev_b32_e32 v2, 1, v70
	v_add3_u32 v1, s49, v1, v2
	ds_read_b128 v[98:101], v1 offset:8192
	ds_read_b128 v[94:97], v1 offset:8256
	ds_read_b128 v[82:85], v1 offset:12544
	ds_read_b128 v[86:89], v1 offset:12608
	ds_read_b128 v[90:93], v1 offset:8320
	ds_read_b128 v[78:81], v1 offset:8384
	ds_read_b128 v[70:73], v1 offset:12672
	ds_read_b128 v[74:77], v1 offset:12736
	v_add_u32_e32 v2, s40, v152
	s_mov_b32 s0, 0
	v_mov_b32_e32 v102, v2
.LBB0_625:
	s_add_i32 s1, s41, s0
	v_mov_b32_e32 v103, s1
	ds_read_b128 v[104:107], v103
	ds_read_b128 v[108:111], v103 offset:16
	ds_read_b128 v[112:115], v103 offset:32
	ds_read_b128 v[116:119], v103 offset:48
	s_waitcnt lgkmcnt(3)
	v_pk_mul_f32 v[120:121], v[180:181], v[104:105] op_sel:[0,1]
	v_pk_fma_f32 v[104:105], v[178:179], v[104:105], v[120:121] op_sel_hi:[1,0,1]
	v_pk_fma_f32 v[104:105], v[182:183], v[106:107], v[104:105] op_sel_hi:[1,0,1]
	v_pk_fma_f32 v[104:105], v[184:185], v[106:107], v[104:105] op_sel:[0,1,0]
	s_waitcnt lgkmcnt(2)
	v_pk_fma_f32 v[104:105], v[186:187], v[108:109], v[104:105] op_sel_hi:[1,0,1]
	v_pk_fma_f32 v[104:105], v[188:189], v[108:109], v[104:105] op_sel:[0,1,0]
	s_waitcnt lgkmcnt(1)
	v_pk_fma_f32 v[104:105], v[190:191], v[110:111], v[104:105] op_sel_hi:[1,0,1]
	v_pk_fma_f32 v[104:105], v[192:193], v[110:111], v[104:105] op_sel:[0,1,0]
	v_pk_mul_f32 v[106:107], v[196:197], v[112:113] op_sel:[0,1]
	v_pk_fma_f32 v[106:107], v[194:195], v[112:113], v[106:107] op_sel_hi:[1,0,1]
	v_pk_fma_f32 v[106:107], v[198:199], v[114:115], v[106:107] op_sel_hi:[1,0,1]
	v_pk_fma_f32 v[106:107], v[200:201], v[114:115], v[106:107] op_sel:[0,1,0]
	s_waitcnt lgkmcnt(0)
	v_mov_b32_e32 v108, v119
	v_pk_fma_f32 v[106:107], v[202:203], v[116:117], v[106:107] op_sel_hi:[1,0,1]
	v_pk_fma_f32 v[106:107], v[204:205], v[116:117], v[106:107] op_sel:[0,1,0]
	v_pk_fma_f32 v[106:107], v[206:207], v[118:119], v[106:107] op_sel_hi:[1,0,1]
	v_pk_fma_f32 v[106:107], v[176:177], v[108:109], v[106:107] op_sel_hi:[1,0,1]
	v_pk_add_f32 v[104:105], v[104:105], v[106:107]
	v_pk_fma_f32 v[104:105], v[128:129], v[174:175], v[104:105] op_sel:[0,1,0] op_sel_hi:[1,0,1]
	v_pk_fma_f32 v[174:175], v[126:127], v[174:175], v[104:105]
	v_cvt_pk_bf16_f32 v103, v174, s0
	v_cvt_pk_bf16_f32 v104, v175, s0
	s_add_i32 s0, s0, 64
	ds_write_b16 v102, v103
	ds_write_b16 v102, v104 offset:128
	v_add_u32_e32 v102, 0x110, v102
	s_cmpk_lg_i32 s0, 0x800
	s_cbranch_scc1 .LBB0_625
	v_cvt_pk_bf16_f32 v46, v46, v47
	v_cvt_pk_bf16_f32 v47, v48, v49
	v_cvt_pk_bf16_f32 v48, v66, v67
	v_cvt_pk_bf16_f32 v49, v68, v69
	v_cvt_pk_bf16_f32 v54, v54, v55
	v_cvt_pk_bf16_f32 v55, v56, v57
	v_cvt_pk_bf16_f32 v57, v52, v53
	v_cvt_pk_bf16_f32 v52, -v58, -v59
	v_cvt_pk_bf16_f32 v53, -v60, -v61
	v_mfma_f32_16x16x32_bf16 v[58:61], v[98:101], v[46:49], 0
	v_cvt_pk_bf16_f32 v56, v50, v51
	v_cvt_pk_bf16_f32 v50, -v62, -v63
	v_cvt_pk_bf16_f32 v51, -v64, -v65
	v_mfma_f32_16x16x32_bf16 v[58:61], v[94:97], v[54:57], v[58:61]
	s_mov_b32 s0, 0
	v_mov_b32_e32 v110, v2
	v_mfma_f32_16x16x32_bf16 v[90:93], v[90:93], v[50:53], v[58:61]
	v_mfma_f32_16x16x32_bf16 v[58:61], v[82:85], v[46:49], 0
	v_mfma_f32_16x16x32_bf16 v[58:61], v[86:89], v[54:57], v[58:61]
	ds_read_b128 v[94:97], v1 offset:8192
	ds_read_b128 v[86:89], v1 offset:12544
	ds_read_b128 v[98:101], v1 offset:8256
	ds_read_b128 v[102:105], v1 offset:12608
	ds_read_b128 v[106:109], v1 offset:8320
	ds_read_b128 v[66:69], v1 offset:12672
	ds_read_b128 v[62:65], v1 offset:8384
	ds_read_b128 v[82:85], v1 offset:12736
; #define LAS __attribute__((address_space(3)))
; DI unsigned pk2(float lo, float hi) { return pg8::cvt_pk_bf16(lo, hi); }
; DI f32x4 mfma16(bf16x8 a, bf16x8 b, f32x4 c) { return __builtin_amdgcn_mfma_f32_16x16x32_bf16(a, b, c, 0, 0, 0); }
; template <int DIRN, int SUB> DI void s5_subtile(const LAS float* UF, LAS bf16* XT, float lr, float li, const f32x2 (&bb)[16], f32x2& x,
;                                                 const bf16x8 (&bfr)[4], f32x4& acc0, f32x4& acc1, int lane) {
;     ...
;     for (int i = 0; i < 32; ++i) { const int r = DIRN ? 31 - i : i;
;         x = s5_step((const LAS f32x4*)(UF + (32 * SUB + r) * 16), bb, lr, li, x);
;         const unsigned pkd = pk2(x.x, x.y); XT[r * 136 + lane] = (bf16)(pkd & 0xffffu); XT[r * 136 + 64 + lane] = (bf16)(pkd >> 16); }
; #pragma unroll
;     for (int ks = 0; ks < 4; ++ks) { const bf16x8 a0 = *(const LAS bf16x8*)(XT + (lane & 15) * 136 + 32 * ks + 8 * (lane >> 4)), a1 = *(const LAS bf16x8*)(XT + (16 + (lane & 15)) * 136 + 32 * ks + 8 * (lane >> 4));
;         acc0 = mfma16(a0, bfr[ks], acc0); acc1 = mfma16(a1, bfr[ks], acc1); }
.LBB0_627:
	s_add_i32 s1, s42, s0
	v_mov_b32_e32 v111, s1
	ds_read_b128 v[112:115], v111
	ds_read_b128 v[116:119], v111 offset:16
	ds_read_b128 v[230:233], v111 offset:32
	ds_read_b128 v[234:237], v111 offset:48
	s_waitcnt lgkmcnt(3)
	v_pk_mul_f32 v[120:121], v[180:181], v[112:113] op_sel:[0,1]
	v_pk_fma_f32 v[112:113], v[178:179], v[112:113], v[120:121] op_sel_hi:[1,0,1]
	v_pk_fma_f32 v[112:113], v[182:183], v[114:115], v[112:113] op_sel_hi:[1,0,1]
	v_pk_fma_f32 v[112:113], v[184:185], v[114:115], v[112:113] op_sel:[0,1,0]
	s_waitcnt lgkmcnt(2)
	v_pk_fma_f32 v[112:113], v[186:187], v[116:117], v[112:113] op_sel_hi:[1,0,1]
	v_pk_fma_f32 v[112:113], v[188:189], v[116:117], v[112:113] op_sel:[0,1,0]
	s_waitcnt lgkmcnt(1)
	v_pk_fma_f32 v[112:113], v[190:191], v[118:119], v[112:113] op_sel_hi:[1,0,1]
	v_pk_fma_f32 v[112:113], v[192:193], v[118:119], v[112:113] op_sel:[0,1,0]
	v_pk_mul_f32 v[114:115], v[196:197], v[230:231] op_sel:[0,1]
	v_pk_fma_f32 v[114:115], v[194:195], v[230:231], v[114:115] op_sel_hi:[1,0,1]
	v_pk_fma_f32 v[114:115], v[198:199], v[232:233], v[114:115] op_sel_hi:[1,0,1]
	v_pk_fma_f32 v[114:115], v[200:201], v[232:233], v[114:115] op_sel:[0,1,0]
	s_waitcnt lgkmcnt(0)
	v_mov_b32_e32 v116, v237
	v_pk_fma_f32 v[114:115], v[202:203], v[234:235], v[114:115] op_sel_hi:[1,0,1]
	v_pk_fma_f32 v[114:115], v[204:205], v[234:235], v[114:115] op_sel:[0,1,0]
	v_pk_fma_f32 v[114:115], v[206:207], v[236:237], v[114:115] op_sel_hi:[1,0,1]
	v_pk_fma_f32 v[114:115], v[176:177], v[116:117], v[114:115] op_sel_hi:[1,0,1]
	v_pk_add_f32 v[112:113], v[112:113], v[114:115]
	v_pk_fma_f32 v[112:113], v[128:129], v[174:175], v[112:113] op_sel:[0,1,0] op_sel_hi:[1,0,1]
	v_pk_fma_f32 v[174:175], v[126:127], v[174:175], v[112:113]
	v_cvt_pk_bf16_f32 v111, v174, s0
	v_cvt_pk_bf16_f32 v112, v175, s0
	s_add_i32 s0, s0, 64
	ds_write_b16 v110, v111
	ds_write_b16 v110, v112 offset:128
	v_add_u32_e32 v110, 0x110, v110
	s_cmpk_lg_i32 s0, 0x800
	s_cbranch_scc1 .LBB0_627
	v_cvt_pk_bf16_f32 v42, -v42, -v43
	v_cvt_pk_bf16_f32 v43, -v44, -v45
	v_cvt_pk_bf16_f32 v44, -v38, -v39
	v_cvt_pk_bf16_f32 v45, -v40, -v41
	v_mfma_f32_16x16x32_bf16 v[86:89], v[86:89], v[46:49], 0
	s_mov_b32 s0, 0
	v_mfma_f32_16x16x32_bf16 v[38:41], v[78:81], v[42:45], v[90:93]
	v_mfma_f32_16x16x32_bf16 v[78:81], v[94:97], v[46:49], 0
	v_mfma_f32_16x16x32_bf16 v[78:81], v[98:101], v[54:57], v[78:81]
	v_mfma_f32_16x16x32_bf16 v[78:81], v[106:109], v[50:53], v[78:81]
	v_mfma_f32_16x16x32_bf16 v[86:89], v[102:105], v[54:57], v[86:89]
	ds_read_b128 v[94:97], v1 offset:8192
	ds_read_b128 v[90:93], v1 offset:12544
	ds_read_b128 v[102:105], v1 offset:8256
	ds_read_b128 v[98:101], v1 offset:12608
	ds_read_b128 v[110:113], v1 offset:8320
	ds_read_b128 v[106:109], v1 offset:12672
	ds_read_b128 v[118:121], v1 offset:8384
	ds_read_b128 v[114:117], v1 offset:12736
.LBB0_629:
	s_add_i32 s1, s43, s0
	v_mov_b32_e32 v158, s1
	ds_read_b128 v[230:233], v158
	ds_read_b128 v[234:237], v158 offset:16
	ds_read_b128 v[238:241], v158 offset:32
	ds_read_b128 v[242:245], v158 offset:48
	s_waitcnt lgkmcnt(3)
	v_pk_mul_f32 v[158:159], v[180:181], v[230:231] op_sel:[0,1]
	v_pk_fma_f32 v[158:159], v[178:179], v[230:231], v[158:159] op_sel_hi:[1,0,1]
	v_pk_fma_f32 v[158:159], v[182:183], v[232:233], v[158:159] op_sel_hi:[1,0,1]
	s_waitcnt lgkmcnt(1)
	v_pk_fma_f32 v[158:159], v[184:185], v[232:233], v[158:159] op_sel:[0,1,0]
	v_pk_fma_f32 v[158:159], v[186:187], v[234:235], v[158:159] op_sel_hi:[1,0,1]
	v_pk_fma_f32 v[158:159], v[188:189], v[234:235], v[158:159] op_sel:[0,1,0]
	v_pk_fma_f32 v[158:159], v[190:191], v[236:237], v[158:159] op_sel_hi:[1,0,1]
	v_pk_fma_f32 v[158:159], v[192:193], v[236:237], v[158:159] op_sel:[0,1,0]
	v_pk_mul_f32 v[160:161], v[196:197], v[238:239] op_sel:[0,1]
	v_pk_fma_f32 v[160:161], v[194:195], v[238:239], v[160:161] op_sel_hi:[1,0,1]
	v_pk_fma_f32 v[160:161], v[198:199], v[240:241], v[160:161] op_sel_hi:[1,0,1]
	v_pk_fma_f32 v[160:161], v[200:201], v[240:241], v[160:161] op_sel:[0,1,0]
	s_waitcnt lgkmcnt(0)
	v_mov_b32_e32 v230, v245
	v_pk_fma_f32 v[160:161], v[202:203], v[242:243], v[160:161] op_sel_hi:[1,0,1]
	v_pk_fma_f32 v[160:161], v[204:205], v[242:243], v[160:161] op_sel:[0,1,0]
	v_pk_fma_f32 v[160:161], v[206:207], v[244:245], v[160:161] op_sel_hi:[1,0,1]
	v_pk_fma_f32 v[160:161], v[176:177], v[230:231], v[160:161] op_sel_hi:[1,0,1]
	v_pk_add_f32 v[158:159], v[158:159], v[160:161]
	v_pk_fma_f32 v[158:159], v[128:129], v[174:175], v[158:159] op_sel:[0,1,0] op_sel_hi:[1,0,1]
	v_pk_fma_f32 v[174:175], v[126:127], v[174:175], v[158:159]
	v_cvt_pk_bf16_f32 v158, v174, s0
	v_cvt_pk_bf16_f32 v159, v175, s0
	s_add_i32 s0, s0, 64
	ds_write_b16 v2, v158
	ds_write_b16 v2, v159 offset:128
	v_add_u32_e32 v2, 0x110, v2
	s_cmpk_eq_i32 s0, 0x800
	s_cbranch_scc0 .LBB0_629
; DI f32x4 mfma16(bf16x8 a, bf16x8 b, f32x4 c) { return __builtin_amdgcn_mfma_f32_16x16x32_bf16(a, b, c, 0, 0, 0); }
; DI void s5_disc(const S5P& P, int dir, int g, int p, float& lr, float& li, f32x2 (&bb)[16]) {
;     const float dt = expf(P.log_dt[dir * 64 + g]); const float are = P.a_re[(dir * 64 + g) * 64 + p], aim = P.a_im[(dir * 64 + g) * 64 + p];
;     const float mag = expf(dt * are); lr = mag * cosf(dt * aim); li = mag * sinf(dt * aim);
; template <int DIRN, int SUB> DI void s5_subtile(const LAS float* UF, LAS bf16* XT, float lr, float li, const f32x2 (&bb)[16], f32x2& x,
;                                                 const bf16x8 (&bfr)[4], f32x4& acc0, f32x4& acc1, int lane) {
;     ...
;         acc0 = mfma16(a0, bfr[ks], acc0); acc1 = mfma16(a1, bfr[ks], acc1); }
	v_mfma_f32_16x16x32_bf16 v[58:61], v[70:73], v[50:53], v[58:61]
	v_readlane_b32 s72, v252, 4
	v_readlane_b32 s84, v252, 16
	v_readlane_b32 s85, v252, 17
	v_mfma_f32_16x16x32_bf16 v[66:69], v[66:69], v[50:53], v[86:89]
	v_readlane_b32 s82, v252, 14
	v_readlane_b32 s83, v252, 15
	s_mov_b32 s0, 0x3fb8aa3b
	v_mfma_f32_16x16x32_bf16 v[62:65], v[62:65], v[42:45], v[78:81]
	v_readlane_b32 s73, v252, 5
	v_readlane_b32 s74, v252, 6
	v_readlane_b32 s75, v252, 7
	v_mfma_f32_16x16x32_bf16 v[58:61], v[74:77], v[42:45], v[58:61]
	v_readlane_b32 s76, v252, 8
	v_readlane_b32 s77, v252, 9
	v_readlane_b32 s78, v252, 10
	v_mfma_f32_16x16x32_bf16 v[66:69], v[82:85], v[42:45], v[66:69]
	ds_read_b128 v[78:81], v1 offset:8192
	ds_read_b128 v[82:85], v1 offset:8256
	v_readlane_b32 s79, v252, 11
	v_readlane_b32 s80, v252, 12
	v_mfma_f32_16x16x32_bf16 v[74:77], v[90:93], v[46:49], 0
	ds_read_b128 v[86:89], v1 offset:12544
	ds_read_b128 v[90:93], v1 offset:12608
	global_load_dword v2, v3, s[22:23] offset:256
	v_readlane_b32 s81, v252, 13
	s_waitcnt lgkmcnt(1)
	v_mfma_f32_16x16x32_bf16 v[86:89], v[86:89], v[46:49], 0
	v_readlane_b32 s86, v252, 18
	v_readlane_b32 s87, v252, 19
	v_mfma_f32_16x16x32_bf16 v[70:73], v[94:97], v[46:49], 0
	ds_read_b128 v[94:97], v1 offset:8320
	v_mfma_f32_16x16x32_bf16 v[78:81], v[78:81], v[46:49], 0
	s_waitcnt lgkmcnt(1)
	v_mfma_f32_16x16x32_bf16 v[86:89], v[90:93], v[54:57], v[86:89]
	v_add_u32_e32 v90, 0x1000, v124
	v_ashrrev_i32_e32 v91, 31, v90
	v_lshlrev_b64 v[90:91], 2, v[90:91]
	v_lshl_add_u64 v[92:93], s[84:85], 0, v[90:91]
	v_mfma_f32_16x16x32_bf16 v[70:73], v[102:105], v[54:57], v[70:73]
	v_lshl_add_u64 v[90:91], s[82:83], 0, v[90:91]
	v_mfma_f32_16x16x32_bf16 v[74:77], v[98:101], v[54:57], v[74:77]
	v_mfma_f32_16x16x32_bf16 v[78:81], v[82:85], v[54:57], v[78:81]
	ds_read_b128 v[82:85], v1 offset:8384
	ds_read_b128 v[98:101], v1 offset:12672
	ds_read_b128 v[102:105], v1 offset:12736
	global_load_dword v93, v[92:93], off
	s_nop 0
	global_load_dword v92, v[90:91], off
	s_waitcnt lgkmcnt(3)
	v_mfma_f32_16x16x32_bf16 v[78:81], v[94:97], v[50:53], v[78:81]
	s_waitcnt lgkmcnt(2)
	v_mfma_f32_16x16x32_bf16 v[78:81], v[82:85], v[42:45], v[78:81]
	s_waitcnt vmcnt(2)
	v_mul_f32_e32 v82, 0x3fb8aa3b, v2
	v_fma_f32 v83, v2, s0, -v82
	v_rndne_f32_e32 v84, v82
	v_fmac_f32_e32 v83, 0x32a5705f, v2
	v_sub_f32_e32 v82, v82, v84
	v_add_f32_e32 v82, v82, v83
	s_waitcnt lgkmcnt(1)
	v_mfma_f32_16x16x32_bf16 v[86:89], v[98:101], v[50:53], v[86:89]
	v_cvt_i32_f32_e32 v90, v84
	v_exp_f32_e32 v91, v82
	s_mov_b32 s0, 0xc2ce8ed0
	v_mfma_f32_16x16x32_bf16 v[70:73], v[110:113], v[50:53], v[70:73]
	v_cmp_ngt_f32_e32 vcc, s0, v2
	s_mov_b32 s0, 0x42b17218
	v_mfma_f32_16x16x32_bf16 v[74:77], v[106:109], v[50:53], v[74:77]
	s_waitcnt lgkmcnt(0)
	v_mfma_f32_16x16x32_bf16 v[82:85], v[102:105], v[42:45], v[86:89]
	v_mfma_f32_16x16x32_bf16 v[70:73], v[118:121], v[42:45], v[70:73]
	s_nop 1
	v_ldexp_f32 v86, v91, v90
	v_cndmask_b32_e32 v86, 0, v86, vcc
	v_cmp_nlt_f32_e32 vcc, s0, v2
	v_mfma_f32_16x16x32_bf16 v[74:77], v[114:117], v[42:45], v[74:77]
	s_brev_b32 s0, 18
	v_cndmask_b32_e32 v86, v219, v86, vcc
	s_waitcnt vmcnt(1)
	v_mul_f32_e32 v87, v86, v93
	v_and_b32_e32 v88, 0x7fffffff, v87
	v_cmp_nlt_f32_e64 s[22:23], |v87|, s0
	s_and_saveexec_b64 s[0:1], s[22:23]
	s_xor_b64 s[24:25], exec, s[0:1]
	s_cbranch_execz .LBB0_632
	v_lshrrev_b32_e32 v2, 23, v88
	v_add_u32_e32 v2, 0xffffff88, v2
	v_cmp_lt_u32_e32 vcc, 63, v2
	s_mov_b32 s10, 0xfe5163ab
	s_nop 0
	v_cndmask_b32_e32 v89, 0, v220, vcc
	v_add_u32_e32 v2, v89, v2
	v_cmp_lt_u32_e64 s[0:1], 31, v2
	s_nop 1
	v_cndmask_b32_e64 v89, 0, v221, s[0:1]
	v_add_u32_e32 v2, v89, v2
	v_cmp_lt_u32_e64 s[8:9], 31, v2
	s_nop 1
	v_cndmask_b32_e64 v89, 0, v221, s[8:9]
	v_add_u32_e32 v89, v89, v2
	v_and_b32_e32 v2, 0x7fffff, v88
	v_or_b32_e32 v104, 0x800000, v2
	v_mad_u64_u32 v[90:91], s[10:11], v104, s10, 0
	v_mov_b32_e32 v2, v91
	s_mov_b32 s10, 0x3c439041
	v_mad_u64_u32 v[94:95], s[10:11], v104, s10, v[2:3]
	v_mov_b32_e32 v2, v95
	s_mov_b32 s10, 0xdb629599
	v_mad_u64_u32 v[96:97], s[10:11], v104, s10, v[2:3]
	v_mov_b32_e32 v2, v97
	s_mov_b32 s10, 0xf534ddc0
	v_mad_u64_u32 v[98:99], s[10:11], v104, s10, v[2:3]
	v_mov_b32_e32 v2, v99
	s_mov_b32 s10, 0xfc2757d1
	v_mad_u64_u32 v[100:101], s[10:11], v104, s10, v[2:3]
	v_mov_b32_e32 v2, v101
	s_mov_b32 s10, 0x4e441529
	v_mad_u64_u32 v[102:103], s[10:11], v104, s10, v[2:3]
	v_mov_b32_e32 v2, v103
	s_mov_b32 s10, 0xa2f9836e
	v_mad_u64_u32 v[104:105], s[10:11], v104, s10, v[2:3]
	v_cndmask_b32_e32 v91, v102, v98, vcc
	v_cndmask_b32_e32 v2, v104, v100, vcc
	v_cndmask_b32_e32 v97, v105, v102, vcc
	v_cndmask_b32_e64 v95, v2, v91, s[0:1]
	v_cndmask_b32_e64 v2, v97, v2, s[0:1]
	v_cndmask_b32_e32 v97, v100, v96, vcc
	v_cndmask_b32_e64 v91, v91, v97, s[0:1]
	v_sub_u32_e32 v99, 32, v89
	v_cmp_eq_u32_e64 s[10:11], 0, v89
	v_cndmask_b32_e32 v89, v98, v94, vcc
	v_cndmask_b32_e64 v2, v2, v95, s[8:9]
	v_cndmask_b32_e64 v95, v95, v91, s[8:9]
	v_cndmask_b32_e64 v94, v97, v89, s[0:1]
	v_alignbit_b32 v100, v2, v95, v99
	v_cndmask_b32_e64 v91, v91, v94, s[8:9]
	v_cndmask_b32_e64 v2, v100, v2, s[10:11]
	v_alignbit_b32 v97, v95, v91, v99
	v_cndmask_b32_e32 v90, v96, v90, vcc
	v_cndmask_b32_e64 v95, v97, v95, s[10:11]
	v_bfe_u32 v100, v2, 29, 1
	v_cndmask_b32_e64 v89, v89, v90, s[0:1]
	v_alignbit_b32 v97, v2, v95, 30
	v_sub_u32_e32 v101, 0, v100
	v_cndmask_b32_e64 v89, v94, v89, s[8:9]
	v_xor_b32_e32 v97, v97, v101
	v_alignbit_b32 v90, v91, v89, v99
	v_cndmask_b32_e64 v90, v90, v91, s[10:11]
	v_ffbh_u32_e32 v94, v97
	v_alignbit_b32 v91, v95, v90, 30
	v_min_u32_e32 v94, 32, v94
	v_alignbit_b32 v89, v90, v89, 30
	v_xor_b32_e32 v91, v91, v101
	v_sub_u32_e32 v95, 31, v94
	v_xor_b32_e32 v89, v89, v101
	v_alignbit_b32 v96, v97, v91, v95
	v_alignbit_b32 v89, v91, v89, v95
	v_alignbit_b32 v90, v96, v89, 9
	v_ffbh_u32_e32 v91, v90
	v_min_u32_e32 v91, 32, v91
	v_lshrrev_b32_e32 v98, 29, v2
	v_not_b32_e32 v95, v91
	v_alignbit_b32 v89, v90, v89, v95
	v_lshlrev_b32_e32 v90, 31, v98
	v_or_b32_e32 v95, 0x33000000, v90
	v_add_lshl_u32 v91, v91, v94, 23
	v_lshrrev_b32_e32 v89, 9, v89
	v_sub_u32_e32 v91, v95, v91
	v_or_b32_e32 v90, 0.5, v90
	v_lshlrev_b32_e32 v94, 23, v94
	v_or_b32_e32 v89, v91, v89
	v_lshrrev_b32_e32 v91, 9, v96
	v_sub_u32_e32 v90, v90, v94
	v_or_b32_e32 v90, v91, v90
	v_mul_f32_e32 v91, 0x3fc90fda, v90
	s_mov_b32 s0, 0x3fc90fda
	v_fma_f32 v94, v90, s0, -v91
	v_fmac_f32_e32 v94, 0x33a22168, v90
	v_fmac_f32_e32 v94, 0x3fc90fda, v89
	v_lshrrev_b32_e32 v2, 30, v2
	v_add_f32_e32 v90, v91, v94
	v_add_u32_e32 v89, v100, v2
	s_andn2_saveexec_b64 s[0:1], s[24:25]
	s_cbranch_execz .LBB0_634
	s_branch .LBB0_633

; template <int DIRN> DI void s5_dir(const S5P& P, const f32x2* END, const LAS float* UF, LAS bf16* XT, int b, int seg, int g, const bf16x8 (&bfr)[4], f32x4 (&acc)[8], int lane) {
;     ...
; #pragma unroll 8
;         for (int j = 0; j < sl; ++j) { const float* ep = (const float*)END + ((size_t)((b * 2 + DIRN) * SNSEG + j)) * 8192 + g * 128 + lane; const f32x2 e = {ep[0], ep[64]}; const float nr = Lr * xr - Li * xi + e.x, ni = Lr * xi + Li * xr + e.y; xr = nr; xi = ni; } }
.Ls5p1_blk_a:
	s_sub_i32 s0, s10, s9
	s_cmp_lt_i32 s0, 8
	s_cbranch_scc1 .Ls5p1_rem_a
	global_load_dword v184, v[200:201], off
	global_load_dword v185, v[200:201], off offset:256
	v_add_co_u32_e32 v200, vcc, 0x8000, v200
	s_nop 1
	v_addc_co_u32_e32 v201, vcc, 0, v201, vcc
	global_load_dword v186, v[200:201], off
	global_load_dword v187, v[200:201], off offset:256
	v_add_co_u32_e32 v200, vcc, 0x8000, v200
	s_nop 1
	v_addc_co_u32_e32 v201, vcc, 0, v201, vcc
	global_load_dword v188, v[200:201], off
	global_load_dword v189, v[200:201], off offset:256
	v_add_co_u32_e32 v200, vcc, 0x8000, v200
	s_nop 1
	v_addc_co_u32_e32 v201, vcc, 0, v201, vcc
	global_load_dword v190, v[200:201], off
	global_load_dword v191, v[200:201], off offset:256
	v_add_co_u32_e32 v200, vcc, 0x8000, v200
	s_nop 1
	v_addc_co_u32_e32 v201, vcc, 0, v201, vcc
	global_load_dword v192, v[200:201], off
	global_load_dword v193, v[200:201], off offset:256
	v_add_co_u32_e32 v200, vcc, 0x8000, v200
	s_nop 1
	v_addc_co_u32_e32 v201, vcc, 0, v201, vcc
	global_load_dword v194, v[200:201], off
	global_load_dword v195, v[200:201], off offset:256
	v_add_co_u32_e32 v200, vcc, 0x8000, v200
	s_nop 1
	v_addc_co_u32_e32 v201, vcc, 0, v201, vcc
	global_load_dword v196, v[200:201], off
	global_load_dword v197, v[200:201], off offset:256
	v_add_co_u32_e32 v200, vcc, 0x8000, v200
	s_nop 1
	v_addc_co_u32_e32 v201, vcc, 0, v201, vcc
	global_load_dword v198, v[200:201], off
	global_load_dword v199, v[200:201], off offset:256
	v_add_co_u32_e32 v200, vcc, 0x8000, v200
	s_nop 1
	v_addc_co_u32_e32 v201, vcc, 0, v201, vcc
	v_pk_mul_f32 v[100:101], v[94:95], v[90:91]
	v_pk_fma_f32 v[104:105], v[96:97], v[90:91], v[100:101] op_sel:[0,0,1] op_sel_hi:[1,1,0] neg_lo:[0,0,1] neg_hi:[0,0,1]
	v_pk_fma_f32 v[90:91], v[96:97], v[90:91], v[100:101] op_sel:[0,0,1] op_sel_hi:[1,1,0]
	v_mov_b32_e32 v105, v91
	s_waitcnt vmcnt(14) lgkmcnt(0)
	v_pk_add_f32 v[90:91], v[104:105], v[184:185]
	v_pk_mul_f32 v[100:101], v[94:95], v[90:91]
	v_pk_fma_f32 v[104:105], v[96:97], v[90:91], v[100:101] op_sel:[0,0,1] op_sel_hi:[1,1,0] neg_lo:[0,0,1] neg_hi:[0,0,1]
	v_pk_fma_f32 v[90:91], v[96:97], v[90:91], v[100:101] op_sel:[0,0,1] op_sel_hi:[1,1,0]
	v_mov_b32_e32 v105, v91
	s_waitcnt vmcnt(12)
	v_pk_add_f32 v[90:91], v[104:105], v[186:187]
	v_pk_mul_f32 v[100:101], v[94:95], v[90:91]
	v_pk_fma_f32 v[104:105], v[96:97], v[90:91], v[100:101] op_sel:[0,0,1] op_sel_hi:[1,1,0] neg_lo:[0,0,1] neg_hi:[0,0,1]
	v_pk_fma_f32 v[90:91], v[96:97], v[90:91], v[100:101] op_sel:[0,0,1] op_sel_hi:[1,1,0]
	v_mov_b32_e32 v105, v91
	s_waitcnt vmcnt(10)
	v_pk_add_f32 v[90:91], v[104:105], v[188:189]
	v_pk_mul_f32 v[100:101], v[94:95], v[90:91]
	v_pk_fma_f32 v[104:105], v[96:97], v[90:91], v[100:101] op_sel:[0,0,1] op_sel_hi:[1,1,0] neg_lo:[0,0,1] neg_hi:[0,0,1]
	v_pk_fma_f32 v[90:91], v[96:97], v[90:91], v[100:101] op_sel:[0,0,1] op_sel_hi:[1,1,0]
	v_mov_b32_e32 v105, v91
	s_waitcnt vmcnt(8)
	v_pk_add_f32 v[90:91], v[104:105], v[190:191]
	v_pk_mul_f32 v[100:101], v[94:95], v[90:91]
	v_pk_fma_f32 v[104:105], v[96:97], v[90:91], v[100:101] op_sel:[0,0,1] op_sel_hi:[1,1,0] neg_lo:[0,0,1] neg_hi:[0,0,1]
	v_pk_fma_f32 v[90:91], v[96:97], v[90:91], v[100:101] op_sel:[0,0,1] op_sel_hi:[1,1,0]
	v_mov_b32_e32 v105, v91
	s_waitcnt vmcnt(6)
	v_pk_add_f32 v[90:91], v[104:105], v[192:193]
	v_pk_mul_f32 v[100:101], v[94:95], v[90:91]
	v_pk_fma_f32 v[104:105], v[96:97], v[90:91], v[100:101] op_sel:[0,0,1] op_sel_hi:[1,1,0] neg_lo:[0,0,1] neg_hi:[0,0,1]
	v_pk_fma_f32 v[90:91], v[96:97], v[90:91], v[100:101] op_sel:[0,0,1] op_sel_hi:[1,1,0]
	v_mov_b32_e32 v105, v91
	s_waitcnt vmcnt(4)
	v_pk_add_f32 v[90:91], v[104:105], v[194:195]
	v_pk_mul_f32 v[100:101], v[94:95], v[90:91]
	v_pk_fma_f32 v[104:105], v[96:97], v[90:91], v[100:101] op_sel:[0,0,1] op_sel_hi:[1,1,0] neg_lo:[0,0,1] neg_hi:[0,0,1]
	v_pk_fma_f32 v[90:91], v[96:97], v[90:91], v[100:101] op_sel:[0,0,1] op_sel_hi:[1,1,0]
	v_mov_b32_e32 v105, v91
	s_waitcnt vmcnt(2)
	v_pk_add_f32 v[90:91], v[104:105], v[196:197]
	v_pk_mul_f32 v[100:101], v[94:95], v[90:91]
	v_pk_fma_f32 v[104:105], v[96:97], v[90:91], v[100:101] op_sel:[0,0,1] op_sel_hi:[1,1,0] neg_lo:[0,0,1] neg_hi:[0,0,1]
	v_pk_fma_f32 v[90:91], v[96:97], v[90:91], v[100:101] op_sel:[0,0,1] op_sel_hi:[1,1,0]
	v_mov_b32_e32 v105, v91
	s_waitcnt vmcnt(0)
	v_pk_add_f32 v[90:91], v[104:105], v[198:199]
	s_add_i32 s9, s9, 8
	s_branch .Ls5p1_blk_a

; template <int DIRN> DI void s5_dir(const S5P& P, const f32x2* END, const LAS float* UF, LAS bf16* XT, int b, int seg, int g, const bf16x8 (&bfr)[4], f32x4 (&acc)[8], int lane) {
;     ...
; #pragma unroll 8
;         for (int j = 0; j < sl; ++j) { const float* ep = (const float*)END + ((size_t)((b * 2 + DIRN) * SNSEG + j)) * 8192 + g * 128 + lane; const f32x2 e = {ep[0], ep[64]}; const float nr = Lr * xr - Li * xi + e.x, ni = Lr * xi + Li * xr + e.y; xr = nr; xi = ni; } }
.Ls5p1_reml_a:
	global_load_dword v184, v[200:201], off
	global_load_dword v185, v[200:201], off offset:256
	v_add_co_u32_e32 v200, vcc, 0x8000, v200
	s_nop 1
	v_addc_co_u32_e32 v201, vcc, 0, v201, vcc
	v_pk_mul_f32 v[100:101], v[94:95], v[90:91]
	v_pk_fma_f32 v[104:105], v[96:97], v[90:91], v[100:101] op_sel:[0,0,1] op_sel_hi:[1,1,0] neg_lo:[0,0,1] neg_hi:[0,0,1]
	v_pk_fma_f32 v[90:91], v[96:97], v[90:91], v[100:101] op_sel:[0,0,1] op_sel_hi:[1,1,0]
	v_mov_b32_e32 v105, v91
	s_waitcnt vmcnt(0) lgkmcnt(0)
	v_pk_add_f32 v[90:91], v[104:105], v[184:185]
	s_add_i32 s0, s0, -1
	s_cmp_lg_u32 s0, 0
	s_cbranch_scc1 .Ls5p1_reml_a
	s_branch .LBB0_650

; #define LAS __attribute__((address_space(3)))
; DI unsigned pk2(float lo, float hi) { return pg8::cvt_pk_bf16(lo, hi); }
; DI f32x4 mfma16(bf16x8 a, bf16x8 b, f32x4 c) { return __builtin_amdgcn_mfma_f32_16x16x32_bf16(a, b, c, 0, 0, 0); }
; template <int DIRN, int SUB> DI void s5_subtile(const LAS float* UF, LAS bf16* XT, float lr, float li, const f32x2 (&bb)[16], f32x2& x,
;                                                 const bf16x8 (&bfr)[4], f32x4& acc0, f32x4& acc1, int lane) {
;     ...
;     for (int i = 0; i < 32; ++i) { const int r = DIRN ? 31 - i : i;
;         x = s5_step((const LAS f32x4*)(UF + (32 * SUB + r) * 16), bb, lr, li, x);
;         const unsigned pkd = pk2(x.x, x.y); XT[r * 136 + lane] = (bf16)(pkd & 0xffffu); XT[r * 136 + 64 + lane] = (bf16)(pkd >> 16); }
; #pragma unroll
;     for (int ks = 0; ks < 4; ++ks) { const bf16x8 a0 = *(const LAS bf16x8*)(XT + (lane & 15) * 136 + 32 * ks + 8 * (lane >> 4)), a1 = *(const LAS bf16x8*)(XT + (16 + (lane & 15)) * 136 + 32 * ks + 8 * (lane >> 4));
;         acc0 = mfma16(a0, bfr[ks], acc0); acc1 = mfma16(a1, bfr[ks], acc1); }
.LBB0_651:
	s_add_i32 s1, s53, s0
	v_mov_b32_e32 v18, s1
	ds_read_b128 v[6:9], v18
	ds_read_b128 v[10:13], v18 offset:16
	ds_read_b128 v[14:17], v18 offset:32
	ds_read_b128 v[18:21], v18 offset:48
	s_waitcnt lgkmcnt(3)
	v_pk_mul_f32 v[22:23], v[96:97], v[6:7] op_sel:[0,1]
	v_pk_fma_f32 v[6:7], v[94:95], v[6:7], v[22:23] op_sel_hi:[1,0,1]
	v_pk_fma_f32 v[6:7], v[34:35], v[8:9], v[6:7] op_sel_hi:[1,0,1]
	v_pk_fma_f32 v[6:7], v[30:31], v[8:9], v[6:7] op_sel:[0,1,0]
	s_waitcnt lgkmcnt(2)
	v_pk_fma_f32 v[6:7], v[32:33], v[10:11], v[6:7] op_sel_hi:[1,0,1]
	v_pk_fma_f32 v[6:7], v[36:37], v[10:11], v[6:7] op_sel:[0,1,0]
	s_waitcnt lgkmcnt(1)
	v_pk_fma_f32 v[6:7], v[98:99], v[12:13], v[6:7] op_sel_hi:[1,0,1]
	v_pk_fma_f32 v[6:7], v[100:101], v[12:13], v[6:7] op_sel:[0,1,0]
	v_pk_mul_f32 v[8:9], v[104:105], v[14:15] op_sel:[0,1]
	v_pk_fma_f32 v[8:9], v[102:103], v[14:15], v[8:9] op_sel_hi:[1,0,1]
	v_pk_fma_f32 v[8:9], v[106:107], v[16:17], v[8:9] op_sel_hi:[1,0,1]
	v_pk_fma_f32 v[8:9], v[108:109], v[16:17], v[8:9] op_sel:[0,1,0]
	s_waitcnt lgkmcnt(0)
	v_mov_b32_e32 v10, v21
	v_pk_fma_f32 v[8:9], v[110:111], v[18:19], v[8:9] op_sel_hi:[1,0,1]
	v_pk_fma_f32 v[8:9], v[112:113], v[18:19], v[8:9] op_sel:[0,1,0]
	v_pk_fma_f32 v[8:9], v[114:115], v[20:21], v[8:9] op_sel_hi:[1,0,1]
	v_pk_fma_f32 v[8:9], v[92:93], v[10:11], v[8:9] op_sel_hi:[1,0,1]
	v_pk_add_f32 v[6:7], v[6:7], v[8:9]
	v_pk_fma_f32 v[6:7], v[88:89], v[90:91], v[6:7] op_sel:[0,1,0] op_sel_hi:[1,0,1]
	v_pk_fma_f32 v[90:91], v[86:87], v[90:91], v[6:7]
	v_cvt_pk_bf16_f32 v6, v90, s0
	v_cvt_pk_bf16_f32 v7, v91, s0
	s_sub_i32 s0, s0, 64
	ds_write_b16 v2, v6
	ds_write_b16 v2, v7 offset:128
	v_add_u32_e32 v2, 0xfffffef0, v2
	s_cmpk_lg_i32 s0, 0xf800
	s_cbranch_scc1 .LBB0_651
	ds_read_b128 v[6:9], v1 offset:8192
	ds_read_b128 v[10:13], v1 offset:12544
	ds_read_b128 v[14:17], v1 offset:8256
	ds_read_b128 v[18:21], v1 offset:12608
	v_add_u32_e32 v2, 0x40f0, v152
	s_movk_i32 s0, 0x17c0
	s_waitcnt lgkmcnt(3)
	v_mfma_f32_16x16x32_bf16 v[6:9], v[6:9], v[46:49], v[78:81]
	v_readlane_b32 s8, v253, 21
	v_readlane_b32 s9, v253, 22
	s_waitcnt lgkmcnt(2)
	v_mfma_f32_16x16x32_bf16 v[10:13], v[10:13], v[46:49], v[82:85]
	s_waitcnt lgkmcnt(1)
	v_mfma_f32_16x16x32_bf16 v[6:9], v[14:17], v[54:57], v[6:9]
	s_waitcnt lgkmcnt(0)
	v_mfma_f32_16x16x32_bf16 v[10:13], v[18:21], v[54:57], v[10:13]
	ds_read_b128 v[14:17], v1 offset:8320
	ds_read_b128 v[18:21], v1 offset:12672
	s_waitcnt lgkmcnt(1)
	v_mfma_f32_16x16x32_bf16 v[6:9], v[14:17], v[50:53], v[6:9]
	s_waitcnt lgkmcnt(0)
	v_mfma_f32_16x16x32_bf16 v[14:17], v[18:21], v[50:53], v[10:13]
	s_nop 2
	ds_read_b128 v[10:13], v1 offset:8384
	ds_read_b128 v[18:21], v1 offset:12736
	s_waitcnt lgkmcnt(1)
	v_mfma_f32_16x16x32_bf16 v[10:13], v[10:13], v[42:45], v[6:9]
	s_waitcnt lgkmcnt(0)
	v_mfma_f32_16x16x32_bf16 v[6:9], v[18:21], v[42:45], v[14:17]
	s_nop 2
	v_mov_b32_e32 v14, v2
.LBB0_653:
	s_add_i32 s1, s49, s0
	v_mov_b32_e32 v15, s1
	ds_read_b128 v[16:19], v15
	ds_read_b128 v[20:23], v15 offset:16
	ds_read_b128 v[24:27], v15 offset:32
	ds_read_b128 v[78:81], v15 offset:48
	s_waitcnt lgkmcnt(3)
	v_pk_mul_f32 v[28:29], v[96:97], v[16:17] op_sel:[0,1]
	v_pk_fma_f32 v[16:17], v[94:95], v[16:17], v[28:29] op_sel_hi:[1,0,1]
	v_pk_fma_f32 v[16:17], v[34:35], v[18:19], v[16:17] op_sel_hi:[1,0,1]
	v_pk_fma_f32 v[16:17], v[30:31], v[18:19], v[16:17] op_sel:[0,1,0]
	s_waitcnt lgkmcnt(2)
	v_pk_fma_f32 v[16:17], v[32:33], v[20:21], v[16:17] op_sel_hi:[1,0,1]
	v_pk_fma_f32 v[16:17], v[36:37], v[20:21], v[16:17] op_sel:[0,1,0]
	s_waitcnt lgkmcnt(1)
	v_pk_fma_f32 v[16:17], v[98:99], v[22:23], v[16:17] op_sel_hi:[1,0,1]
	v_pk_fma_f32 v[16:17], v[100:101], v[22:23], v[16:17] op_sel:[0,1,0]
	v_pk_mul_f32 v[18:19], v[104:105], v[24:25] op_sel:[0,1]
	v_pk_fma_f32 v[18:19], v[102:103], v[24:25], v[18:19] op_sel_hi:[1,0,1]
	v_pk_fma_f32 v[18:19], v[106:107], v[26:27], v[18:19] op_sel_hi:[1,0,1]
	v_pk_fma_f32 v[18:19], v[108:109], v[26:27], v[18:19] op_sel:[0,1,0]
	s_waitcnt lgkmcnt(0)
	v_mov_b32_e32 v20, v81
	v_pk_fma_f32 v[18:19], v[110:111], v[78:79], v[18:19] op_sel_hi:[1,0,1]
	v_pk_fma_f32 v[18:19], v[112:113], v[78:79], v[18:19] op_sel:[0,1,0]
	v_pk_fma_f32 v[18:19], v[114:115], v[80:81], v[18:19] op_sel_hi:[1,0,1]
	v_pk_fma_f32 v[18:19], v[92:93], v[20:21], v[18:19] op_sel_hi:[1,0,1]
	v_pk_add_f32 v[16:17], v[16:17], v[18:19]
	v_pk_fma_f32 v[16:17], v[88:89], v[90:91], v[16:17] op_sel:[0,1,0] op_sel_hi:[1,0,1]
	v_pk_fma_f32 v[90:91], v[86:87], v[90:91], v[16:17]
	v_add_u32_e32 v17, s49, v14
	v_cvt_pk_bf16_f32 v15, v90, s0
	v_cvt_pk_bf16_f32 v16, v91, s0
	s_sub_i32 s0, s0, 64
	v_add_u32_e32 v14, 0xfffffef0, v14
	s_cmpk_lg_i32 s0, 0xfc0
	ds_write_b16 v17, v15
	ds_write_b16 v17, v16 offset:128
	s_cbranch_scc1 .LBB0_653
	ds_read_b128 v[14:17], v1 offset:8192
	ds_read_b128 v[22:25], v1 offset:8256
	ds_read_b128 v[18:21], v1 offset:12544
	s_movk_i32 s0, 0xfc0
	s_waitcnt lgkmcnt(2)
	v_mfma_f32_16x16x32_bf16 v[14:17], v[14:17], v[46:49], v[70:73]
	s_waitcnt lgkmcnt(1)
	v_mfma_f32_16x16x32_bf16 v[14:17], v[22:25], v[54:57], v[14:17]
	ds_read_b128 v[22:25], v1 offset:12608
	s_waitcnt lgkmcnt(1)
	v_mfma_f32_16x16x32_bf16 v[18:21], v[18:21], v[46:49], v[74:77]
	s_waitcnt lgkmcnt(0)
	v_mfma_f32_16x16x32_bf16 v[18:21], v[22:25], v[54:57], v[18:21]
	ds_read_b128 v[22:25], v1 offset:8320
	s_waitcnt lgkmcnt(0)
	v_mfma_f32_16x16x32_bf16 v[14:17], v[22:25], v[50:53], v[14:17]
	ds_read_b128 v[22:25], v1 offset:12672
	s_waitcnt lgkmcnt(0)
	v_mfma_f32_16x16x32_bf16 v[24:27], v[22:25], v[50:53], v[18:21]
	s_nop 2
	ds_read_b128 v[18:21], v1 offset:8384
	v_mov_b32_e32 v22, v2
	s_waitcnt lgkmcnt(0)
	v_mfma_f32_16x16x32_bf16 v[18:21], v[18:21], v[42:45], v[14:17]
	s_nop 2
	ds_read_b128 v[14:17], v1 offset:12736
	s_waitcnt lgkmcnt(0)
	v_mfma_f32_16x16x32_bf16 v[14:17], v[14:17], v[42:45], v[24:27]
; #define LAS __attribute__((address_space(3)))
; DI unsigned pk2(float lo, float hi) { return pg8::cvt_pk_bf16(lo, hi); }
; DI f32x4 mfma16(bf16x8 a, bf16x8 b, f32x4 c) { return __builtin_amdgcn_mfma_f32_16x16x32_bf16(a, b, c, 0, 0, 0); }
; template <int DIRN, int SUB> DI void s5_subtile(const LAS float* UF, LAS bf16* XT, float lr, float li, const f32x2 (&bb)[16], f32x2& x,
;                                                 const bf16x8 (&bfr)[4], f32x4& acc0, f32x4& acc1, int lane) {
;     ...
;     for (int i = 0; i < 32; ++i) { const int r = DIRN ? 31 - i : i;
;         x = s5_step((const LAS f32x4*)(UF + (32 * SUB + r) * 16), bb, lr, li, x);
;         const unsigned pkd = pk2(x.x, x.y); XT[r * 136 + lane] = (bf16)(pkd & 0xffffu); XT[r * 136 + 64 + lane] = (bf16)(pkd >> 16); }
; #pragma unroll
;     for (int ks = 0; ks < 4; ++ks) { const bf16x8 a0 = *(const LAS bf16x8*)(XT + (lane & 15) * 136 + 32 * ks + 8 * (lane >> 4)), a1 = *(const LAS bf16x8*)(XT + (16 + (lane & 15)) * 136 + 32 * ks + 8 * (lane >> 4));
;         acc0 = mfma16(a0, bfr[ks], acc0); acc1 = mfma16(a1, bfr[ks], acc1); }
.LBB0_655:
	s_add_i32 s1, s49, s0
	v_mov_b32_e32 v23, s1
	s_nop 0
	ds_read_b128 v[24:27], v23
	ds_read_b128 v[70:73], v23 offset:16
	ds_read_b128 v[74:77], v23 offset:32
	ds_read_b128 v[78:81], v23 offset:48
	s_waitcnt lgkmcnt(3)
	v_pk_mul_f32 v[28:29], v[96:97], v[24:25] op_sel:[0,1]
	v_pk_fma_f32 v[24:25], v[94:95], v[24:25], v[28:29] op_sel_hi:[1,0,1]
	s_waitcnt lgkmcnt(1)
	v_pk_fma_f32 v[24:25], v[34:35], v[26:27], v[24:25] op_sel_hi:[1,0,1]
	v_pk_fma_f32 v[24:25], v[30:31], v[26:27], v[24:25] op_sel:[0,1,0]
	v_pk_fma_f32 v[24:25], v[32:33], v[70:71], v[24:25] op_sel_hi:[1,0,1]
	v_pk_fma_f32 v[24:25], v[36:37], v[70:71], v[24:25] op_sel:[0,1,0]
	v_pk_fma_f32 v[24:25], v[98:99], v[72:73], v[24:25] op_sel_hi:[1,0,1]
	v_pk_fma_f32 v[24:25], v[100:101], v[72:73], v[24:25] op_sel:[0,1,0]
	v_pk_mul_f32 v[26:27], v[104:105], v[74:75] op_sel:[0,1]
	v_pk_fma_f32 v[26:27], v[102:103], v[74:75], v[26:27] op_sel_hi:[1,0,1]
	v_pk_fma_f32 v[26:27], v[106:107], v[76:77], v[26:27] op_sel_hi:[1,0,1]
	v_pk_fma_f32 v[26:27], v[108:109], v[76:77], v[26:27] op_sel:[0,1,0]
	s_waitcnt lgkmcnt(0)
	v_mov_b32_e32 v28, v81
	v_pk_fma_f32 v[26:27], v[110:111], v[78:79], v[26:27] op_sel_hi:[1,0,1]
	v_pk_fma_f32 v[26:27], v[112:113], v[78:79], v[26:27] op_sel:[0,1,0]
	v_pk_fma_f32 v[26:27], v[114:115], v[80:81], v[26:27] op_sel_hi:[1,0,1]
	v_pk_fma_f32 v[26:27], v[92:93], v[28:29], v[26:27] op_sel_hi:[1,0,1]
	v_pk_add_f32 v[24:25], v[24:25], v[26:27]
	v_pk_fma_f32 v[24:25], v[88:89], v[90:91], v[24:25] op_sel:[0,1,0] op_sel_hi:[1,0,1]
	v_pk_fma_f32 v[90:91], v[86:87], v[90:91], v[24:25]
	v_add_u32_e32 v25, s49, v22
	v_cvt_pk_bf16_f32 v23, v90, s0
	v_cvt_pk_bf16_f32 v24, v91, s0
	s_sub_i32 s0, s0, 64
	v_add_u32_e32 v22, 0xfffffef0, v22
	s_cmpk_lg_i32 s0, 0x7c0
	ds_write_b16 v25, v23
	ds_write_b16 v25, v24 offset:128
	s_cbranch_scc1 .LBB0_655
	ds_read_b128 v[22:25], v1 offset:8192
	ds_read_b128 v[26:29], v1 offset:12544
	s_movk_i32 s0, 0x7c0
	s_waitcnt lgkmcnt(1)
	v_mfma_f32_16x16x32_bf16 v[22:25], v[22:25], v[46:49], v[62:65]
	s_nop 2
	ds_read_b128 v[62:65], v1 offset:8256
	s_waitcnt lgkmcnt(1)
	v_mfma_f32_16x16x32_bf16 v[26:29], v[26:29], v[46:49], v[66:69]
	s_waitcnt lgkmcnt(0)
	v_mfma_f32_16x16x32_bf16 v[22:25], v[62:65], v[54:57], v[22:25]
	ds_read_b128 v[62:65], v1 offset:12608
	s_waitcnt lgkmcnt(0)
	v_mfma_f32_16x16x32_bf16 v[26:29], v[62:65], v[54:57], v[26:29]
	ds_read_b128 v[62:65], v1 offset:8320
	s_waitcnt lgkmcnt(0)
	v_mfma_f32_16x16x32_bf16 v[22:25], v[62:65], v[50:53], v[22:25]
	ds_read_b128 v[62:65], v1 offset:12672
	s_waitcnt lgkmcnt(0)
	v_mfma_f32_16x16x32_bf16 v[62:65], v[62:65], v[50:53], v[26:29]
	s_nop 2
	ds_read_b128 v[26:29], v1 offset:8384
	s_waitcnt lgkmcnt(0)
	v_mfma_f32_16x16x32_bf16 v[26:29], v[26:29], v[42:45], v[22:25]
	s_nop 2
	ds_read_b128 v[22:25], v1 offset:12736
	s_waitcnt lgkmcnt(0)
	v_mfma_f32_16x16x32_bf16 v[22:25], v[22:25], v[42:45], v[62:65]
.LBB0_657:
	s_add_i32 s1, s49, s0
	v_mov_b32_e32 v74, s1
	s_nop 0
	ds_read_b128 v[62:65], v74
	ds_read_b128 v[66:69], v74 offset:16
	ds_read_b128 v[70:73], v74 offset:32
	ds_read_b128 v[74:77], v74 offset:48
	s_waitcnt lgkmcnt(3)
	v_pk_mul_f32 v[78:79], v[96:97], v[62:63] op_sel:[0,1]
	v_pk_fma_f32 v[62:63], v[94:95], v[62:63], v[78:79] op_sel_hi:[1,0,1]
	v_pk_fma_f32 v[62:63], v[34:35], v[64:65], v[62:63] op_sel_hi:[1,0,1]
	v_pk_fma_f32 v[62:63], v[30:31], v[64:65], v[62:63] op_sel:[0,1,0]
	s_waitcnt lgkmcnt(2)
	v_pk_fma_f32 v[62:63], v[32:33], v[66:67], v[62:63] op_sel_hi:[1,0,1]
	v_pk_fma_f32 v[62:63], v[36:37], v[66:67], v[62:63] op_sel:[0,1,0]
	s_waitcnt lgkmcnt(1)
	v_pk_fma_f32 v[62:63], v[98:99], v[68:69], v[62:63] op_sel_hi:[1,0,1]
	v_pk_fma_f32 v[62:63], v[100:101], v[68:69], v[62:63] op_sel:[0,1,0]
	v_pk_mul_f32 v[64:65], v[104:105], v[70:71] op_sel:[0,1]
	v_pk_fma_f32 v[64:65], v[102:103], v[70:71], v[64:65] op_sel_hi:[1,0,1]
	v_pk_fma_f32 v[64:65], v[106:107], v[72:73], v[64:65] op_sel_hi:[1,0,1]
	v_pk_fma_f32 v[64:65], v[108:109], v[72:73], v[64:65] op_sel:[0,1,0]
	s_waitcnt lgkmcnt(0)
	v_mov_b32_e32 v66, v77
	v_pk_fma_f32 v[64:65], v[110:111], v[74:75], v[64:65] op_sel_hi:[1,0,1]
	v_pk_fma_f32 v[64:65], v[112:113], v[74:75], v[64:65] op_sel:[0,1,0]
	v_pk_fma_f32 v[64:65], v[114:115], v[76:77], v[64:65] op_sel_hi:[1,0,1]
	v_pk_fma_f32 v[64:65], v[92:93], v[66:67], v[64:65] op_sel_hi:[1,0,1]
	v_pk_add_f32 v[62:63], v[62:63], v[64:65]
	v_add_u32_e32 v64, s49, v2
	v_pk_fma_f32 v[62:63], v[88:89], v[90:91], v[62:63] op_sel:[0,1,0] op_sel_hi:[1,0,1]
	v_add_u32_e32 v2, 0xfffffef0, v2
	v_pk_fma_f32 v[90:91], v[86:87], v[90:91], v[62:63]
	v_cvt_pk_bf16_f32 v62, v90, s0
	v_cvt_pk_bf16_f32 v63, v91, s0
	s_sub_i32 s0, s0, 64
	s_cmpk_eq_i32 s0, 0xffc0
	ds_write_b16 v64, v62
	ds_write_b16 v64, v63 offset:128
	s_cbranch_scc0 .LBB0_657
; DI bf16 f2bf(float f) { return (bf16)(pk2(f, 0.f) & 0xffffu); }
; DI float gelu_tanh(float x) { const float u = 0.7978845608028654f * (x + 0.044715f * x * x * x); return x * sigm(2.0f * u); }
; DI f32x4 mfma16(bf16x8 a, bf16x8 b, f32x4 c) { return __builtin_amdgcn_mfma_f32_16x16x32_bf16(a, b, c, 0, 0, 0); }
; template <int DIRN, int SUB> DI void s5_subtile(const LAS float* UF, LAS bf16* XT, float lr, float li, const f32x2 (&bb)[16], f32x2& x,
;                                                 const bf16x8 (&bfr)[4], f32x4& acc0, f32x4& acc1, int lane) {
;     ...
;         acc0 = mfma16(a0, bfr[ks], acc0); acc1 = mfma16(a1, bfr[ks], acc1); }
; DI void s5_passC(const Ctx& C, const S5P& P, const bf16* PROJ, const f32x2* END, bf16* YG  , int item_lo, int item_hi) {
;     ...
;         const float dv = P.d[g * 16 + (lane & 15)];
; #pragma unroll
;         for (int r = 0; r < 8; ++r)
; #pragma unroll
;             for (int j = 0; j < 4; ++j) { const int t = 16 * r + (lane >> 4) * 4 + j; const float y = acc[r][j] + dv * UF[t * 16 + (lane & 15)]; YG[(tok0 + t) * 1024 + g * 16 + (lane & 15)] = f2bf(gelu_tanh(y)); }
	ds_read_b128 v[30:33], v1 offset:8192
	ds_read_b128 v[34:37], v1 offset:12544
	v_lshlrev_b32_e32 v2, 2, v125
	v_readlane_b32 s72, v252, 20
	v_readlane_b32 s80, v252, 28
	s_waitcnt lgkmcnt(1)
	v_mfma_f32_16x16x32_bf16 v[30:33], v[30:33], v[46:49], v[38:41]
	v_readlane_b32 s81, v252, 29
	s_lshl_b32 s0, s67, 5
	s_add_u32 s0, s47, s0
	s_waitcnt lgkmcnt(0)
	v_mfma_f32_16x16x32_bf16 v[34:37], v[34:37], v[46:49], v[58:61]
	ds_read_b128 v[38:41], v1 offset:8256
	ds_read_b128 v[46:49], v1 offset:12608
	s_addc_u32 s1, s48, 0
	s_add_i32 s31, s31, s8
	s_waitcnt lgkmcnt(1)
	v_mfma_f32_16x16x32_bf16 v[30:33], v[38:41], v[54:57], v[30:33]
	v_readlane_b32 s76, v252, 24
	v_readlane_b32 s77, v252, 25
	v_readlane_b32 s78, v252, 26
	s_waitcnt lgkmcnt(0)
	v_mfma_f32_16x16x32_bf16 v[34:37], v[46:49], v[54:57], v[34:37]
	ds_read_b128 v[38:41], v1 offset:8320
	ds_read_b128 v[46:49], v1 offset:12672
	v_readlane_b32 s79, v252, 27
	v_readlane_b32 s73, v252, 21
	s_waitcnt lgkmcnt(1)
	v_mfma_f32_16x16x32_bf16 v[30:33], v[38:41], v[50:53], v[30:33]
	v_readlane_b32 s74, v252, 22
	v_readlane_b32 s75, v252, 23
	v_readlane_b32 s82, v252, 30
	s_waitcnt lgkmcnt(0)
	v_mfma_f32_16x16x32_bf16 v[38:41], v[46:49], v[50:53], v[34:37]
	s_nop 2
	ds_read_b128 v[34:37], v1 offset:8384
	ds_read_b128 v[46:49], v1 offset:12736
	v_lshl_or_b32 v1, s67, 6, v2
	global_load_dword v1, v1, s[80:81]
	s_waitcnt lgkmcnt(1)
	v_mfma_f32_16x16x32_bf16 v[34:37], v[34:37], v[42:45], v[30:33]
	v_readlane_b32 s83, v252, 31
	v_readlane_b32 s84, v252, 32
	v_readlane_b32 s85, v252, 33
	s_waitcnt lgkmcnt(0)
	v_mfma_f32_16x16x32_bf16 v[30:33], v[46:49], v[42:45], v[38:41]
	v_ashrrev_i32_e32 v43, 2, v122
	v_add_u32_e32 v42, s49, v2
	v_lshlrev_b32_e32 v2, 1, v125
	v_and_b32_e32 v40, -4, v43
	v_lshl_add_u64 v[38:39], s[0:1], 0, v[2:3]
	v_lshl_add_u32 v2, v40, 6, v42
	ds_read_b32 v2, v2
	v_ashrrev_i32_e32 v41, 31, v40
	v_lshl_add_u64 v[44:45], s[12:13], 0, v[40:41]
	v_lshlrev_b64 v[44:45], 11, v[44:45]
	v_lshl_add_u64 v[44:45], v[38:39], 0, v[44:45]
	v_readlane_b32 s86, v252, 34
	v_readlane_b32 s87, v252, 35
	s_waitcnt vmcnt(0) lgkmcnt(0)
	v_fma_f32 v2, v1, v2, v34
	v_mul_f32_e32 v34, 0x3d372713, v2
	v_mul_f32_e32 v34, v2, v34
	v_fma_f32 v34, v2, v34, v2
	v_mul_f32_e32 v34, 0x3f4c422a, v34
	v_add_f32_e32 v34, v34, v34
	v_mul_f32_e32 v34, 0xbfb8aa3b, v34
	v_exp_f32_e32 v34, v34
	s_nop 0
	v_add_f32_e32 v34, 1.0, v34
	v_rcp_f32_e32 v34, v34
	s_nop 0
	v_mul_f32_e32 v2, v2, v34
	v_cvt_pk_bf16_f32 v2, v2, s0
	v_or_b32_e32 v34, 1, v40
	global_store_short v[44:45], v2, off
	v_lshl_add_u32 v2, v34, 6, v42
	ds_read_b32 v2, v2
	s_waitcnt lgkmcnt(0)
	v_fma_f32 v2, v1, v2, v35
	v_mul_f32_e32 v35, 0x3d372713, v2
	v_mul_f32_e32 v35, v2, v35
	v_fma_f32 v35, v2, v35, v2
	v_mul_f32_e32 v35, 0x3f4c422a, v35
	v_add_f32_e32 v35, v35, v35
	v_mul_f32_e32 v35, 0xbfb8aa3b, v35
	v_exp_f32_e32 v35, v35
	s_nop 0
	v_add_f32_e32 v35, 1.0, v35
	v_rcp_f32_e32 v35, v35
	s_nop 0
	v_mul_f32_e32 v2, v2, v35
	v_ashrrev_i32_e32 v35, 31, v34
	v_lshl_add_u64 v[34:35], s[12:13], 0, v[34:35]
	v_lshlrev_b64 v[34:35], 11, v[34:35]
	v_cvt_pk_bf16_f32 v2, v2, s0
	v_lshl_add_u64 v[34:35], v[38:39], 0, v[34:35]
	global_store_short v[34:35], v2, off
	v_or_b32_e32 v34, 2, v40
	v_lshl_add_u32 v2, v34, 6, v42
	ds_read_b32 v2, v2
	s_waitcnt lgkmcnt(0)
	v_fma_f32 v2, v1, v2, v36
	v_mul_f32_e32 v35, 0x3d372713, v2
	v_mul_f32_e32 v35, v2, v35
	v_fma_f32 v35, v2, v35, v2
	v_mul_f32_e32 v35, 0x3f4c422a, v35
	v_add_f32_e32 v35, v35, v35
	v_mul_f32_e32 v35, 0xbfb8aa3b, v35
	v_exp_f32_e32 v35, v35
	s_nop 0
	v_add_f32_e32 v35, 1.0, v35
	v_rcp_f32_e32 v35, v35
	s_nop 0
	v_mul_f32_e32 v2, v2, v35
	v_ashrrev_i32_e32 v35, 31, v34
	v_lshl_add_u64 v[34:35], s[12:13], 0, v[34:35]
	v_lshlrev_b64 v[34:35], 11, v[34:35]
	v_cvt_pk_bf16_f32 v2, v2, s0
	v_lshl_add_u64 v[34:35], v[38:39], 0, v[34:35]
	global_store_short v[34:35], v2, off
	v_or_b32_e32 v34, 3, v43
	v_lshl_add_u32 v2, v34, 6, v42
	ds_read_b32 v2, v2
	v_ashrrev_i32_e32 v35, 31, v34
	v_lshl_add_u64 v[34:35], s[12:13], 0, v[34:35]
	v_lshlrev_b64 v[34:35], 11, v[34:35]
	v_lshl_add_u64 v[34:35], v[38:39], 0, v[34:35]
	s_waitcnt lgkmcnt(0)
	v_fmac_f32_e32 v37, v1, v2
	v_mul_f32_e32 v2, 0x3d372713, v37
	v_mul_f32_e32 v2, v37, v2
	v_fma_f32 v2, v37, v2, v37
	v_mul_f32_e32 v2, 0x3f4c422a, v2
	v_add_f32_e32 v2, v2, v2
	v_mul_f32_e32 v2, 0xbfb8aa3b, v2
	v_exp_f32_e32 v2, v2
	s_nop 0
	v_add_f32_e32 v2, 1.0, v2
	v_rcp_f32_e32 v2, v2
	s_nop 0
	v_mul_f32_e32 v2, v37, v2
	v_cvt_pk_bf16_f32 v2, v2, s0
	global_store_short v[34:35], v2, off
	v_add_u32_e32 v34, 16, v40
	v_lshl_add_u32 v2, v34, 6, v42
	ds_read_b32 v2, v2
	v_ashrrev_i32_e32 v35, 31, v34
	v_lshl_add_u64 v[34:35], s[12:13], 0, v[34:35]
	v_lshlrev_b64 v[34:35], 11, v[34:35]
	v_lshl_add_u64 v[34:35], v[38:39], 0, v[34:35]
	s_waitcnt lgkmcnt(0)
	v_fma_f32 v2, v1, v2, v30
	v_mul_f32_e32 v30, 0x3d372713, v2
	v_mul_f32_e32 v30, v2, v30
	v_fma_f32 v30, v2, v30, v2
	v_mul_f32_e32 v30, 0x3f4c422a, v30
	v_add_f32_e32 v30, v30, v30
	v_mul_f32_e32 v30, 0xbfb8aa3b, v30
	v_exp_f32_e32 v30, v30
	s_nop 0
	v_add_f32_e32 v30, 1.0, v30
	v_rcp_f32_e32 v30, v30
	s_nop 0
	v_mul_f32_e32 v2, v2, v30
	v_cvt_pk_bf16_f32 v2, v2, s0
	v_add_u32_e32 v30, 17, v40
	global_store_short v[34:35], v2, off
	v_lshl_add_u32 v2, v30, 6, v42
	ds_read_b32 v2, v2
	s_waitcnt lgkmcnt(0)
; DI bf16 f2bf(float f) { return (bf16)(pk2(f, 0.f) & 0xffffu); }
; DI float gelu_tanh(float x) { const float u = 0.7978845608028654f * (x + 0.044715f * x * x * x); return x * sigm(2.0f * u); }
; DI void s5_passC(const Ctx& C, const S5P& P, const bf16* PROJ, const f32x2* END, bf16* YG  , int item_lo, int item_hi) {
;     ...
;         const float dv = P.d[g * 16 + (lane & 15)];
; #pragma unroll
;         for (int r = 0; r < 8; ++r)
; #pragma unroll
;             for (int j = 0; j < 4; ++j) { const int t = 16 * r + (lane >> 4) * 4 + j; const float y = acc[r][j] + dv * UF[t * 16 + (lane & 15)]; YG[(tok0 + t) * 1024 + g * 16 + (lane & 15)] = f2bf(gelu_tanh(y)); }
	v_fma_f32 v2, v1, v2, v31
	v_mul_f32_e32 v31, 0x3d372713, v2
	v_mul_f32_e32 v31, v2, v31
	v_fma_f32 v31, v2, v31, v2
	v_mul_f32_e32 v31, 0x3f4c422a, v31
	v_add_f32_e32 v31, v31, v31
	v_mul_f32_e32 v31, 0xbfb8aa3b, v31
	v_exp_f32_e32 v31, v31
	s_nop 0
	v_add_f32_e32 v31, 1.0, v31
	v_rcp_f32_e32 v31, v31
	s_nop 0
	v_mul_f32_e32 v2, v2, v31
	v_ashrrev_i32_e32 v31, 31, v30
	v_lshl_add_u64 v[30:31], s[12:13], 0, v[30:31]
	v_lshlrev_b64 v[30:31], 11, v[30:31]
	v_cvt_pk_bf16_f32 v2, v2, s0
	v_lshl_add_u64 v[30:31], v[38:39], 0, v[30:31]
	global_store_short v[30:31], v2, off
	v_add_u32_e32 v30, 18, v40
	v_lshl_add_u32 v2, v30, 6, v42
	ds_read_b32 v2, v2
	s_waitcnt lgkmcnt(0)
	v_fma_f32 v2, v1, v2, v32
	v_mul_f32_e32 v31, 0x3d372713, v2
	v_mul_f32_e32 v31, v2, v31
	v_fma_f32 v31, v2, v31, v2
	v_mul_f32_e32 v31, 0x3f4c422a, v31
	v_add_f32_e32 v31, v31, v31
	v_mul_f32_e32 v31, 0xbfb8aa3b, v31
	v_exp_f32_e32 v31, v31
	s_nop 0
	v_add_f32_e32 v31, 1.0, v31
	v_rcp_f32_e32 v31, v31
	s_nop 0
	v_mul_f32_e32 v2, v2, v31
	v_ashrrev_i32_e32 v31, 31, v30
	v_lshl_add_u64 v[30:31], s[12:13], 0, v[30:31]
	v_lshlrev_b64 v[30:31], 11, v[30:31]
	v_cvt_pk_bf16_f32 v2, v2, s0
	v_lshl_add_u64 v[30:31], v[38:39], 0, v[30:31]
	global_store_short v[30:31], v2, off
	v_add_u32_e32 v30, 19, v40
	v_lshl_add_u32 v2, v30, 6, v42
	ds_read_b32 v2, v2
	v_ashrrev_i32_e32 v31, 31, v30
	v_lshl_add_u64 v[30:31], s[12:13], 0, v[30:31]
	v_lshlrev_b64 v[30:31], 11, v[30:31]
	v_lshl_add_u64 v[30:31], v[38:39], 0, v[30:31]
	s_waitcnt lgkmcnt(0)
	v_fmac_f32_e32 v33, v1, v2
	v_mul_f32_e32 v2, 0x3d372713, v33
	v_mul_f32_e32 v2, v33, v2
	v_fma_f32 v2, v33, v2, v33
	v_mul_f32_e32 v2, 0x3f4c422a, v2
	v_add_f32_e32 v2, v2, v2
	v_mul_f32_e32 v2, 0xbfb8aa3b, v2
	v_exp_f32_e32 v2, v2
	s_nop 0
	v_add_f32_e32 v2, 1.0, v2
	v_rcp_f32_e32 v2, v2
	s_nop 0
	v_mul_f32_e32 v2, v33, v2
	v_cvt_pk_bf16_f32 v2, v2, s0
	global_store_short v[30:31], v2, off
	v_add_u32_e32 v30, 32, v40
	v_lshl_add_u32 v2, v30, 6, v42
	ds_read_b32 v2, v2
	v_ashrrev_i32_e32 v31, 31, v30
	v_lshl_add_u64 v[30:31], s[12:13], 0, v[30:31]
	v_lshlrev_b64 v[30:31], 11, v[30:31]
	v_lshl_add_u64 v[30:31], v[38:39], 0, v[30:31]
	s_waitcnt lgkmcnt(0)
	v_fma_f32 v2, v1, v2, v26
	v_mul_f32_e32 v26, 0x3d372713, v2
	v_mul_f32_e32 v26, v2, v26
	v_fma_f32 v26, v2, v26, v2
	v_mul_f32_e32 v26, 0x3f4c422a, v26
	v_add_f32_e32 v26, v26, v26
	v_mul_f32_e32 v26, 0xbfb8aa3b, v26
	v_exp_f32_e32 v26, v26
	s_nop 0
	v_add_f32_e32 v26, 1.0, v26
	v_rcp_f32_e32 v26, v26
	s_nop 0
	v_mul_f32_e32 v2, v2, v26
	v_cvt_pk_bf16_f32 v2, v2, s0
	v_add_u32_e32 v26, 33, v40
	global_store_short v[30:31], v2, off
	v_lshl_add_u32 v2, v26, 6, v42
	ds_read_b32 v2, v2
	s_waitcnt lgkmcnt(0)
	v_fma_f32 v2, v1, v2, v27
	v_mul_f32_e32 v27, 0x3d372713, v2
	v_mul_f32_e32 v27, v2, v27
	v_fma_f32 v27, v2, v27, v2
	v_mul_f32_e32 v27, 0x3f4c422a, v27
	v_add_f32_e32 v27, v27, v27
	v_mul_f32_e32 v27, 0xbfb8aa3b, v27
	v_exp_f32_e32 v27, v27
	s_nop 0
	v_add_f32_e32 v27, 1.0, v27
	v_rcp_f32_e32 v27, v27
	s_nop 0
	v_mul_f32_e32 v2, v2, v27
	v_ashrrev_i32_e32 v27, 31, v26
	v_lshl_add_u64 v[26:27], s[12:13], 0, v[26:27]
	v_lshlrev_b64 v[26:27], 11, v[26:27]
	v_cvt_pk_bf16_f32 v2, v2, s0
	v_lshl_add_u64 v[26:27], v[38:39], 0, v[26:27]
	global_store_short v[26:27], v2, off
	v_add_u32_e32 v26, 34, v40
	v_lshl_add_u32 v2, v26, 6, v42
	ds_read_b32 v2, v2
	s_waitcnt lgkmcnt(0)
	v_fma_f32 v2, v1, v2, v28
	v_mul_f32_e32 v27, 0x3d372713, v2
	v_mul_f32_e32 v27, v2, v27
	v_fma_f32 v27, v2, v27, v2
	v_mul_f32_e32 v27, 0x3f4c422a, v27
	v_add_f32_e32 v27, v27, v27
	v_mul_f32_e32 v27, 0xbfb8aa3b, v27
	v_exp_f32_e32 v27, v27
	s_nop 0
	v_add_f32_e32 v27, 1.0, v27
	v_rcp_f32_e32 v27, v27
	s_nop 0
	v_mul_f32_e32 v2, v2, v27
	v_ashrrev_i32_e32 v27, 31, v26
	v_lshl_add_u64 v[26:27], s[12:13], 0, v[26:27]
	v_lshlrev_b64 v[26:27], 11, v[26:27]
	v_cvt_pk_bf16_f32 v2, v2, s0
	v_lshl_add_u64 v[26:27], v[38:39], 0, v[26:27]
	global_store_short v[26:27], v2, off
	v_add_u32_e32 v26, 35, v40
	v_lshl_add_u32 v2, v26, 6, v42
	ds_read_b32 v2, v2
	v_ashrrev_i32_e32 v27, 31, v26
	v_lshl_add_u64 v[26:27], s[12:13], 0, v[26:27]
	v_lshlrev_b64 v[26:27], 11, v[26:27]
	v_lshl_add_u64 v[26:27], v[38:39], 0, v[26:27]
	s_waitcnt lgkmcnt(0)
	v_fmac_f32_e32 v29, v1, v2
	v_mul_f32_e32 v2, 0x3d372713, v29
	v_mul_f32_e32 v2, v29, v2
	v_fma_f32 v2, v29, v2, v29
	v_mul_f32_e32 v2, 0x3f4c422a, v2
	v_add_f32_e32 v2, v2, v2
	v_mul_f32_e32 v2, 0xbfb8aa3b, v2
	v_exp_f32_e32 v2, v2
	s_nop 0
	v_add_f32_e32 v2, 1.0, v2
	v_rcp_f32_e32 v2, v2
	s_nop 0
	v_mul_f32_e32 v2, v29, v2
	v_cvt_pk_bf16_f32 v2, v2, s0
	global_store_short v[26:27], v2, off
	v_add_u32_e32 v26, 48, v40
	v_lshl_add_u32 v2, v26, 6, v42
	ds_read_b32 v2, v2
	v_ashrrev_i32_e32 v27, 31, v26
	v_lshl_add_u64 v[26:27], s[12:13], 0, v[26:27]
	v_lshlrev_b64 v[26:27], 11, v[26:27]
	v_lshl_add_u64 v[26:27], v[38:39], 0, v[26:27]
	s_waitcnt lgkmcnt(0)
	v_fma_f32 v2, v1, v2, v22
	v_mul_f32_e32 v22, 0x3d372713, v2
	v_mul_f32_e32 v22, v2, v22
	v_fma_f32 v22, v2, v22, v2
	v_mul_f32_e32 v22, 0x3f4c422a, v22
	v_add_f32_e32 v22, v22, v22
	v_mul_f32_e32 v22, 0xbfb8aa3b, v22
	v_exp_f32_e32 v22, v22
	s_nop 0
	v_add_f32_e32 v22, 1.0, v22
	v_rcp_f32_e32 v22, v22
	s_nop 0
	v_mul_f32_e32 v2, v2, v22
	v_cvt_pk_bf16_f32 v2, v2, s0
	v_add_u32_e32 v22, 49, v40
	global_store_short v[26:27], v2, off
	v_lshl_add_u32 v2, v22, 6, v42
	ds_read_b32 v2, v2
	s_waitcnt lgkmcnt(0)
; DI bf16 f2bf(float f) { return (bf16)(pk2(f, 0.f) & 0xffffu); }
; DI float gelu_tanh(float x) { const float u = 0.7978845608028654f * (x + 0.044715f * x * x * x); return x * sigm(2.0f * u); }
; DI void s5_passC(const Ctx& C, const S5P& P, const bf16* PROJ, const f32x2* END, bf16* YG  , int item_lo, int item_hi) {
;     ...
;         const float dv = P.d[g * 16 + (lane & 15)];
; #pragma unroll
;         for (int r = 0; r < 8; ++r)
; #pragma unroll
;             for (int j = 0; j < 4; ++j) { const int t = 16 * r + (lane >> 4) * 4 + j; const float y = acc[r][j] + dv * UF[t * 16 + (lane & 15)]; YG[(tok0 + t) * 1024 + g * 16 + (lane & 15)] = f2bf(gelu_tanh(y)); }
	v_fma_f32 v2, v1, v2, v23
	v_mul_f32_e32 v23, 0x3d372713, v2
	v_mul_f32_e32 v23, v2, v23
	v_fma_f32 v23, v2, v23, v2
	v_mul_f32_e32 v23, 0x3f4c422a, v23
	v_add_f32_e32 v23, v23, v23
	v_mul_f32_e32 v23, 0xbfb8aa3b, v23
	v_exp_f32_e32 v23, v23
	s_nop 0
	v_add_f32_e32 v23, 1.0, v23
	v_rcp_f32_e32 v23, v23
	s_nop 0
	v_mul_f32_e32 v2, v2, v23
	v_ashrrev_i32_e32 v23, 31, v22
	v_lshl_add_u64 v[22:23], s[12:13], 0, v[22:23]
	v_lshlrev_b64 v[22:23], 11, v[22:23]
	v_cvt_pk_bf16_f32 v2, v2, s0
	v_lshl_add_u64 v[22:23], v[38:39], 0, v[22:23]
	global_store_short v[22:23], v2, off
	v_add_u32_e32 v22, 50, v40
	v_lshl_add_u32 v2, v22, 6, v42
	ds_read_b32 v2, v2
	s_waitcnt lgkmcnt(0)
	v_fma_f32 v2, v1, v2, v24
	v_mul_f32_e32 v23, 0x3d372713, v2
	v_mul_f32_e32 v23, v2, v23
	v_fma_f32 v23, v2, v23, v2
	v_mul_f32_e32 v23, 0x3f4c422a, v23
	v_add_f32_e32 v23, v23, v23
	v_mul_f32_e32 v23, 0xbfb8aa3b, v23
	v_exp_f32_e32 v23, v23
	s_nop 0
	v_add_f32_e32 v23, 1.0, v23
	v_rcp_f32_e32 v23, v23
	s_nop 0
	v_mul_f32_e32 v2, v2, v23
	v_ashrrev_i32_e32 v23, 31, v22
	v_lshl_add_u64 v[22:23], s[12:13], 0, v[22:23]
	v_lshlrev_b64 v[22:23], 11, v[22:23]
	v_cvt_pk_bf16_f32 v2, v2, s0
	v_lshl_add_u64 v[22:23], v[38:39], 0, v[22:23]
	global_store_short v[22:23], v2, off
	v_add_u32_e32 v22, 51, v40
	v_lshl_add_u32 v2, v22, 6, v42
	ds_read_b32 v2, v2
	v_ashrrev_i32_e32 v23, 31, v22
	v_lshl_add_u64 v[22:23], s[12:13], 0, v[22:23]
	v_lshlrev_b64 v[22:23], 11, v[22:23]
	v_lshl_add_u64 v[22:23], v[38:39], 0, v[22:23]
	s_waitcnt lgkmcnt(0)
	v_fmac_f32_e32 v25, v1, v2
	v_mul_f32_e32 v2, 0x3d372713, v25
	v_mul_f32_e32 v2, v25, v2
	v_fma_f32 v2, v25, v2, v25
	v_mul_f32_e32 v2, 0x3f4c422a, v2
	v_add_f32_e32 v2, v2, v2
	v_mul_f32_e32 v2, 0xbfb8aa3b, v2
	v_exp_f32_e32 v2, v2
	s_nop 0
	v_add_f32_e32 v2, 1.0, v2
	v_rcp_f32_e32 v2, v2
	s_nop 0
	v_mul_f32_e32 v2, v25, v2
	v_cvt_pk_bf16_f32 v2, v2, s0
	global_store_short v[22:23], v2, off
	v_add_u32_e32 v22, 64, v40
	v_lshl_add_u32 v2, v22, 6, v42
	ds_read_b32 v2, v2
	v_ashrrev_i32_e32 v23, 31, v22
	v_lshl_add_u64 v[22:23], s[12:13], 0, v[22:23]
	v_lshlrev_b64 v[22:23], 11, v[22:23]
	v_lshl_add_u64 v[22:23], v[38:39], 0, v[22:23]
	s_waitcnt lgkmcnt(0)
	v_fma_f32 v2, v1, v2, v18
	v_mul_f32_e32 v18, 0x3d372713, v2
	v_mul_f32_e32 v18, v2, v18
	v_fma_f32 v18, v2, v18, v2
	v_mul_f32_e32 v18, 0x3f4c422a, v18
	v_add_f32_e32 v18, v18, v18
	v_mul_f32_e32 v18, 0xbfb8aa3b, v18
	v_exp_f32_e32 v18, v18
	s_nop 0
	v_add_f32_e32 v18, 1.0, v18
	v_rcp_f32_e32 v18, v18
	s_nop 0
	v_mul_f32_e32 v2, v2, v18
	v_cvt_pk_bf16_f32 v2, v2, s0
	v_add_u32_e32 v18, 0x41, v40
	global_store_short v[22:23], v2, off
	v_lshl_add_u32 v2, v18, 6, v42
	ds_read_b32 v2, v2
	s_waitcnt lgkmcnt(0)
	v_fma_f32 v2, v1, v2, v19
	v_mul_f32_e32 v19, 0x3d372713, v2
	v_mul_f32_e32 v19, v2, v19
	v_fma_f32 v19, v2, v19, v2
	v_mul_f32_e32 v19, 0x3f4c422a, v19
	v_add_f32_e32 v19, v19, v19
	v_mul_f32_e32 v19, 0xbfb8aa3b, v19
	v_exp_f32_e32 v19, v19
	s_nop 0
	v_add_f32_e32 v19, 1.0, v19
	v_rcp_f32_e32 v19, v19
	s_nop 0
	v_mul_f32_e32 v2, v2, v19
	v_ashrrev_i32_e32 v19, 31, v18
	v_lshl_add_u64 v[18:19], s[12:13], 0, v[18:19]
	v_lshlrev_b64 v[18:19], 11, v[18:19]
	v_cvt_pk_bf16_f32 v2, v2, s0
	v_lshl_add_u64 v[18:19], v[38:39], 0, v[18:19]
	global_store_short v[18:19], v2, off
	v_add_u32_e32 v18, 0x42, v40
	v_lshl_add_u32 v2, v18, 6, v42
	ds_read_b32 v2, v2
	s_waitcnt lgkmcnt(0)
	v_fma_f32 v2, v1, v2, v20
	v_mul_f32_e32 v19, 0x3d372713, v2
	v_mul_f32_e32 v19, v2, v19
	v_fma_f32 v19, v2, v19, v2
	v_mul_f32_e32 v19, 0x3f4c422a, v19
	v_add_f32_e32 v19, v19, v19
	v_mul_f32_e32 v19, 0xbfb8aa3b, v19
	v_exp_f32_e32 v19, v19
	s_nop 0
	v_add_f32_e32 v19, 1.0, v19
	v_rcp_f32_e32 v19, v19
	s_nop 0
	v_mul_f32_e32 v2, v2, v19
	v_ashrrev_i32_e32 v19, 31, v18
	v_lshl_add_u64 v[18:19], s[12:13], 0, v[18:19]
	v_lshlrev_b64 v[18:19], 11, v[18:19]
	v_cvt_pk_bf16_f32 v2, v2, s0
	v_lshl_add_u64 v[18:19], v[38:39], 0, v[18:19]
	global_store_short v[18:19], v2, off
	v_add_u32_e32 v18, 0x43, v40
	v_lshl_add_u32 v2, v18, 6, v42
	ds_read_b32 v2, v2
	v_ashrrev_i32_e32 v19, 31, v18
	v_lshl_add_u64 v[18:19], s[12:13], 0, v[18:19]
	v_lshlrev_b64 v[18:19], 11, v[18:19]
	v_lshl_add_u64 v[18:19], v[38:39], 0, v[18:19]
	s_waitcnt lgkmcnt(0)
	v_fmac_f32_e32 v21, v1, v2
	v_mul_f32_e32 v2, 0x3d372713, v21
	v_mul_f32_e32 v2, v21, v2
	v_fma_f32 v2, v21, v2, v21
	v_mul_f32_e32 v2, 0x3f4c422a, v2
	v_add_f32_e32 v2, v2, v2
	v_mul_f32_e32 v2, 0xbfb8aa3b, v2
	v_exp_f32_e32 v2, v2
	s_nop 0
	v_add_f32_e32 v2, 1.0, v2
	v_rcp_f32_e32 v2, v2
	s_nop 0
	v_mul_f32_e32 v2, v21, v2
	v_cvt_pk_bf16_f32 v2, v2, s0
	global_store_short v[18:19], v2, off
	v_add_u32_e32 v18, 0x50, v40
	v_lshl_add_u32 v2, v18, 6, v42
	ds_read_b32 v2, v2
	v_ashrrev_i32_e32 v19, 31, v18
	v_lshl_add_u64 v[18:19], s[12:13], 0, v[18:19]
	v_lshlrev_b64 v[18:19], 11, v[18:19]
	v_lshl_add_u64 v[18:19], v[38:39], 0, v[18:19]
	s_waitcnt lgkmcnt(0)
	v_fma_f32 v2, v1, v2, v14
	v_mul_f32_e32 v14, 0x3d372713, v2
	v_mul_f32_e32 v14, v2, v14
	v_fma_f32 v14, v2, v14, v2
	v_mul_f32_e32 v14, 0x3f4c422a, v14
	v_add_f32_e32 v14, v14, v14
	v_mul_f32_e32 v14, 0xbfb8aa3b, v14
	v_exp_f32_e32 v14, v14
	s_nop 0
	v_add_f32_e32 v14, 1.0, v14
	v_rcp_f32_e32 v14, v14
	s_nop 0
	v_mul_f32_e32 v2, v2, v14
	v_cvt_pk_bf16_f32 v2, v2, s0
	v_add_u32_e32 v14, 0x51, v40
	global_store_short v[18:19], v2, off
	v_lshl_add_u32 v2, v14, 6, v42
	ds_read_b32 v2, v2
	s_waitcnt lgkmcnt(0)
; DI bf16 f2bf(float f) { return (bf16)(pk2(f, 0.f) & 0xffffu); }
; DI float gelu_tanh(float x) { const float u = 0.7978845608028654f * (x + 0.044715f * x * x * x); return x * sigm(2.0f * u); }
; DI void s5_passC(const Ctx& C, const S5P& P, const bf16* PROJ, const f32x2* END, bf16* YG  , int item_lo, int item_hi) {
;     ...
;         const float dv = P.d[g * 16 + (lane & 15)];
; #pragma unroll
;         for (int r = 0; r < 8; ++r)
; #pragma unroll
;             for (int j = 0; j < 4; ++j) { const int t = 16 * r + (lane >> 4) * 4 + j; const float y = acc[r][j] + dv * UF[t * 16 + (lane & 15)]; YG[(tok0 + t) * 1024 + g * 16 + (lane & 15)] = f2bf(gelu_tanh(y)); }
	v_fma_f32 v2, v1, v2, v15
	v_mul_f32_e32 v15, 0x3d372713, v2
	v_mul_f32_e32 v15, v2, v15
	v_fma_f32 v15, v2, v15, v2
	v_mul_f32_e32 v15, 0x3f4c422a, v15
	v_add_f32_e32 v15, v15, v15
	v_mul_f32_e32 v15, 0xbfb8aa3b, v15
	v_exp_f32_e32 v15, v15
	s_nop 0
	v_add_f32_e32 v15, 1.0, v15
	v_rcp_f32_e32 v15, v15
	s_nop 0
	v_mul_f32_e32 v2, v2, v15
	v_ashrrev_i32_e32 v15, 31, v14
	v_lshl_add_u64 v[14:15], s[12:13], 0, v[14:15]
	v_lshlrev_b64 v[14:15], 11, v[14:15]
	v_cvt_pk_bf16_f32 v2, v2, s0
	v_lshl_add_u64 v[14:15], v[38:39], 0, v[14:15]
	global_store_short v[14:15], v2, off
	v_add_u32_e32 v14, 0x52, v40
	v_lshl_add_u32 v2, v14, 6, v42
	ds_read_b32 v2, v2
	s_waitcnt lgkmcnt(0)
	v_fma_f32 v2, v1, v2, v16
	v_mul_f32_e32 v15, 0x3d372713, v2
	v_mul_f32_e32 v15, v2, v15
	v_fma_f32 v15, v2, v15, v2
	v_mul_f32_e32 v15, 0x3f4c422a, v15
	v_add_f32_e32 v15, v15, v15
	v_mul_f32_e32 v15, 0xbfb8aa3b, v15
	v_exp_f32_e32 v15, v15
	s_nop 0
	v_add_f32_e32 v15, 1.0, v15
	v_rcp_f32_e32 v15, v15
	s_nop 0
	v_mul_f32_e32 v2, v2, v15
	v_ashrrev_i32_e32 v15, 31, v14
	v_lshl_add_u64 v[14:15], s[12:13], 0, v[14:15]
	v_lshlrev_b64 v[14:15], 11, v[14:15]
	v_cvt_pk_bf16_f32 v2, v2, s0
	v_lshl_add_u64 v[14:15], v[38:39], 0, v[14:15]
	global_store_short v[14:15], v2, off
	v_add_u32_e32 v14, 0x53, v40
	v_lshl_add_u32 v2, v14, 6, v42
	ds_read_b32 v2, v2
	v_ashrrev_i32_e32 v15, 31, v14
	v_lshl_add_u64 v[14:15], s[12:13], 0, v[14:15]
	v_lshlrev_b64 v[14:15], 11, v[14:15]
	v_lshl_add_u64 v[14:15], v[38:39], 0, v[14:15]
	s_waitcnt lgkmcnt(0)
	v_fmac_f32_e32 v17, v1, v2
	v_mul_f32_e32 v2, 0x3d372713, v17
	v_mul_f32_e32 v2, v17, v2
	v_fma_f32 v2, v17, v2, v17
	v_mul_f32_e32 v2, 0x3f4c422a, v2
	v_add_f32_e32 v2, v2, v2
	v_mul_f32_e32 v2, 0xbfb8aa3b, v2
	v_exp_f32_e32 v2, v2
	s_nop 0
	v_add_f32_e32 v2, 1.0, v2
	v_rcp_f32_e32 v2, v2
	s_nop 0
	v_mul_f32_e32 v2, v17, v2
	v_cvt_pk_bf16_f32 v2, v2, s0
	global_store_short v[14:15], v2, off
	v_add_u32_e32 v14, 0x60, v40
	v_lshl_add_u32 v2, v14, 6, v42
	ds_read_b32 v2, v2
	v_ashrrev_i32_e32 v15, 31, v14
	v_lshl_add_u64 v[14:15], s[12:13], 0, v[14:15]
	v_lshlrev_b64 v[14:15], 11, v[14:15]
	v_lshl_add_u64 v[14:15], v[38:39], 0, v[14:15]
	s_waitcnt lgkmcnt(0)
	v_fma_f32 v2, v1, v2, v10
	v_mul_f32_e32 v10, 0x3d372713, v2
	v_mul_f32_e32 v10, v2, v10
	v_fma_f32 v10, v2, v10, v2
	v_mul_f32_e32 v10, 0x3f4c422a, v10
	v_add_f32_e32 v10, v10, v10
	v_mul_f32_e32 v10, 0xbfb8aa3b, v10
	v_exp_f32_e32 v10, v10
	s_nop 0
	v_add_f32_e32 v10, 1.0, v10
	v_rcp_f32_e32 v10, v10
	s_nop 0
	v_mul_f32_e32 v2, v2, v10
	v_cvt_pk_bf16_f32 v2, v2, s0
	v_add_u32_e32 v10, 0x61, v40
	global_store_short v[14:15], v2, off
	v_lshl_add_u32 v2, v10, 6, v42
	ds_read_b32 v2, v2
	s_waitcnt lgkmcnt(0)
	v_fma_f32 v2, v1, v2, v11
	v_mul_f32_e32 v11, 0x3d372713, v2
	v_mul_f32_e32 v11, v2, v11
	v_fma_f32 v11, v2, v11, v2
	v_mul_f32_e32 v11, 0x3f4c422a, v11
	v_add_f32_e32 v11, v11, v11
	v_mul_f32_e32 v11, 0xbfb8aa3b, v11
	v_exp_f32_e32 v11, v11
	s_nop 0
	v_add_f32_e32 v11, 1.0, v11
	v_rcp_f32_e32 v11, v11
	s_nop 0
	v_mul_f32_e32 v2, v2, v11
	v_ashrrev_i32_e32 v11, 31, v10
	v_lshl_add_u64 v[10:11], s[12:13], 0, v[10:11]
	v_lshlrev_b64 v[10:11], 11, v[10:11]
	v_cvt_pk_bf16_f32 v2, v2, s0
	v_lshl_add_u64 v[10:11], v[38:39], 0, v[10:11]
	global_store_short v[10:11], v2, off
	v_add_u32_e32 v10, 0x62, v40
	v_lshl_add_u32 v2, v10, 6, v42
	ds_read_b32 v2, v2
	s_waitcnt lgkmcnt(0)
; DI bf16 f2bf(float f) { return (bf16)(pk2(f, 0.f) & 0xffffu); }
; DI float gelu_tanh(float x) { const float u = 0.7978845608028654f * (x + 0.044715f * x * x * x); return x * sigm(2.0f * u); }
; DI void s5_passC(const Ctx& C, const S5P& P, const bf16* PROJ, const f32x2* END, bf16* YG  , int item_lo, int item_hi) {
;     ...
;     for (int item = item_lo + C.gw; item < item_hi; item += C.ngw) {
;     ...
;         const float dv = P.d[g * 16 + (lane & 15)];
; #pragma unroll
;         for (int r = 0; r < 8; ++r)
; #pragma unroll
;             for (int j = 0; j < 4; ++j) { const int t = 16 * r + (lane >> 4) * 4 + j; const float y = acc[r][j] + dv * UF[t * 16 + (lane & 15)]; YG[(tok0 + t) * 1024 + g * 16 + (lane & 15)] = f2bf(gelu_tanh(y)); }
;         asm volatile("s_waitcnt lgkmcnt(0)" ::: "memory");
;     }
	v_fma_f32 v2, v1, v2, v12
	v_mul_f32_e32 v11, 0x3d372713, v2
	v_mul_f32_e32 v11, v2, v11
	v_fma_f32 v11, v2, v11, v2
	v_mul_f32_e32 v11, 0x3f4c422a, v11
	v_add_f32_e32 v11, v11, v11
	v_mul_f32_e32 v11, 0xbfb8aa3b, v11
	v_exp_f32_e32 v11, v11
	s_nop 0
	v_add_f32_e32 v11, 1.0, v11
	v_rcp_f32_e32 v11, v11
	s_nop 0
	v_mul_f32_e32 v2, v2, v11
	v_ashrrev_i32_e32 v11, 31, v10
	v_lshl_add_u64 v[10:11], s[12:13], 0, v[10:11]
	v_lshlrev_b64 v[10:11], 11, v[10:11]
	v_cvt_pk_bf16_f32 v2, v2, s0
	v_lshl_add_u64 v[10:11], v[38:39], 0, v[10:11]
	global_store_short v[10:11], v2, off
	v_add_u32_e32 v10, 0x63, v40
	v_lshl_add_u32 v2, v10, 6, v42
	ds_read_b32 v2, v2
	v_ashrrev_i32_e32 v11, 31, v10
	v_lshl_add_u64 v[10:11], s[12:13], 0, v[10:11]
	v_lshlrev_b64 v[10:11], 11, v[10:11]
	v_lshl_add_u64 v[10:11], v[38:39], 0, v[10:11]
	s_waitcnt lgkmcnt(0)
	v_fmac_f32_e32 v13, v1, v2
	v_mul_f32_e32 v2, 0x3d372713, v13
	v_mul_f32_e32 v2, v13, v2
	v_fma_f32 v2, v13, v2, v13
	v_mul_f32_e32 v2, 0x3f4c422a, v2
	v_add_f32_e32 v2, v2, v2
	v_mul_f32_e32 v2, 0xbfb8aa3b, v2
	v_exp_f32_e32 v2, v2
	s_nop 0
	v_add_f32_e32 v2, 1.0, v2
	v_rcp_f32_e32 v2, v2
	s_nop 0
	v_mul_f32_e32 v2, v13, v2
	v_cvt_pk_bf16_f32 v2, v2, s0
	global_store_short v[10:11], v2, off
	v_add_u32_e32 v10, 0x70, v40
	v_lshl_add_u32 v2, v10, 6, v42
	ds_read_b32 v2, v2
	v_ashrrev_i32_e32 v11, 31, v10
	v_lshl_add_u64 v[10:11], s[12:13], 0, v[10:11]
	v_lshlrev_b64 v[10:11], 11, v[10:11]
	v_lshl_add_u64 v[10:11], v[38:39], 0, v[10:11]
	s_waitcnt lgkmcnt(0)
	v_fma_f32 v2, v1, v2, v6
	v_mul_f32_e32 v6, 0x3d372713, v2
	v_mul_f32_e32 v6, v2, v6
	v_fma_f32 v6, v2, v6, v2
	v_mul_f32_e32 v6, 0x3f4c422a, v6
	v_add_f32_e32 v6, v6, v6
	v_mul_f32_e32 v6, 0xbfb8aa3b, v6
	v_exp_f32_e32 v6, v6
	s_nop 0
	v_add_f32_e32 v6, 1.0, v6
	v_rcp_f32_e32 v6, v6
	s_nop 0
	v_mul_f32_e32 v2, v2, v6
	v_cvt_pk_bf16_f32 v2, v2, s0
	v_add_u32_e32 v6, 0x71, v40
	global_store_short v[10:11], v2, off
	v_lshl_add_u32 v2, v6, 6, v42
	ds_read_b32 v2, v2
	s_waitcnt lgkmcnt(0)
	v_fma_f32 v2, v1, v2, v7
	v_mul_f32_e32 v7, 0x3d372713, v2
	v_mul_f32_e32 v7, v2, v7
	v_fma_f32 v7, v2, v7, v2
	v_mul_f32_e32 v7, 0x3f4c422a, v7
	v_add_f32_e32 v7, v7, v7
	v_mul_f32_e32 v7, 0xbfb8aa3b, v7
	v_exp_f32_e32 v7, v7
	s_nop 0
	v_add_f32_e32 v7, 1.0, v7
	v_rcp_f32_e32 v7, v7
	s_nop 0
	v_mul_f32_e32 v2, v2, v7
	v_ashrrev_i32_e32 v7, 31, v6
	v_lshl_add_u64 v[6:7], s[12:13], 0, v[6:7]
	v_lshlrev_b64 v[6:7], 11, v[6:7]
	v_cvt_pk_bf16_f32 v2, v2, s0
	v_lshl_add_u64 v[6:7], v[38:39], 0, v[6:7]
	global_store_short v[6:7], v2, off
	v_add_u32_e32 v6, 0x72, v40
	v_lshl_add_u32 v2, v6, 6, v42
	ds_read_b32 v2, v2
	s_waitcnt lgkmcnt(0)
	v_fma_f32 v2, v1, v2, v8
	v_mul_f32_e32 v7, 0x3d372713, v2
	v_mul_f32_e32 v7, v2, v7
	v_fma_f32 v7, v2, v7, v2
	v_mul_f32_e32 v7, 0x3f4c422a, v7
	v_add_f32_e32 v7, v7, v7
	v_mul_f32_e32 v7, 0xbfb8aa3b, v7
	v_exp_f32_e32 v7, v7
	s_nop 0
	v_add_f32_e32 v7, 1.0, v7
	v_rcp_f32_e32 v7, v7
	s_nop 0
	v_mul_f32_e32 v2, v2, v7
	v_ashrrev_i32_e32 v7, 31, v6
	v_lshl_add_u64 v[6:7], s[12:13], 0, v[6:7]
	v_lshlrev_b64 v[6:7], 11, v[6:7]
	v_cvt_pk_bf16_f32 v2, v2, s0
	v_lshl_add_u64 v[6:7], v[38:39], 0, v[6:7]
	global_store_short v[6:7], v2, off
	v_add_u32_e32 v6, 0x73, v40
	v_lshl_add_u32 v2, v6, 6, v42
	ds_read_b32 v2, v2
	v_ashrrev_i32_e32 v7, 31, v6
	v_lshl_add_u64 v[6:7], s[12:13], 0, v[6:7]
	v_lshlrev_b64 v[6:7], 11, v[6:7]
	v_lshl_add_u64 v[6:7], v[38:39], 0, v[6:7]
	s_waitcnt lgkmcnt(0)
	v_fmac_f32_e32 v9, v1, v2
	v_mul_f32_e32 v1, 0x3d372713, v9
	v_mul_f32_e32 v1, v9, v1
	v_fma_f32 v1, v9, v1, v9
	v_mul_f32_e32 v1, 0x3f4c422a, v1
	v_add_f32_e32 v1, v1, v1
	v_mul_f32_e32 v1, 0xbfb8aa3b, v1
	v_exp_f32_e32 v1, v1
	s_nop 0
	v_add_f32_e32 v1, 1.0, v1
	v_rcp_f32_e32 v1, v1
	s_nop 0
	v_mul_f32_e32 v1, v9, v1
	v_cvt_pk_bf16_f32 v1, v1, s0
	global_store_short v[6:7], v1, off
	s_waitcnt lgkmcnt(0)
	v_readlane_b32 s0, v255, 52
	s_add_i32 s30, s30, s0
	s_cmpk_lt_i32 s30, 0x1800
	s_cbranch_scc1 .LBB0_606

; template <int DIRN> DI void s5_dir(const S5P& P, const f32x2* END, const LAS float* UF, LAS bf16* XT, int b, int seg, int g, const bf16x8 (&bfr)[4], f32x4 (&acc)[8], int lane) {
;     ...
;     const int sl = DIRN ? SNSEG - 1 - seg : seg; float xr = 0.f, xi = 0.f;
;     { float Lr = lr, Li = li;
; #pragma unroll
;         for (int i = 0; i < 7; ++i) { const float nr = Lr * Lr - Li * Li, ni = 2.0f * Lr * Li; Lr = nr; Li = ni; }
; #pragma unroll 8
;         for (int j = 0; j < sl; ++j) { const float* ep = (const float*)END + ((size_t)((b * 2 + DIRN) * SNSEG + j)) * 8192 + g * 128 + lane; const f32x2 e = {ep[0], ep[64]}; const float nr = Lr * xr - Li * xi + e.x, ni = Lr * xi + Li * xr + e.y; xr = nr; xi = ni; } }
.LBB0_691:
	global_load_dword v184, v[80:81], off
	global_load_dword v185, v[80:81], off offset:256
	v_add_co_u32_e32 v80, vcc, 0x8000, v80
	s_nop 1
	v_addc_co_u32_e32 v81, vcc, 0, v81, vcc
	global_load_dword v186, v[80:81], off
	global_load_dword v187, v[80:81], off offset:256
	v_add_co_u32_e32 v80, vcc, 0x8000, v80
	s_nop 1
	v_addc_co_u32_e32 v81, vcc, 0, v81, vcc
	global_load_dword v188, v[80:81], off
	global_load_dword v189, v[80:81], off offset:256
	v_add_co_u32_e32 v80, vcc, 0x8000, v80
	s_nop 1
	v_addc_co_u32_e32 v81, vcc, 0, v81, vcc
	global_load_dword v190, v[80:81], off
	global_load_dword v191, v[80:81], off offset:256
	v_add_co_u32_e32 v80, vcc, 0x8000, v80
	s_nop 1
	v_addc_co_u32_e32 v81, vcc, 0, v81, vcc
	global_load_dword v192, v[80:81], off
	global_load_dword v193, v[80:81], off offset:256
	v_add_co_u32_e32 v80, vcc, 0x8000, v80
	s_nop 1
	v_addc_co_u32_e32 v81, vcc, 0, v81, vcc
	global_load_dword v194, v[80:81], off
	global_load_dword v195, v[80:81], off offset:256
	v_add_co_u32_e32 v80, vcc, 0x8000, v80
	s_nop 1
	v_addc_co_u32_e32 v81, vcc, 0, v81, vcc
	global_load_dword v196, v[80:81], off
	global_load_dword v197, v[80:81], off offset:256
	v_add_co_u32_e32 v80, vcc, 0x8000, v80
	s_nop 1
	v_addc_co_u32_e32 v81, vcc, 0, v81, vcc
	global_load_dword v198, v[80:81], off
	global_load_dword v199, v[80:81], off offset:256
	v_add_co_u32_e32 v80, vcc, 0x8000, v80
	s_nop 1
	v_addc_co_u32_e32 v81, vcc, 0, v81, vcc
	s_add_i32 s1, s1, 8
	v_pk_mul_f32 v[84:85], v[74:75], v[172:173] op_sel:[0,1] op_sel_hi:[1,0]
	v_pk_fma_f32 v[88:89], v[76:77], v[172:173], v[84:85]
	v_pk_fma_f32 v[82:83], v[76:77], v[172:173], v[84:85] neg_lo:[0,0,1] neg_hi:[0,0,1]
	v_mov_b32_e32 v83, v89
	s_waitcnt vmcnt(14) lgkmcnt(0)
	v_pk_add_f32 v[172:173], v[82:83], v[184:185]
	v_pk_mul_f32 v[84:85], v[74:75], v[172:173] op_sel:[0,1] op_sel_hi:[1,0]
	v_pk_fma_f32 v[88:89], v[76:77], v[172:173], v[84:85]
	v_pk_fma_f32 v[82:83], v[76:77], v[172:173], v[84:85] neg_lo:[0,0,1] neg_hi:[0,0,1]
	v_mov_b32_e32 v83, v89
	s_waitcnt vmcnt(12)
	v_pk_add_f32 v[172:173], v[82:83], v[186:187]
	v_pk_mul_f32 v[84:85], v[74:75], v[172:173] op_sel:[0,1] op_sel_hi:[1,0]
	v_pk_fma_f32 v[88:89], v[76:77], v[172:173], v[84:85]
	v_pk_fma_f32 v[82:83], v[76:77], v[172:173], v[84:85] neg_lo:[0,0,1] neg_hi:[0,0,1]
	v_mov_b32_e32 v83, v89
	s_waitcnt vmcnt(10)
	v_pk_add_f32 v[172:173], v[82:83], v[188:189]
	v_pk_mul_f32 v[84:85], v[74:75], v[172:173] op_sel:[0,1] op_sel_hi:[1,0]
	v_pk_fma_f32 v[88:89], v[76:77], v[172:173], v[84:85]
	v_pk_fma_f32 v[82:83], v[76:77], v[172:173], v[84:85] neg_lo:[0,0,1] neg_hi:[0,0,1]
	v_mov_b32_e32 v83, v89
	s_waitcnt vmcnt(8)
	v_pk_add_f32 v[172:173], v[82:83], v[190:191]
	v_pk_mul_f32 v[84:85], v[74:75], v[172:173] op_sel:[0,1] op_sel_hi:[1,0]
	v_pk_fma_f32 v[88:89], v[76:77], v[172:173], v[84:85]
	v_pk_fma_f32 v[82:83], v[76:77], v[172:173], v[84:85] neg_lo:[0,0,1] neg_hi:[0,0,1]
	v_mov_b32_e32 v83, v89
	s_waitcnt vmcnt(6)
	v_pk_add_f32 v[172:173], v[82:83], v[192:193]
	v_pk_mul_f32 v[84:85], v[74:75], v[172:173] op_sel:[0,1] op_sel_hi:[1,0]
	v_pk_fma_f32 v[88:89], v[76:77], v[172:173], v[84:85]
	v_pk_fma_f32 v[82:83], v[76:77], v[172:173], v[84:85] neg_lo:[0,0,1] neg_hi:[0,0,1]
	v_mov_b32_e32 v83, v89
	s_waitcnt vmcnt(4)
	v_pk_add_f32 v[172:173], v[82:83], v[194:195]
	v_pk_mul_f32 v[84:85], v[74:75], v[172:173] op_sel:[0,1] op_sel_hi:[1,0]
	v_pk_fma_f32 v[88:89], v[76:77], v[172:173], v[84:85]
	v_pk_fma_f32 v[82:83], v[76:77], v[172:173], v[84:85] neg_lo:[0,0,1] neg_hi:[0,0,1]
	v_mov_b32_e32 v83, v89
	s_waitcnt vmcnt(2)
	v_pk_add_f32 v[172:173], v[82:83], v[196:197]
	v_pk_mul_f32 v[84:85], v[74:75], v[172:173] op_sel:[0,1] op_sel_hi:[1,0]
	v_pk_fma_f32 v[88:89], v[76:77], v[172:173], v[84:85]
	v_pk_fma_f32 v[82:83], v[76:77], v[172:173], v[84:85] neg_lo:[0,0,1] neg_hi:[0,0,1]
	v_mov_b32_e32 v83, v89
	s_waitcnt vmcnt(0)
	v_pk_add_f32 v[172:173], v[82:83], v[198:199]
	s_cmp_eq_u32 s11, s1
	s_cbranch_scc0 .LBB0_691
	s_bfe_u32 s1, s54, 0x30006
	s_cmp_eq_u32 s1, 0
	s_cbranch_scc0 .LBB0_694
	s_branch .LBB0_696

; #define LAS __attribute__((address_space(3)))
; DI unsigned pk2(float lo, float hi) { return pg8::cvt_pk_bf16(lo, hi); }
; DI f32x4 mfma16(bf16x8 a, bf16x8 b, f32x4 c) { return __builtin_amdgcn_mfma_f32_16x16x32_bf16(a, b, c, 0, 0, 0); }
; template <int DIRN, int SUB> DI void s5_subtile(const LAS float* UF, LAS bf16* XT, float lr, float li, const f32x2 (&bb)[16], f32x2& x,
;                                                 const bf16x8 (&bfr)[4], f32x4& acc0, f32x4& acc1, int lane) {
;     ...
;     for (int i = 0; i < 32; ++i) { const int r = DIRN ? 31 - i : i;
;         x = s5_step((const LAS f32x4*)(UF + (32 * SUB + r) * 16), bb, lr, li, x);
;         const unsigned pkd = pk2(x.x, x.y); XT[r * 136 + lane] = (bf16)(pkd & 0xffffu); XT[r * 136 + 64 + lane] = (bf16)(pkd >> 16); }
; #pragma unroll
;     for (int ks = 0; ks < 4; ++ks) { const bf16x8 a0 = *(const LAS bf16x8*)(XT + (lane & 15) * 136 + 32 * ks + 8 * (lane >> 4)), a1 = *(const LAS bf16x8*)(XT + (16 + (lane & 15)) * 136 + 32 * ks + 8 * (lane >> 4));
;         acc0 = mfma16(a0, bfr[ks], acc0); acc1 = mfma16(a1, bfr[ks], acc1); }
.LBB0_697:
	s_add_i32 s1, s49, s0
	v_mov_b32_e32 v71, s1
	ds_read_b128 v[72:75], v71
	ds_read_b128 v[76:79], v71 offset:16
	ds_read_b128 v[80:83], v71 offset:32
	ds_read_b128 v[84:87], v71 offset:48
	s_waitcnt lgkmcnt(3)
	v_pk_mul_f32 v[88:89], v[178:179], v[72:73] op_sel:[0,1]
	v_pk_fma_f32 v[72:73], v[176:177], v[72:73], v[88:89] op_sel_hi:[1,0,1]
	v_pk_fma_f32 v[72:73], v[180:181], v[74:75], v[72:73] op_sel_hi:[1,0,1]
	v_pk_fma_f32 v[72:73], v[182:183], v[74:75], v[72:73] op_sel:[0,1,0]
	s_waitcnt lgkmcnt(2)
	v_pk_fma_f32 v[72:73], v[184:185], v[76:77], v[72:73] op_sel_hi:[1,0,1]
	v_pk_fma_f32 v[72:73], v[186:187], v[76:77], v[72:73] op_sel:[0,1,0]
	s_waitcnt lgkmcnt(1)
	v_pk_fma_f32 v[72:73], v[188:189], v[78:79], v[72:73] op_sel_hi:[1,0,1]
	v_pk_fma_f32 v[72:73], v[190:191], v[78:79], v[72:73] op_sel:[0,1,0]
	v_pk_mul_f32 v[74:75], v[194:195], v[80:81] op_sel:[0,1]
	v_pk_fma_f32 v[74:75], v[192:193], v[80:81], v[74:75] op_sel_hi:[1,0,1]
	v_pk_fma_f32 v[74:75], v[196:197], v[82:83], v[74:75] op_sel_hi:[1,0,1]
	v_pk_fma_f32 v[74:75], v[198:199], v[82:83], v[74:75] op_sel:[0,1,0]
	s_waitcnt lgkmcnt(0)
	v_mov_b32_e32 v76, v87
	v_pk_fma_f32 v[74:75], v[200:201], v[84:85], v[74:75] op_sel_hi:[1,0,1]
	v_pk_fma_f32 v[74:75], v[202:203], v[84:85], v[74:75] op_sel:[0,1,0]
	v_pk_fma_f32 v[74:75], v[204:205], v[86:87], v[74:75] op_sel_hi:[1,0,1]
	v_pk_fma_f32 v[74:75], v[174:175], v[76:77], v[74:75] op_sel_hi:[1,0,1]
	v_pk_add_f32 v[72:73], v[72:73], v[74:75]
	v_pk_fma_f32 v[72:73], v[140:141], v[172:173], v[72:73] op_sel:[0,1,0] op_sel_hi:[1,0,1]
	v_pk_fma_f32 v[172:173], v[136:137], v[172:173], v[72:73]
	v_add_u32_e32 v73, s49, v2
	v_cvt_pk_bf16_f32 v71, v172, s0
	v_cvt_pk_bf16_f32 v72, v173, s0
	s_add_i32 s0, s0, 64
	v_add_u32_e32 v2, 0x110, v2
	s_cmpk_lg_i32 s0, 0x800
	ds_write_b16 v73, v71
	ds_write_b16 v73, v72 offset:128
	s_cbranch_scc1 .LBB0_697
	v_and_b32_e32 v123, 15, v0
	v_mul_u32_u24_e32 v2, 0x110, v123
	v_lshlrev_b32_e32 v70, 1, v70
	v_add3_u32 v152, s49, v2, v70
	ds_read_b128 v[98:101], v152 offset:8192
	ds_read_b128 v[94:97], v152 offset:8256
	ds_read_b128 v[82:85], v152 offset:12544
	ds_read_b128 v[86:89], v152 offset:12608
	ds_read_b128 v[90:93], v152 offset:8320
	ds_read_b128 v[78:81], v152 offset:8384
	ds_read_b128 v[70:73], v152 offset:12672
	ds_read_b128 v[74:77], v152 offset:12736
	v_add_u32_e32 v2, s35, v206
	s_mov_b32 s0, 0
	v_mov_b32_e32 v102, v2
.LBB0_699:
	s_add_i32 s1, s40, s0
	v_mov_b32_e32 v103, s1
	ds_read_b128 v[104:107], v103
	ds_read_b128 v[108:111], v103 offset:16
	ds_read_b128 v[112:115], v103 offset:32
	ds_read_b128 v[116:119], v103 offset:48
	s_waitcnt lgkmcnt(3)
	v_pk_mul_f32 v[120:121], v[178:179], v[104:105] op_sel:[0,1]
	v_pk_fma_f32 v[104:105], v[176:177], v[104:105], v[120:121] op_sel_hi:[1,0,1]
	v_pk_fma_f32 v[104:105], v[180:181], v[106:107], v[104:105] op_sel_hi:[1,0,1]
	v_pk_fma_f32 v[104:105], v[182:183], v[106:107], v[104:105] op_sel:[0,1,0]
	s_waitcnt lgkmcnt(2)
	v_pk_fma_f32 v[104:105], v[184:185], v[108:109], v[104:105] op_sel_hi:[1,0,1]
	v_pk_fma_f32 v[104:105], v[186:187], v[108:109], v[104:105] op_sel:[0,1,0]
	s_waitcnt lgkmcnt(1)
	v_pk_fma_f32 v[104:105], v[188:189], v[110:111], v[104:105] op_sel_hi:[1,0,1]
	v_pk_fma_f32 v[104:105], v[190:191], v[110:111], v[104:105] op_sel:[0,1,0]
	v_pk_mul_f32 v[106:107], v[194:195], v[112:113] op_sel:[0,1]
	v_pk_fma_f32 v[106:107], v[192:193], v[112:113], v[106:107] op_sel_hi:[1,0,1]
	v_pk_fma_f32 v[106:107], v[196:197], v[114:115], v[106:107] op_sel_hi:[1,0,1]
	v_pk_fma_f32 v[106:107], v[198:199], v[114:115], v[106:107] op_sel:[0,1,0]
	s_waitcnt lgkmcnt(0)
	v_mov_b32_e32 v108, v119
	v_pk_fma_f32 v[106:107], v[200:201], v[116:117], v[106:107] op_sel_hi:[1,0,1]
	v_pk_fma_f32 v[106:107], v[202:203], v[116:117], v[106:107] op_sel:[0,1,0]
	v_pk_fma_f32 v[106:107], v[204:205], v[118:119], v[106:107] op_sel_hi:[1,0,1]
	v_pk_fma_f32 v[106:107], v[174:175], v[108:109], v[106:107] op_sel_hi:[1,0,1]
	v_pk_add_f32 v[104:105], v[104:105], v[106:107]
	v_pk_fma_f32 v[104:105], v[140:141], v[172:173], v[104:105] op_sel:[0,1,0] op_sel_hi:[1,0,1]
	v_pk_fma_f32 v[172:173], v[136:137], v[172:173], v[104:105]
	v_cvt_pk_bf16_f32 v103, v172, s0
	v_cvt_pk_bf16_f32 v104, v173, s0
	s_add_i32 s0, s0, 64
	ds_write_b16 v102, v103
	ds_write_b16 v102, v104 offset:128
	v_add_u32_e32 v102, 0x110, v102
	s_cmpk_lg_i32 s0, 0x800
	s_cbranch_scc1 .LBB0_699
	v_cvt_pk_bf16_f32 v38, v38, v39
	v_cvt_pk_bf16_f32 v39, v40, v41
	v_cvt_pk_bf16_f32 v40, v66, v67
	v_cvt_pk_bf16_f32 v41, v68, v69
	v_cvt_pk_bf16_f32 v46, v46, v47
	v_cvt_pk_bf16_f32 v47, v48, v49
	v_cvt_pk_bf16_f32 v49, v44, v45
	v_cvt_pk_bf16_f32 v44, -v58, -v59
	v_cvt_pk_bf16_f32 v45, -v60, -v61
	v_mfma_f32_16x16x32_bf16 v[58:61], v[98:101], v[38:41], 0
	v_cvt_pk_bf16_f32 v48, v42, v43
	v_cvt_pk_bf16_f32 v42, -v62, -v63
	v_cvt_pk_bf16_f32 v43, -v64, -v65
	v_mfma_f32_16x16x32_bf16 v[58:61], v[94:97], v[46:49], v[58:61]
	s_mov_b32 s0, 0
	v_mov_b32_e32 v110, v2
	v_mfma_f32_16x16x32_bf16 v[90:93], v[90:93], v[42:45], v[58:61]
	v_mfma_f32_16x16x32_bf16 v[58:61], v[82:85], v[38:41], 0
	v_mfma_f32_16x16x32_bf16 v[58:61], v[86:89], v[46:49], v[58:61]
	ds_read_b128 v[94:97], v152 offset:8192
	ds_read_b128 v[86:89], v152 offset:12544
	ds_read_b128 v[98:101], v152 offset:8256
	ds_read_b128 v[102:105], v152 offset:12608
	ds_read_b128 v[106:109], v152 offset:8320
	ds_read_b128 v[66:69], v152 offset:12672
	ds_read_b128 v[62:65], v152 offset:8384
	ds_read_b128 v[82:85], v152 offset:12736
; #define LAS __attribute__((address_space(3)))
; DI unsigned pk2(float lo, float hi) { return pg8::cvt_pk_bf16(lo, hi); }
; DI f32x4 mfma16(bf16x8 a, bf16x8 b, f32x4 c) { return __builtin_amdgcn_mfma_f32_16x16x32_bf16(a, b, c, 0, 0, 0); }
; template <int DIRN, int SUB> DI void s5_subtile(const LAS float* UF, LAS bf16* XT, float lr, float li, const f32x2 (&bb)[16], f32x2& x,
;                                                 const bf16x8 (&bfr)[4], f32x4& acc0, f32x4& acc1, int lane) {
;     ...
;     for (int i = 0; i < 32; ++i) { const int r = DIRN ? 31 - i : i;
;         x = s5_step((const LAS f32x4*)(UF + (32 * SUB + r) * 16), bb, lr, li, x);
;         const unsigned pkd = pk2(x.x, x.y); XT[r * 136 + lane] = (bf16)(pkd & 0xffffu); XT[r * 136 + 64 + lane] = (bf16)(pkd >> 16); }
; #pragma unroll
;     for (int ks = 0; ks < 4; ++ks) { const bf16x8 a0 = *(const LAS bf16x8*)(XT + (lane & 15) * 136 + 32 * ks + 8 * (lane >> 4)), a1 = *(const LAS bf16x8*)(XT + (16 + (lane & 15)) * 136 + 32 * ks + 8 * (lane >> 4));
;         acc0 = mfma16(a0, bfr[ks], acc0); acc1 = mfma16(a1, bfr[ks], acc1); }
.LBB0_701:
	s_add_i32 s1, s41, s0
	v_mov_b32_e32 v111, s1
	ds_read_b128 v[112:115], v111
	ds_read_b128 v[116:119], v111 offset:16
	ds_read_b128 v[230:233], v111 offset:32
	ds_read_b128 v[234:237], v111 offset:48
	s_waitcnt lgkmcnt(3)
	v_pk_mul_f32 v[120:121], v[178:179], v[112:113] op_sel:[0,1]
	v_pk_fma_f32 v[112:113], v[176:177], v[112:113], v[120:121] op_sel_hi:[1,0,1]
	v_pk_fma_f32 v[112:113], v[180:181], v[114:115], v[112:113] op_sel_hi:[1,0,1]
	v_pk_fma_f32 v[112:113], v[182:183], v[114:115], v[112:113] op_sel:[0,1,0]
	s_waitcnt lgkmcnt(2)
	v_pk_fma_f32 v[112:113], v[184:185], v[116:117], v[112:113] op_sel_hi:[1,0,1]
	v_pk_fma_f32 v[112:113], v[186:187], v[116:117], v[112:113] op_sel:[0,1,0]
	s_waitcnt lgkmcnt(1)
	v_pk_fma_f32 v[112:113], v[188:189], v[118:119], v[112:113] op_sel_hi:[1,0,1]
	v_pk_fma_f32 v[112:113], v[190:191], v[118:119], v[112:113] op_sel:[0,1,0]
	v_pk_mul_f32 v[114:115], v[194:195], v[230:231] op_sel:[0,1]
	v_pk_fma_f32 v[114:115], v[192:193], v[230:231], v[114:115] op_sel_hi:[1,0,1]
	v_pk_fma_f32 v[114:115], v[196:197], v[232:233], v[114:115] op_sel_hi:[1,0,1]
	v_pk_fma_f32 v[114:115], v[198:199], v[232:233], v[114:115] op_sel:[0,1,0]
	s_waitcnt lgkmcnt(0)
	v_mov_b32_e32 v116, v237
	v_pk_fma_f32 v[114:115], v[200:201], v[234:235], v[114:115] op_sel_hi:[1,0,1]
	v_pk_fma_f32 v[114:115], v[202:203], v[234:235], v[114:115] op_sel:[0,1,0]
	v_pk_fma_f32 v[114:115], v[204:205], v[236:237], v[114:115] op_sel_hi:[1,0,1]
	v_pk_fma_f32 v[114:115], v[174:175], v[116:117], v[114:115] op_sel_hi:[1,0,1]
	v_pk_add_f32 v[112:113], v[112:113], v[114:115]
	v_pk_fma_f32 v[112:113], v[140:141], v[172:173], v[112:113] op_sel:[0,1,0] op_sel_hi:[1,0,1]
	v_pk_fma_f32 v[172:173], v[136:137], v[172:173], v[112:113]
	v_cvt_pk_bf16_f32 v111, v172, s0
	v_cvt_pk_bf16_f32 v112, v173, s0
	s_add_i32 s0, s0, 64
	ds_write_b16 v110, v111
	ds_write_b16 v110, v112 offset:128
	v_add_u32_e32 v110, 0x110, v110
	s_cmpk_lg_i32 s0, 0x800
	s_cbranch_scc1 .LBB0_701
	v_cvt_pk_bf16_f32 v54, -v54, -v55
	v_cvt_pk_bf16_f32 v55, -v56, -v57
	v_cvt_pk_bf16_f32 v56, -v50, -v51
	v_cvt_pk_bf16_f32 v57, -v52, -v53
	v_mfma_f32_16x16x32_bf16 v[86:89], v[86:89], v[38:41], 0
	s_mov_b32 s0, 0
	v_mfma_f32_16x16x32_bf16 v[50:53], v[78:81], v[54:57], v[90:93]
	v_mfma_f32_16x16x32_bf16 v[78:81], v[94:97], v[38:41], 0
	v_mfma_f32_16x16x32_bf16 v[78:81], v[98:101], v[46:49], v[78:81]
	v_mfma_f32_16x16x32_bf16 v[78:81], v[106:109], v[42:45], v[78:81]
	v_mfma_f32_16x16x32_bf16 v[86:89], v[102:105], v[46:49], v[86:89]
	ds_read_b128 v[94:97], v152 offset:8192
	ds_read_b128 v[90:93], v152 offset:12544
	ds_read_b128 v[102:105], v152 offset:8256
	ds_read_b128 v[98:101], v152 offset:12608
	ds_read_b128 v[110:113], v152 offset:8320
	ds_read_b128 v[106:109], v152 offset:12672
	ds_read_b128 v[118:121], v152 offset:8384
	ds_read_b128 v[114:117], v152 offset:12736
.LBB0_703:
	s_add_i32 s1, s42, s0
	v_mov_b32_e32 v158, s1
	ds_read_b128 v[230:233], v158
	ds_read_b128 v[234:237], v158 offset:16
	ds_read_b128 v[238:241], v158 offset:32
	ds_read_b128 v[242:245], v158 offset:48
	s_waitcnt lgkmcnt(3)
	v_pk_mul_f32 v[158:159], v[178:179], v[230:231] op_sel:[0,1]
	v_pk_fma_f32 v[158:159], v[176:177], v[230:231], v[158:159] op_sel_hi:[1,0,1]
	v_pk_fma_f32 v[158:159], v[180:181], v[232:233], v[158:159] op_sel_hi:[1,0,1]
	s_waitcnt lgkmcnt(1)
	v_pk_fma_f32 v[158:159], v[182:183], v[232:233], v[158:159] op_sel:[0,1,0]
	v_pk_fma_f32 v[158:159], v[184:185], v[234:235], v[158:159] op_sel_hi:[1,0,1]
	v_pk_fma_f32 v[158:159], v[186:187], v[234:235], v[158:159] op_sel:[0,1,0]
	v_pk_fma_f32 v[158:159], v[188:189], v[236:237], v[158:159] op_sel_hi:[1,0,1]
	v_pk_fma_f32 v[158:159], v[190:191], v[236:237], v[158:159] op_sel:[0,1,0]
	v_pk_mul_f32 v[160:161], v[194:195], v[238:239] op_sel:[0,1]
	v_pk_fma_f32 v[160:161], v[192:193], v[238:239], v[160:161] op_sel_hi:[1,0,1]
	v_pk_fma_f32 v[160:161], v[196:197], v[240:241], v[160:161] op_sel_hi:[1,0,1]
	v_pk_fma_f32 v[160:161], v[198:199], v[240:241], v[160:161] op_sel:[0,1,0]
	s_waitcnt lgkmcnt(0)
	v_mov_b32_e32 v230, v245
	v_pk_fma_f32 v[160:161], v[200:201], v[242:243], v[160:161] op_sel_hi:[1,0,1]
	v_pk_fma_f32 v[160:161], v[202:203], v[242:243], v[160:161] op_sel:[0,1,0]
	v_pk_fma_f32 v[160:161], v[204:205], v[244:245], v[160:161] op_sel_hi:[1,0,1]
	v_pk_fma_f32 v[160:161], v[174:175], v[230:231], v[160:161] op_sel_hi:[1,0,1]
	v_pk_add_f32 v[158:159], v[158:159], v[160:161]
	v_pk_fma_f32 v[158:159], v[140:141], v[172:173], v[158:159] op_sel:[0,1,0] op_sel_hi:[1,0,1]
	v_pk_fma_f32 v[172:173], v[136:137], v[172:173], v[158:159]
	v_cvt_pk_bf16_f32 v158, v172, s0
	v_cvt_pk_bf16_f32 v159, v173, s0
	s_add_i32 s0, s0, 64
	ds_write_b16 v2, v158
	ds_write_b16 v2, v159 offset:128
	v_add_u32_e32 v2, 0x110, v2
	s_cmpk_eq_i32 s0, 0x800
	s_cbranch_scc0 .LBB0_703
; #define LAS __attribute__((address_space(3)))
; DI f32x4 mfma16(bf16x8 a, bf16x8 b, f32x4 c) { return __builtin_amdgcn_mfma_f32_16x16x32_bf16(a, b, c, 0, 0, 0); }
; DI void s5_disc(const S5P& P, int dir, int g, int p, float& lr, float& li, f32x2 (&bb)[16]) {
;     const float dt = expf(P.log_dt[dir * 64 + g]); const float are = P.a_re[(dir * 64 + g) * 64 + p], aim = P.a_im[(dir * 64 + g) * 64 + p];
;     const float mag = expf(dt * are); lr = mag * cosf(dt * aim); li = mag * sinf(dt * aim);
;     const float den = are * are + aim * aim, nr = lr - 1.0f; const float cr = (nr * are + li * aim) / den, ci = (li * are - nr * aim) / den;
;     const f32x4* br = (const f32x4*)(P.b_re + (size_t)(g * 64 + p) * 16); const f32x4* bi = (const f32x4*)(P.b_im + (size_t)(g * 64 + p) * 16);
; #pragma unroll
;     for (int q = 0; q < 4; ++q) { const f32x4 r = br[q], i = bi[q];
; #pragma unroll
;         for (int e = 0; e < 4; ++e) bb[4 * q + e] = (f32x2){cr * r[e] - ci * i[e], cr * i[e] + ci * r[e]}; }
; template <int DIRN, int SUB> DI void s5_subtile(const LAS float* UF, LAS bf16* XT, float lr, float li, const f32x2 (&bb)[16], f32x2& x,
;                                                 const bf16x8 (&bfr)[4], f32x4& acc0, f32x4& acc1, int lane) {
;     ...
;     for (int ks = 0; ks < 4; ++ks) { const bf16x8 a0 = *(const LAS bf16x8*)(XT + (lane & 15) * 136 + 32 * ks + 8 * (lane >> 4)), a1 = *(const LAS bf16x8*)(XT + (16 + (lane & 15)) * 136 + 32 * ks + 8 * (lane >> 4));
;         acc0 = mfma16(a0, bfr[ks], acc0); acc1 = mfma16(a1, bfr[ks], acc1); }
	v_mfma_f32_16x16x32_bf16 v[58:61], v[70:73], v[42:45], v[58:61]
	v_readlane_b32 s16, v252, 4
	v_readlane_b32 s28, v252, 16
	v_readlane_b32 s29, v252, 17
	v_mfma_f32_16x16x32_bf16 v[66:69], v[66:69], v[42:45], v[86:89]
	v_readlane_b32 s26, v252, 14
	v_readlane_b32 s27, v252, 15
	s_mov_b32 s0, 0x3fb8aa3b
	v_mfma_f32_16x16x32_bf16 v[62:65], v[62:65], v[54:57], v[78:81]
	v_readlane_b32 s20, v252, 8
	v_readlane_b32 s21, v252, 9
	v_readlane_b32 s22, v252, 10
	v_mfma_f32_16x16x32_bf16 v[58:61], v[74:77], v[54:57], v[58:61]
	v_readlane_b32 s23, v252, 11
	v_readlane_b32 s17, v252, 5
	v_readlane_b32 s18, v252, 6
	v_mfma_f32_16x16x32_bf16 v[66:69], v[82:85], v[54:57], v[66:69]
	ds_read_b128 v[78:81], v152 offset:8192
	ds_read_b128 v[82:85], v152 offset:8256
	v_readlane_b32 s19, v252, 7
	v_readlane_b32 s24, v252, 12
	v_mfma_f32_16x16x32_bf16 v[74:77], v[90:93], v[38:41], 0
	ds_read_b128 v[86:89], v152 offset:12544
	ds_read_b128 v[90:93], v152 offset:12608
	global_load_dword v2, v3, s[70:71] offset:256
	v_readlane_b32 s25, v252, 13
	s_waitcnt lgkmcnt(1)
	v_mfma_f32_16x16x32_bf16 v[86:89], v[86:89], v[38:41], 0
	v_readlane_b32 s30, v252, 18
	v_readlane_b32 s31, v252, 19
	v_mfma_f32_16x16x32_bf16 v[70:73], v[94:97], v[38:41], 0
	ds_read_b128 v[94:97], v152 offset:8320
	v_mfma_f32_16x16x32_bf16 v[78:81], v[78:81], v[38:41], 0
	s_waitcnt lgkmcnt(1)
	v_mfma_f32_16x16x32_bf16 v[86:89], v[90:93], v[46:49], v[86:89]
	v_add_u32_e32 v90, 0x1000, v122
	v_ashrrev_i32_e32 v91, 31, v90
	v_lshlrev_b64 v[90:91], 2, v[90:91]
	v_lshl_add_u64 v[92:93], s[28:29], 0, v[90:91]
	v_mfma_f32_16x16x32_bf16 v[70:73], v[102:105], v[46:49], v[70:73]
	v_lshl_add_u64 v[90:91], s[26:27], 0, v[90:91]
	v_mfma_f32_16x16x32_bf16 v[74:77], v[98:101], v[46:49], v[74:77]
	v_mfma_f32_16x16x32_bf16 v[78:81], v[82:85], v[46:49], v[78:81]
	ds_read_b128 v[82:85], v152 offset:8384
	ds_read_b128 v[98:101], v152 offset:12672
	ds_read_b128 v[102:105], v152 offset:12736
	global_load_dword v93, v[92:93], off
	s_nop 0
	global_load_dword v92, v[90:91], off
	s_waitcnt lgkmcnt(3)
	v_mfma_f32_16x16x32_bf16 v[78:81], v[94:97], v[42:45], v[78:81]
	s_waitcnt lgkmcnt(2)
	v_mfma_f32_16x16x32_bf16 v[78:81], v[82:85], v[54:57], v[78:81]
	s_waitcnt vmcnt(2)
	v_mul_f32_e32 v82, 0x3fb8aa3b, v2
	v_fma_f32 v83, v2, s0, -v82
	v_rndne_f32_e32 v84, v82
	v_fmac_f32_e32 v83, 0x32a5705f, v2
	v_sub_f32_e32 v82, v82, v84
	v_add_f32_e32 v82, v82, v83
	s_waitcnt lgkmcnt(1)
	v_mfma_f32_16x16x32_bf16 v[86:89], v[98:101], v[42:45], v[86:89]
	v_cvt_i32_f32_e32 v90, v84
	v_exp_f32_e32 v91, v82
	s_mov_b32 s0, 0xc2ce8ed0
	v_mfma_f32_16x16x32_bf16 v[70:73], v[110:113], v[42:45], v[70:73]
	v_cmp_ngt_f32_e32 vcc, s0, v2
	s_mov_b32 s0, 0x42b17218
	v_mfma_f32_16x16x32_bf16 v[74:77], v[106:109], v[42:45], v[74:77]
	s_waitcnt lgkmcnt(0)
	v_mfma_f32_16x16x32_bf16 v[82:85], v[102:105], v[54:57], v[86:89]
	v_mfma_f32_16x16x32_bf16 v[70:73], v[118:121], v[54:57], v[70:73]
	s_nop 1
	v_ldexp_f32 v86, v91, v90
	v_cndmask_b32_e32 v86, 0, v86, vcc
	v_cmp_nlt_f32_e32 vcc, s0, v2
	v_mfma_f32_16x16x32_bf16 v[74:77], v[114:117], v[54:57], v[74:77]
	s_brev_b32 s0, 18
	v_cndmask_b32_e32 v86, v219, v86, vcc
	s_waitcnt vmcnt(1)
	v_mul_f32_e32 v87, v86, v93
	v_and_b32_e32 v88, 0x7fffffff, v87
	v_cmp_nlt_f32_e64 s[20:21], |v87|, s0
	s_and_saveexec_b64 s[0:1], s[20:21]
	s_xor_b64 s[22:23], exec, s[0:1]
	s_cbranch_execz .LBB0_706
	v_lshrrev_b32_e32 v2, 23, v88
	v_add_u32_e32 v2, 0xffffff88, v2
	v_cmp_lt_u32_e32 vcc, 63, v2
	s_mov_b32 s10, 0xfe5163ab
	s_nop 0
	v_cndmask_b32_e32 v89, 0, v220, vcc
	v_add_u32_e32 v2, v89, v2
	v_cmp_lt_u32_e64 s[0:1], 31, v2
	s_nop 1
	v_cndmask_b32_e64 v89, 0, v221, s[0:1]
	v_add_u32_e32 v2, v89, v2
	v_cmp_lt_u32_e64 s[8:9], 31, v2
	s_nop 1
	v_cndmask_b32_e64 v89, 0, v221, s[8:9]
	v_add_u32_e32 v89, v89, v2
	v_and_b32_e32 v2, 0x7fffff, v88
	v_or_b32_e32 v104, 0x800000, v2
	v_mad_u64_u32 v[90:91], s[10:11], v104, s10, 0
	v_mov_b32_e32 v2, v91
	s_mov_b32 s10, 0x3c439041
	v_mad_u64_u32 v[94:95], s[10:11], v104, s10, v[2:3]
	v_mov_b32_e32 v2, v95
	s_mov_b32 s10, 0xdb629599
	v_mad_u64_u32 v[96:97], s[10:11], v104, s10, v[2:3]
	v_mov_b32_e32 v2, v97
	s_mov_b32 s10, 0xf534ddc0
	v_mad_u64_u32 v[98:99], s[10:11], v104, s10, v[2:3]
	v_mov_b32_e32 v2, v99
	s_mov_b32 s10, 0xfc2757d1
	v_mad_u64_u32 v[100:101], s[10:11], v104, s10, v[2:3]
	v_mov_b32_e32 v2, v101
	s_mov_b32 s10, 0x4e441529
	v_mad_u64_u32 v[102:103], s[10:11], v104, s10, v[2:3]
	v_mov_b32_e32 v2, v103
	s_mov_b32 s10, 0xa2f9836e
	v_mad_u64_u32 v[104:105], s[10:11], v104, s10, v[2:3]
	v_cndmask_b32_e32 v91, v102, v98, vcc
	v_cndmask_b32_e32 v2, v104, v100, vcc
	v_cndmask_b32_e32 v97, v105, v102, vcc
	v_cndmask_b32_e64 v95, v2, v91, s[0:1]
	v_cndmask_b32_e64 v2, v97, v2, s[0:1]
	v_cndmask_b32_e32 v97, v100, v96, vcc
	v_cndmask_b32_e64 v91, v91, v97, s[0:1]
	v_sub_u32_e32 v99, 32, v89
	v_cmp_eq_u32_e64 s[10:11], 0, v89
	v_cndmask_b32_e32 v89, v98, v94, vcc
	v_cndmask_b32_e64 v2, v2, v95, s[8:9]
	v_cndmask_b32_e64 v95, v95, v91, s[8:9]
	v_cndmask_b32_e64 v94, v97, v89, s[0:1]
	v_alignbit_b32 v100, v2, v95, v99
	v_cndmask_b32_e64 v91, v91, v94, s[8:9]
	v_cndmask_b32_e64 v2, v100, v2, s[10:11]
	v_alignbit_b32 v97, v95, v91, v99
	v_cndmask_b32_e32 v90, v96, v90, vcc
	v_cndmask_b32_e64 v95, v97, v95, s[10:11]
	v_bfe_u32 v100, v2, 29, 1
	v_cndmask_b32_e64 v89, v89, v90, s[0:1]
	v_alignbit_b32 v97, v2, v95, 30
	v_sub_u32_e32 v101, 0, v100
	v_cndmask_b32_e64 v89, v94, v89, s[8:9]
	v_xor_b32_e32 v97, v97, v101
	v_alignbit_b32 v90, v91, v89, v99
	v_cndmask_b32_e64 v90, v90, v91, s[10:11]
	v_ffbh_u32_e32 v94, v97
	v_alignbit_b32 v91, v95, v90, 30
	v_min_u32_e32 v94, 32, v94
	v_alignbit_b32 v89, v90, v89, 30
	v_xor_b32_e32 v91, v91, v101
	v_sub_u32_e32 v95, 31, v94
	v_xor_b32_e32 v89, v89, v101
	v_alignbit_b32 v96, v97, v91, v95
	v_alignbit_b32 v89, v91, v89, v95
	v_alignbit_b32 v90, v96, v89, 9
	v_ffbh_u32_e32 v91, v90
	v_min_u32_e32 v91, 32, v91
	v_lshrrev_b32_e32 v98, 29, v2
	v_not_b32_e32 v95, v91
	v_alignbit_b32 v89, v90, v89, v95
	v_lshlrev_b32_e32 v90, 31, v98
	v_or_b32_e32 v95, 0x33000000, v90
	v_add_lshl_u32 v91, v91, v94, 23
	v_lshrrev_b32_e32 v89, 9, v89
	v_sub_u32_e32 v91, v95, v91
	v_or_b32_e32 v90, 0.5, v90
	v_lshlrev_b32_e32 v94, 23, v94
	v_or_b32_e32 v89, v91, v89
	v_lshrrev_b32_e32 v91, 9, v96
	v_sub_u32_e32 v90, v90, v94
	v_or_b32_e32 v90, v91, v90
	v_mul_f32_e32 v91, 0x3fc90fda, v90
	s_mov_b32 s0, 0x3fc90fda
	v_fma_f32 v94, v90, s0, -v91
	v_fmac_f32_e32 v94, 0x33a22168, v90
	v_fmac_f32_e32 v94, 0x3fc90fda, v89
	v_lshrrev_b32_e32 v2, 30, v2
	v_add_f32_e32 v90, v91, v94
	v_add_u32_e32 v89, v100, v2

; #define LAS __attribute__((address_space(3)))
; DI unsigned pk2(float lo, float hi) { return pg8::cvt_pk_bf16(lo, hi); }
; DI f32x4 mfma16(bf16x8 a, bf16x8 b, f32x4 c) { return __builtin_amdgcn_mfma_f32_16x16x32_bf16(a, b, c, 0, 0, 0); }
; template <int DIRN, int SUB> DI void s5_subtile(const LAS float* UF, LAS bf16* XT, float lr, float li, const f32x2 (&bb)[16], f32x2& x,
;                                                 const bf16x8 (&bfr)[4], f32x4& acc0, f32x4& acc1, int lane) {
;     ...
;     for (int i = 0; i < 32; ++i) { const int r = DIRN ? 31 - i : i;
;         x = s5_step((const LAS f32x4*)(UF + (32 * SUB + r) * 16), bb, lr, li, x);
;         const unsigned pkd = pk2(x.x, x.y); XT[r * 136 + lane] = (bf16)(pkd & 0xffffu); XT[r * 136 + 64 + lane] = (bf16)(pkd >> 16); }
; #pragma unroll
;     for (int ks = 0; ks < 4; ++ks) { const bf16x8 a0 = *(const LAS bf16x8*)(XT + (lane & 15) * 136 + 32 * ks + 8 * (lane >> 4)), a1 = *(const LAS bf16x8*)(XT + (16 + (lane & 15)) * 136 + 32 * ks + 8 * (lane >> 4));
;         acc0 = mfma16(a0, bfr[ks], acc0); acc1 = mfma16(a1, bfr[ks], acc1); }
.LBB0_725:
	s_add_i32 s1, s43, s0
	v_mov_b32_e32 v2, s1
	ds_read_b128 v[6:9], v2
	ds_read_b128 v[10:13], v2 offset:16
	ds_read_b128 v[14:17], v2 offset:32
	ds_read_b128 v[18:21], v2 offset:48
	s_waitcnt lgkmcnt(3)
	v_pk_mul_f32 v[22:23], v[96:97], v[6:7] op_sel:[0,1]
	v_pk_fma_f32 v[6:7], v[94:95], v[6:7], v[22:23] op_sel_hi:[1,0,1]
	v_mov_b32_e32 v2, v9
	v_pk_fma_f32 v[6:7], v[34:35], v[8:9], v[6:7] op_sel_hi:[1,0,1]
	s_waitcnt lgkmcnt(1)
	v_pk_mul_f32 v[8:9], v[104:105], v[14:15] op_sel:[0,1]
	v_pk_fma_f32 v[6:7], v[30:31], v[2:3], v[6:7] op_sel_hi:[1,0,1]
	v_pk_fma_f32 v[6:7], v[32:33], v[10:11], v[6:7] op_sel_hi:[1,0,1]
	v_pk_fma_f32 v[8:9], v[102:103], v[14:15], v[8:9] op_sel_hi:[1,0,1]
	v_pk_fma_f32 v[6:7], v[36:37], v[10:11], v[6:7] op_sel:[0,1,0]
	v_pk_fma_f32 v[8:9], v[106:107], v[16:17], v[8:9] op_sel_hi:[1,0,1]
	v_pk_fma_f32 v[6:7], v[98:99], v[12:13], v[6:7] op_sel_hi:[1,0,1]
	v_pk_fma_f32 v[6:7], v[100:101], v[12:13], v[6:7] op_sel:[0,1,0]
	v_pk_fma_f32 v[8:9], v[108:109], v[16:17], v[8:9] op_sel:[0,1,0]
	s_waitcnt lgkmcnt(0)
	v_pk_fma_f32 v[8:9], v[110:111], v[18:19], v[8:9] op_sel_hi:[1,0,1]
	v_pk_fma_f32 v[8:9], v[112:113], v[18:19], v[8:9] op_sel:[0,1,0]
	v_pk_fma_f32 v[8:9], v[114:115], v[20:21], v[8:9] op_sel_hi:[1,0,1]
	v_pk_fma_f32 v[8:9], v[92:93], v[20:21], v[8:9] op_sel:[0,1,0]
	v_pk_add_f32 v[6:7], v[6:7], v[8:9]
	v_pk_fma_f32 v[6:7], v[88:89], v[90:91], v[6:7] op_sel:[0,1,0] op_sel_hi:[1,0,1]
	v_pk_fma_f32 v[90:91], v[86:87], v[90:91], v[6:7]
	v_cvt_pk_bf16_f32 v2, v90, s0
	v_cvt_pk_bf16_f32 v6, v91, s0
	s_sub_i32 s0, s0, 64
	ds_write_b16 v1, v2
	ds_write_b16 v1, v6 offset:128
	v_add_u32_e32 v1, 0xfffffef0, v1
	s_cmpk_lg_i32 s0, 0xf800
	s_cbranch_scc1 .LBB0_725
	ds_read_b128 v[6:9], v152 offset:8192
	ds_read_b128 v[10:13], v152 offset:12544
	ds_read_b128 v[14:17], v152 offset:8256
	ds_read_b128 v[18:21], v152 offset:12608
	v_add_u32_e32 v1, 0x40f0, v206
	s_movk_i32 s0, 0x17c0
	s_waitcnt lgkmcnt(3)
	v_mfma_f32_16x16x32_bf16 v[6:9], v[6:9], v[38:41], v[78:81]
	v_mov_b32_e32 v2, v1
	s_waitcnt lgkmcnt(2)
	v_mfma_f32_16x16x32_bf16 v[10:13], v[10:13], v[38:41], v[82:85]
	s_waitcnt lgkmcnt(1)
	v_mfma_f32_16x16x32_bf16 v[6:9], v[14:17], v[46:49], v[6:9]
	s_waitcnt lgkmcnt(0)
	v_mfma_f32_16x16x32_bf16 v[10:13], v[18:21], v[46:49], v[10:13]
	ds_read_b128 v[14:17], v152 offset:8320
	ds_read_b128 v[18:21], v152 offset:12672
	s_waitcnt lgkmcnt(1)
	v_mfma_f32_16x16x32_bf16 v[6:9], v[14:17], v[42:45], v[6:9]
	s_waitcnt lgkmcnt(0)
	v_mfma_f32_16x16x32_bf16 v[14:17], v[18:21], v[42:45], v[10:13]
	s_nop 2
	ds_read_b128 v[10:13], v152 offset:8384
	ds_read_b128 v[18:21], v152 offset:12736
	s_waitcnt lgkmcnt(1)
	v_mfma_f32_16x16x32_bf16 v[10:13], v[10:13], v[54:57], v[6:9]
	s_waitcnt lgkmcnt(0)
	v_mfma_f32_16x16x32_bf16 v[6:9], v[18:21], v[54:57], v[14:17]
.LBB0_727:
	s_add_i32 s1, s49, s0
	v_mov_b32_e32 v26, s1
	s_nop 0
	ds_read_b128 v[14:17], v26
	ds_read_b128 v[18:21], v26 offset:16
	ds_read_b128 v[22:25], v26 offset:32
	ds_read_b128 v[26:29], v26 offset:48
	s_waitcnt lgkmcnt(3)
	v_pk_mul_f32 v[78:79], v[96:97], v[14:15] op_sel:[0,1]
	v_pk_fma_f32 v[14:15], v[94:95], v[14:15], v[78:79] op_sel_hi:[1,0,1]
	v_pk_fma_f32 v[14:15], v[34:35], v[16:17], v[14:15] op_sel_hi:[1,0,1]
	v_pk_fma_f32 v[14:15], v[30:31], v[16:17], v[14:15] op_sel:[0,1,0]
	s_waitcnt lgkmcnt(2)
	v_pk_fma_f32 v[14:15], v[32:33], v[18:19], v[14:15] op_sel_hi:[1,0,1]
	v_pk_fma_f32 v[14:15], v[36:37], v[18:19], v[14:15] op_sel:[0,1,0]
	s_waitcnt lgkmcnt(1)
	v_pk_fma_f32 v[14:15], v[98:99], v[20:21], v[14:15] op_sel_hi:[1,0,1]
	v_pk_fma_f32 v[14:15], v[100:101], v[20:21], v[14:15] op_sel:[0,1,0]
	v_pk_mul_f32 v[16:17], v[104:105], v[22:23] op_sel:[0,1]
	v_pk_fma_f32 v[16:17], v[102:103], v[22:23], v[16:17] op_sel_hi:[1,0,1]
	v_pk_fma_f32 v[16:17], v[106:107], v[24:25], v[16:17] op_sel_hi:[1,0,1]
	v_pk_fma_f32 v[16:17], v[108:109], v[24:25], v[16:17] op_sel:[0,1,0]
	s_waitcnt lgkmcnt(0)
	v_mov_b32_e32 v18, v29
	v_pk_fma_f32 v[16:17], v[110:111], v[26:27], v[16:17] op_sel_hi:[1,0,1]
	v_pk_fma_f32 v[16:17], v[112:113], v[26:27], v[16:17] op_sel:[0,1,0]
	v_pk_fma_f32 v[16:17], v[114:115], v[28:29], v[16:17] op_sel_hi:[1,0,1]
	v_pk_fma_f32 v[16:17], v[92:93], v[18:19], v[16:17] op_sel_hi:[1,0,1]
	v_pk_add_f32 v[14:15], v[14:15], v[16:17]
	v_add_u32_e32 v16, s49, v2
	v_pk_fma_f32 v[14:15], v[88:89], v[90:91], v[14:15] op_sel:[0,1,0] op_sel_hi:[1,0,1]
	v_add_u32_e32 v2, 0xfffffef0, v2
	v_pk_fma_f32 v[90:91], v[86:87], v[90:91], v[14:15]
	v_cvt_pk_bf16_f32 v14, v90, s0
	v_cvt_pk_bf16_f32 v15, v91, s0
	s_sub_i32 s0, s0, 64
	s_cmpk_lg_i32 s0, 0xfc0
	ds_write_b16 v16, v14
	ds_write_b16 v16, v15 offset:128
	s_cbranch_scc1 .LBB0_727
	ds_read_b128 v[14:17], v152 offset:8192
	ds_read_b128 v[22:25], v152 offset:8256
	ds_read_b128 v[18:21], v152 offset:12544
	s_movk_i32 s0, 0xfc0
	v_mov_b32_e32 v2, v1
	s_waitcnt lgkmcnt(2)
	v_mfma_f32_16x16x32_bf16 v[14:17], v[14:17], v[38:41], v[70:73]
	s_waitcnt lgkmcnt(1)
	v_mfma_f32_16x16x32_bf16 v[14:17], v[22:25], v[46:49], v[14:17]
	ds_read_b128 v[22:25], v152 offset:12608
	s_waitcnt lgkmcnt(1)
	v_mfma_f32_16x16x32_bf16 v[18:21], v[18:21], v[38:41], v[74:77]
	s_waitcnt lgkmcnt(0)
	v_mfma_f32_16x16x32_bf16 v[18:21], v[22:25], v[46:49], v[18:21]
	ds_read_b128 v[22:25], v152 offset:8320
	s_waitcnt lgkmcnt(0)
	v_mfma_f32_16x16x32_bf16 v[14:17], v[22:25], v[42:45], v[14:17]
	ds_read_b128 v[22:25], v152 offset:12672
	s_waitcnt lgkmcnt(0)
	v_mfma_f32_16x16x32_bf16 v[22:25], v[22:25], v[42:45], v[18:21]
	s_nop 2
	ds_read_b128 v[18:21], v152 offset:8384
	s_waitcnt lgkmcnt(0)
	v_mfma_f32_16x16x32_bf16 v[18:21], v[18:21], v[54:57], v[14:17]
	s_nop 2
	ds_read_b128 v[14:17], v152 offset:12736
	s_waitcnt lgkmcnt(0)
	v_mfma_f32_16x16x32_bf16 v[14:17], v[14:17], v[54:57], v[22:25]
; #define LAS __attribute__((address_space(3)))
; DI unsigned pk2(float lo, float hi) { return pg8::cvt_pk_bf16(lo, hi); }
; DI f32x4 mfma16(bf16x8 a, bf16x8 b, f32x4 c) { return __builtin_amdgcn_mfma_f32_16x16x32_bf16(a, b, c, 0, 0, 0); }
; template <int DIRN, int SUB> DI void s5_subtile(const LAS float* UF, LAS bf16* XT, float lr, float li, const f32x2 (&bb)[16], f32x2& x,
;                                                 const bf16x8 (&bfr)[4], f32x4& acc0, f32x4& acc1, int lane) {
;     ...
;     for (int i = 0; i < 32; ++i) { const int r = DIRN ? 31 - i : i;
;         x = s5_step((const LAS f32x4*)(UF + (32 * SUB + r) * 16), bb, lr, li, x);
;         const unsigned pkd = pk2(x.x, x.y); XT[r * 136 + lane] = (bf16)(pkd & 0xffffu); XT[r * 136 + 64 + lane] = (bf16)(pkd >> 16); }
; #pragma unroll
;     for (int ks = 0; ks < 4; ++ks) { const bf16x8 a0 = *(const LAS bf16x8*)(XT + (lane & 15) * 136 + 32 * ks + 8 * (lane >> 4)), a1 = *(const LAS bf16x8*)(XT + (16 + (lane & 15)) * 136 + 32 * ks + 8 * (lane >> 4));
;         acc0 = mfma16(a0, bfr[ks], acc0); acc1 = mfma16(a1, bfr[ks], acc1); }
.LBB0_729:
	s_add_i32 s1, s49, s0
	v_mov_b32_e32 v74, s1
	s_nop 0
	ds_read_b128 v[22:25], v74
	ds_read_b128 v[26:29], v74 offset:16
	ds_read_b128 v[70:73], v74 offset:32
	ds_read_b128 v[74:77], v74 offset:48
	s_waitcnt lgkmcnt(3)
	v_pk_mul_f32 v[78:79], v[96:97], v[22:23] op_sel:[0,1]
	v_pk_fma_f32 v[22:23], v[94:95], v[22:23], v[78:79] op_sel_hi:[1,0,1]
	v_pk_fma_f32 v[22:23], v[34:35], v[24:25], v[22:23] op_sel_hi:[1,0,1]
	v_pk_fma_f32 v[22:23], v[30:31], v[24:25], v[22:23] op_sel:[0,1,0]
	s_waitcnt lgkmcnt(2)
	v_pk_fma_f32 v[22:23], v[32:33], v[26:27], v[22:23] op_sel_hi:[1,0,1]
	v_pk_fma_f32 v[22:23], v[36:37], v[26:27], v[22:23] op_sel:[0,1,0]
	s_waitcnt lgkmcnt(1)
	v_pk_fma_f32 v[22:23], v[98:99], v[28:29], v[22:23] op_sel_hi:[1,0,1]
	v_pk_fma_f32 v[22:23], v[100:101], v[28:29], v[22:23] op_sel:[0,1,0]
	v_pk_mul_f32 v[24:25], v[104:105], v[70:71] op_sel:[0,1]
	v_pk_fma_f32 v[24:25], v[102:103], v[70:71], v[24:25] op_sel_hi:[1,0,1]
	v_pk_fma_f32 v[24:25], v[106:107], v[72:73], v[24:25] op_sel_hi:[1,0,1]
	v_pk_fma_f32 v[24:25], v[108:109], v[72:73], v[24:25] op_sel:[0,1,0]
	s_waitcnt lgkmcnt(0)
	v_mov_b32_e32 v26, v77
	v_pk_fma_f32 v[24:25], v[110:111], v[74:75], v[24:25] op_sel_hi:[1,0,1]
	v_pk_fma_f32 v[24:25], v[112:113], v[74:75], v[24:25] op_sel:[0,1,0]
	v_pk_fma_f32 v[24:25], v[114:115], v[76:77], v[24:25] op_sel_hi:[1,0,1]
	v_pk_fma_f32 v[24:25], v[92:93], v[26:27], v[24:25] op_sel_hi:[1,0,1]
	v_pk_add_f32 v[22:23], v[22:23], v[24:25]
	v_add_u32_e32 v24, s49, v2
	v_pk_fma_f32 v[22:23], v[88:89], v[90:91], v[22:23] op_sel:[0,1,0] op_sel_hi:[1,0,1]
	v_add_u32_e32 v2, 0xfffffef0, v2
	v_pk_fma_f32 v[90:91], v[86:87], v[90:91], v[22:23]
	v_cvt_pk_bf16_f32 v22, v90, s0
	v_cvt_pk_bf16_f32 v23, v91, s0
	s_sub_i32 s0, s0, 64
	s_cmpk_lg_i32 s0, 0x7c0
	ds_write_b16 v24, v22
	ds_write_b16 v24, v23 offset:128
	s_cbranch_scc1 .LBB0_729
	ds_read_b128 v[22:25], v152 offset:8192
	ds_read_b128 v[26:29], v152 offset:12544
	s_movk_i32 s0, 0x7c0
	s_waitcnt lgkmcnt(1)
	v_mfma_f32_16x16x32_bf16 v[22:25], v[22:25], v[38:41], v[62:65]
	s_nop 2
	ds_read_b128 v[62:65], v152 offset:8256
	s_waitcnt lgkmcnt(1)
	v_mfma_f32_16x16x32_bf16 v[26:29], v[26:29], v[38:41], v[66:69]
	s_waitcnt lgkmcnt(0)
	v_mfma_f32_16x16x32_bf16 v[22:25], v[62:65], v[46:49], v[22:25]
	ds_read_b128 v[62:65], v152 offset:12608
	s_waitcnt lgkmcnt(0)
	v_mfma_f32_16x16x32_bf16 v[26:29], v[62:65], v[46:49], v[26:29]
	ds_read_b128 v[62:65], v152 offset:8320
	s_waitcnt lgkmcnt(0)
	v_mfma_f32_16x16x32_bf16 v[22:25], v[62:65], v[42:45], v[22:25]
	ds_read_b128 v[62:65], v152 offset:12672
	s_waitcnt lgkmcnt(0)
	v_mfma_f32_16x16x32_bf16 v[62:65], v[62:65], v[42:45], v[26:29]
	s_nop 2
	ds_read_b128 v[26:29], v152 offset:8384
	s_waitcnt lgkmcnt(0)
	v_mfma_f32_16x16x32_bf16 v[26:29], v[26:29], v[54:57], v[22:25]
	s_nop 2
	ds_read_b128 v[22:25], v152 offset:12736
	s_waitcnt lgkmcnt(0)
	v_mfma_f32_16x16x32_bf16 v[22:25], v[22:25], v[54:57], v[62:65]
.LBB0_731:
	s_add_i32 s1, s49, s0
	v_mov_b32_e32 v2, s1
	s_nop 0
	ds_read_b128 v[62:65], v2
	ds_read_b128 v[66:69], v2 offset:16
	ds_read_b128 v[70:73], v2 offset:32
	ds_read_b128 v[74:77], v2 offset:48
	s_waitcnt lgkmcnt(3)
	v_pk_mul_f32 v[78:79], v[96:97], v[62:63] op_sel:[0,1]
	v_pk_fma_f32 v[62:63], v[94:95], v[62:63], v[78:79] op_sel_hi:[1,0,1]
	v_mov_b32_e32 v2, v65
	v_pk_fma_f32 v[62:63], v[34:35], v[64:65], v[62:63] op_sel_hi:[1,0,1]
	s_waitcnt lgkmcnt(1)
	v_pk_mul_f32 v[64:65], v[104:105], v[70:71] op_sel:[0,1]
	v_pk_fma_f32 v[62:63], v[30:31], v[2:3], v[62:63] op_sel_hi:[1,0,1]
	v_pk_fma_f32 v[62:63], v[32:33], v[66:67], v[62:63] op_sel_hi:[1,0,1]
	v_pk_fma_f32 v[64:65], v[102:103], v[70:71], v[64:65] op_sel_hi:[1,0,1]
	v_pk_fma_f32 v[62:63], v[36:37], v[66:67], v[62:63] op_sel:[0,1,0]
	v_pk_fma_f32 v[64:65], v[106:107], v[72:73], v[64:65] op_sel_hi:[1,0,1]
	v_pk_fma_f32 v[62:63], v[98:99], v[68:69], v[62:63] op_sel_hi:[1,0,1]
	v_pk_fma_f32 v[62:63], v[100:101], v[68:69], v[62:63] op_sel:[0,1,0]
	v_pk_fma_f32 v[64:65], v[108:109], v[72:73], v[64:65] op_sel:[0,1,0]
	s_waitcnt lgkmcnt(0)
	v_pk_fma_f32 v[64:65], v[110:111], v[74:75], v[64:65] op_sel_hi:[1,0,1]
	v_pk_fma_f32 v[64:65], v[112:113], v[74:75], v[64:65] op_sel:[0,1,0]
	v_pk_fma_f32 v[64:65], v[114:115], v[76:77], v[64:65] op_sel_hi:[1,0,1]
	v_pk_fma_f32 v[64:65], v[92:93], v[76:77], v[64:65] op_sel:[0,1,0]
	v_pk_add_f32 v[62:63], v[62:63], v[64:65]
	v_pk_fma_f32 v[62:63], v[88:89], v[90:91], v[62:63] op_sel:[0,1,0] op_sel_hi:[1,0,1]
	v_pk_fma_f32 v[90:91], v[86:87], v[90:91], v[62:63]
	v_add_u32_e32 v63, s49, v1
	v_cvt_pk_bf16_f32 v2, v90, s0
	v_cvt_pk_bf16_f32 v62, v91, s0
	s_sub_i32 s0, s0, 64
	v_add_u32_e32 v1, 0xfffffef0, v1
	s_cmpk_eq_i32 s0, 0xffc0
	ds_write_b16 v63, v2
	ds_write_b16 v63, v62 offset:128
	s_cbranch_scc0 .LBB0_731
; DI bf16 f2bf(float f) { return (bf16)(pk2(f, 0.f) & 0xffffu); }
; DI float gelu_tanh(float x) { const float u = 0.7978845608028654f * (x + 0.044715f * x * x * x); return x * sigm(2.0f * u); }
; DI void s5_passC(const Ctx& C, const S5P& P, const bf16* PROJ, const f32x2* END, bf16* YG  , int item_lo, int item_hi) {
;     ...
;         const float dv = P.d[g * 16 + (lane & 15)];
; #pragma unroll
;         for (int r = 0; r < 8; ++r)
; #pragma unroll
;             for (int j = 0; j < 4; ++j) { const int t = 16 * r + (lane >> 4) * 4 + j; const float y = acc[r][j] + dv * UF[t * 16 + (lane & 15)]; YG[(tok0 + t) * 1024 + g * 16 + (lane & 15)] = f2bf(gelu_tanh(y)); }
;         asm volatile("s_waitcnt lgkmcnt(0)" ::: "memory");
	ds_read_b128 v[30:33], v152 offset:8192
	ds_read_b128 v[34:37], v152 offset:12544
	v_lshlrev_b32_e32 v1, 2, v123
	v_readlane_b32 s16, v252, 20
	v_lshl_or_b32 v2, s52, 6, v1
	s_waitcnt lgkmcnt(1)
	v_mfma_f32_16x16x32_bf16 v[30:33], v[30:33], v[38:41], v[50:53]
	v_readlane_b32 s24, v252, 28
	v_readlane_b32 s25, v252, 29
	s_lshl_b32 s0, s52, 5
	s_waitcnt lgkmcnt(0)
	v_mfma_f32_16x16x32_bf16 v[34:37], v[34:37], v[38:41], v[58:61]
	ds_read_b128 v[38:41], v152 offset:8256
	ds_read_b128 v[50:53], v152 offset:12608
	s_add_u32 s0, s47, s0
	s_addc_u32 s1, s48, 0
	s_waitcnt lgkmcnt(1)
	v_mfma_f32_16x16x32_bf16 v[30:33], v[38:41], v[46:49], v[30:33]
	v_readlane_b32 s17, v252, 21
	v_readlane_b32 s18, v252, 22
	v_readlane_b32 s19, v252, 23
	s_waitcnt lgkmcnt(0)
	v_mfma_f32_16x16x32_bf16 v[34:37], v[50:53], v[46:49], v[34:37]
	ds_read_b128 v[38:41], v152 offset:8320
	ds_read_b128 v[46:49], v152 offset:12672
	v_readlane_b32 s20, v252, 24
	v_readlane_b32 s21, v252, 25
	s_waitcnt lgkmcnt(1)
	v_mfma_f32_16x16x32_bf16 v[30:33], v[38:41], v[42:45], v[30:33]
	v_readlane_b32 s22, v252, 26
	v_readlane_b32 s23, v252, 27
	v_readlane_b32 s26, v252, 30
	s_waitcnt lgkmcnt(0)
	v_mfma_f32_16x16x32_bf16 v[38:41], v[46:49], v[42:45], v[34:37]
	s_nop 2
	ds_read_b128 v[34:37], v152 offset:8384
	ds_read_b128 v[42:45], v152 offset:12736
	v_readlane_b32 s27, v252, 31
	v_readlane_b32 s28, v252, 32
	s_waitcnt lgkmcnt(1)
	v_mfma_f32_16x16x32_bf16 v[34:37], v[34:37], v[54:57], v[30:33]
	v_readlane_b32 s29, v252, 33
	v_readlane_b32 s30, v252, 34
	v_readlane_b32 s31, v252, 35
	s_waitcnt lgkmcnt(0)
	v_mfma_f32_16x16x32_bf16 v[30:33], v[42:45], v[54:57], v[38:41]
	v_ashrrev_i32_e32 v44, 2, v0
	s_nop 1
	global_load_dword v40, v2, s[24:25]
	v_and_b32_e32 v38, -4, v44
	v_add_u32_e32 v41, s49, v1
	v_lshlrev_b32_e32 v2, 1, v123
	v_lshl_add_u64 v[0:1], s[0:1], 0, v[2:3]
	v_lshl_add_u32 v2, v38, 6, v41
	ds_read_b32 v2, v2
	v_ashrrev_i32_e32 v39, 31, v38
	v_lshl_add_u64 v[42:43], s[12:13], 0, v[38:39]
	v_lshlrev_b64 v[42:43], 11, v[42:43]
	v_lshl_add_u64 v[42:43], v[0:1], 0, v[42:43]
	s_waitcnt vmcnt(0) lgkmcnt(0)
	v_fma_f32 v2, v40, v2, v34
	v_mul_f32_e32 v34, 0x3d372713, v2
	v_mul_f32_e32 v34, v2, v34
	v_fma_f32 v34, v2, v34, v2
	v_mul_f32_e32 v34, 0x3f4c422a, v34
	v_add_f32_e32 v34, v34, v34
	v_mul_f32_e32 v34, 0xbfb8aa3b, v34
	v_exp_f32_e32 v34, v34
	s_nop 0
	v_add_f32_e32 v34, 1.0, v34
	v_rcp_f32_e32 v34, v34
	s_nop 0
	v_mul_f32_e32 v2, v2, v34
	v_cvt_pk_bf16_f32 v2, v2, s0
	v_or_b32_e32 v34, 1, v38
	global_store_short v[42:43], v2, off
	v_lshl_add_u32 v2, v34, 6, v41
	ds_read_b32 v2, v2
	s_waitcnt lgkmcnt(0)
	v_fma_f32 v2, v40, v2, v35
	v_mul_f32_e32 v35, 0x3d372713, v2
	v_mul_f32_e32 v35, v2, v35
	v_fma_f32 v35, v2, v35, v2
	v_mul_f32_e32 v35, 0x3f4c422a, v35
	v_add_f32_e32 v35, v35, v35
	v_mul_f32_e32 v35, 0xbfb8aa3b, v35
	v_exp_f32_e32 v35, v35
	s_nop 0
	v_add_f32_e32 v35, 1.0, v35
	v_rcp_f32_e32 v35, v35
	s_nop 0
	v_mul_f32_e32 v2, v2, v35
	v_ashrrev_i32_e32 v35, 31, v34
	v_lshl_add_u64 v[34:35], s[12:13], 0, v[34:35]
	v_lshlrev_b64 v[34:35], 11, v[34:35]
	v_cvt_pk_bf16_f32 v2, v2, s0
	v_lshl_add_u64 v[34:35], v[0:1], 0, v[34:35]
	global_store_short v[34:35], v2, off
	v_or_b32_e32 v34, 2, v38
	v_lshl_add_u32 v2, v34, 6, v41
	ds_read_b32 v2, v2
	s_waitcnt lgkmcnt(0)
	v_fma_f32 v2, v40, v2, v36
	v_mul_f32_e32 v35, 0x3d372713, v2
	v_mul_f32_e32 v35, v2, v35
	v_fma_f32 v35, v2, v35, v2
	v_mul_f32_e32 v35, 0x3f4c422a, v35
	v_add_f32_e32 v35, v35, v35
	v_mul_f32_e32 v35, 0xbfb8aa3b, v35
	v_exp_f32_e32 v35, v35
	s_nop 0
	v_add_f32_e32 v35, 1.0, v35
	v_rcp_f32_e32 v35, v35
	s_nop 0
	v_mul_f32_e32 v2, v2, v35
	v_ashrrev_i32_e32 v35, 31, v34
	v_lshl_add_u64 v[34:35], s[12:13], 0, v[34:35]
	v_lshlrev_b64 v[34:35], 11, v[34:35]
	v_cvt_pk_bf16_f32 v2, v2, s0
	v_lshl_add_u64 v[34:35], v[0:1], 0, v[34:35]
	global_store_short v[34:35], v2, off
	v_or_b32_e32 v34, 3, v44
	v_lshl_add_u32 v2, v34, 6, v41
	ds_read_b32 v2, v2
	v_ashrrev_i32_e32 v35, 31, v34
	v_lshl_add_u64 v[34:35], s[12:13], 0, v[34:35]
	v_lshlrev_b64 v[34:35], 11, v[34:35]
	v_lshl_add_u64 v[34:35], v[0:1], 0, v[34:35]
	s_waitcnt lgkmcnt(0)
	v_fmac_f32_e32 v37, v40, v2
	v_mul_f32_e32 v2, 0x3d372713, v37
	v_mul_f32_e32 v2, v37, v2
	v_fma_f32 v2, v37, v2, v37
	v_mul_f32_e32 v2, 0x3f4c422a, v2
	v_add_f32_e32 v2, v2, v2
	v_mul_f32_e32 v2, 0xbfb8aa3b, v2
	v_exp_f32_e32 v2, v2
	s_nop 0
	v_add_f32_e32 v2, 1.0, v2
	v_rcp_f32_e32 v2, v2
	s_nop 0
	v_mul_f32_e32 v2, v37, v2
	v_cvt_pk_bf16_f32 v2, v2, s0
	global_store_short v[34:35], v2, off
	v_add_u32_e32 v34, 16, v38
	v_lshl_add_u32 v2, v34, 6, v41
	ds_read_b32 v2, v2
	v_ashrrev_i32_e32 v35, 31, v34
	v_lshl_add_u64 v[34:35], s[12:13], 0, v[34:35]
	v_lshlrev_b64 v[34:35], 11, v[34:35]
	v_lshl_add_u64 v[34:35], v[0:1], 0, v[34:35]
	s_waitcnt lgkmcnt(0)
	v_fma_f32 v2, v40, v2, v30
	v_mul_f32_e32 v30, 0x3d372713, v2
	v_mul_f32_e32 v30, v2, v30
	v_fma_f32 v30, v2, v30, v2
	v_mul_f32_e32 v30, 0x3f4c422a, v30
	v_add_f32_e32 v30, v30, v30
	v_mul_f32_e32 v30, 0xbfb8aa3b, v30
	v_exp_f32_e32 v30, v30
	s_nop 0
	v_add_f32_e32 v30, 1.0, v30
	v_rcp_f32_e32 v30, v30
	s_nop 0
	v_mul_f32_e32 v2, v2, v30
	v_cvt_pk_bf16_f32 v2, v2, s0
	v_add_u32_e32 v30, 17, v38
	global_store_short v[34:35], v2, off
	v_lshl_add_u32 v2, v30, 6, v41
	ds_read_b32 v2, v2
	s_waitcnt lgkmcnt(0)
	v_fma_f32 v2, v40, v2, v31
	v_mul_f32_e32 v31, 0x3d372713, v2
	v_mul_f32_e32 v31, v2, v31
	v_fma_f32 v31, v2, v31, v2
	v_mul_f32_e32 v31, 0x3f4c422a, v31
	v_add_f32_e32 v31, v31, v31
	v_mul_f32_e32 v31, 0xbfb8aa3b, v31
	v_exp_f32_e32 v31, v31
	s_nop 0
	v_add_f32_e32 v31, 1.0, v31
	v_rcp_f32_e32 v31, v31
	s_nop 0
	v_mul_f32_e32 v2, v2, v31
	v_ashrrev_i32_e32 v31, 31, v30
	v_lshl_add_u64 v[30:31], s[12:13], 0, v[30:31]
	v_lshlrev_b64 v[30:31], 11, v[30:31]
	v_cvt_pk_bf16_f32 v2, v2, s0
	v_lshl_add_u64 v[30:31], v[0:1], 0, v[30:31]
	global_store_short v[30:31], v2, off
	v_add_u32_e32 v30, 18, v38
	v_lshl_add_u32 v2, v30, 6, v41
	ds_read_b32 v2, v2
	s_waitcnt lgkmcnt(0)
; DI bf16 f2bf(float f) { return (bf16)(pk2(f, 0.f) & 0xffffu); }
; DI float gelu_tanh(float x) { const float u = 0.7978845608028654f * (x + 0.044715f * x * x * x); return x * sigm(2.0f * u); }
; DI void s5_passC(const Ctx& C, const S5P& P, const bf16* PROJ, const f32x2* END, bf16* YG  , int item_lo, int item_hi) {
;     ...
;         const float dv = P.d[g * 16 + (lane & 15)];
; #pragma unroll
;         for (int r = 0; r < 8; ++r)
; #pragma unroll
;             for (int j = 0; j < 4; ++j) { const int t = 16 * r + (lane >> 4) * 4 + j; const float y = acc[r][j] + dv * UF[t * 16 + (lane & 15)]; YG[(tok0 + t) * 1024 + g * 16 + (lane & 15)] = f2bf(gelu_tanh(y)); }
;         asm volatile("s_waitcnt lgkmcnt(0)" ::: "memory");
	v_fma_f32 v2, v40, v2, v32
	v_mul_f32_e32 v31, 0x3d372713, v2
	v_mul_f32_e32 v31, v2, v31
	v_fma_f32 v31, v2, v31, v2
	v_mul_f32_e32 v31, 0x3f4c422a, v31
	v_add_f32_e32 v31, v31, v31
	v_mul_f32_e32 v31, 0xbfb8aa3b, v31
	v_exp_f32_e32 v31, v31
	s_nop 0
	v_add_f32_e32 v31, 1.0, v31
	v_rcp_f32_e32 v31, v31
	s_nop 0
	v_mul_f32_e32 v2, v2, v31
	v_ashrrev_i32_e32 v31, 31, v30
	v_lshl_add_u64 v[30:31], s[12:13], 0, v[30:31]
	v_lshlrev_b64 v[30:31], 11, v[30:31]
	v_cvt_pk_bf16_f32 v2, v2, s0
	v_lshl_add_u64 v[30:31], v[0:1], 0, v[30:31]
	global_store_short v[30:31], v2, off
	v_add_u32_e32 v30, 19, v38
	v_lshl_add_u32 v2, v30, 6, v41
	ds_read_b32 v2, v2
	v_ashrrev_i32_e32 v31, 31, v30
	v_lshl_add_u64 v[30:31], s[12:13], 0, v[30:31]
	v_lshlrev_b64 v[30:31], 11, v[30:31]
	v_lshl_add_u64 v[30:31], v[0:1], 0, v[30:31]
	s_waitcnt lgkmcnt(0)
	v_fmac_f32_e32 v33, v40, v2
	v_mul_f32_e32 v2, 0x3d372713, v33
	v_mul_f32_e32 v2, v33, v2
	v_fma_f32 v2, v33, v2, v33
	v_mul_f32_e32 v2, 0x3f4c422a, v2
	v_add_f32_e32 v2, v2, v2
	v_mul_f32_e32 v2, 0xbfb8aa3b, v2
	v_exp_f32_e32 v2, v2
	s_nop 0
	v_add_f32_e32 v2, 1.0, v2
	v_rcp_f32_e32 v2, v2
	s_nop 0
	v_mul_f32_e32 v2, v33, v2
	v_cvt_pk_bf16_f32 v2, v2, s0
	global_store_short v[30:31], v2, off
	v_add_u32_e32 v30, 32, v38
	v_lshl_add_u32 v2, v30, 6, v41
	ds_read_b32 v2, v2
	v_ashrrev_i32_e32 v31, 31, v30
	v_lshl_add_u64 v[30:31], s[12:13], 0, v[30:31]
	v_lshlrev_b64 v[30:31], 11, v[30:31]
	v_lshl_add_u64 v[30:31], v[0:1], 0, v[30:31]
	s_waitcnt lgkmcnt(0)
	v_fma_f32 v2, v40, v2, v26
	v_mul_f32_e32 v26, 0x3d372713, v2
	v_mul_f32_e32 v26, v2, v26
	v_fma_f32 v26, v2, v26, v2
	v_mul_f32_e32 v26, 0x3f4c422a, v26
	v_add_f32_e32 v26, v26, v26
	v_mul_f32_e32 v26, 0xbfb8aa3b, v26
	v_exp_f32_e32 v26, v26
	s_nop 0
	v_add_f32_e32 v26, 1.0, v26
	v_rcp_f32_e32 v26, v26
	s_nop 0
	v_mul_f32_e32 v2, v2, v26
	v_cvt_pk_bf16_f32 v2, v2, s0
	v_add_u32_e32 v26, 33, v38
	global_store_short v[30:31], v2, off
	v_lshl_add_u32 v2, v26, 6, v41
	ds_read_b32 v2, v2
	s_waitcnt lgkmcnt(0)
	v_fma_f32 v2, v40, v2, v27
	v_mul_f32_e32 v27, 0x3d372713, v2
	v_mul_f32_e32 v27, v2, v27
	v_fma_f32 v27, v2, v27, v2
	v_mul_f32_e32 v27, 0x3f4c422a, v27
	v_add_f32_e32 v27, v27, v27
	v_mul_f32_e32 v27, 0xbfb8aa3b, v27
	v_exp_f32_e32 v27, v27
	s_nop 0
	v_add_f32_e32 v27, 1.0, v27
	v_rcp_f32_e32 v27, v27
	s_nop 0
	v_mul_f32_e32 v2, v2, v27
	v_ashrrev_i32_e32 v27, 31, v26
	v_lshl_add_u64 v[26:27], s[12:13], 0, v[26:27]
	v_lshlrev_b64 v[26:27], 11, v[26:27]
	v_cvt_pk_bf16_f32 v2, v2, s0
	v_lshl_add_u64 v[26:27], v[0:1], 0, v[26:27]
	global_store_short v[26:27], v2, off
	v_add_u32_e32 v26, 34, v38
	v_lshl_add_u32 v2, v26, 6, v41
	ds_read_b32 v2, v2
	s_waitcnt lgkmcnt(0)
	v_fma_f32 v2, v40, v2, v28
	v_mul_f32_e32 v27, 0x3d372713, v2
	v_mul_f32_e32 v27, v2, v27
	v_fma_f32 v27, v2, v27, v2
	v_mul_f32_e32 v27, 0x3f4c422a, v27
	v_add_f32_e32 v27, v27, v27
	v_mul_f32_e32 v27, 0xbfb8aa3b, v27
	v_exp_f32_e32 v27, v27
	s_nop 0
	v_add_f32_e32 v27, 1.0, v27
	v_rcp_f32_e32 v27, v27
	s_nop 0
	v_mul_f32_e32 v2, v2, v27
	v_ashrrev_i32_e32 v27, 31, v26
	v_lshl_add_u64 v[26:27], s[12:13], 0, v[26:27]
	v_lshlrev_b64 v[26:27], 11, v[26:27]
	v_cvt_pk_bf16_f32 v2, v2, s0
	v_lshl_add_u64 v[26:27], v[0:1], 0, v[26:27]
	global_store_short v[26:27], v2, off
	v_add_u32_e32 v26, 35, v38
	v_lshl_add_u32 v2, v26, 6, v41
	ds_read_b32 v2, v2
	v_ashrrev_i32_e32 v27, 31, v26
	v_lshl_add_u64 v[26:27], s[12:13], 0, v[26:27]
	v_lshlrev_b64 v[26:27], 11, v[26:27]
	v_lshl_add_u64 v[26:27], v[0:1], 0, v[26:27]
	s_waitcnt lgkmcnt(0)
	v_fmac_f32_e32 v29, v40, v2
	v_mul_f32_e32 v2, 0x3d372713, v29
	v_mul_f32_e32 v2, v29, v2
	v_fma_f32 v2, v29, v2, v29
	v_mul_f32_e32 v2, 0x3f4c422a, v2
	v_add_f32_e32 v2, v2, v2
	v_mul_f32_e32 v2, 0xbfb8aa3b, v2
	v_exp_f32_e32 v2, v2
	s_nop 0
	v_add_f32_e32 v2, 1.0, v2
	v_rcp_f32_e32 v2, v2
	s_nop 0
	v_mul_f32_e32 v2, v29, v2
	v_cvt_pk_bf16_f32 v2, v2, s0
	global_store_short v[26:27], v2, off
	v_add_u32_e32 v26, 48, v38
	v_lshl_add_u32 v2, v26, 6, v41
	ds_read_b32 v2, v2
	v_ashrrev_i32_e32 v27, 31, v26
	v_lshl_add_u64 v[26:27], s[12:13], 0, v[26:27]
	v_lshlrev_b64 v[26:27], 11, v[26:27]
	v_lshl_add_u64 v[26:27], v[0:1], 0, v[26:27]
	s_waitcnt lgkmcnt(0)
	v_fma_f32 v2, v40, v2, v22
	v_mul_f32_e32 v22, 0x3d372713, v2
	v_mul_f32_e32 v22, v2, v22
	v_fma_f32 v22, v2, v22, v2
	v_mul_f32_e32 v22, 0x3f4c422a, v22
	v_add_f32_e32 v22, v22, v22
	v_mul_f32_e32 v22, 0xbfb8aa3b, v22
	v_exp_f32_e32 v22, v22
	s_nop 0
	v_add_f32_e32 v22, 1.0, v22
	v_rcp_f32_e32 v22, v22
	s_nop 0
	v_mul_f32_e32 v2, v2, v22
	v_cvt_pk_bf16_f32 v2, v2, s0
	v_add_u32_e32 v22, 49, v38
	global_store_short v[26:27], v2, off
	v_lshl_add_u32 v2, v22, 6, v41
	ds_read_b32 v2, v2
	s_waitcnt lgkmcnt(0)
	v_fma_f32 v2, v40, v2, v23
	v_mul_f32_e32 v23, 0x3d372713, v2
	v_mul_f32_e32 v23, v2, v23
	v_fma_f32 v23, v2, v23, v2
	v_mul_f32_e32 v23, 0x3f4c422a, v23
	v_add_f32_e32 v23, v23, v23
	v_mul_f32_e32 v23, 0xbfb8aa3b, v23
	v_exp_f32_e32 v23, v23
	s_nop 0
	v_add_f32_e32 v23, 1.0, v23
	v_rcp_f32_e32 v23, v23
	s_nop 0
	v_mul_f32_e32 v2, v2, v23
	v_ashrrev_i32_e32 v23, 31, v22
	v_lshl_add_u64 v[22:23], s[12:13], 0, v[22:23]
	v_lshlrev_b64 v[22:23], 11, v[22:23]
	v_cvt_pk_bf16_f32 v2, v2, s0
	v_lshl_add_u64 v[22:23], v[0:1], 0, v[22:23]
	global_store_short v[22:23], v2, off
	v_add_u32_e32 v22, 50, v38
	v_lshl_add_u32 v2, v22, 6, v41
	ds_read_b32 v2, v2
	s_waitcnt lgkmcnt(0)
; DI bf16 f2bf(float f) { return (bf16)(pk2(f, 0.f) & 0xffffu); }
; DI float gelu_tanh(float x) { const float u = 0.7978845608028654f * (x + 0.044715f * x * x * x); return x * sigm(2.0f * u); }
; DI void s5_passC(const Ctx& C, const S5P& P, const bf16* PROJ, const f32x2* END, bf16* YG  , int item_lo, int item_hi) {
;     ...
;         const float dv = P.d[g * 16 + (lane & 15)];
; #pragma unroll
;         for (int r = 0; r < 8; ++r)
; #pragma unroll
;             for (int j = 0; j < 4; ++j) { const int t = 16 * r + (lane >> 4) * 4 + j; const float y = acc[r][j] + dv * UF[t * 16 + (lane & 15)]; YG[(tok0 + t) * 1024 + g * 16 + (lane & 15)] = f2bf(gelu_tanh(y)); }
;         asm volatile("s_waitcnt lgkmcnt(0)" ::: "memory");
	v_fma_f32 v2, v40, v2, v24
	v_mul_f32_e32 v23, 0x3d372713, v2
	v_mul_f32_e32 v23, v2, v23
	v_fma_f32 v23, v2, v23, v2
	v_mul_f32_e32 v23, 0x3f4c422a, v23
	v_add_f32_e32 v23, v23, v23
	v_mul_f32_e32 v23, 0xbfb8aa3b, v23
	v_exp_f32_e32 v23, v23
	s_nop 0
	v_add_f32_e32 v23, 1.0, v23
	v_rcp_f32_e32 v23, v23
	s_nop 0
	v_mul_f32_e32 v2, v2, v23
	v_ashrrev_i32_e32 v23, 31, v22
	v_lshl_add_u64 v[22:23], s[12:13], 0, v[22:23]
	v_lshlrev_b64 v[22:23], 11, v[22:23]
	v_cvt_pk_bf16_f32 v2, v2, s0
	v_lshl_add_u64 v[22:23], v[0:1], 0, v[22:23]
	global_store_short v[22:23], v2, off
	v_add_u32_e32 v22, 51, v38
	v_lshl_add_u32 v2, v22, 6, v41
	ds_read_b32 v2, v2
	v_ashrrev_i32_e32 v23, 31, v22
	v_lshl_add_u64 v[22:23], s[12:13], 0, v[22:23]
	v_lshlrev_b64 v[22:23], 11, v[22:23]
	v_lshl_add_u64 v[22:23], v[0:1], 0, v[22:23]
	s_waitcnt lgkmcnt(0)
	v_fmac_f32_e32 v25, v40, v2
	v_mul_f32_e32 v2, 0x3d372713, v25
	v_mul_f32_e32 v2, v25, v2
	v_fma_f32 v2, v25, v2, v25
	v_mul_f32_e32 v2, 0x3f4c422a, v2
	v_add_f32_e32 v2, v2, v2
	v_mul_f32_e32 v2, 0xbfb8aa3b, v2
	v_exp_f32_e32 v2, v2
	s_nop 0
	v_add_f32_e32 v2, 1.0, v2
	v_rcp_f32_e32 v2, v2
	s_nop 0
	v_mul_f32_e32 v2, v25, v2
	v_cvt_pk_bf16_f32 v2, v2, s0
	global_store_short v[22:23], v2, off
	v_add_u32_e32 v22, 64, v38
	v_lshl_add_u32 v2, v22, 6, v41
	ds_read_b32 v2, v2
	v_ashrrev_i32_e32 v23, 31, v22
	v_lshl_add_u64 v[22:23], s[12:13], 0, v[22:23]
	v_lshlrev_b64 v[22:23], 11, v[22:23]
	v_lshl_add_u64 v[22:23], v[0:1], 0, v[22:23]
	s_waitcnt lgkmcnt(0)
	v_fma_f32 v2, v40, v2, v18
	v_mul_f32_e32 v18, 0x3d372713, v2
	v_mul_f32_e32 v18, v2, v18
	v_fma_f32 v18, v2, v18, v2
	v_mul_f32_e32 v18, 0x3f4c422a, v18
	v_add_f32_e32 v18, v18, v18
	v_mul_f32_e32 v18, 0xbfb8aa3b, v18
	v_exp_f32_e32 v18, v18
	s_nop 0
	v_add_f32_e32 v18, 1.0, v18
	v_rcp_f32_e32 v18, v18
	s_nop 0
	v_mul_f32_e32 v2, v2, v18
	v_cvt_pk_bf16_f32 v2, v2, s0
	v_add_u32_e32 v18, 0x41, v38
	global_store_short v[22:23], v2, off
	v_lshl_add_u32 v2, v18, 6, v41
	ds_read_b32 v2, v2
	s_waitcnt lgkmcnt(0)
	v_fma_f32 v2, v40, v2, v19
	v_mul_f32_e32 v19, 0x3d372713, v2
	v_mul_f32_e32 v19, v2, v19
	v_fma_f32 v19, v2, v19, v2
	v_mul_f32_e32 v19, 0x3f4c422a, v19
	v_add_f32_e32 v19, v19, v19
	v_mul_f32_e32 v19, 0xbfb8aa3b, v19
	v_exp_f32_e32 v19, v19
	s_nop 0
	v_add_f32_e32 v19, 1.0, v19
	v_rcp_f32_e32 v19, v19
	s_nop 0
	v_mul_f32_e32 v2, v2, v19
	v_ashrrev_i32_e32 v19, 31, v18
	v_lshl_add_u64 v[18:19], s[12:13], 0, v[18:19]
	v_lshlrev_b64 v[18:19], 11, v[18:19]
	v_cvt_pk_bf16_f32 v2, v2, s0
	v_lshl_add_u64 v[18:19], v[0:1], 0, v[18:19]
	global_store_short v[18:19], v2, off
	v_add_u32_e32 v18, 0x42, v38
	v_lshl_add_u32 v2, v18, 6, v41
	ds_read_b32 v2, v2
	s_waitcnt lgkmcnt(0)
	v_fma_f32 v2, v40, v2, v20
	v_mul_f32_e32 v19, 0x3d372713, v2
	v_mul_f32_e32 v19, v2, v19
	v_fma_f32 v19, v2, v19, v2
	v_mul_f32_e32 v19, 0x3f4c422a, v19
	v_add_f32_e32 v19, v19, v19
	v_mul_f32_e32 v19, 0xbfb8aa3b, v19
	v_exp_f32_e32 v19, v19
	s_nop 0
	v_add_f32_e32 v19, 1.0, v19
	v_rcp_f32_e32 v19, v19
	s_nop 0
	v_mul_f32_e32 v2, v2, v19
	v_ashrrev_i32_e32 v19, 31, v18
	v_lshl_add_u64 v[18:19], s[12:13], 0, v[18:19]
	v_lshlrev_b64 v[18:19], 11, v[18:19]
	v_cvt_pk_bf16_f32 v2, v2, s0
	v_lshl_add_u64 v[18:19], v[0:1], 0, v[18:19]
	global_store_short v[18:19], v2, off
	v_add_u32_e32 v18, 0x43, v38
	v_lshl_add_u32 v2, v18, 6, v41
	ds_read_b32 v2, v2
	v_ashrrev_i32_e32 v19, 31, v18
	v_lshl_add_u64 v[18:19], s[12:13], 0, v[18:19]
	v_lshlrev_b64 v[18:19], 11, v[18:19]
	v_lshl_add_u64 v[18:19], v[0:1], 0, v[18:19]
	s_waitcnt lgkmcnt(0)
	v_fmac_f32_e32 v21, v40, v2
	v_mul_f32_e32 v2, 0x3d372713, v21
	v_mul_f32_e32 v2, v21, v2
	v_fma_f32 v2, v21, v2, v21
	v_mul_f32_e32 v2, 0x3f4c422a, v2
	v_add_f32_e32 v2, v2, v2
	v_mul_f32_e32 v2, 0xbfb8aa3b, v2
	v_exp_f32_e32 v2, v2
	s_nop 0
	v_add_f32_e32 v2, 1.0, v2
	v_rcp_f32_e32 v2, v2
	s_nop 0
	v_mul_f32_e32 v2, v21, v2
	v_cvt_pk_bf16_f32 v2, v2, s0
	global_store_short v[18:19], v2, off
	v_add_u32_e32 v18, 0x50, v38
	v_lshl_add_u32 v2, v18, 6, v41
	ds_read_b32 v2, v2
	v_ashrrev_i32_e32 v19, 31, v18
	v_lshl_add_u64 v[18:19], s[12:13], 0, v[18:19]
	v_lshlrev_b64 v[18:19], 11, v[18:19]
	v_lshl_add_u64 v[18:19], v[0:1], 0, v[18:19]
	s_waitcnt lgkmcnt(0)
	v_fma_f32 v2, v40, v2, v14
	v_mul_f32_e32 v14, 0x3d372713, v2
	v_mul_f32_e32 v14, v2, v14
	v_fma_f32 v14, v2, v14, v2
	v_mul_f32_e32 v14, 0x3f4c422a, v14
	v_add_f32_e32 v14, v14, v14
	v_mul_f32_e32 v14, 0xbfb8aa3b, v14
	v_exp_f32_e32 v14, v14
	s_nop 0
	v_add_f32_e32 v14, 1.0, v14
	v_rcp_f32_e32 v14, v14
	s_nop 0
	v_mul_f32_e32 v2, v2, v14
	v_cvt_pk_bf16_f32 v2, v2, s0
	v_add_u32_e32 v14, 0x51, v38
	global_store_short v[18:19], v2, off
	v_lshl_add_u32 v2, v14, 6, v41
	ds_read_b32 v2, v2
	s_waitcnt lgkmcnt(0)
	v_fma_f32 v2, v40, v2, v15
	v_mul_f32_e32 v15, 0x3d372713, v2
	v_mul_f32_e32 v15, v2, v15
	v_fma_f32 v15, v2, v15, v2
	v_mul_f32_e32 v15, 0x3f4c422a, v15
	v_add_f32_e32 v15, v15, v15
	v_mul_f32_e32 v15, 0xbfb8aa3b, v15
	v_exp_f32_e32 v15, v15
	s_nop 0
	v_add_f32_e32 v15, 1.0, v15
	v_rcp_f32_e32 v15, v15
	s_nop 0
	v_mul_f32_e32 v2, v2, v15
	v_ashrrev_i32_e32 v15, 31, v14
	v_lshl_add_u64 v[14:15], s[12:13], 0, v[14:15]
	v_lshlrev_b64 v[14:15], 11, v[14:15]
	v_cvt_pk_bf16_f32 v2, v2, s0
	v_lshl_add_u64 v[14:15], v[0:1], 0, v[14:15]
	global_store_short v[14:15], v2, off
	v_add_u32_e32 v14, 0x52, v38
	v_lshl_add_u32 v2, v14, 6, v41
	ds_read_b32 v2, v2
	s_waitcnt lgkmcnt(0)
; #define LAS __attribute__((address_space(3)))
; DI float bflo(unsigned w) { return __uint_as_float(w << 16); }
; DI float bfhi(unsigned w) { return __uint_as_float(w & 0xffff0000u); }
; DI unsigned pk2(float lo, float hi) { return pg8::cvt_pk_bf16(lo, hi); }
; DI bf16 f2bf(float f) { return (bf16)(pk2(f, 0.f) & 0xffffu); }
; DI float gelu_tanh(float x) { const float u = 0.7978845608028654f * (x + 0.044715f * x * x * x); return x * sigm(2.0f * u); }
; DI void s5_passC(const Ctx& C, const S5P& P, const bf16* PROJ, const f32x2* END, bf16* YG  , int item_lo, int item_hi) {
;     ...
;     for (int item = item_lo + C.gw; item < item_hi; item += C.ngw) {
;         int lane = C.lane; asm volatile("" : "+v"(lane));
;         const int g = item & 63, seg = (item >> 6) & (SNSEG - 1), b = item >> 12; const size_t tok0 = (size_t)b * SEQ + seg * SSEG;
; #pragma unroll
;         for (int i = 0; i < 4; ++i) { const int q = lane + 64 * i, tl = q >> 1, hf = q & 1; const v4u v = *(const v4u*)(PROJ + ((size_t)g * T + tok0 + tl) * 16 + hf * 8);
;             *(LAS f32x4*)(UF + tl * 16 + hf * 8) = (f32x4){bflo(v.x), bfhi(v.x), bflo(v.y), bfhi(v.y)}; *(LAS f32x4*)(UF + tl * 16 + hf * 8 + 4) = (f32x4){bflo(v.z), bfhi(v.z), bflo(v.w), bfhi(v.w)}; }
;         bf16x8 bfr[4];
; #pragma unroll
;         for (int ks = 0; ks < 4; ++ks) { const float* src = (ks < 2 ? P.c_re : P.c_im) + (size_t)(g * 16 + (lane & 15)) * 64 + 32 * (ks & 1) + 8 * (lane >> 4); const f32x4 a = *(const f32x4*)src, bq = *(const f32x4*)(src + 4);
;             const float sg = ks < 2 ? 1.0f : -1.0f; v4u w; w.x = pk2(sg * a.x, sg * a.y); w.y = pk2(sg * a.z, sg * a.w); w.z = pk2(sg * bq.x, sg * bq.y); w.w = pk2(sg * bq.z, sg * bq.w); bfr[ks] = __builtin_bit_cast(bf16x8, w); }
;         f32x4 acc[8];
; #pragma unroll
;         for (int r = 0; r < 8; ++r) acc[r] = (f32x4){0.f, 0.f, 0.f, 0.f};
;         s5_dir<0>(P, END, UF, XT, b, seg, g, bfr, acc, lane);
;         s5_dir<1>(P, END, UF, XT, b, seg, g, bfr, acc, lane);
;         const float dv = P.d[g * 16 + (lane & 15)];
; #pragma unroll
;         for (int r = 0; r < 8; ++r)
; #pragma unroll
;             for (int j = 0; j < 4; ++j) { const int t = 16 * r + (lane >> 4) * 4 + j; const float y = acc[r][j] + dv * UF[t * 16 + (lane & 15)]; YG[(tok0 + t) * 1024 + g * 16 + (lane & 15)] = f2bf(gelu_tanh(y)); }
;         asm volatile("s_waitcnt lgkmcnt(0)" ::: "memory");
	v_fma_f32 v2, v40, v2, v16
	v_mul_f32_e32 v15, 0x3d372713, v2
	v_mul_f32_e32 v15, v2, v15
	v_fma_f32 v15, v2, v15, v2
	v_mul_f32_e32 v15, 0x3f4c422a, v15
	v_add_f32_e32 v15, v15, v15
	v_mul_f32_e32 v15, 0xbfb8aa3b, v15
	v_exp_f32_e32 v15, v15
	s_nop 0
	v_add_f32_e32 v15, 1.0, v15
	v_rcp_f32_e32 v15, v15
	s_nop 0
	v_mul_f32_e32 v2, v2, v15
	v_ashrrev_i32_e32 v15, 31, v14
	v_lshl_add_u64 v[14:15], s[12:13], 0, v[14:15]
	v_lshlrev_b64 v[14:15], 11, v[14:15]
	v_cvt_pk_bf16_f32 v2, v2, s0
	v_lshl_add_u64 v[14:15], v[0:1], 0, v[14:15]
	global_store_short v[14:15], v2, off
	v_add_u32_e32 v14, 0x53, v38
	v_lshl_add_u32 v2, v14, 6, v41
	ds_read_b32 v2, v2
	v_ashrrev_i32_e32 v15, 31, v14
	v_lshl_add_u64 v[14:15], s[12:13], 0, v[14:15]
	v_lshlrev_b64 v[14:15], 11, v[14:15]
	v_lshl_add_u64 v[14:15], v[0:1], 0, v[14:15]
	s_waitcnt lgkmcnt(0)
	v_fmac_f32_e32 v17, v40, v2
	v_mul_f32_e32 v2, 0x3d372713, v17
	v_mul_f32_e32 v2, v17, v2
	v_fma_f32 v2, v17, v2, v17
	v_mul_f32_e32 v2, 0x3f4c422a, v2
	v_add_f32_e32 v2, v2, v2
	v_mul_f32_e32 v2, 0xbfb8aa3b, v2
	v_exp_f32_e32 v2, v2
	s_nop 0
	v_add_f32_e32 v2, 1.0, v2
	v_rcp_f32_e32 v2, v2
	s_nop 0
	v_mul_f32_e32 v2, v17, v2
	v_cvt_pk_bf16_f32 v2, v2, s0
	global_store_short v[14:15], v2, off
	v_add_u32_e32 v14, 0x60, v38
	v_lshl_add_u32 v2, v14, 6, v41
	ds_read_b32 v2, v2
	v_ashrrev_i32_e32 v15, 31, v14
	v_lshl_add_u64 v[14:15], s[12:13], 0, v[14:15]
	v_lshlrev_b64 v[14:15], 11, v[14:15]
	v_lshl_add_u64 v[14:15], v[0:1], 0, v[14:15]
	s_waitcnt lgkmcnt(0)
	v_fma_f32 v2, v40, v2, v10
	v_mul_f32_e32 v10, 0x3d372713, v2
	v_mul_f32_e32 v10, v2, v10
	v_fma_f32 v10, v2, v10, v2
	v_mul_f32_e32 v10, 0x3f4c422a, v10
	v_add_f32_e32 v10, v10, v10
	v_mul_f32_e32 v10, 0xbfb8aa3b, v10
	v_exp_f32_e32 v10, v10
	s_nop 0
	v_add_f32_e32 v10, 1.0, v10
	v_rcp_f32_e32 v10, v10
	s_nop 0
	v_mul_f32_e32 v2, v2, v10
	v_cvt_pk_bf16_f32 v2, v2, s0
	v_add_u32_e32 v10, 0x61, v38
	global_store_short v[14:15], v2, off
	v_lshl_add_u32 v2, v10, 6, v41
	ds_read_b32 v2, v2
	s_waitcnt lgkmcnt(0)
	v_fma_f32 v2, v40, v2, v11
	v_mul_f32_e32 v11, 0x3d372713, v2
	v_mul_f32_e32 v11, v2, v11
	v_fma_f32 v11, v2, v11, v2
	v_mul_f32_e32 v11, 0x3f4c422a, v11
	v_add_f32_e32 v11, v11, v11
	v_mul_f32_e32 v11, 0xbfb8aa3b, v11
	v_exp_f32_e32 v11, v11
	s_nop 0
	v_add_f32_e32 v11, 1.0, v11
	v_rcp_f32_e32 v11, v11
	s_nop 0
	v_mul_f32_e32 v2, v2, v11
	v_ashrrev_i32_e32 v11, 31, v10
	v_lshl_add_u64 v[10:11], s[12:13], 0, v[10:11]
	v_lshlrev_b64 v[10:11], 11, v[10:11]
	v_cvt_pk_bf16_f32 v2, v2, s0
	v_lshl_add_u64 v[10:11], v[0:1], 0, v[10:11]
	global_store_short v[10:11], v2, off
	v_add_u32_e32 v10, 0x62, v38
	v_lshl_add_u32 v2, v10, 6, v41
	ds_read_b32 v2, v2
	s_waitcnt lgkmcnt(0)
	v_fma_f32 v2, v40, v2, v12
	v_mul_f32_e32 v11, 0x3d372713, v2
	v_mul_f32_e32 v11, v2, v11
	v_fma_f32 v11, v2, v11, v2
	v_mul_f32_e32 v11, 0x3f4c422a, v11
	v_add_f32_e32 v11, v11, v11
	v_mul_f32_e32 v11, 0xbfb8aa3b, v11
	v_exp_f32_e32 v11, v11
	s_nop 0
	v_add_f32_e32 v11, 1.0, v11
	v_rcp_f32_e32 v11, v11
	s_nop 0
	v_mul_f32_e32 v2, v2, v11
	v_ashrrev_i32_e32 v11, 31, v10
	v_lshl_add_u64 v[10:11], s[12:13], 0, v[10:11]
	v_lshlrev_b64 v[10:11], 11, v[10:11]
	v_cvt_pk_bf16_f32 v2, v2, s0
	v_lshl_add_u64 v[10:11], v[0:1], 0, v[10:11]
	global_store_short v[10:11], v2, off
	v_add_u32_e32 v10, 0x63, v38
	v_lshl_add_u32 v2, v10, 6, v41
	ds_read_b32 v2, v2
	v_ashrrev_i32_e32 v11, 31, v10
	v_lshl_add_u64 v[10:11], s[12:13], 0, v[10:11]
	v_lshlrev_b64 v[10:11], 11, v[10:11]
	v_lshl_add_u64 v[10:11], v[0:1], 0, v[10:11]
	s_waitcnt lgkmcnt(0)
	v_fmac_f32_e32 v13, v40, v2
	v_mul_f32_e32 v2, 0x3d372713, v13
	v_mul_f32_e32 v2, v13, v2
	v_fma_f32 v2, v13, v2, v13
	v_mul_f32_e32 v2, 0x3f4c422a, v2
	v_add_f32_e32 v2, v2, v2
	v_mul_f32_e32 v2, 0xbfb8aa3b, v2
	v_exp_f32_e32 v2, v2
	s_nop 0
	v_add_f32_e32 v2, 1.0, v2
	v_rcp_f32_e32 v2, v2
	s_nop 0
	v_mul_f32_e32 v2, v13, v2
	v_cvt_pk_bf16_f32 v2, v2, s0
	global_store_short v[10:11], v2, off
	v_add_u32_e32 v10, 0x70, v38
	v_lshl_add_u32 v2, v10, 6, v41
	ds_read_b32 v2, v2
	v_ashrrev_i32_e32 v11, 31, v10
	v_lshl_add_u64 v[10:11], s[12:13], 0, v[10:11]
	v_lshlrev_b64 v[10:11], 11, v[10:11]
	v_lshl_add_u64 v[10:11], v[0:1], 0, v[10:11]
	s_waitcnt lgkmcnt(0)
	v_fma_f32 v2, v40, v2, v6
	v_mul_f32_e32 v6, 0x3d372713, v2
	v_mul_f32_e32 v6, v2, v6
	v_fma_f32 v6, v2, v6, v2
	v_mul_f32_e32 v6, 0x3f4c422a, v6
	v_add_f32_e32 v6, v6, v6
	v_mul_f32_e32 v6, 0xbfb8aa3b, v6
	v_exp_f32_e32 v6, v6
	s_nop 0
	v_add_f32_e32 v6, 1.0, v6
	v_rcp_f32_e32 v6, v6
	s_nop 0
	v_mul_f32_e32 v2, v2, v6
	v_cvt_pk_bf16_f32 v2, v2, s0
	v_add_u32_e32 v6, 0x71, v38
	global_store_short v[10:11], v2, off
	v_lshl_add_u32 v2, v6, 6, v41
	ds_read_b32 v2, v2
	s_waitcnt lgkmcnt(0)
	v_fma_f32 v2, v40, v2, v7
	v_mul_f32_e32 v7, 0x3d372713, v2
	v_mul_f32_e32 v7, v2, v7
	v_fma_f32 v7, v2, v7, v2
	v_mul_f32_e32 v7, 0x3f4c422a, v7
	v_add_f32_e32 v7, v7, v7
	v_mul_f32_e32 v7, 0xbfb8aa3b, v7
	v_exp_f32_e32 v7, v7
	s_nop 0
	v_add_f32_e32 v7, 1.0, v7
	v_rcp_f32_e32 v7, v7
	s_nop 0
	v_mul_f32_e32 v2, v2, v7
	v_ashrrev_i32_e32 v7, 31, v6
	v_lshl_add_u64 v[6:7], s[12:13], 0, v[6:7]
	v_lshlrev_b64 v[6:7], 11, v[6:7]
	v_cvt_pk_bf16_f32 v2, v2, s0
	v_lshl_add_u64 v[6:7], v[0:1], 0, v[6:7]
	global_store_short v[6:7], v2, off
	v_add_u32_e32 v6, 0x72, v38
	v_lshl_add_u32 v2, v6, 6, v41
	ds_read_b32 v2, v2
	s_waitcnt lgkmcnt(0)
	v_fma_f32 v2, v40, v2, v8
	v_mul_f32_e32 v7, 0x3d372713, v2
	v_mul_f32_e32 v7, v2, v7
	v_fma_f32 v7, v2, v7, v2
	v_mul_f32_e32 v7, 0x3f4c422a, v7
	v_add_f32_e32 v7, v7, v7
	v_mul_f32_e32 v7, 0xbfb8aa3b, v7
	v_exp_f32_e32 v7, v7
	s_nop 0
	v_add_f32_e32 v7, 1.0, v7
	v_rcp_f32_e32 v7, v7
	s_nop 0
	v_mul_f32_e32 v2, v2, v7
	v_ashrrev_i32_e32 v7, 31, v6
	v_lshl_add_u64 v[6:7], s[12:13], 0, v[6:7]
	v_lshlrev_b64 v[6:7], 11, v[6:7]
	v_cvt_pk_bf16_f32 v2, v2, s0
	v_lshl_add_u64 v[6:7], v[0:1], 0, v[6:7]
	global_store_short v[6:7], v2, off
	v_add_u32_e32 v6, 0x73, v38
	v_lshl_add_u32 v2, v6, 6, v41
	ds_read_b32 v2, v2
	v_ashrrev_i32_e32 v7, 31, v6
	v_lshl_add_u64 v[6:7], s[12:13], 0, v[6:7]
	v_lshlrev_b64 v[6:7], 11, v[6:7]
	v_lshl_add_u64 v[0:1], v[0:1], 0, v[6:7]
	s_waitcnt lgkmcnt(0)
	v_fmac_f32_e32 v9, v40, v2
	v_mul_f32_e32 v2, 0x3d372713, v9
	v_mul_f32_e32 v2, v9, v2
	v_fma_f32 v2, v9, v2, v9
	v_mul_f32_e32 v2, 0x3f4c422a, v2
	v_add_f32_e32 v2, v2, v2
	v_mul_f32_e32 v2, 0xbfb8aa3b, v2
	v_exp_f32_e32 v2, v2
	s_nop 0
	v_add_f32_e32 v2, 1.0, v2
	v_rcp_f32_e32 v2, v2
	s_nop 0
	v_mul_f32_e32 v2, v9, v2
	v_cvt_pk_bf16_f32 v2, v2, s0
	global_store_short v[0:1], v2, off
	s_waitcnt lgkmcnt(0)
	s_add_i32 s0, s54, 0x400
	s_cmpk_gt_i32 s54, 0x1bff
	s_mov_b32 s54, s0
	s_cbranch_scc0 .LBB0_680

; DI float bflo(unsigned w) { return __uint_as_float(w << 16); }
; DI float bfhi(unsigned w) { return __uint_as_float(w & 0xffff0000u); }
; template <int ACT  > DI void hnorm_phase(const Ctx& C, const bf16* HF, const bf16* HB, const float* g, const bf16* gate, int ldg, bf16* Y  ) {
;     for (int it0 = 2 * C.gw; it0 < T * 4; it0 += 2 * C.ngw) {
;         v2u a[2], b[2], gt[2]; f32x4 gv[2]; size_t o[2]; int hh[2], tk[2];
; #pragma unroll
;         for (int u = 0; u < 2; ++u) { const int it = it0 + u; tk[u] = it >> 2; hh[u] = it & 3; o[u] = (size_t)tk[u] * 1024 + hh[u] * 256 + 4 * C.lane;
;             a[u] = *(const v2u*)(HF + o[u]); b[u] = *(const v2u*)(HB + o[u]); gv[u] = *(const f32x4*)(g + hh[u] * 256 + 4 * C.lane); gt[u] = *(const v2u*)(gate + (size_t)tk[u] * ldg + hh[u] * 256 + 4 * C.lane); }
; #pragma unroll
;         for (int u = 0; u < 2; ++u) {
;             float v[4] = {bflo(a[u].x) + bflo(b[u].x), bfhi(a[u].x) + bfhi(b[u].x), bflo(a[u].y) + bflo(b[u].y), bfhi(a[u].y) + bfhi(b[u].y)};
;             const float rstd = 1.0f / sqrtf(wave_sum((v[0] * v[0] + v[1] * v[1]) + (v[2] * v[2] + v[3] * v[3])) * (1.0f / 256.0f) + EPS);
.LBB0_804:
	s_ashr_i32 s16, s20, 2
	s_ashr_i32 s17, s16, 31
	s_lshl_b64 s[0:1], s[16:17], 10
	v_mov_b32_e32 v7, s1
	v_or_b32_e32 v2, s0, v0
	s_lshl_b64 s[0:1], s[16:17], 13
	v_lshl_add_u64 v[8:9], v[12:13], 0, s[0:1]
	s_and_b32 s0, s21, 0x200
	v_or_b32_e32 v6, s0, v2
	v_lshlrev_b64 v[14:15], 1, v[6:7]
	v_lshl_add_u64 v[16:17], s[12:13], 0, v[14:15]
	v_lshl_add_u64 v[14:15], s[14:15], 0, v[14:15]
	s_lshl_b32 s92, s0, 2
	global_load_dwordx2 v[20:21], v[16:17], off
	global_load_dwordx2 v[30:31], v[14:15], off
	v_lshl_add_u64 v[14:15], v[10:11], 0, s[92:93]
	s_lshl_b32 s92, s0, 1
	v_lshl_add_u64 v[32:33], v[8:9], 0, s[92:93]
	global_load_dwordx2 v[34:35], v[32:33], off
	v_or_b32_e32 v6, 0x100, v6
	v_lshlrev_b64 v[6:7], 1, v[6:7]
	v_lshl_add_u64 v[8:9], s[12:13], 0, v[6:7]
	v_lshl_add_u64 v[6:7], s[14:15], 0, v[6:7]
	global_load_dwordx4 v[26:29], v[14:15], off
	global_load_dwordx2 v[16:17], v[8:9], off
	s_waitcnt lgkmcnt(0)
	global_load_dwordx2 v[18:19], v[6:7], off
	s_nop 0
	global_load_dwordx4 v[6:9], v[14:15], off offset:1024
	s_nop 0
	global_load_dwordx2 v[14:15], v[32:33], off offset:512
	s_waitcnt vmcnt(0)
	v_lshlrev_b32_e32 v32, 16, v21
	v_and_b32_e32 v33, 0xffff0000, v21
	v_lshlrev_b32_e32 v36, 16, v31
	v_and_b32_e32 v37, 0xffff0000, v31
	v_pk_add_f32 v[32:33], v[32:33], v[36:37]
	v_lshlrev_b32_e32 v36, 16, v35
	v_mul_f32_e32 v2, 0xbfb8aa3b, v36
	v_exp_f32_e32 v2, v2
	v_and_b32_e32 v37, 0xffff0000, v35
	v_and_b32_e32 v21, 0xffff0000, v30
	v_mov_b32_e32 v31, v32
	v_add_f32_e32 v2, 1.0, v2
	v_rcp_f32_e32 v38, v2
	v_mul_f32_e32 v2, 0xbfb8aa3b, v37
	v_exp_f32_e32 v2, v2
	s_nop 0
	v_add_f32_e32 v2, 1.0, v2
	v_rcp_f32_e32 v39, v2
	s_nop 0
	v_pk_mul_f32 v[36:37], v[38:39], v[36:37]
	v_lshlrev_b32_e32 v38, 16, v20
	v_and_b32_e32 v39, 0xffff0000, v20
	v_lshlrev_b32_e32 v20, 16, v30
	v_pk_add_f32 v[20:21], v[38:39], v[20:21]
	v_mov_b32_e32 v39, v33
	v_mov_b32_e32 v38, v21
	v_mov_b32_e32 v30, v20
	v_pk_mul_f32 v[38:39], v[38:39], v[38:39]
	v_pk_fma_f32 v[30:31], v[30:31], v[30:31], v[38:39]
	v_lshlrev_b32_e32 v38, 16, v34
	v_mul_f32_e32 v2, 0xbfb8aa3b, v38
	v_exp_f32_e32 v2, v2
	v_and_b32_e32 v39, 0xffff0000, v34
	v_add_f32_e32 v2, 1.0, v2
	v_rcp_f32_e32 v34, v2
	v_mul_f32_e32 v2, 0xbfb8aa3b, v39
	v_exp_f32_e32 v2, v2
	s_nop 0
	v_add_f32_e32 v2, 1.0, v2
	v_rcp_f32_e32 v35, v2
	v_add_f32_e32 v2, v30, v31
	ds_bpermute_b32 v30, v1, v2
	v_pk_mul_f32 v[34:35], v[34:35], v[38:39]
	s_waitcnt lgkmcnt(0)
	v_add_f32_e32 v2, v2, v30
	ds_bpermute_b32 v30, v5, v2
	s_waitcnt lgkmcnt(0)
	v_add_f32_e32 v2, v2, v30
	ds_bpermute_b32 v30, v22, v2
	s_waitcnt lgkmcnt(0)
	v_add_f32_e32 v2, v2, v30
	ds_bpermute_b32 v30, v23, v2
	s_waitcnt lgkmcnt(0)
	v_add_f32_e32 v2, v2, v30
	ds_bpermute_b32 v30, v24, v2
	s_waitcnt lgkmcnt(0)
	v_add_f32_e32 v2, v2, v30
	ds_bpermute_b32 v30, v25, v2
	s_waitcnt lgkmcnt(0)
; DI float bflo(unsigned w) { return __uint_as_float(w << 16); }
; DI float bfhi(unsigned w) { return __uint_as_float(w & 0xffff0000u); }
; DI unsigned pk2(float lo, float hi) { return pg8::cvt_pk_bf16(lo, hi); }
; DI float sigm(float x) { return __builtin_amdgcn_rcpf(1.0f + __expf(-x)); }
; template <int ACT  > DI void hnorm_phase(const Ctx& C, const bf16* HF, const bf16* HB, const float* g, const bf16* gate, int ldg, bf16* Y  ) {
;     ...
;             const float rstd = 1.0f / sqrtf(wave_sum((v[0] * v[0] + v[1] * v[1]) + (v[2] * v[2] + v[3] * v[3])) * (1.0f / 256.0f) + EPS);
;             float z[4] = {bflo(gt[u].x), bfhi(gt[u].x), bflo(gt[u].y), bfhi(gt[u].y)}, r[4];
; #pragma unroll
;             for (int i = 0; i < 4; ++i) { const float s = sigm(z[i]); r[i] = v[i] * rstd * gv[u][i] * (ACT == 0 ? s : z[i] * s); }
;             v2u w; w.x = pk2(r[0], r[1]); w.y = pk2(r[2], r[3]); *(v2u*)(Y + (size_t)tk[u] * D + hh[u] * 256 + 4 * C.lane) = w; }
	v_add_f32_e32 v2, v2, v30
	v_fmamk_f32 v2, v2, 0x3b800000, v209
	v_cmp_gt_f32_e32 vcc, s89, v2
	v_mul_f32_e32 v30, 0x4f800000, v2
	s_nop 0
	v_cndmask_b32_e32 v2, v2, v30, vcc
	v_sqrt_f32_e32 v30, v2
	s_nop 0
	v_add_u32_e32 v31, -1, v30
	v_fma_f32 v38, -v31, v30, v2
	v_cmp_ge_f32_e64 s[0:1], 0, v38
	v_add_u32_e32 v38, 1, v30
	s_nop 0
	v_cndmask_b32_e64 v31, v30, v31, s[0:1]
	v_fma_f32 v30, -v38, v30, v2
	v_cmp_lt_f32_e64 s[0:1], 0, v30
	s_nop 1
	v_cndmask_b32_e64 v30, v31, v38, s[0:1]
	v_mul_f32_e32 v31, 0x37800000, v30
	v_cndmask_b32_e32 v30, v30, v31, vcc
	v_cmp_class_f32_e32 vcc, v2, v210
	s_nop 1
	v_cndmask_b32_e32 v2, v30, v2, vcc
	v_div_scale_f32 v30, s[0:1], v2, v2, 1.0
	v_rcp_f32_e32 v31, v30
	s_lshl_b64 s[0:1], s[16:17], 12
	s_add_u32 s0, s18, s0
	s_addc_u32 s1, s19, s1
	v_fma_f32 v38, -v30, v31, 1.0
	v_fmac_f32_e32 v31, v38, v31
	v_div_scale_f32 v38, vcc, 1.0, v2, 1.0
	v_mul_f32_e32 v39, v38, v31
	v_fma_f32 v40, -v30, v39, v38
	v_fmac_f32_e32 v39, v40, v31
	v_fma_f32 v30, -v30, v39, v38
	v_div_fmas_f32 v30, v30, v31, v39
	v_div_fixup_f32 v2, v30, v2, 1.0
	v_pk_mul_f32 v[20:21], v[20:21], v[2:3] op_sel_hi:[1,0]
	s_add_u32 s0, s0, s92
	v_pk_mul_f32 v[20:21], v[26:27], v[20:21]
	v_pk_mul_f32 v[26:27], v[32:33], v[2:3] op_sel_hi:[1,0]
	v_pk_mul_f32 v[20:21], v[34:35], v[20:21]
	v_pk_mul_f32 v[26:27], v[28:29], v[26:27]
	s_addc_u32 s1, s1, 0
	v_pk_mul_f32 v[26:27], v[36:37], v[26:27]
	v_lshlrev_b32_e32 v2, 1, v0
	v_cvt_pk_bf16_f32 v20, v20, v21
	v_cvt_pk_bf16_f32 v21, v26, v27
	v_lshl_add_u64 v[26:27], s[0:1], 0, v[2:3]
	global_store_dwordx2 v[26:27], v[20:21], off
	v_lshlrev_b32_e32 v20, 16, v17
	v_and_b32_e32 v21, 0xffff0000, v17
	v_lshlrev_b32_e32 v28, 16, v19
	v_and_b32_e32 v29, 0xffff0000, v19
	v_pk_add_f32 v[20:21], v[20:21], v[28:29]
	v_lshlrev_b32_e32 v28, 16, v15
	v_mul_f32_e32 v2, 0xbfb8aa3b, v28
	v_exp_f32_e32 v2, v2
	v_and_b32_e32 v29, 0xffff0000, v15
	v_and_b32_e32 v17, 0xffff0000, v18
	v_mov_b32_e32 v19, v20
	v_add_f32_e32 v2, 1.0, v2
	v_rcp_f32_e32 v30, v2
	v_mul_f32_e32 v2, 0xbfb8aa3b, v29
	v_exp_f32_e32 v2, v2
	s_add_i32 s20, s20, s90
	s_add_i32 s21, s21, s4
	s_cmp_lt_i32 s20, 0x10000
	v_add_f32_e32 v2, 1.0, v2
	v_rcp_f32_e32 v31, v2
	s_nop 0
	v_pk_mul_f32 v[28:29], v[30:31], v[28:29]
	v_lshlrev_b32_e32 v30, 16, v16
	v_and_b32_e32 v31, 0xffff0000, v16
	v_lshlrev_b32_e32 v16, 16, v18
	v_pk_add_f32 v[16:17], v[30:31], v[16:17]
	v_mov_b32_e32 v31, v21
	v_mov_b32_e32 v30, v17
	v_mov_b32_e32 v18, v16
	v_pk_mul_f32 v[30:31], v[30:31], v[30:31]
	v_pk_fma_f32 v[18:19], v[18:19], v[18:19], v[30:31]
	v_lshlrev_b32_e32 v30, 16, v14
	v_mul_f32_e32 v2, 0xbfb8aa3b, v30
	v_exp_f32_e32 v2, v2
	v_and_b32_e32 v31, 0xffff0000, v14
	v_add_f32_e32 v2, 1.0, v2
	v_rcp_f32_e32 v14, v2
	v_mul_f32_e32 v2, 0xbfb8aa3b, v31
	v_exp_f32_e32 v2, v2
	s_nop 0
	v_add_f32_e32 v2, 1.0, v2
	v_rcp_f32_e32 v15, v2
	v_add_f32_e32 v2, v18, v19
	ds_bpermute_b32 v18, v1, v2
	v_pk_mul_f32 v[14:15], v[14:15], v[30:31]
	s_waitcnt lgkmcnt(0)
	v_add_f32_e32 v2, v2, v18
	ds_bpermute_b32 v18, v5, v2
	s_waitcnt lgkmcnt(0)
	v_add_f32_e32 v2, v2, v18
	ds_bpermute_b32 v18, v22, v2
	s_waitcnt lgkmcnt(0)
	v_add_f32_e32 v2, v2, v18
	ds_bpermute_b32 v18, v23, v2
	s_waitcnt lgkmcnt(0)
	v_add_f32_e32 v2, v2, v18
	ds_bpermute_b32 v18, v24, v2
	s_waitcnt lgkmcnt(0)
	v_add_f32_e32 v2, v2, v18
	ds_bpermute_b32 v18, v25, v2
	s_waitcnt lgkmcnt(0)
	v_add_f32_e32 v2, v2, v18
	v_fmamk_f32 v2, v2, 0x3b800000, v209
	v_cmp_gt_f32_e32 vcc, s89, v2
	v_mul_f32_e32 v18, 0x4f800000, v2
	s_nop 0
	v_cndmask_b32_e32 v2, v2, v18, vcc
	v_sqrt_f32_e32 v18, v2
	s_nop 0
	v_add_u32_e32 v19, -1, v18
	v_fma_f32 v30, -v19, v18, v2
	v_cmp_ge_f32_e64 s[0:1], 0, v30
	v_add_u32_e32 v30, 1, v18
	s_nop 0
	v_cndmask_b32_e64 v19, v18, v19, s[0:1]
	v_fma_f32 v18, -v30, v18, v2
	v_cmp_lt_f32_e64 s[0:1], 0, v18
	s_nop 1
	v_cndmask_b32_e64 v18, v19, v30, s[0:1]
	v_mul_f32_e32 v19, 0x37800000, v18
	v_cndmask_b32_e32 v18, v18, v19, vcc
	v_cmp_class_f32_e32 vcc, v2, v210
	s_nop 1
	v_cndmask_b32_e32 v2, v18, v2, vcc
	v_div_scale_f32 v18, s[0:1], v2, v2, 1.0
	v_rcp_f32_e32 v19, v18
	s_nop 0
	v_fma_f32 v30, -v18, v19, 1.0
	v_fmac_f32_e32 v19, v30, v19
	v_div_scale_f32 v30, vcc, 1.0, v2, 1.0
	v_mul_f32_e32 v31, v30, v19
	v_fma_f32 v32, -v18, v31, v30
	v_fmac_f32_e32 v31, v32, v19
	v_fma_f32 v18, -v18, v31, v30
	v_div_fmas_f32 v18, v18, v19, v31
	v_div_fixup_f32 v2, v18, v2, 1.0
	v_pk_mul_f32 v[16:17], v[16:17], v[2:3] op_sel_hi:[1,0]
	v_pk_mul_f32 v[6:7], v[6:7], v[16:17]
	v_pk_mul_f32 v[6:7], v[14:15], v[6:7]
	v_pk_mul_f32 v[14:15], v[20:21], v[2:3] op_sel_hi:[1,0]
	v_cvt_pk_bf16_f32 v6, v6, v7
	v_pk_mul_f32 v[8:9], v[8:9], v[14:15]
	v_pk_mul_f32 v[8:9], v[28:29], v[8:9]
	v_cvt_pk_bf16_f32 v7, v8, v9
	global_store_dwordx2 v[26:27], v[6:7], off offset:512
	s_cbranch_scc1 .LBB0_804

;     __device__ __forceinline__ void operator()(const f32x4 (&acc)[2][2][4][2], const Unit& u, int wr, int wc, int fr, int fq) const {
;     ...
;             for (int m = 0; m < 4; ++m) { const size_t off = (size_t)(row0 + ai * HALF + m * 16) * ldc + col0; float ss = 0.f;
; #pragma unroll
;                 for (int bj = 0; bj < 2; ++bj)
; #pragma unroll
;                     for (int n = 0; n < 2; ++n) { const f32x4 bs = *(const f32x4*)(base + off + bj * HALF + n * 16); const f32x4 o = bs + acc[ai][bj][m][n] * scale;
;                         *(f32x4*)(out + off + bj * HALF + n * 16) = o;
;                         if (xg) { ss += (o[0] * o[0] + o[1] * o[1]) + (o[2] * o[2] + o[3] * o[3]); const f32x4 og = o * gv[bj][n];
;                             typedef unsigned u32x2v __attribute__((ext_vector_type(2))); u32x2v w; w.x = cvt_pk_bf16(og[0], og[1]); w.y = cvt_pk_bf16(og[2], og[3]); *(u32x2v*)(xg + off + bj * HALF + n * 16) = w; } }
;                 if (xg) { ss += __shfl_xor(ss, 16); ss += __shfl_xor(ss, 32); if (fq == 0) atomicAdd(rowss + row0 + ai * HALF + m * 16, (rowss_t)(ss * 16777216.0f)); } }
.LBB0_908:
	s_or_b64 exec, exec, s[26:27]
	v_or_b32_e32 v138, 16, v170
	s_waitcnt lgkmcnt(0)
	v_ashrrev_i32_e32 v139, 31, v138
	v_lshlrev_b64 v[138:139], 11, v[138:139]
	v_lshl_add_u64 v[142:143], v[138:139], 0, v[168:169]
	v_lshl_add_u64 v[144:145], v[142:143], 2, s[12:13]
	global_load_dwordx4 v[138:141], v[144:145], off
	global_load_dwordx4 v[182:185], v[144:145], off offset:64
	global_load_dwordx4 v[186:189], v[144:145], off offset:512
	global_load_dwordx4 v[190:193], v[144:145], off offset:576
	v_lshl_add_u64 v[142:143], v[142:143], 1, s[14:15]
	s_waitcnt vmcnt(3) lgkmcnt(0)
	v_pk_add_f32 v[132:133], v[132:133], v[140:141]
	v_pk_add_f32 v[130:131], v[130:131], v[138:139]
	v_pk_mul_f32 v[138:139], v[100:101], v[132:133]
	v_pk_mul_f32 v[140:141], v[98:99], v[130:131]
	global_store_dwordx4 v[144:145], v[130:133], off
	v_cvt_pk_bf16_f32 v140, v140, v141
	v_cvt_pk_bf16_f32 v141, v138, v139
	global_store_dwordx2 v[142:143], v[140:141], off
	v_mul_f32_e32 v131, v131, v131
	v_mul_f32_e32 v133, v133, v133
	v_fmac_f32_e32 v131, v130, v130
	v_fmac_f32_e32 v133, v132, v132
	v_add_f32_e32 v130, v131, v133
	s_waitcnt vmcnt(4) lgkmcnt(0)
	v_pk_add_f32 v[128:129], v[128:129], v[184:185]
	v_pk_add_f32 v[126:127], v[126:127], v[182:183]
	v_pk_mul_f32 v[138:139], v[96:97], v[128:129]
	v_pk_mul_f32 v[140:141], v[94:95], v[126:127]
	global_store_dwordx4 v[144:145], v[126:129], off offset:64
	v_cvt_pk_bf16_f32 v140, v140, v141
	v_cvt_pk_bf16_f32 v141, v138, v139
	global_store_dwordx2 v[142:143], v[140:141], off offset:32
	v_mul_f32_e32 v127, v127, v127
	v_mul_f32_e32 v129, v129, v129
	v_fmac_f32_e32 v127, v126, v126
	v_fmac_f32_e32 v129, v128, v128
	v_add_f32_e32 v126, v127, v129
	v_add_f32_e32 v126, v130, v126
	s_waitcnt vmcnt(5) lgkmcnt(0)
	v_pk_add_f32 v[124:125], v[124:125], v[188:189]
	v_pk_add_f32 v[122:123], v[122:123], v[186:187]
	v_pk_mul_f32 v[138:139], v[88:89], v[124:125]
	v_pk_mul_f32 v[140:141], v[86:87], v[122:123]
	global_store_dwordx4 v[144:145], v[122:125], off offset:512
	v_cvt_pk_bf16_f32 v140, v140, v141
	v_cvt_pk_bf16_f32 v141, v138, v139
	global_store_dwordx2 v[142:143], v[140:141], off offset:256
	v_mul_f32_e32 v123, v123, v123
	v_mul_f32_e32 v125, v125, v125
	v_fmac_f32_e32 v123, v122, v122
	v_fmac_f32_e32 v125, v124, v124
	v_add_f32_e32 v122, v123, v125
	v_add_f32_e32 v124, v126, v122
	s_waitcnt vmcnt(6) lgkmcnt(0)
	v_pk_add_f32 v[122:123], v[120:121], v[192:193]
	v_pk_add_f32 v[120:121], v[118:119], v[190:191]
	v_mul_f32_e32 v119, v123, v123
	v_mul_f32_e32 v118, v121, v121
	v_fmac_f32_e32 v118, v120, v120
	v_fmac_f32_e32 v119, v122, v122
	v_add_f32_e32 v118, v118, v119
	v_add_f32_e32 v118, v124, v118
	ds_bpermute_b32 v119, v136, v118
	global_store_dwordx4 v[144:145], v[120:123], off offset:576
	s_waitcnt lgkmcnt(0)
	v_add_f32_e32 v118, v118, v119
	ds_bpermute_b32 v119, v137, v118
	v_pk_mul_f32 v[122:123], v[80:81], v[122:123]
	v_pk_mul_f32 v[120:121], v[78:79], v[120:121]
	v_cvt_pk_bf16_f32 v120, v120, v121
	v_cvt_pk_bf16_f32 v121, v122, v123
	global_store_dwordx2 v[142:143], v[120:121], off offset:288
	s_and_saveexec_b64 s[26:27], s[8:9]
	s_mov_b32 s82, 0xf000000
	s_mov_b64 s[80:81], 0x2000
	s_cbranch_execz .LBB0_910
	s_waitcnt lgkmcnt(0)
	v_add_f32_e32 v118, v118, v119
	v_mul_f32_e32 v118, 0x4b800000, v118
	v_trunc_f32_e32 v118, v118
	v_mul_f32_e32 v119, 0x2f800000, v118
	v_floor_f32_e32 v119, v119
	v_fmac_f32_e32 v118, 0xcf800000, v119
	v_cvt_u32_f32_e32 v118, v118
	v_cvt_u32_f32_e32 v119, v119
	global_atomic_add_x2 v[134:135], v[118:119], off offset:128
.LBB0_910:
	s_or_b64 exec, exec, s[26:27]
	v_or_b32_e32 v118, 32, v170
	s_waitcnt lgkmcnt(0)
	v_ashrrev_i32_e32 v119, 31, v118
	v_lshlrev_b64 v[118:119], 11, v[118:119]
	v_lshl_add_u64 v[122:123], v[118:119], 0, v[168:169]
	v_lshl_add_u64 v[124:125], v[122:123], 2, s[12:13]
	global_load_dwordx4 v[118:121], v[124:125], off
	global_load_dwordx4 v[182:185], v[124:125], off offset:64
	global_load_dwordx4 v[186:189], v[124:125], off offset:512
	global_load_dwordx4 v[190:193], v[124:125], off offset:576
	v_lshl_add_u64 v[122:123], v[122:123], 1, s[14:15]
	s_waitcnt vmcnt(3) lgkmcnt(0)
	v_pk_add_f32 v[116:117], v[116:117], v[120:121]
	v_pk_add_f32 v[114:115], v[114:115], v[118:119]
	v_pk_mul_f32 v[118:119], v[100:101], v[116:117]
	v_pk_mul_f32 v[120:121], v[98:99], v[114:115]
	global_store_dwordx4 v[124:125], v[114:117], off
	v_cvt_pk_bf16_f32 v120, v120, v121
	v_cvt_pk_bf16_f32 v121, v118, v119
	global_store_dwordx2 v[122:123], v[120:121], off
	v_mul_f32_e32 v115, v115, v115
	v_mul_f32_e32 v117, v117, v117
	v_fmac_f32_e32 v115, v114, v114
	v_fmac_f32_e32 v117, v116, v116
	v_add_f32_e32 v114, v115, v117
	s_waitcnt vmcnt(4) lgkmcnt(0)
	v_pk_add_f32 v[112:113], v[112:113], v[184:185]
	v_pk_add_f32 v[110:111], v[110:111], v[182:183]
	v_pk_mul_f32 v[118:119], v[96:97], v[112:113]
	v_pk_mul_f32 v[120:121], v[94:95], v[110:111]
	global_store_dwordx4 v[124:125], v[110:113], off offset:64
	v_cvt_pk_bf16_f32 v120, v120, v121
	v_cvt_pk_bf16_f32 v121, v118, v119
	global_store_dwordx2 v[122:123], v[120:121], off offset:32
	v_mul_f32_e32 v111, v111, v111
	v_mul_f32_e32 v113, v113, v113
	v_fmac_f32_e32 v111, v110, v110
	v_fmac_f32_e32 v113, v112, v112
	v_add_f32_e32 v110, v111, v113
	v_add_f32_e32 v110, v114, v110
	s_waitcnt vmcnt(5) lgkmcnt(0)
	v_pk_add_f32 v[108:109], v[108:109], v[188:189]
	v_pk_add_f32 v[106:107], v[106:107], v[186:187]
	v_pk_mul_f32 v[118:119], v[88:89], v[108:109]
	v_pk_mul_f32 v[120:121], v[86:87], v[106:107]
	global_store_dwordx4 v[124:125], v[106:109], off offset:512
	v_cvt_pk_bf16_f32 v120, v120, v121
	v_cvt_pk_bf16_f32 v121, v118, v119
	global_store_dwordx2 v[122:123], v[120:121], off offset:256
	v_mul_f32_e32 v107, v107, v107
	v_mul_f32_e32 v109, v109, v109
	v_fmac_f32_e32 v107, v106, v106
	v_fmac_f32_e32 v109, v108, v108
	v_add_f32_e32 v106, v107, v109
	v_add_f32_e32 v108, v110, v106
	s_waitcnt vmcnt(6) lgkmcnt(0)
	v_pk_add_f32 v[106:107], v[104:105], v[192:193]
	v_pk_add_f32 v[104:105], v[102:103], v[190:191]
	v_mul_f32_e32 v103, v107, v107
	v_mul_f32_e32 v102, v105, v105
	v_fmac_f32_e32 v102, v104, v104
	v_fmac_f32_e32 v103, v106, v106
	v_add_f32_e32 v102, v102, v103
	v_add_f32_e32 v102, v108, v102
	ds_bpermute_b32 v103, v136, v102
	global_store_dwordx4 v[124:125], v[104:107], off offset:576
	s_waitcnt lgkmcnt(0)
	v_add_f32_e32 v102, v102, v103
	ds_bpermute_b32 v103, v137, v102
	v_pk_mul_f32 v[106:107], v[80:81], v[106:107]
	v_pk_mul_f32 v[104:105], v[78:79], v[104:105]
	v_cvt_pk_bf16_f32 v104, v104, v105
	v_cvt_pk_bf16_f32 v105, v106, v107
	global_store_dwordx2 v[122:123], v[104:105], off offset:288
	s_and_saveexec_b64 s[26:27], s[8:9]
	s_cbranch_execz .LBB0_912
	s_waitcnt lgkmcnt(0)
	v_add_f32_e32 v102, v102, v103
	v_mul_f32_e32 v102, 0x4b800000, v102
	v_trunc_f32_e32 v102, v102
	v_mul_f32_e32 v103, 0x2f800000, v102
	v_floor_f32_e32 v103, v103
	v_fmac_f32_e32 v102, 0xcf800000, v103
	v_cvt_u32_f32_e32 v102, v102
	v_cvt_u32_f32_e32 v103, v103
	global_atomic_add_x2 v[134:135], v[102:103], off offset:256
;     __device__ __forceinline__ void operator()(const f32x4 (&acc)[2][2][4][2], const Unit& u, int wr, int wc, int fr, int fq) const {
;     ...
;             for (int m = 0; m < 4; ++m) { const size_t off = (size_t)(row0 + ai * HALF + m * 16) * ldc + col0; float ss = 0.f;
; #pragma unroll
;                 for (int bj = 0; bj < 2; ++bj)
; #pragma unroll
;                     for (int n = 0; n < 2; ++n) { const f32x4 bs = *(const f32x4*)(base + off + bj * HALF + n * 16); const f32x4 o = bs + acc[ai][bj][m][n] * scale;
;                         *(f32x4*)(out + off + bj * HALF + n * 16) = o;
;                         if (xg) { ss += (o[0] * o[0] + o[1] * o[1]) + (o[2] * o[2] + o[3] * o[3]); const f32x4 og = o * gv[bj][n];
;                             typedef unsigned u32x2v __attribute__((ext_vector_type(2))); u32x2v w; w.x = cvt_pk_bf16(og[0], og[1]); w.y = cvt_pk_bf16(og[2], og[3]); *(u32x2v*)(xg + off + bj * HALF + n * 16) = w; } }
;                 if (xg) { ss += __shfl_xor(ss, 16); ss += __shfl_xor(ss, 32); if (fq == 0) atomicAdd(rowss + row0 + ai * HALF + m * 16, (rowss_t)(ss * 16777216.0f)); } }
.LBB0_912:
	s_or_b64 exec, exec, s[26:27]
	v_or_b32_e32 v102, 48, v170
	s_waitcnt lgkmcnt(0)
	v_ashrrev_i32_e32 v103, 31, v102
	v_lshlrev_b64 v[102:103], 11, v[102:103]
	v_lshl_add_u64 v[106:107], v[102:103], 0, v[168:169]
	v_lshl_add_u64 v[108:109], v[106:107], 2, s[12:13]
	global_load_dwordx4 v[102:105], v[108:109], off
	global_load_dwordx4 v[182:185], v[108:109], off offset:64
	global_load_dwordx4 v[186:189], v[108:109], off offset:512
	global_load_dwordx4 v[190:193], v[108:109], off offset:576
	v_lshl_add_u64 v[106:107], v[106:107], 1, s[14:15]
	s_waitcnt vmcnt(3) lgkmcnt(0)
	v_pk_add_f32 v[92:93], v[92:93], v[104:105]
	v_pk_add_f32 v[90:91], v[90:91], v[102:103]
	v_pk_mul_f32 v[102:103], v[100:101], v[92:93]
	v_pk_mul_f32 v[104:105], v[98:99], v[90:91]
	global_store_dwordx4 v[108:109], v[90:93], off
	v_cvt_pk_bf16_f32 v104, v104, v105
	v_cvt_pk_bf16_f32 v105, v102, v103
	global_store_dwordx2 v[106:107], v[104:105], off
	v_mul_f32_e32 v91, v91, v91
	v_mul_f32_e32 v93, v93, v93
	v_fmac_f32_e32 v91, v90, v90
	v_fmac_f32_e32 v93, v92, v92
	v_add_f32_e32 v90, v91, v93
	s_waitcnt vmcnt(4) lgkmcnt(0)
	v_pk_add_f32 v[84:85], v[84:85], v[184:185]
	v_pk_add_f32 v[82:83], v[82:83], v[182:183]
	v_pk_mul_f32 v[102:103], v[96:97], v[84:85]
	v_pk_mul_f32 v[104:105], v[94:95], v[82:83]
	global_store_dwordx4 v[108:109], v[82:85], off offset:64
	v_cvt_pk_bf16_f32 v104, v104, v105
	v_cvt_pk_bf16_f32 v105, v102, v103
	global_store_dwordx2 v[106:107], v[104:105], off offset:32
	v_mul_f32_e32 v83, v83, v83
	v_mul_f32_e32 v85, v85, v85
	v_fmac_f32_e32 v83, v82, v82
	v_fmac_f32_e32 v85, v84, v84
	v_add_f32_e32 v82, v83, v85
	v_add_f32_e32 v82, v90, v82
	s_waitcnt vmcnt(5) lgkmcnt(0)
	v_pk_add_f32 v[76:77], v[76:77], v[188:189]
	v_pk_add_f32 v[74:75], v[74:75], v[186:187]
	v_pk_mul_f32 v[102:103], v[88:89], v[76:77]
	v_pk_mul_f32 v[104:105], v[86:87], v[74:75]
	global_store_dwordx4 v[108:109], v[74:77], off offset:512
	v_cvt_pk_bf16_f32 v104, v104, v105
	v_cvt_pk_bf16_f32 v105, v102, v103
	global_store_dwordx2 v[106:107], v[104:105], off offset:256
	v_mul_f32_e32 v75, v75, v75
	v_mul_f32_e32 v77, v77, v77
	v_fmac_f32_e32 v75, v74, v74
	v_fmac_f32_e32 v77, v76, v76
	v_add_f32_e32 v74, v75, v77
	v_add_f32_e32 v76, v82, v74
	s_waitcnt vmcnt(6) lgkmcnt(0)
	v_pk_add_f32 v[74:75], v[72:73], v[192:193]
	v_pk_add_f32 v[72:73], v[70:71], v[190:191]
	v_mul_f32_e32 v71, v75, v75
	v_mul_f32_e32 v70, v73, v73
	v_fmac_f32_e32 v70, v72, v72
	v_fmac_f32_e32 v71, v74, v74
	v_add_f32_e32 v70, v70, v71
	v_add_f32_e32 v70, v76, v70
	ds_bpermute_b32 v71, v136, v70
	global_store_dwordx4 v[108:109], v[72:75], off offset:576
	s_waitcnt lgkmcnt(0)
	v_add_f32_e32 v70, v70, v71
	ds_bpermute_b32 v71, v137, v70
	v_pk_mul_f32 v[74:75], v[80:81], v[74:75]
	v_pk_mul_f32 v[72:73], v[78:79], v[72:73]
	v_cvt_pk_bf16_f32 v72, v72, v73
	v_cvt_pk_bf16_f32 v73, v74, v75
	global_store_dwordx2 v[106:107], v[72:73], off offset:288
	s_and_saveexec_b64 s[26:27], s[8:9]
	v_readlane_b32 s84, v253, 20
	s_mov_b32 s83, s54
	s_cbranch_execz .LBB0_914
	s_waitcnt lgkmcnt(0)
	v_add_f32_e32 v70, v70, v71
	v_mul_f32_e32 v70, 0x4b800000, v70
	v_trunc_f32_e32 v70, v70
	v_mul_f32_e32 v71, 0x2f800000, v70
	v_floor_f32_e32 v71, v71
	v_fmac_f32_e32 v70, 0xcf800000, v71
	v_cvt_u32_f32_e32 v70, v70
	v_cvt_u32_f32_e32 v71, v71
	global_atomic_add_x2 v[134:135], v[70:71], off offset:384
.LBB0_914:
	s_or_b64 exec, exec, s[26:27]
	s_mov_b64 s[6:7], 0x40000
	v_lshl_add_u64 v[74:75], v[166:167], 0, s[6:7]
	v_lshl_add_u64 v[76:77], v[74:75], 2, s[12:13]
	s_waitcnt lgkmcnt(0)
	global_load_dwordx4 v[70:73], v[76:77], off
	global_load_dwordx4 v[182:185], v[76:77], off offset:64
	global_load_dwordx4 v[186:189], v[76:77], off offset:512
	global_load_dwordx4 v[190:193], v[76:77], off offset:576
	v_lshl_add_u64 v[74:75], v[74:75], 1, s[14:15]
	s_waitcnt vmcnt(3) lgkmcnt(0)
	v_pk_add_f32 v[68:69], v[68:69], v[72:73]
	v_pk_add_f32 v[66:67], v[66:67], v[70:71]
	v_pk_mul_f32 v[70:71], v[100:101], v[68:69]
	v_pk_mul_f32 v[72:73], v[98:99], v[66:67]
	global_store_dwordx4 v[76:77], v[66:69], off
	v_cvt_pk_bf16_f32 v72, v72, v73
	v_cvt_pk_bf16_f32 v73, v70, v71
	global_store_dwordx2 v[74:75], v[72:73], off
	v_mul_f32_e32 v67, v67, v67
	v_mul_f32_e32 v69, v69, v69
	v_fmac_f32_e32 v67, v66, v66
	v_fmac_f32_e32 v69, v68, v68
	v_add_f32_e32 v66, v67, v69
	s_waitcnt vmcnt(4) lgkmcnt(0)
	v_pk_add_f32 v[64:65], v[64:65], v[184:185]
	v_pk_add_f32 v[62:63], v[62:63], v[182:183]
	v_pk_mul_f32 v[70:71], v[96:97], v[64:65]
	v_pk_mul_f32 v[72:73], v[94:95], v[62:63]
	global_store_dwordx4 v[76:77], v[62:65], off offset:64
	v_cvt_pk_bf16_f32 v72, v72, v73
	v_cvt_pk_bf16_f32 v73, v70, v71
	global_store_dwordx2 v[74:75], v[72:73], off offset:32
	v_mul_f32_e32 v63, v63, v63
	v_mul_f32_e32 v65, v65, v65
	v_fmac_f32_e32 v63, v62, v62
	v_fmac_f32_e32 v65, v64, v64
	v_add_f32_e32 v62, v63, v65
	v_add_f32_e32 v62, v66, v62
	s_waitcnt vmcnt(5) lgkmcnt(0)
	v_pk_add_f32 v[60:61], v[60:61], v[188:189]
	v_pk_add_f32 v[58:59], v[58:59], v[186:187]
	v_pk_mul_f32 v[70:71], v[88:89], v[60:61]
	v_pk_mul_f32 v[72:73], v[86:87], v[58:59]
	global_store_dwordx4 v[76:77], v[58:61], off offset:512
	v_cvt_pk_bf16_f32 v72, v72, v73
	v_cvt_pk_bf16_f32 v73, v70, v71
	global_store_dwordx2 v[74:75], v[72:73], off offset:256
	v_mul_f32_e32 v59, v59, v59
	v_mul_f32_e32 v61, v61, v61
	v_fmac_f32_e32 v59, v58, v58
	v_fmac_f32_e32 v61, v60, v60
	v_add_f32_e32 v58, v59, v61
	v_add_f32_e32 v60, v62, v58
	s_waitcnt vmcnt(6) lgkmcnt(0)
	v_pk_add_f32 v[58:59], v[56:57], v[192:193]
	v_pk_add_f32 v[56:57], v[54:55], v[190:191]
	v_mul_f32_e32 v55, v59, v59
	v_mul_f32_e32 v54, v57, v57
	v_fmac_f32_e32 v54, v56, v56
	v_fmac_f32_e32 v55, v58, v58
	v_add_f32_e32 v54, v54, v55
	v_add_f32_e32 v54, v60, v54
	ds_bpermute_b32 v55, v136, v54
	global_store_dwordx4 v[76:77], v[56:59], off offset:576
	s_waitcnt lgkmcnt(0)
	v_add_f32_e32 v54, v54, v55
	ds_bpermute_b32 v55, v137, v54
	v_pk_mul_f32 v[58:59], v[80:81], v[58:59]
	v_pk_mul_f32 v[56:57], v[78:79], v[56:57]
	v_cvt_pk_bf16_f32 v56, v56, v57
	v_cvt_pk_bf16_f32 v57, v58, v59
	global_store_dwordx2 v[74:75], v[56:57], off offset:288
	s_and_saveexec_b64 s[26:27], s[8:9]
	s_cbranch_execz .LBB0_916
	s_waitcnt lgkmcnt(0)
	v_add_f32_e32 v54, v54, v55
	v_mul_f32_e32 v54, 0x4b800000, v54
	v_trunc_f32_e32 v54, v54
	v_mul_f32_e32 v55, 0x2f800000, v54
	v_floor_f32_e32 v55, v55
	v_fmac_f32_e32 v54, 0xcf800000, v55
	v_cvt_u32_f32_e32 v54, v54
	v_cvt_u32_f32_e32 v55, v55
	global_atomic_add_x2 v[134:135], v[54:55], off offset:1024
;     __device__ __forceinline__ void operator()(const f32x4 (&acc)[2][2][4][2], const Unit& u, int wr, int wc, int fr, int fq) const {
;     ...
;             for (int m = 0; m < 4; ++m) { const size_t off = (size_t)(row0 + ai * HALF + m * 16) * ldc + col0; float ss = 0.f;
; #pragma unroll
;                 for (int bj = 0; bj < 2; ++bj)
; #pragma unroll
;                     for (int n = 0; n < 2; ++n) { const f32x4 bs = *(const f32x4*)(base + off + bj * HALF + n * 16); const f32x4 o = bs + acc[ai][bj][m][n] * scale;
;                         *(f32x4*)(out + off + bj * HALF + n * 16) = o;
;                         if (xg) { ss += (o[0] * o[0] + o[1] * o[1]) + (o[2] * o[2] + o[3] * o[3]); const f32x4 og = o * gv[bj][n];
;                             typedef unsigned u32x2v __attribute__((ext_vector_type(2))); u32x2v w; w.x = cvt_pk_bf16(og[0], og[1]); w.y = cvt_pk_bf16(og[2], og[3]); *(u32x2v*)(xg + off + bj * HALF + n * 16) = w; } }
;                 if (xg) { ss += __shfl_xor(ss, 16); ss += __shfl_xor(ss, 32); if (fq == 0) atomicAdd(rowss + row0 + ai * HALF + m * 16, (rowss_t)(ss * 16777216.0f)); } }
.LBB0_916:
	s_or_b64 exec, exec, s[26:27]
	s_mov_b64 s[6:7], 0x48000
	v_lshl_add_u64 v[58:59], v[166:167], 0, s[6:7]
	v_lshl_add_u64 v[60:61], v[58:59], 2, s[12:13]
	s_waitcnt lgkmcnt(0)
	global_load_dwordx4 v[54:57], v[60:61], off
	global_load_dwordx4 v[182:185], v[60:61], off offset:64
	global_load_dwordx4 v[186:189], v[60:61], off offset:512
	global_load_dwordx4 v[190:193], v[60:61], off offset:576
	v_lshl_add_u64 v[58:59], v[58:59], 1, s[14:15]
	s_waitcnt vmcnt(3) lgkmcnt(0)
	v_pk_add_f32 v[52:53], v[52:53], v[56:57]
	v_pk_add_f32 v[50:51], v[50:51], v[54:55]
	v_pk_mul_f32 v[54:55], v[100:101], v[52:53]
	v_pk_mul_f32 v[56:57], v[98:99], v[50:51]
	global_store_dwordx4 v[60:61], v[50:53], off
	v_cvt_pk_bf16_f32 v56, v56, v57
	v_cvt_pk_bf16_f32 v57, v54, v55
	global_store_dwordx2 v[58:59], v[56:57], off
	v_mul_f32_e32 v51, v51, v51
	v_mul_f32_e32 v53, v53, v53
	v_fmac_f32_e32 v51, v50, v50
	v_fmac_f32_e32 v53, v52, v52
	v_add_f32_e32 v50, v51, v53
	s_waitcnt vmcnt(4) lgkmcnt(0)
	v_pk_add_f32 v[48:49], v[48:49], v[184:185]
	v_pk_add_f32 v[46:47], v[46:47], v[182:183]
	v_pk_mul_f32 v[54:55], v[96:97], v[48:49]
	v_pk_mul_f32 v[56:57], v[94:95], v[46:47]
	global_store_dwordx4 v[60:61], v[46:49], off offset:64
	v_cvt_pk_bf16_f32 v56, v56, v57
	v_cvt_pk_bf16_f32 v57, v54, v55
	global_store_dwordx2 v[58:59], v[56:57], off offset:32
	v_mul_f32_e32 v47, v47, v47
	v_mul_f32_e32 v49, v49, v49
	v_fmac_f32_e32 v47, v46, v46
	v_fmac_f32_e32 v49, v48, v48
	v_add_f32_e32 v46, v47, v49
	v_add_f32_e32 v46, v50, v46
	s_waitcnt vmcnt(5) lgkmcnt(0)
	v_pk_add_f32 v[44:45], v[44:45], v[188:189]
	v_pk_add_f32 v[42:43], v[42:43], v[186:187]
	v_pk_mul_f32 v[54:55], v[88:89], v[44:45]
	v_pk_mul_f32 v[56:57], v[86:87], v[42:43]
	global_store_dwordx4 v[60:61], v[42:45], off offset:512
	v_cvt_pk_bf16_f32 v56, v56, v57
	v_cvt_pk_bf16_f32 v57, v54, v55
	global_store_dwordx2 v[58:59], v[56:57], off offset:256
	v_mul_f32_e32 v43, v43, v43
	v_mul_f32_e32 v45, v45, v45
	v_fmac_f32_e32 v43, v42, v42
	v_fmac_f32_e32 v45, v44, v44
	v_add_f32_e32 v42, v43, v45
	v_add_f32_e32 v44, v46, v42
	s_waitcnt vmcnt(6) lgkmcnt(0)
	v_pk_add_f32 v[42:43], v[40:41], v[192:193]
	v_pk_add_f32 v[40:41], v[38:39], v[190:191]
	v_mul_f32_e32 v39, v43, v43
	v_mul_f32_e32 v38, v41, v41
	v_fmac_f32_e32 v38, v40, v40
	v_fmac_f32_e32 v39, v42, v42
	v_add_f32_e32 v38, v38, v39
	v_add_f32_e32 v38, v44, v38
	ds_bpermute_b32 v39, v136, v38
	global_store_dwordx4 v[60:61], v[40:43], off offset:576
	s_waitcnt lgkmcnt(0)
	v_add_f32_e32 v38, v38, v39
	ds_bpermute_b32 v39, v137, v38
	v_pk_mul_f32 v[42:43], v[80:81], v[42:43]
	v_pk_mul_f32 v[40:41], v[78:79], v[40:41]
	v_cvt_pk_bf16_f32 v40, v40, v41
	v_cvt_pk_bf16_f32 v41, v42, v43
	global_store_dwordx2 v[58:59], v[40:41], off offset:288
	s_and_saveexec_b64 s[26:27], s[8:9]
	s_cbranch_execz .LBB0_918
	s_waitcnt lgkmcnt(0)
	v_add_f32_e32 v38, v38, v39
	v_mul_f32_e32 v38, 0x4b800000, v38
	v_trunc_f32_e32 v38, v38
	v_mul_f32_e32 v39, 0x2f800000, v38
	v_floor_f32_e32 v39, v39
	v_fmac_f32_e32 v38, 0xcf800000, v39
	v_cvt_u32_f32_e32 v38, v38
	v_cvt_u32_f32_e32 v39, v39
	global_atomic_add_x2 v[134:135], v[38:39], off offset:1152
;     __device__ __forceinline__ void operator()(const f32x4 (&acc)[2][2][4][2], const Unit& u, int wr, int wc, int fr, int fq) const {
;     ...
;             for (int m = 0; m < 4; ++m) { const size_t off = (size_t)(row0 + ai * HALF + m * 16) * ldc + col0; float ss = 0.f;
; #pragma unroll
;                 for (int bj = 0; bj < 2; ++bj)
; #pragma unroll
;                     for (int n = 0; n < 2; ++n) { const f32x4 bs = *(const f32x4*)(base + off + bj * HALF + n * 16); const f32x4 o = bs + acc[ai][bj][m][n] * scale;
;                         *(f32x4*)(out + off + bj * HALF + n * 16) = o;
;                         if (xg) { ss += (o[0] * o[0] + o[1] * o[1]) + (o[2] * o[2] + o[3] * o[3]); const f32x4 og = o * gv[bj][n];
;                             typedef unsigned u32x2v __attribute__((ext_vector_type(2))); u32x2v w; w.x = cvt_pk_bf16(og[0], og[1]); w.y = cvt_pk_bf16(og[2], og[3]); *(u32x2v*)(xg + off + bj * HALF + n * 16) = w; } }
;                 if (xg) { ss += __shfl_xor(ss, 16); ss += __shfl_xor(ss, 32); if (fq == 0) atomicAdd(rowss + row0 + ai * HALF + m * 16, (rowss_t)(ss * 16777216.0f)); } }
.LBB0_918:
	s_or_b64 exec, exec, s[26:27]
	s_mov_b64 s[6:7], 0x50000
	v_lshl_add_u64 v[42:43], v[166:167], 0, s[6:7]
	v_lshl_add_u64 v[44:45], v[42:43], 2, s[12:13]
	s_waitcnt lgkmcnt(0)
	global_load_dwordx4 v[38:41], v[44:45], off
	global_load_dwordx4 v[182:185], v[44:45], off offset:64
	global_load_dwordx4 v[186:189], v[44:45], off offset:512
	global_load_dwordx4 v[190:193], v[44:45], off offset:576
	v_lshl_add_u64 v[42:43], v[42:43], 1, s[14:15]
	s_waitcnt vmcnt(3) lgkmcnt(0)
	v_pk_add_f32 v[36:37], v[36:37], v[40:41]
	v_pk_add_f32 v[34:35], v[34:35], v[38:39]
	v_pk_mul_f32 v[38:39], v[100:101], v[36:37]
	v_pk_mul_f32 v[40:41], v[98:99], v[34:35]
	global_store_dwordx4 v[44:45], v[34:37], off
	v_cvt_pk_bf16_f32 v40, v40, v41
	v_cvt_pk_bf16_f32 v41, v38, v39
	global_store_dwordx2 v[42:43], v[40:41], off
	v_mul_f32_e32 v35, v35, v35
	v_mul_f32_e32 v37, v37, v37
	v_fmac_f32_e32 v35, v34, v34
	v_fmac_f32_e32 v37, v36, v36
	v_add_f32_e32 v34, v35, v37
	s_waitcnt vmcnt(4) lgkmcnt(0)
	v_pk_add_f32 v[32:33], v[32:33], v[184:185]
	v_pk_add_f32 v[30:31], v[30:31], v[182:183]
	v_pk_mul_f32 v[38:39], v[96:97], v[32:33]
	v_pk_mul_f32 v[40:41], v[94:95], v[30:31]
	global_store_dwordx4 v[44:45], v[30:33], off offset:64
	v_cvt_pk_bf16_f32 v40, v40, v41
	v_cvt_pk_bf16_f32 v41, v38, v39
	global_store_dwordx2 v[42:43], v[40:41], off offset:32
	v_mul_f32_e32 v31, v31, v31
	v_mul_f32_e32 v33, v33, v33
	v_fmac_f32_e32 v31, v30, v30
	v_fmac_f32_e32 v33, v32, v32
	v_add_f32_e32 v30, v31, v33
	v_add_f32_e32 v30, v34, v30
	s_waitcnt vmcnt(5) lgkmcnt(0)
	v_pk_add_f32 v[28:29], v[28:29], v[188:189]
	v_pk_add_f32 v[26:27], v[26:27], v[186:187]
	v_pk_mul_f32 v[38:39], v[88:89], v[28:29]
	v_pk_mul_f32 v[40:41], v[86:87], v[26:27]
	global_store_dwordx4 v[44:45], v[26:29], off offset:512
	v_cvt_pk_bf16_f32 v40, v40, v41
	v_cvt_pk_bf16_f32 v41, v38, v39
	global_store_dwordx2 v[42:43], v[40:41], off offset:256
	v_mul_f32_e32 v27, v27, v27
	v_mul_f32_e32 v29, v29, v29
	v_fmac_f32_e32 v27, v26, v26
	v_fmac_f32_e32 v29, v28, v28
	v_add_f32_e32 v26, v27, v29
	v_add_f32_e32 v28, v30, v26
	s_waitcnt vmcnt(6) lgkmcnt(0)
	v_pk_add_f32 v[26:27], v[24:25], v[192:193]
	v_pk_add_f32 v[24:25], v[22:23], v[190:191]
	v_mul_f32_e32 v23, v27, v27
	v_mul_f32_e32 v22, v25, v25
	v_fmac_f32_e32 v22, v24, v24
	v_fmac_f32_e32 v23, v26, v26
	v_add_f32_e32 v22, v22, v23
	v_add_f32_e32 v22, v28, v22
	ds_bpermute_b32 v23, v136, v22
	global_store_dwordx4 v[44:45], v[24:27], off offset:576
	s_waitcnt lgkmcnt(0)
	v_add_f32_e32 v22, v22, v23
	ds_bpermute_b32 v23, v137, v22
	v_pk_mul_f32 v[26:27], v[80:81], v[26:27]
	v_pk_mul_f32 v[24:25], v[78:79], v[24:25]
	v_cvt_pk_bf16_f32 v24, v24, v25
	v_cvt_pk_bf16_f32 v25, v26, v27
	global_store_dwordx2 v[42:43], v[24:25], off offset:288
	s_and_saveexec_b64 s[26:27], s[8:9]
	s_cbranch_execz .LBB0_920
	s_waitcnt lgkmcnt(0)
	v_add_f32_e32 v22, v22, v23
	v_mul_f32_e32 v22, 0x4b800000, v22
	v_trunc_f32_e32 v22, v22
	v_mul_f32_e32 v23, 0x2f800000, v22
	v_floor_f32_e32 v23, v23
	v_fmac_f32_e32 v22, 0xcf800000, v23
	v_cvt_u32_f32_e32 v22, v22
	v_cvt_u32_f32_e32 v23, v23
	global_atomic_add_x2 v[134:135], v[22:23], off offset:1280
.LBB0_920:
	s_or_b64 exec, exec, s[26:27]
	s_mov_b64 s[6:7], 0x58000
	v_lshl_add_u64 v[26:27], v[166:167], 0, s[6:7]
	v_lshl_add_u64 v[28:29], v[26:27], 2, s[12:13]
	s_waitcnt lgkmcnt(0)
	global_load_dwordx4 v[22:25], v[28:29], off
	global_load_dwordx4 v[182:185], v[28:29], off offset:64
	global_load_dwordx4 v[186:189], v[28:29], off offset:512
	global_load_dwordx4 v[190:193], v[28:29], off offset:576
	v_lshl_add_u64 v[26:27], v[26:27], 1, s[14:15]
	s_waitcnt vmcnt(3) lgkmcnt(0)
	v_pk_add_f32 v[20:21], v[20:21], v[24:25]
	v_pk_add_f32 v[18:19], v[18:19], v[22:23]
	v_pk_mul_f32 v[22:23], v[100:101], v[20:21]
	v_pk_mul_f32 v[24:25], v[98:99], v[18:19]
	global_store_dwordx4 v[28:29], v[18:21], off
	v_cvt_pk_bf16_f32 v24, v24, v25
	v_cvt_pk_bf16_f32 v25, v22, v23
	global_store_dwordx2 v[26:27], v[24:25], off
	v_mul_f32_e32 v19, v19, v19
	v_mul_f32_e32 v21, v21, v21
	v_fmac_f32_e32 v19, v18, v18
	v_fmac_f32_e32 v21, v20, v20
	v_add_f32_e32 v18, v19, v21
	s_waitcnt vmcnt(4) lgkmcnt(0)
	v_pk_add_f32 v[16:17], v[16:17], v[184:185]
	v_pk_add_f32 v[14:15], v[14:15], v[182:183]
	v_pk_mul_f32 v[22:23], v[96:97], v[16:17]
	v_pk_mul_f32 v[24:25], v[94:95], v[14:15]
	global_store_dwordx4 v[28:29], v[14:17], off offset:64
	v_cvt_pk_bf16_f32 v24, v24, v25
	v_cvt_pk_bf16_f32 v25, v22, v23
	global_store_dwordx2 v[26:27], v[24:25], off offset:32
	v_mul_f32_e32 v15, v15, v15
	v_mul_f32_e32 v17, v17, v17
	v_fmac_f32_e32 v15, v14, v14
	v_fmac_f32_e32 v17, v16, v16
	v_add_f32_e32 v14, v15, v17
	v_add_f32_e32 v14, v18, v14
	s_waitcnt vmcnt(5) lgkmcnt(0)
	v_pk_add_f32 v[12:13], v[12:13], v[188:189]
	v_pk_add_f32 v[10:11], v[10:11], v[186:187]
	v_pk_mul_f32 v[22:23], v[88:89], v[12:13]
	v_pk_mul_f32 v[24:25], v[86:87], v[10:11]
	global_store_dwordx4 v[28:29], v[10:13], off offset:512
	v_cvt_pk_bf16_f32 v24, v24, v25
	v_cvt_pk_bf16_f32 v25, v22, v23
	global_store_dwordx2 v[26:27], v[24:25], off offset:256
	v_mul_f32_e32 v11, v11, v11
	v_mul_f32_e32 v13, v13, v13
	v_fmac_f32_e32 v11, v10, v10
	v_fmac_f32_e32 v13, v12, v12
	v_add_f32_e32 v10, v11, v13
	v_add_f32_e32 v12, v14, v10
	s_waitcnt vmcnt(6) lgkmcnt(0)
	v_pk_add_f32 v[10:11], v[8:9], v[192:193]
	v_pk_add_f32 v[8:9], v[6:7], v[190:191]
	v_mul_f32_e32 v7, v11, v11
	v_mul_f32_e32 v6, v9, v9
	v_fmac_f32_e32 v6, v8, v8
	v_fmac_f32_e32 v7, v10, v10
	v_add_f32_e32 v6, v6, v7
	v_add_f32_e32 v6, v12, v6
	ds_bpermute_b32 v7, v136, v6
	global_store_dwordx4 v[28:29], v[8:11], off offset:576
	s_waitcnt lgkmcnt(0)
	v_add_f32_e32 v6, v6, v7
	ds_bpermute_b32 v7, v137, v6
	v_pk_mul_f32 v[10:11], v[80:81], v[10:11]
	v_pk_mul_f32 v[8:9], v[78:79], v[8:9]
	v_cvt_pk_bf16_f32 v8, v8, v9
	v_cvt_pk_bf16_f32 v9, v10, v11
	global_store_dwordx2 v[26:27], v[8:9], off offset:288
	s_and_saveexec_b64 s[26:27], s[8:9]
	s_cbranch_execz .LBB0_897
	s_waitcnt lgkmcnt(0)
	v_add_f32_e32 v6, v6, v7
	v_mul_f32_e32 v6, 0x4b800000, v6
	v_trunc_f32_e32 v6, v6
	v_mul_f32_e32 v7, 0x2f800000, v6
	v_floor_f32_e32 v7, v7
	v_fmac_f32_e32 v6, 0xcf800000, v7
	v_cvt_u32_f32_e32 v6, v6
	v_cvt_u32_f32_e32 v7, v7
	global_atomic_add_x2 v[134:135], v[6:7], off offset:1408
	s_branch .LBB0_897

; DI float bflo(unsigned w) { return __uint_as_float(w << 16); }
; DI float bfhi(unsigned w) { return __uint_as_float(w & 0xffff0000u); }
; DI unsigned pk2(float lo, float hi) { return pg8::cvt_pk_bf16(lo, hi); }
; DI void lru_pass3(const Ctx& C, const bf16* LA, const bf16* BV, const f32x2* AGG, const bf16* PROJ, float* HT, bf16* YMIX) {
;     ...
;         for (int i = 0; i < LSEG; ++i) { const unsigned lw = *(const unsigned*)(la0 + i * 1024), bw = *(const unsigned*)(bv0 + i * 1024);
;             h0 = __expf(bflo(lw)) * h0 + bflo(bw); h1 = __expf(bfhi(lw)) * h1 + bfhi(bw); *(unsigned*)(yp + i * D) = pk2(h0, h1); }
.LBB0_1355:
	global_load_dword v100, v[40:41], off
	global_load_dword v101, v[40:41], off offset:2048
	global_load_dword v124, v[42:43], off
	global_load_dword v125, v[42:43], off offset:2048
	v_lshl_add_u64 v[40:41], v[40:41], 0, v[46:47]
	v_lshl_add_u64 v[42:43], v[42:43], 0, v[46:47]
	global_load_dword v102, v[40:41], off
	global_load_dword v103, v[40:41], off offset:2048
	global_load_dword v126, v[42:43], off
	global_load_dword v127, v[42:43], off offset:2048
	v_lshl_add_u64 v[40:41], v[40:41], 0, v[46:47]
	v_lshl_add_u64 v[42:43], v[42:43], 0, v[46:47]
	global_load_dword v104, v[40:41], off
	global_load_dword v105, v[40:41], off offset:2048
	global_load_dword v128, v[42:43], off
	global_load_dword v129, v[42:43], off offset:2048
	v_lshl_add_u64 v[40:41], v[40:41], 0, v[46:47]
	v_lshl_add_u64 v[42:43], v[42:43], 0, v[46:47]
	global_load_dword v106, v[40:41], off
	global_load_dword v107, v[40:41], off offset:2048
	global_load_dword v130, v[42:43], off
	global_load_dword v131, v[42:43], off offset:2048
	v_lshl_add_u64 v[40:41], v[40:41], 0, v[46:47]
	v_lshl_add_u64 v[42:43], v[42:43], 0, v[46:47]
	global_load_dword v108, v[40:41], off
	global_load_dword v109, v[40:41], off offset:2048
	global_load_dword v132, v[42:43], off
	global_load_dword v133, v[42:43], off offset:2048
	v_lshl_add_u64 v[40:41], v[40:41], 0, v[46:47]
	v_lshl_add_u64 v[42:43], v[42:43], 0, v[46:47]
	global_load_dword v110, v[40:41], off
	global_load_dword v111, v[40:41], off offset:2048
	global_load_dword v134, v[42:43], off
	global_load_dword v135, v[42:43], off offset:2048
	v_lshl_add_u64 v[40:41], v[40:41], 0, v[46:47]
	v_lshl_add_u64 v[42:43], v[42:43], 0, v[46:47]
	global_load_dword v112, v[40:41], off
	global_load_dword v113, v[40:41], off offset:2048
	global_load_dword v136, v[42:43], off
	global_load_dword v137, v[42:43], off offset:2048
	v_lshl_add_u64 v[40:41], v[40:41], 0, v[46:47]
	v_lshl_add_u64 v[42:43], v[42:43], 0, v[46:47]
	global_load_dword v114, v[40:41], off
	global_load_dword v115, v[40:41], off offset:2048
	global_load_dword v138, v[42:43], off
	global_load_dword v139, v[42:43], off offset:2048
	v_lshl_add_u64 v[40:41], v[40:41], 0, v[46:47]
	v_lshl_add_u64 v[42:43], v[42:43], 0, v[46:47]
	s_waitcnt vmcnt(29) lgkmcnt(0)
	v_lshlrev_b32_e32 v20, 16, v100
	v_and_b32_e32 v21, 0xffff0000, v100
	v_mul_f32_e32 v20, 0x3fb8aa3b, v20
	v_mul_f32_e32 v21, 0x3fb8aa3b, v21
	v_exp_f32_e32 v20, v20
	v_exp_f32_e32 v21, v21
	v_lshlrev_b32_e32 v22, 16, v124
	v_and_b32_e32 v23, 0xffff0000, v124
	v_pk_fma_f32 v[24:25], v[24:25], v[20:21], v[22:23]
	v_cvt_pk_bf16_f32 v11, v24, v25
	global_store_dword v[44:45], v11, off
	v_lshl_add_u64 v[44:45], v[44:45], 0, v[46:47]
	s_waitcnt vmcnt(29)
	v_lshlrev_b32_e32 v20, 16, v101
	v_and_b32_e32 v21, 0xffff0000, v101
	v_mul_f32_e32 v20, 0x3fb8aa3b, v20
	v_mul_f32_e32 v21, 0x3fb8aa3b, v21
	v_exp_f32_e32 v20, v20
	v_exp_f32_e32 v21, v21
	v_lshlrev_b32_e32 v22, 16, v125
	v_and_b32_e32 v23, 0xffff0000, v125
	v_pk_fma_f32 v[24:25], v[24:25], v[20:21], v[22:23]
	v_cvt_pk_bf16_f32 v11, v24, v25
	global_store_dword v[44:45], v11, off
	v_lshl_add_u64 v[44:45], v[44:45], 0, v[46:47]
	s_waitcnt vmcnt(27)
	v_lshlrev_b32_e32 v20, 16, v102
	v_and_b32_e32 v21, 0xffff0000, v102
	v_mul_f32_e32 v20, 0x3fb8aa3b, v20
	v_mul_f32_e32 v21, 0x3fb8aa3b, v21
	v_exp_f32_e32 v20, v20
	v_exp_f32_e32 v21, v21
	v_lshlrev_b32_e32 v22, 16, v126
	v_and_b32_e32 v23, 0xffff0000, v126
	v_pk_fma_f32 v[24:25], v[24:25], v[20:21], v[22:23]
	v_cvt_pk_bf16_f32 v11, v24, v25
	global_store_dword v[44:45], v11, off
	v_lshl_add_u64 v[44:45], v[44:45], 0, v[46:47]
	s_waitcnt vmcnt(27)
	v_lshlrev_b32_e32 v20, 16, v103
	v_and_b32_e32 v21, 0xffff0000, v103
	v_mul_f32_e32 v20, 0x3fb8aa3b, v20
	v_mul_f32_e32 v21, 0x3fb8aa3b, v21
	v_exp_f32_e32 v20, v20
	v_exp_f32_e32 v21, v21
	v_lshlrev_b32_e32 v22, 16, v127
	v_and_b32_e32 v23, 0xffff0000, v127
	v_pk_fma_f32 v[24:25], v[24:25], v[20:21], v[22:23]
	v_cvt_pk_bf16_f32 v11, v24, v25
	global_store_dword v[44:45], v11, off
	v_lshl_add_u64 v[44:45], v[44:45], 0, v[46:47]
	s_waitcnt vmcnt(25)
	v_lshlrev_b32_e32 v20, 16, v104
	v_and_b32_e32 v21, 0xffff0000, v104
	v_mul_f32_e32 v20, 0x3fb8aa3b, v20
	v_mul_f32_e32 v21, 0x3fb8aa3b, v21
	v_exp_f32_e32 v20, v20
	v_exp_f32_e32 v21, v21
	v_lshlrev_b32_e32 v22, 16, v128
	v_and_b32_e32 v23, 0xffff0000, v128
	v_pk_fma_f32 v[24:25], v[24:25], v[20:21], v[22:23]
	v_cvt_pk_bf16_f32 v11, v24, v25
	global_store_dword v[44:45], v11, off
	v_lshl_add_u64 v[44:45], v[44:45], 0, v[46:47]
	s_waitcnt vmcnt(25)
	v_lshlrev_b32_e32 v20, 16, v105
	v_and_b32_e32 v21, 0xffff0000, v105
	v_mul_f32_e32 v20, 0x3fb8aa3b, v20
	v_mul_f32_e32 v21, 0x3fb8aa3b, v21
	v_exp_f32_e32 v20, v20
	v_exp_f32_e32 v21, v21
	v_lshlrev_b32_e32 v22, 16, v129
	v_and_b32_e32 v23, 0xffff0000, v129
	v_pk_fma_f32 v[24:25], v[24:25], v[20:21], v[22:23]
	v_cvt_pk_bf16_f32 v11, v24, v25
	global_store_dword v[44:45], v11, off
	v_lshl_add_u64 v[44:45], v[44:45], 0, v[46:47]
	s_waitcnt vmcnt(23)
; DI float bflo(unsigned w) { return __uint_as_float(w << 16); }
; DI float bfhi(unsigned w) { return __uint_as_float(w & 0xffff0000u); }
; DI unsigned pk2(float lo, float hi) { return pg8::cvt_pk_bf16(lo, hi); }
; DI void lru_pass3(const Ctx& C, const bf16* LA, const bf16* BV, const f32x2* AGG, const bf16* PROJ, float* HT, bf16* YMIX) {
;     ...
;         for (int i = 0; i < LSEG; ++i) { const unsigned lw = *(const unsigned*)(la0 + i * 1024), bw = *(const unsigned*)(bv0 + i * 1024);
;             h0 = __expf(bflo(lw)) * h0 + bflo(bw); h1 = __expf(bfhi(lw)) * h1 + bfhi(bw); *(unsigned*)(yp + i * D) = pk2(h0, h1); }
;         h0 = 0.f; h1 = 0.f;
; #pragma unroll 8
;         for (int s = 0; s < LNSEG - 1 - seg; ++s) { const f32x4 e = *(const f32x4*)(AGG + ((size_t)((b * 2 + 1) * LNSEG + s)) * 1024 + ch); h0 = e.x * h0 + e.y; h1 = e.z * h1 + e.w; }
	v_lshlrev_b32_e32 v20, 16, v106
	v_and_b32_e32 v21, 0xffff0000, v106
	v_mul_f32_e32 v20, 0x3fb8aa3b, v20
	v_mul_f32_e32 v21, 0x3fb8aa3b, v21
	v_exp_f32_e32 v20, v20
	v_exp_f32_e32 v21, v21
	v_lshlrev_b32_e32 v22, 16, v130
	v_and_b32_e32 v23, 0xffff0000, v130
	v_pk_fma_f32 v[24:25], v[24:25], v[20:21], v[22:23]
	v_cvt_pk_bf16_f32 v11, v24, v25
	global_store_dword v[44:45], v11, off
	v_lshl_add_u64 v[44:45], v[44:45], 0, v[46:47]
	s_waitcnt vmcnt(23)
	v_lshlrev_b32_e32 v20, 16, v107
	v_and_b32_e32 v21, 0xffff0000, v107
	v_mul_f32_e32 v20, 0x3fb8aa3b, v20
	v_mul_f32_e32 v21, 0x3fb8aa3b, v21
	v_exp_f32_e32 v20, v20
	v_exp_f32_e32 v21, v21
	v_lshlrev_b32_e32 v22, 16, v131
	v_and_b32_e32 v23, 0xffff0000, v131
	v_pk_fma_f32 v[24:25], v[24:25], v[20:21], v[22:23]
	v_cvt_pk_bf16_f32 v11, v24, v25
	global_store_dword v[44:45], v11, off
	v_lshl_add_u64 v[44:45], v[44:45], 0, v[46:47]
	s_waitcnt vmcnt(21)
	v_lshlrev_b32_e32 v20, 16, v108
	v_and_b32_e32 v21, 0xffff0000, v108
	v_mul_f32_e32 v20, 0x3fb8aa3b, v20
	v_mul_f32_e32 v21, 0x3fb8aa3b, v21
	v_exp_f32_e32 v20, v20
	v_exp_f32_e32 v21, v21
	v_lshlrev_b32_e32 v22, 16, v132
	v_and_b32_e32 v23, 0xffff0000, v132
	v_pk_fma_f32 v[24:25], v[24:25], v[20:21], v[22:23]
	v_cvt_pk_bf16_f32 v11, v24, v25
	global_store_dword v[44:45], v11, off
	v_lshl_add_u64 v[44:45], v[44:45], 0, v[46:47]
	s_waitcnt vmcnt(21)
	v_lshlrev_b32_e32 v20, 16, v109
	v_and_b32_e32 v21, 0xffff0000, v109
	v_mul_f32_e32 v20, 0x3fb8aa3b, v20
	v_mul_f32_e32 v21, 0x3fb8aa3b, v21
	v_exp_f32_e32 v20, v20
	v_exp_f32_e32 v21, v21
	v_lshlrev_b32_e32 v22, 16, v133
	v_and_b32_e32 v23, 0xffff0000, v133
	v_pk_fma_f32 v[24:25], v[24:25], v[20:21], v[22:23]
	v_cvt_pk_bf16_f32 v11, v24, v25
	global_store_dword v[44:45], v11, off
	v_lshl_add_u64 v[44:45], v[44:45], 0, v[46:47]
	s_waitcnt vmcnt(19)
	v_lshlrev_b32_e32 v20, 16, v110
	v_and_b32_e32 v21, 0xffff0000, v110
	v_mul_f32_e32 v20, 0x3fb8aa3b, v20
	v_mul_f32_e32 v21, 0x3fb8aa3b, v21
	v_exp_f32_e32 v20, v20
	v_exp_f32_e32 v21, v21
	v_lshlrev_b32_e32 v22, 16, v134
	v_and_b32_e32 v23, 0xffff0000, v134
	v_pk_fma_f32 v[24:25], v[24:25], v[20:21], v[22:23]
	v_cvt_pk_bf16_f32 v11, v24, v25
	global_store_dword v[44:45], v11, off
	v_lshl_add_u64 v[44:45], v[44:45], 0, v[46:47]
	s_waitcnt vmcnt(19)
	v_lshlrev_b32_e32 v20, 16, v111
	v_and_b32_e32 v21, 0xffff0000, v111
	v_mul_f32_e32 v20, 0x3fb8aa3b, v20
	v_mul_f32_e32 v21, 0x3fb8aa3b, v21
	v_exp_f32_e32 v20, v20
	v_exp_f32_e32 v21, v21
	v_lshlrev_b32_e32 v22, 16, v135
	v_and_b32_e32 v23, 0xffff0000, v135
	v_pk_fma_f32 v[24:25], v[24:25], v[20:21], v[22:23]
	v_cvt_pk_bf16_f32 v11, v24, v25
	global_store_dword v[44:45], v11, off
	v_lshl_add_u64 v[44:45], v[44:45], 0, v[46:47]
	s_waitcnt vmcnt(17)
	v_lshlrev_b32_e32 v20, 16, v112
	v_and_b32_e32 v21, 0xffff0000, v112
	v_mul_f32_e32 v20, 0x3fb8aa3b, v20
	v_mul_f32_e32 v21, 0x3fb8aa3b, v21
	v_exp_f32_e32 v20, v20
	v_exp_f32_e32 v21, v21
	v_lshlrev_b32_e32 v22, 16, v136
	v_and_b32_e32 v23, 0xffff0000, v136
	v_pk_fma_f32 v[24:25], v[24:25], v[20:21], v[22:23]
	v_cvt_pk_bf16_f32 v11, v24, v25
	global_store_dword v[44:45], v11, off
	v_lshl_add_u64 v[44:45], v[44:45], 0, v[46:47]
	s_waitcnt vmcnt(17)
	v_lshlrev_b32_e32 v20, 16, v113
	v_and_b32_e32 v21, 0xffff0000, v113
	v_mul_f32_e32 v20, 0x3fb8aa3b, v20
	v_mul_f32_e32 v21, 0x3fb8aa3b, v21
	v_exp_f32_e32 v20, v20
	v_exp_f32_e32 v21, v21
	v_lshlrev_b32_e32 v22, 16, v137
	v_and_b32_e32 v23, 0xffff0000, v137
	v_pk_fma_f32 v[24:25], v[24:25], v[20:21], v[22:23]
	v_cvt_pk_bf16_f32 v11, v24, v25
	global_store_dword v[44:45], v11, off
	v_lshl_add_u64 v[44:45], v[44:45], 0, v[46:47]
	s_waitcnt vmcnt(15)
	v_lshlrev_b32_e32 v20, 16, v114
	v_and_b32_e32 v21, 0xffff0000, v114
	v_mul_f32_e32 v20, 0x3fb8aa3b, v20
	v_mul_f32_e32 v21, 0x3fb8aa3b, v21
	v_exp_f32_e32 v20, v20
	v_exp_f32_e32 v21, v21
	v_lshlrev_b32_e32 v22, 16, v138
	v_and_b32_e32 v23, 0xffff0000, v138
	v_pk_fma_f32 v[24:25], v[24:25], v[20:21], v[22:23]
	v_cvt_pk_bf16_f32 v11, v24, v25
	global_store_dword v[44:45], v11, off
	v_lshl_add_u64 v[44:45], v[44:45], 0, v[46:47]
	s_waitcnt vmcnt(15)
	v_lshlrev_b32_e32 v20, 16, v115
	v_and_b32_e32 v21, 0xffff0000, v115
	v_mul_f32_e32 v20, 0x3fb8aa3b, v20
	v_mul_f32_e32 v21, 0x3fb8aa3b, v21
	v_exp_f32_e32 v20, v20
	v_exp_f32_e32 v21, v21
	v_lshlrev_b32_e32 v22, 16, v139
	v_and_b32_e32 v23, 0xffff0000, v139
	v_pk_fma_f32 v[24:25], v[24:25], v[20:21], v[22:23]
	v_cvt_pk_bf16_f32 v11, v24, v25
	global_store_dword v[44:45], v11, off
	v_lshl_add_u64 v[44:45], v[44:45], 0, v[46:47]
	s_add_i32 s8, s8, -16
	s_cmp_eq_u32 s8, 0
	s_cbranch_scc0 .LBB0_1355
	v_mov_b32_e32 v19, 0
	v_cmp_ne_u32_e32 vcc, 63, v29
	v_mov_b32_e32 v18, v19
	s_and_saveexec_b64 s[8:9], vcc
	s_cbranch_execz .LBB0_1366
	v_xor_b32_e32 v11, 63, v29
	v_xor_b32_e32 v20, 63, v13
	v_lshlrev_b32_e32 v16, 7, v10
	v_cmp_lt_u32_e32 vcc, 7, v11
	v_mov_b32_e32 v18, v3
	v_mov_b32_e32 v19, v3
	v_mov_b32_e32 v13, 0
	s_and_saveexec_b64 s[10:11], vcc
	s_cbranch_execz .LBB0_1361
	v_and_b32_e32 v18, 63, v20
	v_mov_b32_e32 v19, v3
	v_cmp_lt_u64_e32 vcc, 1, v[18:19]
	v_ashrrev_i32_e32 v17, 31, v16
	s_mov_b32 s16, 0
	v_cndmask_b32_e32 v13, 1, v18, vcc
	v_lshlrev_b64 v[18:19], 13, v[16:17]
	v_lshl_or_b32 v18, v12, 3, v18
	v_lshlrev_b32_e32 v13, 13, v13
	v_lshl_add_u64 v[24:25], s[72:73], 0, v[18:19]
	v_mov_b32_e32 v18, 0
	v_and_b32_e32 v22, 0x70000, v13
	s_mov_b64 s[12:13], 0
	s_mov_b64 s[14:15], 0
	v_mov_b32_e32 v19, v18

; DI float bflo(unsigned w) { return __uint_as_float(w << 16); }
; DI float bfhi(unsigned w) { return __uint_as_float(w & 0xffff0000u); }
; DI unsigned pk2(float lo, float hi) { return pg8::cvt_pk_bf16(lo, hi); }
; DI float gelu_tanh(float x) { const float u = 0.7978845608028654f * (x + 0.044715f * x * x * x); return x * sigm(2.0f * u); }
; DI void lru_pass3(const Ctx& C, const bf16* LA, const bf16* BV, const f32x2* AGG, const bf16* PROJ, float* HT, bf16* YMIX) {
;     ...
;         for (int i = LSEG - 1; i >= 0; --i) { const unsigned lw = *(const unsigned*)(la1 + i * 1024), bw = *(const unsigned*)(bv1 + i * 1024), gw = *(const unsigned*)(gp + (size_t)i * AB_N), fw = *(const unsigned*)(yp + i * D);
;             h0 = __expf(bflo(lw)) * h0 + bflo(bw); h1 = __expf(bfhi(lw)) * h1 + bfhi(bw);
;             *(unsigned*)(yp + i * D) = pk2(gelu_tanh(bflo(gw)) * (bflo(fw) + h0), gelu_tanh(bfhi(gw)) * (bfhi(fw) + h1)); }
.LBB0_1367:
	global_load_dword v100, v[40:41], off
	global_load_dword v101, v[40:41], off offset:-2048
	global_load_dword v108, v[42:43], off
	global_load_dword v109, v[42:43], off offset:-2048
	global_load_dword v124, v[36:37], off
	v_lshl_add_u64 v[36:37], v[36:37], 0, v[52:53]
	global_load_dword v125, v[36:37], off
	v_lshl_add_u64 v[36:37], v[36:37], 0, v[52:53]
	global_load_dword v132, v[38:39], off
	global_load_dword v133, v[38:39], off offset:-4096
	v_lshl_add_u64 v[40:41], v[40:41], 0, v[50:51]
	v_lshl_add_u64 v[42:43], v[42:43], 0, v[50:51]
	v_lshl_add_u64 v[38:39], v[38:39], 0, v[54:55]
	global_load_dword v102, v[40:41], off
	global_load_dword v103, v[40:41], off offset:-2048
	global_load_dword v110, v[42:43], off
	global_load_dword v111, v[42:43], off offset:-2048
	global_load_dword v126, v[36:37], off
	v_lshl_add_u64 v[36:37], v[36:37], 0, v[52:53]
	global_load_dword v127, v[36:37], off
	v_lshl_add_u64 v[36:37], v[36:37], 0, v[52:53]
	global_load_dword v134, v[38:39], off
	global_load_dword v135, v[38:39], off offset:-4096
	v_lshl_add_u64 v[40:41], v[40:41], 0, v[50:51]
	v_lshl_add_u64 v[42:43], v[42:43], 0, v[50:51]
	v_lshl_add_u64 v[38:39], v[38:39], 0, v[54:55]
	global_load_dword v104, v[40:41], off
	global_load_dword v105, v[40:41], off offset:-2048
	global_load_dword v112, v[42:43], off
	global_load_dword v113, v[42:43], off offset:-2048
	global_load_dword v128, v[36:37], off
	v_lshl_add_u64 v[36:37], v[36:37], 0, v[52:53]
	global_load_dword v129, v[36:37], off
	v_lshl_add_u64 v[36:37], v[36:37], 0, v[52:53]
	global_load_dword v136, v[38:39], off
	global_load_dword v137, v[38:39], off offset:-4096
	v_lshl_add_u64 v[40:41], v[40:41], 0, v[50:51]
	v_lshl_add_u64 v[42:43], v[42:43], 0, v[50:51]
	v_lshl_add_u64 v[38:39], v[38:39], 0, v[54:55]
	global_load_dword v106, v[40:41], off
	global_load_dword v107, v[40:41], off offset:-2048
	global_load_dword v114, v[42:43], off
	global_load_dword v115, v[42:43], off offset:-2048
	global_load_dword v130, v[36:37], off
	v_lshl_add_u64 v[36:37], v[36:37], 0, v[52:53]
	global_load_dword v131, v[36:37], off
	v_lshl_add_u64 v[36:37], v[36:37], 0, v[52:53]
	global_load_dword v138, v[38:39], off
	global_load_dword v139, v[38:39], off offset:-4096
	v_lshl_add_u64 v[40:41], v[40:41], 0, v[50:51]
	v_lshl_add_u64 v[42:43], v[42:43], 0, v[50:51]
	v_lshl_add_u64 v[38:39], v[38:39], 0, v[54:55]
	s_waitcnt vmcnt(25) lgkmcnt(0)
	v_lshlrev_b32_e32 v26, 16, v100
	v_and_b32_e32 v27, 0xffff0000, v100
	v_mul_f32_e32 v26, 0x3fb8aa3b, v26
	v_mul_f32_e32 v27, 0x3fb8aa3b, v27
	v_exp_f32_e32 v26, v26
	v_exp_f32_e32 v27, v27
	v_lshlrev_b32_e32 v30, 16, v108
	v_and_b32_e32 v31, 0xffff0000, v108
	v_pk_fma_f32 v[18:19], v[18:19], v[26:27], v[30:31]
	v_lshlrev_b32_e32 v26, 16, v124
	v_mul_f32_e32 v29, 0x3d372713, v26
	v_and_b32_e32 v27, 0xffff0000, v124
	v_mul_f32_e32 v29, v29, v26
	v_mov_b32_e32 v32, v26
	v_fmac_f32_e32 v32, v29, v32
	v_mul_f32_e32 v29, 0x3f4c422a, v32
	v_add_f32_e32 v29, v29, v29
	v_mul_f32_e32 v29, 0xbfb8aa3b, v29
	v_exp_f32_e32 v29, v29
	v_lshlrev_b32_e32 v30, 16, v132
	v_and_b32_e32 v31, 0xffff0000, v132
	v_mov_b32_e32 v33, v27
	v_add_f32_e32 v29, 1.0, v29
	v_rcp_f32_e32 v32, v29
	v_mul_f32_e32 v29, 0x3d372713, v27
	v_mul_f32_e32 v29, v29, v27
	v_fmac_f32_e32 v33, v29, v33
	v_mul_f32_e32 v29, 0x3f4c422a, v33
	v_add_f32_e32 v29, v29, v29
	v_mul_f32_e32 v29, 0xbfb8aa3b, v29
	v_exp_f32_e32 v29, v29
	v_pk_add_f32 v[30:31], v[18:19], v[30:31]
	v_add_f32_e32 v29, 1.0, v29
	v_rcp_f32_e32 v33, v29
	s_nop 0
	v_pk_mul_f32 v[26:27], v[32:33], v[26:27]
	v_pk_mul_f32 v[26:27], v[30:31], v[26:27]
	v_cvt_pk_bf16_f32 v26, v26, v27
	global_store_dword v[44:45], v26, off
	v_lshl_add_u64 v[44:45], v[44:45], 0, v[50:51]
	s_waitcnt vmcnt(25)
	v_lshlrev_b32_e32 v26, 16, v101
	v_and_b32_e32 v27, 0xffff0000, v101
	v_mul_f32_e32 v26, 0x3fb8aa3b, v26
	v_mul_f32_e32 v27, 0x3fb8aa3b, v27
	v_exp_f32_e32 v26, v26
	v_exp_f32_e32 v27, v27
	v_lshlrev_b32_e32 v30, 16, v109
	v_and_b32_e32 v31, 0xffff0000, v109
	v_pk_fma_f32 v[18:19], v[18:19], v[26:27], v[30:31]
	v_lshlrev_b32_e32 v26, 16, v125
	v_mul_f32_e32 v29, 0x3d372713, v26
	v_and_b32_e32 v27, 0xffff0000, v125
	v_mul_f32_e32 v29, v29, v26
	v_mov_b32_e32 v32, v26
	v_fmac_f32_e32 v32, v29, v32
	v_mul_f32_e32 v29, 0x3f4c422a, v32
	v_add_f32_e32 v29, v29, v29
	v_mul_f32_e32 v29, 0xbfb8aa3b, v29
	v_exp_f32_e32 v29, v29
	v_lshlrev_b32_e32 v30, 16, v133
	v_and_b32_e32 v31, 0xffff0000, v133
	v_mov_b32_e32 v33, v27
	v_add_f32_e32 v29, 1.0, v29
	v_rcp_f32_e32 v32, v29
	v_mul_f32_e32 v29, 0x3d372713, v27
	v_mul_f32_e32 v29, v29, v27
	v_fmac_f32_e32 v33, v29, v33
	v_mul_f32_e32 v29, 0x3f4c422a, v33
	v_add_f32_e32 v29, v29, v29
	v_mul_f32_e32 v29, 0xbfb8aa3b, v29
	v_exp_f32_e32 v29, v29
	v_pk_add_f32 v[30:31], v[18:19], v[30:31]
	v_add_f32_e32 v29, 1.0, v29
	v_rcp_f32_e32 v33, v29
	s_nop 0
	v_pk_mul_f32 v[26:27], v[32:33], v[26:27]
	v_pk_mul_f32 v[26:27], v[30:31], v[26:27]
	v_cvt_pk_bf16_f32 v26, v26, v27
	global_store_dword v[44:45], v26, off
	v_lshl_add_u64 v[44:45], v[44:45], 0, v[50:51]
	s_waitcnt vmcnt(19)
; DI float bflo(unsigned w) { return __uint_as_float(w << 16); }
; DI float bfhi(unsigned w) { return __uint_as_float(w & 0xffff0000u); }
; DI unsigned pk2(float lo, float hi) { return pg8::cvt_pk_bf16(lo, hi); }
; DI float gelu_tanh(float x) { const float u = 0.7978845608028654f * (x + 0.044715f * x * x * x); return x * sigm(2.0f * u); }
; DI void lru_pass3(const Ctx& C, const bf16* LA, const bf16* BV, const f32x2* AGG, const bf16* PROJ, float* HT, bf16* YMIX) {
;     ...
;         for (int i = LSEG - 1; i >= 0; --i) { const unsigned lw = *(const unsigned*)(la1 + i * 1024), bw = *(const unsigned*)(bv1 + i * 1024), gw = *(const unsigned*)(gp + (size_t)i * AB_N), fw = *(const unsigned*)(yp + i * D);
;             h0 = __expf(bflo(lw)) * h0 + bflo(bw); h1 = __expf(bfhi(lw)) * h1 + bfhi(bw);
;             *(unsigned*)(yp + i * D) = pk2(gelu_tanh(bflo(gw)) * (bflo(fw) + h0), gelu_tanh(bfhi(gw)) * (bfhi(fw) + h1)); }
	v_lshlrev_b32_e32 v26, 16, v102
	v_and_b32_e32 v27, 0xffff0000, v102
	v_mul_f32_e32 v26, 0x3fb8aa3b, v26
	v_mul_f32_e32 v27, 0x3fb8aa3b, v27
	v_exp_f32_e32 v26, v26
	v_exp_f32_e32 v27, v27
	v_lshlrev_b32_e32 v30, 16, v110
	v_and_b32_e32 v31, 0xffff0000, v110
	v_pk_fma_f32 v[18:19], v[18:19], v[26:27], v[30:31]
	v_lshlrev_b32_e32 v26, 16, v126
	v_mul_f32_e32 v29, 0x3d372713, v26
	v_and_b32_e32 v27, 0xffff0000, v126
	v_mul_f32_e32 v29, v29, v26
	v_mov_b32_e32 v32, v26
	v_fmac_f32_e32 v32, v29, v32
	v_mul_f32_e32 v29, 0x3f4c422a, v32
	v_add_f32_e32 v29, v29, v29
	v_mul_f32_e32 v29, 0xbfb8aa3b, v29
	v_exp_f32_e32 v29, v29
	v_lshlrev_b32_e32 v30, 16, v134
	v_and_b32_e32 v31, 0xffff0000, v134
	v_mov_b32_e32 v33, v27
	v_add_f32_e32 v29, 1.0, v29
	v_rcp_f32_e32 v32, v29
	v_mul_f32_e32 v29, 0x3d372713, v27
	v_mul_f32_e32 v29, v29, v27
	v_fmac_f32_e32 v33, v29, v33
	v_mul_f32_e32 v29, 0x3f4c422a, v33
	v_add_f32_e32 v29, v29, v29
	v_mul_f32_e32 v29, 0xbfb8aa3b, v29
	v_exp_f32_e32 v29, v29
	v_pk_add_f32 v[30:31], v[18:19], v[30:31]
	v_add_f32_e32 v29, 1.0, v29
	v_rcp_f32_e32 v33, v29
	s_nop 0
	v_pk_mul_f32 v[26:27], v[32:33], v[26:27]
	v_pk_mul_f32 v[26:27], v[30:31], v[26:27]
	v_cvt_pk_bf16_f32 v26, v26, v27
	global_store_dword v[44:45], v26, off
	v_lshl_add_u64 v[44:45], v[44:45], 0, v[50:51]
	s_waitcnt vmcnt(19)
	v_lshlrev_b32_e32 v26, 16, v103
	v_and_b32_e32 v27, 0xffff0000, v103
	v_mul_f32_e32 v26, 0x3fb8aa3b, v26
	v_mul_f32_e32 v27, 0x3fb8aa3b, v27
	v_exp_f32_e32 v26, v26
	v_exp_f32_e32 v27, v27
	v_lshlrev_b32_e32 v30, 16, v111
	v_and_b32_e32 v31, 0xffff0000, v111
	v_pk_fma_f32 v[18:19], v[18:19], v[26:27], v[30:31]
	v_lshlrev_b32_e32 v26, 16, v127
	v_mul_f32_e32 v29, 0x3d372713, v26
	v_and_b32_e32 v27, 0xffff0000, v127
	v_mul_f32_e32 v29, v29, v26
	v_mov_b32_e32 v32, v26
	v_fmac_f32_e32 v32, v29, v32
	v_mul_f32_e32 v29, 0x3f4c422a, v32
	v_add_f32_e32 v29, v29, v29
	v_mul_f32_e32 v29, 0xbfb8aa3b, v29
	v_exp_f32_e32 v29, v29
	v_lshlrev_b32_e32 v30, 16, v135
	v_and_b32_e32 v31, 0xffff0000, v135
	v_mov_b32_e32 v33, v27
	v_add_f32_e32 v29, 1.0, v29
	v_rcp_f32_e32 v32, v29
	v_mul_f32_e32 v29, 0x3d372713, v27
	v_mul_f32_e32 v29, v29, v27
	v_fmac_f32_e32 v33, v29, v33
	v_mul_f32_e32 v29, 0x3f4c422a, v33
	v_add_f32_e32 v29, v29, v29
	v_mul_f32_e32 v29, 0xbfb8aa3b, v29
	v_exp_f32_e32 v29, v29
	v_pk_add_f32 v[30:31], v[18:19], v[30:31]
	v_add_f32_e32 v29, 1.0, v29
	v_rcp_f32_e32 v33, v29
	s_nop 0
	v_pk_mul_f32 v[26:27], v[32:33], v[26:27]
	v_pk_mul_f32 v[26:27], v[30:31], v[26:27]
	v_cvt_pk_bf16_f32 v26, v26, v27
	global_store_dword v[44:45], v26, off
	v_lshl_add_u64 v[44:45], v[44:45], 0, v[50:51]
	s_waitcnt vmcnt(13)
	v_lshlrev_b32_e32 v26, 16, v104
	v_and_b32_e32 v27, 0xffff0000, v104
	v_mul_f32_e32 v26, 0x3fb8aa3b, v26
	v_mul_f32_e32 v27, 0x3fb8aa3b, v27
	v_exp_f32_e32 v26, v26
	v_exp_f32_e32 v27, v27
	v_lshlrev_b32_e32 v30, 16, v112
	v_and_b32_e32 v31, 0xffff0000, v112
	v_pk_fma_f32 v[18:19], v[18:19], v[26:27], v[30:31]
	v_lshlrev_b32_e32 v26, 16, v128
	v_mul_f32_e32 v29, 0x3d372713, v26
	v_and_b32_e32 v27, 0xffff0000, v128
	v_mul_f32_e32 v29, v29, v26
	v_mov_b32_e32 v32, v26
	v_fmac_f32_e32 v32, v29, v32
	v_mul_f32_e32 v29, 0x3f4c422a, v32
	v_add_f32_e32 v29, v29, v29
	v_mul_f32_e32 v29, 0xbfb8aa3b, v29
	v_exp_f32_e32 v29, v29
	v_lshlrev_b32_e32 v30, 16, v136
	v_and_b32_e32 v31, 0xffff0000, v136
	v_mov_b32_e32 v33, v27
	v_add_f32_e32 v29, 1.0, v29
	v_rcp_f32_e32 v32, v29
	v_mul_f32_e32 v29, 0x3d372713, v27
	v_mul_f32_e32 v29, v29, v27
	v_fmac_f32_e32 v33, v29, v33
	v_mul_f32_e32 v29, 0x3f4c422a, v33
	v_add_f32_e32 v29, v29, v29
	v_mul_f32_e32 v29, 0xbfb8aa3b, v29
	v_exp_f32_e32 v29, v29
	v_pk_add_f32 v[30:31], v[18:19], v[30:31]
	v_add_f32_e32 v29, 1.0, v29
	v_rcp_f32_e32 v33, v29
	s_nop 0
	v_pk_mul_f32 v[26:27], v[32:33], v[26:27]
	v_pk_mul_f32 v[26:27], v[30:31], v[26:27]
	v_cvt_pk_bf16_f32 v26, v26, v27
	global_store_dword v[44:45], v26, off
	v_lshl_add_u64 v[44:45], v[44:45], 0, v[50:51]
	s_waitcnt vmcnt(13)
; DI float bflo(unsigned w) { return __uint_as_float(w << 16); }
; DI float bfhi(unsigned w) { return __uint_as_float(w & 0xffff0000u); }
; DI unsigned pk2(float lo, float hi) { return pg8::cvt_pk_bf16(lo, hi); }
; DI float gelu_tanh(float x) { const float u = 0.7978845608028654f * (x + 0.044715f * x * x * x); return x * sigm(2.0f * u); }
; DI void lru_pass3(const Ctx& C, const bf16* LA, const bf16* BV, const f32x2* AGG, const bf16* PROJ, float* HT, bf16* YMIX) {
;     ...
;         for (int i = LSEG - 1; i >= 0; --i) { const unsigned lw = *(const unsigned*)(la1 + i * 1024), bw = *(const unsigned*)(bv1 + i * 1024), gw = *(const unsigned*)(gp + (size_t)i * AB_N), fw = *(const unsigned*)(yp + i * D);
;             h0 = __expf(bflo(lw)) * h0 + bflo(bw); h1 = __expf(bfhi(lw)) * h1 + bfhi(bw);
;             *(unsigned*)(yp + i * D) = pk2(gelu_tanh(bflo(gw)) * (bflo(fw) + h0), gelu_tanh(bfhi(gw)) * (bfhi(fw) + h1)); }
	v_lshlrev_b32_e32 v26, 16, v105
	v_and_b32_e32 v27, 0xffff0000, v105
	v_mul_f32_e32 v26, 0x3fb8aa3b, v26
	v_mul_f32_e32 v27, 0x3fb8aa3b, v27
	v_exp_f32_e32 v26, v26
	v_exp_f32_e32 v27, v27
	v_lshlrev_b32_e32 v30, 16, v113
	v_and_b32_e32 v31, 0xffff0000, v113
	v_pk_fma_f32 v[18:19], v[18:19], v[26:27], v[30:31]
	v_lshlrev_b32_e32 v26, 16, v129
	v_mul_f32_e32 v29, 0x3d372713, v26
	v_and_b32_e32 v27, 0xffff0000, v129
	v_mul_f32_e32 v29, v29, v26
	v_mov_b32_e32 v32, v26
	v_fmac_f32_e32 v32, v29, v32
	v_mul_f32_e32 v29, 0x3f4c422a, v32
	v_add_f32_e32 v29, v29, v29
	v_mul_f32_e32 v29, 0xbfb8aa3b, v29
	v_exp_f32_e32 v29, v29
	v_lshlrev_b32_e32 v30, 16, v137
	v_and_b32_e32 v31, 0xffff0000, v137
	v_mov_b32_e32 v33, v27
	v_add_f32_e32 v29, 1.0, v29
	v_rcp_f32_e32 v32, v29
	v_mul_f32_e32 v29, 0x3d372713, v27
	v_mul_f32_e32 v29, v29, v27
	v_fmac_f32_e32 v33, v29, v33
	v_mul_f32_e32 v29, 0x3f4c422a, v33
	v_add_f32_e32 v29, v29, v29
	v_mul_f32_e32 v29, 0xbfb8aa3b, v29
	v_exp_f32_e32 v29, v29
	v_pk_add_f32 v[30:31], v[18:19], v[30:31]
	v_add_f32_e32 v29, 1.0, v29
	v_rcp_f32_e32 v33, v29
	s_nop 0
	v_pk_mul_f32 v[26:27], v[32:33], v[26:27]
	v_pk_mul_f32 v[26:27], v[30:31], v[26:27]
	v_cvt_pk_bf16_f32 v26, v26, v27
	global_store_dword v[44:45], v26, off
	v_lshl_add_u64 v[44:45], v[44:45], 0, v[50:51]
	s_waitcnt vmcnt(7)
	v_lshlrev_b32_e32 v26, 16, v106
	v_and_b32_e32 v27, 0xffff0000, v106
	v_mul_f32_e32 v26, 0x3fb8aa3b, v26
	v_mul_f32_e32 v27, 0x3fb8aa3b, v27
	v_exp_f32_e32 v26, v26
	v_exp_f32_e32 v27, v27
	v_lshlrev_b32_e32 v30, 16, v114
	v_and_b32_e32 v31, 0xffff0000, v114
	v_pk_fma_f32 v[18:19], v[18:19], v[26:27], v[30:31]
	v_lshlrev_b32_e32 v26, 16, v130
	v_mul_f32_e32 v29, 0x3d372713, v26
	v_and_b32_e32 v27, 0xffff0000, v130
	v_mul_f32_e32 v29, v29, v26
	v_mov_b32_e32 v32, v26
	v_fmac_f32_e32 v32, v29, v32
	v_mul_f32_e32 v29, 0x3f4c422a, v32
	v_add_f32_e32 v29, v29, v29
	v_mul_f32_e32 v29, 0xbfb8aa3b, v29
	v_exp_f32_e32 v29, v29
	v_lshlrev_b32_e32 v30, 16, v138
	v_and_b32_e32 v31, 0xffff0000, v138
	v_mov_b32_e32 v33, v27
	v_add_f32_e32 v29, 1.0, v29
	v_rcp_f32_e32 v32, v29
	v_mul_f32_e32 v29, 0x3d372713, v27
	v_mul_f32_e32 v29, v29, v27
	v_fmac_f32_e32 v33, v29, v33
	v_mul_f32_e32 v29, 0x3f4c422a, v33
	v_add_f32_e32 v29, v29, v29
	v_mul_f32_e32 v29, 0xbfb8aa3b, v29
	v_exp_f32_e32 v29, v29
	v_pk_add_f32 v[30:31], v[18:19], v[30:31]
	v_add_f32_e32 v29, 1.0, v29
	v_rcp_f32_e32 v33, v29
	s_nop 0
	v_pk_mul_f32 v[26:27], v[32:33], v[26:27]
	v_pk_mul_f32 v[26:27], v[30:31], v[26:27]
	v_cvt_pk_bf16_f32 v26, v26, v27
	global_store_dword v[44:45], v26, off
	v_lshl_add_u64 v[44:45], v[44:45], 0, v[50:51]
	s_waitcnt vmcnt(7)
	v_lshlrev_b32_e32 v26, 16, v107
	v_and_b32_e32 v27, 0xffff0000, v107
	v_mul_f32_e32 v26, 0x3fb8aa3b, v26
	v_mul_f32_e32 v27, 0x3fb8aa3b, v27
	v_exp_f32_e32 v26, v26
	v_exp_f32_e32 v27, v27
	v_lshlrev_b32_e32 v30, 16, v115
	v_and_b32_e32 v31, 0xffff0000, v115
	v_pk_fma_f32 v[18:19], v[18:19], v[26:27], v[30:31]
	v_lshlrev_b32_e32 v26, 16, v131
	v_mul_f32_e32 v29, 0x3d372713, v26
	v_and_b32_e32 v27, 0xffff0000, v131
	v_mul_f32_e32 v29, v29, v26
	v_mov_b32_e32 v32, v26
	v_fmac_f32_e32 v32, v29, v32
	v_mul_f32_e32 v29, 0x3f4c422a, v32
	v_add_f32_e32 v29, v29, v29
	v_mul_f32_e32 v29, 0xbfb8aa3b, v29
	v_exp_f32_e32 v29, v29
	v_lshlrev_b32_e32 v30, 16, v139
	v_and_b32_e32 v31, 0xffff0000, v139
	v_mov_b32_e32 v33, v27
	v_add_f32_e32 v29, 1.0, v29
	v_rcp_f32_e32 v32, v29
	v_mul_f32_e32 v29, 0x3d372713, v27
	v_mul_f32_e32 v29, v29, v27
	v_fmac_f32_e32 v33, v29, v33
	v_mul_f32_e32 v29, 0x3f4c422a, v33
	v_add_f32_e32 v29, v29, v29
	v_mul_f32_e32 v29, 0xbfb8aa3b, v29
	v_exp_f32_e32 v29, v29
	v_pk_add_f32 v[30:31], v[18:19], v[30:31]
	v_add_f32_e32 v29, 1.0, v29
	v_rcp_f32_e32 v33, v29
	s_nop 0
	v_pk_mul_f32 v[26:27], v[32:33], v[26:27]
	v_pk_mul_f32 v[26:27], v[30:31], v[26:27]
	v_cvt_pk_bf16_f32 v26, v26, v27
	global_store_dword v[44:45], v26, off
	v_lshl_add_u64 v[44:45], v[44:45], 0, v[50:51]
	s_add_i32 s8, s8, 8
	s_cmp_eq_u32 s8, 0
	s_cbranch_scc0 .LBB0_1367
	v_add_u32_e32 v1, s76, v1
	v_cmp_lt_i32_e32 vcc, s77, v1
	s_or_b64 s[46:47], vcc, s[46:47]
	v_add_u32_e32 v28, s71, v28
	s_andn2_b64 exec, exec, s[46:47]
	s_cbranch_execnz .LBB0_1342

; DI float bflo(unsigned w) { return __uint_as_float(w << 16); }
; DI float bfhi(unsigned w) { return __uint_as_float(w & 0xffff0000u); }
; template <int ACT  > DI void hnorm_phase(const Ctx& C, const bf16* HF, const bf16* HB, const float* g, const bf16* gate, int ldg, bf16* Y  ) {
;     for (int it0 = 2 * C.gw; it0 < T * 4; it0 += 2 * C.ngw) {
;         v2u a[2], b[2], gt[2]; f32x4 gv[2]; size_t o[2]; int hh[2], tk[2];
; #pragma unroll
;         for (int u = 0; u < 2; ++u) { const int it = it0 + u; tk[u] = it >> 2; hh[u] = it & 3; o[u] = (size_t)tk[u] * 1024 + hh[u] * 256 + 4 * C.lane;
;             a[u] = *(const v2u*)(HF + o[u]); b[u] = *(const v2u*)(HB + o[u]); gv[u] = *(const f32x4*)(g + hh[u] * 256 + 4 * C.lane); gt[u] = *(const v2u*)(gate + (size_t)tk[u] * ldg + hh[u] * 256 + 4 * C.lane); }
; #pragma unroll
;         for (int u = 0; u < 2; ++u) {
;             float v[4] = {bflo(a[u].x) + bflo(b[u].x), bfhi(a[u].x) + bfhi(b[u].x), bflo(a[u].y) + bflo(b[u].y), bfhi(a[u].y) + bfhi(b[u].y)};
;             const float rstd = 1.0f / sqrtf(wave_sum((v[0] * v[0] + v[1] * v[1]) + (v[2] * v[2] + v[3] * v[3])) * (1.0f / 256.0f) + EPS);
.LBB0_1549:
	s_ashr_i32 s12, s16, 2
	s_ashr_i32 s13, s12, 31
	s_lshl_b64 s[0:1], s[12:13], 10
	v_mov_b32_e32 v7, s1
	v_or_b32_e32 v2, s0, v0
	v_mad_i64_i32 v[8:9], s[0:1], s12, v226, v[12:13]
	s_and_b32 s0, s17, 0x200
	s_lshl_b32 s92, s0, 2
	v_lshl_add_u64 v[18:19], v[10:11], 0, s[92:93]
	s_lshl_b32 s92, s0, 1
	v_lshl_add_u64 v[32:33], v[8:9], 0, s[92:93]
	global_load_dwordx2 v[34:35], v[32:33], off
	v_or_b32_e32 v6, s0, v2
	v_lshlrev_b64 v[14:15], 1, v[6:7]
	v_lshl_add_u64 v[16:17], s[8:9], 0, v[14:15]
	v_lshl_add_u64 v[14:15], s[10:11], 0, v[14:15]
	global_load_dwordx2 v[20:21], v[16:17], off
	global_load_dwordx2 v[30:31], v[14:15], off
	v_or_b32_e32 v6, 0x100, v6
	v_lshlrev_b64 v[6:7], 1, v[6:7]
	v_lshl_add_u64 v[8:9], s[8:9], 0, v[6:7]
	v_lshl_add_u64 v[6:7], s[10:11], 0, v[6:7]
	global_load_dwordx4 v[26:29], v[18:19], off
	global_load_dwordx2 v[14:15], v[8:9], off
	global_load_dwordx2 v[16:17], v[6:7], off
	s_nop 0
	global_load_dwordx4 v[6:9], v[18:19], off offset:1024
	s_nop 0
	global_load_dwordx2 v[18:19], v[32:33], off offset:512
	s_waitcnt vmcnt(0) lgkmcnt(0)
	v_lshlrev_b32_e32 v2, 16, v34
	v_mul_f32_e32 v2, 0xbfb8aa3b, v2
	v_exp_f32_e32 v2, v2
	v_and_b32_e32 v33, 0xffff0000, v34
	v_lshlrev_b32_e32 v34, 16, v35
	v_and_b32_e32 v35, 0xffff0000, v35
	v_add_f32_e32 v2, 1.0, v2
	v_rcp_f32_e32 v32, v2
	v_mul_f32_e32 v2, 0xbfb8aa3b, v33
	v_exp_f32_e32 v2, v2
	v_lshlrev_b32_e32 v36, 16, v21
	v_and_b32_e32 v37, 0xffff0000, v21
	v_lshlrev_b32_e32 v38, 16, v31
	v_add_f32_e32 v2, 1.0, v2
	v_rcp_f32_e32 v33, v2
	v_mul_f32_e32 v2, 0xbfb8aa3b, v34
	v_exp_f32_e32 v2, v2
	v_and_b32_e32 v39, 0xffff0000, v31
	v_pk_add_f32 v[36:37], v[36:37], v[38:39]
	v_lshlrev_b32_e32 v38, 16, v20
	v_add_f32_e32 v2, 1.0, v2
	v_rcp_f32_e32 v34, v2
	v_mul_f32_e32 v2, 0xbfb8aa3b, v35
	v_exp_f32_e32 v2, v2
	v_and_b32_e32 v39, 0xffff0000, v20
	v_lshlrev_b32_e32 v20, 16, v30
	v_and_b32_e32 v21, 0xffff0000, v30
	v_pk_add_f32 v[20:21], v[38:39], v[20:21]
	v_mov_b32_e32 v39, v37
	v_mov_b32_e32 v38, v21
	v_mov_b32_e32 v30, v20
	v_mov_b32_e32 v31, v36
	v_pk_mul_f32 v[38:39], v[38:39], v[38:39]
	v_add_f32_e32 v2, 1.0, v2
	v_pk_fma_f32 v[30:31], v[30:31], v[30:31], v[38:39]
	v_rcp_f32_e32 v35, v2
	v_add_f32_e32 v2, v30, v31
	ds_bpermute_b32 v30, v1, v2
	s_waitcnt lgkmcnt(0)
	v_add_f32_e32 v2, v2, v30
	ds_bpermute_b32 v30, v5, v2
	s_waitcnt lgkmcnt(0)
	v_add_f32_e32 v2, v2, v30
	ds_bpermute_b32 v30, v22, v2
	s_waitcnt lgkmcnt(0)
	v_add_f32_e32 v2, v2, v30
	ds_bpermute_b32 v30, v23, v2
	s_waitcnt lgkmcnt(0)
	v_add_f32_e32 v2, v2, v30
	ds_bpermute_b32 v30, v24, v2
	s_waitcnt lgkmcnt(0)
	v_add_f32_e32 v2, v2, v30
	ds_bpermute_b32 v30, v25, v2
	s_waitcnt lgkmcnt(0)
; DI float bflo(unsigned w) { return __uint_as_float(w << 16); }
; DI float bfhi(unsigned w) { return __uint_as_float(w & 0xffff0000u); }
; DI unsigned pk2(float lo, float hi) { return pg8::cvt_pk_bf16(lo, hi); }
; DI float sigm(float x) { return __builtin_amdgcn_rcpf(1.0f + __expf(-x)); }
; template <int ACT  > DI void hnorm_phase(const Ctx& C, const bf16* HF, const bf16* HB, const float* g, const bf16* gate, int ldg, bf16* Y  ) {
;     ...
;             const float rstd = 1.0f / sqrtf(wave_sum((v[0] * v[0] + v[1] * v[1]) + (v[2] * v[2] + v[3] * v[3])) * (1.0f / 256.0f) + EPS);
;             float z[4] = {bflo(gt[u].x), bfhi(gt[u].x), bflo(gt[u].y), bfhi(gt[u].y)}, r[4];
; #pragma unroll
;             for (int i = 0; i < 4; ++i) { const float s = sigm(z[i]); r[i] = v[i] * rstd * gv[u][i] * (ACT == 0 ? s : z[i] * s); }
;             v2u w; w.x = pk2(r[0], r[1]); w.y = pk2(r[2], r[3]); *(v2u*)(Y + (size_t)tk[u] * D + hh[u] * 256 + 4 * C.lane) = w; }
	v_add_f32_e32 v2, v2, v30
	v_fmamk_f32 v2, v2, 0x3b800000, v209
	v_cmp_gt_f32_e32 vcc, s89, v2
	v_mul_f32_e32 v30, 0x4f800000, v2
	s_nop 0
	v_cndmask_b32_e32 v2, v2, v30, vcc
	v_sqrt_f32_e32 v30, v2
	s_nop 0
	v_add_u32_e32 v31, -1, v30
	v_fma_f32 v38, -v31, v30, v2
	v_cmp_ge_f32_e64 s[0:1], 0, v38
	v_add_u32_e32 v38, 1, v30
	s_nop 0
	v_cndmask_b32_e64 v31, v30, v31, s[0:1]
	v_fma_f32 v30, -v38, v30, v2
	v_cmp_lt_f32_e64 s[0:1], 0, v30
	s_nop 1
	v_cndmask_b32_e64 v30, v31, v38, s[0:1]
	v_mul_f32_e32 v31, 0x37800000, v30
	v_cndmask_b32_e32 v30, v30, v31, vcc
	v_cmp_class_f32_e32 vcc, v2, v210
	s_nop 1
	v_cndmask_b32_e32 v2, v30, v2, vcc
	v_div_scale_f32 v30, s[0:1], v2, v2, 1.0
	v_rcp_f32_e32 v31, v30
	s_lshl_b64 s[0:1], s[12:13], 12
	s_add_u32 s0, s14, s0
	s_addc_u32 s1, s15, s1
	v_fma_f32 v38, -v30, v31, 1.0
	v_fmac_f32_e32 v31, v38, v31
	v_div_scale_f32 v38, vcc, 1.0, v2, 1.0
	v_mul_f32_e32 v39, v38, v31
	v_fma_f32 v40, -v30, v39, v38
	v_fmac_f32_e32 v39, v40, v31
	v_fma_f32 v30, -v30, v39, v38
	v_div_fmas_f32 v30, v30, v31, v39
	v_div_fixup_f32 v2, v30, v2, 1.0
	v_pk_mul_f32 v[20:21], v[20:21], v[2:3] op_sel_hi:[1,0]
	s_add_u32 s0, s0, s92
	v_pk_mul_f32 v[20:21], v[26:27], v[20:21]
	v_pk_mul_f32 v[26:27], v[36:37], v[2:3] op_sel_hi:[1,0]
	v_pk_mul_f32 v[20:21], v[32:33], v[20:21]
	v_pk_mul_f32 v[26:27], v[28:29], v[26:27]
	s_addc_u32 s1, s1, 0
	v_pk_mul_f32 v[26:27], v[34:35], v[26:27]
	v_lshlrev_b32_e32 v2, 1, v0
	v_cvt_pk_bf16_f32 v20, v20, v21
	v_cvt_pk_bf16_f32 v21, v26, v27
	v_lshl_add_u64 v[26:27], s[0:1], 0, v[2:3]
	v_lshlrev_b32_e32 v2, 16, v18
	v_mul_f32_e32 v2, 0xbfb8aa3b, v2
	v_exp_f32_e32 v2, v2
	global_store_dwordx2 v[26:27], v[20:21], off
	v_and_b32_e32 v20, 0xffff0000, v18
	v_lshlrev_b32_e32 v21, 16, v19
	v_add_f32_e32 v2, 1.0, v2
	v_rcp_f32_e32 v18, v2
	v_mul_f32_e32 v2, 0xbfb8aa3b, v20
	v_exp_f32_e32 v2, v2
	v_and_b32_e32 v28, 0xffff0000, v19
	v_and_b32_e32 v29, 0xffff0000, v15
	v_lshlrev_b32_e32 v30, 16, v17
	v_add_f32_e32 v2, 1.0, v2
	v_rcp_f32_e32 v19, v2
	v_mul_f32_e32 v2, 0xbfb8aa3b, v21
	v_exp_f32_e32 v2, v2
	v_and_b32_e32 v31, 0xffff0000, v17
	s_add_i32 s16, s16, s90
	s_add_i32 s17, s17, s4
	v_add_f32_e32 v2, 1.0, v2
	v_rcp_f32_e32 v20, v2
	v_mul_f32_e32 v2, 0xbfb8aa3b, v28
	v_lshlrev_b32_e32 v28, 16, v15
	v_exp_f32_e32 v2, v2
	v_pk_add_f32 v[28:29], v[28:29], v[30:31]
	v_lshlrev_b32_e32 v30, 16, v14
	v_and_b32_e32 v31, 0xffff0000, v14
	v_lshlrev_b32_e32 v14, 16, v16
	v_and_b32_e32 v15, 0xffff0000, v16
	v_pk_add_f32 v[14:15], v[30:31], v[14:15]
	v_mov_b32_e32 v31, v29
	v_mov_b32_e32 v30, v15
	v_mov_b32_e32 v16, v14
	v_mov_b32_e32 v17, v28
	v_pk_mul_f32 v[30:31], v[30:31], v[30:31]
	v_add_f32_e32 v2, 1.0, v2
	v_pk_fma_f32 v[16:17], v[16:17], v[16:17], v[30:31]
	v_rcp_f32_e32 v21, v2
	v_add_f32_e32 v2, v16, v17
	ds_bpermute_b32 v16, v1, v2
	s_cmp_lt_i32 s16, 0x10000
	s_waitcnt lgkmcnt(0)
	v_add_f32_e32 v2, v2, v16
	ds_bpermute_b32 v16, v5, v2
	s_waitcnt lgkmcnt(0)
	v_add_f32_e32 v2, v2, v16
	ds_bpermute_b32 v16, v22, v2
	s_waitcnt lgkmcnt(0)
	v_add_f32_e32 v2, v2, v16
	ds_bpermute_b32 v16, v23, v2
	s_waitcnt lgkmcnt(0)
	v_add_f32_e32 v2, v2, v16
	ds_bpermute_b32 v16, v24, v2
	s_waitcnt lgkmcnt(0)
	v_add_f32_e32 v2, v2, v16
	ds_bpermute_b32 v16, v25, v2
	s_waitcnt lgkmcnt(0)
	v_add_f32_e32 v2, v2, v16
	v_fmamk_f32 v2, v2, 0x3b800000, v209
	v_cmp_gt_f32_e32 vcc, s89, v2
	v_mul_f32_e32 v16, 0x4f800000, v2
	s_nop 0
	v_cndmask_b32_e32 v2, v2, v16, vcc
	v_sqrt_f32_e32 v16, v2
	s_nop 0
	v_add_u32_e32 v17, -1, v16
	v_fma_f32 v30, -v17, v16, v2
	v_cmp_ge_f32_e64 s[0:1], 0, v30
	v_add_u32_e32 v30, 1, v16
	s_nop 0
	v_cndmask_b32_e64 v17, v16, v17, s[0:1]
	v_fma_f32 v16, -v30, v16, v2
	v_cmp_lt_f32_e64 s[0:1], 0, v16
	s_nop 1
	v_cndmask_b32_e64 v16, v17, v30, s[0:1]
	v_mul_f32_e32 v17, 0x37800000, v16
	v_cndmask_b32_e32 v16, v16, v17, vcc
	v_cmp_class_f32_e32 vcc, v2, v210
	s_nop 1
	v_cndmask_b32_e32 v2, v16, v2, vcc
	v_div_scale_f32 v16, s[0:1], v2, v2, 1.0
	v_rcp_f32_e32 v17, v16
	s_nop 0
	v_fma_f32 v30, -v16, v17, 1.0
	v_fmac_f32_e32 v17, v30, v17
	v_div_scale_f32 v30, vcc, 1.0, v2, 1.0
	v_mul_f32_e32 v31, v30, v17
	v_fma_f32 v32, -v16, v31, v30
	v_fmac_f32_e32 v31, v32, v17
	v_fma_f32 v16, -v16, v31, v30
	v_div_fmas_f32 v16, v16, v17, v31
	v_div_fixup_f32 v2, v16, v2, 1.0
	v_pk_mul_f32 v[14:15], v[14:15], v[2:3] op_sel_hi:[1,0]
	v_pk_mul_f32 v[6:7], v[6:7], v[14:15]
	v_pk_mul_f32 v[14:15], v[28:29], v[2:3] op_sel_hi:[1,0]
	v_pk_mul_f32 v[6:7], v[18:19], v[6:7]
	v_pk_mul_f32 v[8:9], v[8:9], v[14:15]
	v_cvt_pk_bf16_f32 v6, v6, v7
	v_pk_mul_f32 v[8:9], v[20:21], v[8:9]
	v_cvt_pk_bf16_f32 v7, v8, v9
	global_store_dwordx2 v[26:27], v[6:7], off offset:512
	s_cbranch_scc1 .LBB0_1549

;     __device__ __forceinline__ void operator()(const f32x4 (&acc)[2][2][4][2], const Unit& u, int wr, int wc, int fr, int fq) const {
;     ...
;             for (int m = 0; m < 4; ++m) { const size_t off = (size_t)(row0 + ai * HALF + m * 16) * ldc + col0; float ss = 0.f;
; #pragma unroll
;                 for (int bj = 0; bj < 2; ++bj)
; #pragma unroll
;                     for (int n = 0; n < 2; ++n) { const f32x4 bs = *(const f32x4*)(base + off + bj * HALF + n * 16); const f32x4 o = bs + acc[ai][bj][m][n] * scale;
;                         *(f32x4*)(out + off + bj * HALF + n * 16) = o;
;                         if (xg) { ss += (o[0] * o[0] + o[1] * o[1]) + (o[2] * o[2] + o[3] * o[3]); const f32x4 og = o * gv[bj][n];
;                             typedef unsigned u32x2v __attribute__((ext_vector_type(2))); u32x2v w; w.x = cvt_pk_bf16(og[0], og[1]); w.y = cvt_pk_bf16(og[2], og[3]); *(u32x2v*)(xg + off + bj * HALF + n * 16) = w; } }
;                 if (xg) { ss += __shfl_xor(ss, 16); ss += __shfl_xor(ss, 32); if (fq == 0) atomicAdd(rowss + row0 + ai * HALF + m * 16, (rowss_t)(ss * 16777216.0f)); } }
.LBB0_1633:
	s_or_b64 exec, exec, s[24:25]
	v_or_b32_e32 v138, 16, v170
	s_waitcnt lgkmcnt(0)
	v_ashrrev_i32_e32 v139, 31, v138
	v_lshlrev_b64 v[138:139], 11, v[138:139]
	v_lshl_add_u64 v[142:143], v[138:139], 0, v[168:169]
	v_lshl_add_u64 v[144:145], v[142:143], 2, s[10:11]
	global_load_dwordx4 v[138:141], v[144:145], off
	global_load_dwordx4 v[182:185], v[144:145], off offset:64
	global_load_dwordx4 v[186:189], v[144:145], off offset:512
	global_load_dwordx4 v[190:193], v[144:145], off offset:576
	v_lshl_add_u64 v[142:143], v[142:143], 1, s[12:13]
	s_waitcnt vmcnt(3) lgkmcnt(0)
	v_pk_add_f32 v[132:133], v[132:133], v[140:141]
	v_pk_add_f32 v[130:131], v[130:131], v[138:139]
	v_pk_mul_f32 v[138:139], v[100:101], v[132:133]
	v_pk_mul_f32 v[140:141], v[98:99], v[130:131]
	global_store_dwordx4 v[144:145], v[130:133], off
	v_cvt_pk_bf16_f32 v140, v140, v141
	v_cvt_pk_bf16_f32 v141, v138, v139
	global_store_dwordx2 v[142:143], v[140:141], off
	v_mul_f32_e32 v131, v131, v131
	v_mul_f32_e32 v133, v133, v133
	v_fmac_f32_e32 v131, v130, v130
	v_fmac_f32_e32 v133, v132, v132
	v_add_f32_e32 v130, v131, v133
	s_waitcnt vmcnt(4) lgkmcnt(0)
	v_pk_add_f32 v[128:129], v[128:129], v[184:185]
	v_pk_add_f32 v[126:127], v[126:127], v[182:183]
	v_pk_mul_f32 v[138:139], v[96:97], v[128:129]
	v_pk_mul_f32 v[140:141], v[94:95], v[126:127]
	global_store_dwordx4 v[144:145], v[126:129], off offset:64
	v_cvt_pk_bf16_f32 v140, v140, v141
	v_cvt_pk_bf16_f32 v141, v138, v139
	global_store_dwordx2 v[142:143], v[140:141], off offset:32
	v_mul_f32_e32 v127, v127, v127
	v_mul_f32_e32 v129, v129, v129
	v_fmac_f32_e32 v127, v126, v126
	v_fmac_f32_e32 v129, v128, v128
	v_add_f32_e32 v126, v127, v129
	v_add_f32_e32 v126, v130, v126
	s_waitcnt vmcnt(5) lgkmcnt(0)
	v_pk_add_f32 v[124:125], v[124:125], v[188:189]
	v_pk_add_f32 v[122:123], v[122:123], v[186:187]
	v_pk_mul_f32 v[138:139], v[92:93], v[124:125]
	v_pk_mul_f32 v[140:141], v[90:91], v[122:123]
	global_store_dwordx4 v[144:145], v[122:125], off offset:512
	v_cvt_pk_bf16_f32 v140, v140, v141
	v_cvt_pk_bf16_f32 v141, v138, v139
	global_store_dwordx2 v[142:143], v[140:141], off offset:256
	v_mul_f32_e32 v123, v123, v123
	v_mul_f32_e32 v125, v125, v125
	v_fmac_f32_e32 v123, v122, v122
	v_fmac_f32_e32 v125, v124, v124
	v_add_f32_e32 v122, v123, v125
	v_add_f32_e32 v124, v126, v122
	s_waitcnt vmcnt(6) lgkmcnt(0)
	v_pk_add_f32 v[122:123], v[120:121], v[192:193]
	v_pk_add_f32 v[120:121], v[118:119], v[190:191]
	v_mul_f32_e32 v119, v123, v123
	v_mul_f32_e32 v118, v121, v121
	v_fmac_f32_e32 v118, v120, v120
	v_fmac_f32_e32 v119, v122, v122
	v_add_f32_e32 v118, v118, v119
	v_add_f32_e32 v118, v124, v118
	ds_bpermute_b32 v119, v136, v118
	global_store_dwordx4 v[144:145], v[120:123], off offset:576
	s_waitcnt lgkmcnt(0)
	v_add_f32_e32 v118, v118, v119
	ds_bpermute_b32 v119, v137, v118
	v_pk_mul_f32 v[122:123], v[80:81], v[122:123]
	v_pk_mul_f32 v[120:121], v[78:79], v[120:121]
	v_cvt_pk_bf16_f32 v120, v120, v121
	v_cvt_pk_bf16_f32 v121, v122, v123
	global_store_dwordx2 v[142:143], v[120:121], off offset:288
	s_and_saveexec_b64 s[24:25], s[6:7]
	v_readlane_b32 s28, v253, 4
	s_cbranch_execz .LBB0_1635
	s_waitcnt lgkmcnt(0)
	v_add_f32_e32 v118, v118, v119
	v_mul_f32_e32 v118, 0x4b800000, v118
	v_trunc_f32_e32 v118, v118
	v_mul_f32_e32 v119, 0x2f800000, v118
	v_floor_f32_e32 v119, v119
	v_fmac_f32_e32 v118, 0xcf800000, v119
	v_cvt_u32_f32_e32 v118, v118
	v_cvt_u32_f32_e32 v119, v119
	global_atomic_add_x2 v[134:135], v[118:119], off offset:128
.LBB0_1635:
	s_or_b64 exec, exec, s[24:25]
	v_or_b32_e32 v118, 32, v170
	s_waitcnt lgkmcnt(0)
	v_ashrrev_i32_e32 v119, 31, v118
	v_lshlrev_b64 v[118:119], 11, v[118:119]
	v_lshl_add_u64 v[122:123], v[118:119], 0, v[168:169]
	v_lshl_add_u64 v[124:125], v[122:123], 2, s[10:11]
	global_load_dwordx4 v[118:121], v[124:125], off
	global_load_dwordx4 v[182:185], v[124:125], off offset:64
	global_load_dwordx4 v[186:189], v[124:125], off offset:512
	global_load_dwordx4 v[190:193], v[124:125], off offset:576
	v_lshl_add_u64 v[122:123], v[122:123], 1, s[12:13]
	s_waitcnt vmcnt(3) lgkmcnt(0)
	v_pk_add_f32 v[116:117], v[116:117], v[120:121]
	v_pk_add_f32 v[114:115], v[114:115], v[118:119]
	v_pk_mul_f32 v[118:119], v[100:101], v[116:117]
	v_pk_mul_f32 v[120:121], v[98:99], v[114:115]
	global_store_dwordx4 v[124:125], v[114:117], off
	v_cvt_pk_bf16_f32 v120, v120, v121
	v_cvt_pk_bf16_f32 v121, v118, v119
	global_store_dwordx2 v[122:123], v[120:121], off
	v_mul_f32_e32 v115, v115, v115
	v_mul_f32_e32 v117, v117, v117
	v_fmac_f32_e32 v115, v114, v114
	v_fmac_f32_e32 v117, v116, v116
	v_add_f32_e32 v114, v115, v117
	s_waitcnt vmcnt(4) lgkmcnt(0)
	v_pk_add_f32 v[112:113], v[112:113], v[184:185]
	v_pk_add_f32 v[110:111], v[110:111], v[182:183]
	v_pk_mul_f32 v[118:119], v[96:97], v[112:113]
	v_pk_mul_f32 v[120:121], v[94:95], v[110:111]
	global_store_dwordx4 v[124:125], v[110:113], off offset:64
	v_cvt_pk_bf16_f32 v120, v120, v121
	v_cvt_pk_bf16_f32 v121, v118, v119
	global_store_dwordx2 v[122:123], v[120:121], off offset:32
	v_mul_f32_e32 v111, v111, v111
	v_mul_f32_e32 v113, v113, v113
	v_fmac_f32_e32 v111, v110, v110
	v_fmac_f32_e32 v113, v112, v112
	v_add_f32_e32 v110, v111, v113
	v_add_f32_e32 v110, v114, v110
	s_waitcnt vmcnt(5) lgkmcnt(0)
	v_pk_add_f32 v[108:109], v[108:109], v[188:189]
	v_pk_add_f32 v[106:107], v[106:107], v[186:187]
	v_pk_mul_f32 v[118:119], v[92:93], v[108:109]
	v_pk_mul_f32 v[120:121], v[90:91], v[106:107]
	global_store_dwordx4 v[124:125], v[106:109], off offset:512
	v_cvt_pk_bf16_f32 v120, v120, v121
	v_cvt_pk_bf16_f32 v121, v118, v119
	global_store_dwordx2 v[122:123], v[120:121], off offset:256
	v_mul_f32_e32 v107, v107, v107
	v_mul_f32_e32 v109, v109, v109
	v_fmac_f32_e32 v107, v106, v106
	v_fmac_f32_e32 v109, v108, v108
	v_add_f32_e32 v106, v107, v109
	v_add_f32_e32 v108, v110, v106
	s_waitcnt vmcnt(6) lgkmcnt(0)
	v_pk_add_f32 v[106:107], v[104:105], v[192:193]
	v_pk_add_f32 v[104:105], v[102:103], v[190:191]
	v_mul_f32_e32 v103, v107, v107
	v_mul_f32_e32 v102, v105, v105
	v_fmac_f32_e32 v102, v104, v104
	v_fmac_f32_e32 v103, v106, v106
	v_add_f32_e32 v102, v102, v103
	v_add_f32_e32 v102, v108, v102
	ds_bpermute_b32 v103, v136, v102
	global_store_dwordx4 v[124:125], v[104:107], off offset:576
	s_waitcnt lgkmcnt(0)
	v_add_f32_e32 v102, v102, v103
	ds_bpermute_b32 v103, v137, v102
	v_pk_mul_f32 v[106:107], v[80:81], v[106:107]
	v_pk_mul_f32 v[104:105], v[78:79], v[104:105]
	v_cvt_pk_bf16_f32 v104, v104, v105
	v_cvt_pk_bf16_f32 v105, v106, v107
	global_store_dwordx2 v[122:123], v[104:105], off offset:288
	s_and_saveexec_b64 s[24:25], s[6:7]
	v_readlane_b32 s74, v253, 12
	v_readlane_b32 s75, v253, 13
	v_readlane_b32 s85, v253, 15
	v_readlane_b32 s90, v253, 16
	v_readlane_b32 s76, v253, 17
	v_readlane_b32 s72, v253, 19
	v_readlane_b32 s84, v253, 20
	s_mov_b32 s86, 0x800000
	s_mov_b32 s82, 0xf000000
	s_mov_b64 s[80:81], 0x2000
	s_mov_b32 s83, s54
	v_readlane_b32 s77, v253, 18
	s_cbranch_execz .LBB0_1637
;     __device__ __forceinline__ void operator()(const f32x4 (&acc)[2][2][4][2], const Unit& u, int wr, int wc, int fr, int fq) const {
;     ...
;             for (int m = 0; m < 4; ++m) { const size_t off = (size_t)(row0 + ai * HALF + m * 16) * ldc + col0; float ss = 0.f;
; #pragma unroll
;                 for (int bj = 0; bj < 2; ++bj)
; #pragma unroll
;                     for (int n = 0; n < 2; ++n) { const f32x4 bs = *(const f32x4*)(base + off + bj * HALF + n * 16); const f32x4 o = bs + acc[ai][bj][m][n] * scale;
;                         *(f32x4*)(out + off + bj * HALF + n * 16) = o;
;                         if (xg) { ss += (o[0] * o[0] + o[1] * o[1]) + (o[2] * o[2] + o[3] * o[3]); const f32x4 og = o * gv[bj][n];
;                             typedef unsigned u32x2v __attribute__((ext_vector_type(2))); u32x2v w; w.x = cvt_pk_bf16(og[0], og[1]); w.y = cvt_pk_bf16(og[2], og[3]); *(u32x2v*)(xg + off + bj * HALF + n * 16) = w; } }
;                 if (xg) { ss += __shfl_xor(ss, 16); ss += __shfl_xor(ss, 32); if (fq == 0) atomicAdd(rowss + row0 + ai * HALF + m * 16, (rowss_t)(ss * 16777216.0f)); } }
	s_waitcnt lgkmcnt(0)
	v_add_f32_e32 v102, v102, v103
	v_mul_f32_e32 v102, 0x4b800000, v102
	v_trunc_f32_e32 v102, v102
	v_mul_f32_e32 v103, 0x2f800000, v102
	v_floor_f32_e32 v103, v103
	v_fmac_f32_e32 v102, 0xcf800000, v103
	v_cvt_u32_f32_e32 v102, v102
	v_cvt_u32_f32_e32 v103, v103
	global_atomic_add_x2 v[134:135], v[102:103], off offset:256
.LBB0_1637:
	s_or_b64 exec, exec, s[24:25]
	v_or_b32_e32 v102, 48, v170
	s_waitcnt lgkmcnt(0)
	v_ashrrev_i32_e32 v103, 31, v102
	v_lshlrev_b64 v[102:103], 11, v[102:103]
	v_lshl_add_u64 v[106:107], v[102:103], 0, v[168:169]
	v_lshl_add_u64 v[108:109], v[106:107], 2, s[10:11]
	global_load_dwordx4 v[102:105], v[108:109], off
	global_load_dwordx4 v[182:185], v[108:109], off offset:64
	global_load_dwordx4 v[186:189], v[108:109], off offset:512
	global_load_dwordx4 v[190:193], v[108:109], off offset:576
	v_lshl_add_u64 v[106:107], v[106:107], 1, s[12:13]
	s_waitcnt vmcnt(3) lgkmcnt(0)
	v_pk_add_f32 v[88:89], v[88:89], v[104:105]
	v_pk_add_f32 v[86:87], v[86:87], v[102:103]
	v_pk_mul_f32 v[102:103], v[100:101], v[88:89]
	v_pk_mul_f32 v[104:105], v[98:99], v[86:87]
	global_store_dwordx4 v[108:109], v[86:89], off
	v_cvt_pk_bf16_f32 v104, v104, v105
	v_cvt_pk_bf16_f32 v105, v102, v103
	global_store_dwordx2 v[106:107], v[104:105], off
	v_mul_f32_e32 v87, v87, v87
	v_mul_f32_e32 v89, v89, v89
	v_fmac_f32_e32 v87, v86, v86
	v_fmac_f32_e32 v89, v88, v88
	v_add_f32_e32 v86, v87, v89
	s_waitcnt vmcnt(4) lgkmcnt(0)
	v_pk_add_f32 v[84:85], v[84:85], v[184:185]
	v_pk_add_f32 v[82:83], v[82:83], v[182:183]
	v_pk_mul_f32 v[102:103], v[96:97], v[84:85]
	v_pk_mul_f32 v[104:105], v[94:95], v[82:83]
	global_store_dwordx4 v[108:109], v[82:85], off offset:64
	v_cvt_pk_bf16_f32 v104, v104, v105
	v_cvt_pk_bf16_f32 v105, v102, v103
	global_store_dwordx2 v[106:107], v[104:105], off offset:32
	v_mul_f32_e32 v83, v83, v83
	v_mul_f32_e32 v85, v85, v85
	v_fmac_f32_e32 v83, v82, v82
	v_fmac_f32_e32 v85, v84, v84
	v_add_f32_e32 v82, v83, v85
	v_add_f32_e32 v82, v86, v82
	s_waitcnt vmcnt(5) lgkmcnt(0)
	v_pk_add_f32 v[76:77], v[76:77], v[188:189]
	v_pk_add_f32 v[74:75], v[74:75], v[186:187]
	v_pk_mul_f32 v[102:103], v[92:93], v[76:77]
	v_pk_mul_f32 v[104:105], v[90:91], v[74:75]
	global_store_dwordx4 v[108:109], v[74:77], off offset:512
	v_cvt_pk_bf16_f32 v104, v104, v105
	v_cvt_pk_bf16_f32 v105, v102, v103
	global_store_dwordx2 v[106:107], v[104:105], off offset:256
	v_mul_f32_e32 v75, v75, v75
	v_mul_f32_e32 v77, v77, v77
	v_fmac_f32_e32 v75, v74, v74
	v_fmac_f32_e32 v77, v76, v76
	v_add_f32_e32 v74, v75, v77
	v_add_f32_e32 v76, v82, v74
	s_waitcnt vmcnt(6) lgkmcnt(0)
	v_pk_add_f32 v[74:75], v[72:73], v[192:193]
	v_pk_add_f32 v[72:73], v[70:71], v[190:191]
	v_mul_f32_e32 v71, v75, v75
	v_mul_f32_e32 v70, v73, v73
	v_fmac_f32_e32 v70, v72, v72
	v_fmac_f32_e32 v71, v74, v74
	v_add_f32_e32 v70, v70, v71
	v_add_f32_e32 v70, v76, v70
	ds_bpermute_b32 v71, v136, v70
	global_store_dwordx4 v[108:109], v[72:75], off offset:576
	s_waitcnt lgkmcnt(0)
	v_add_f32_e32 v70, v70, v71
	ds_bpermute_b32 v71, v137, v70
	v_pk_mul_f32 v[74:75], v[80:81], v[74:75]
	v_pk_mul_f32 v[72:73], v[78:79], v[72:73]
	v_cvt_pk_bf16_f32 v72, v72, v73
	v_cvt_pk_bf16_f32 v73, v74, v75
	global_store_dwordx2 v[106:107], v[72:73], off offset:288
	s_and_saveexec_b64 s[24:25], s[6:7]
	s_cbranch_execz .LBB0_1639
	s_waitcnt lgkmcnt(0)
	v_add_f32_e32 v70, v70, v71
	v_mul_f32_e32 v70, 0x4b800000, v70
	v_trunc_f32_e32 v70, v70
	v_mul_f32_e32 v71, 0x2f800000, v70
	v_floor_f32_e32 v71, v71
	v_fmac_f32_e32 v70, 0xcf800000, v71
	v_cvt_u32_f32_e32 v70, v70
	v_cvt_u32_f32_e32 v71, v71
	global_atomic_add_x2 v[134:135], v[70:71], off offset:384
.LBB0_1639:
	s_or_b64 exec, exec, s[24:25]
	s_mov_b64 s[24:25], 0x40000
	v_lshl_add_u64 v[74:75], v[166:167], 0, s[24:25]
	v_lshl_add_u64 v[76:77], v[74:75], 2, s[10:11]
	s_waitcnt lgkmcnt(0)
	global_load_dwordx4 v[70:73], v[76:77], off
	global_load_dwordx4 v[182:185], v[76:77], off offset:64
	global_load_dwordx4 v[186:189], v[76:77], off offset:512
	global_load_dwordx4 v[190:193], v[76:77], off offset:576
	v_lshl_add_u64 v[74:75], v[74:75], 1, s[12:13]
	s_waitcnt vmcnt(3) lgkmcnt(0)
	v_pk_add_f32 v[68:69], v[68:69], v[72:73]
	v_pk_add_f32 v[66:67], v[66:67], v[70:71]
	v_pk_mul_f32 v[70:71], v[100:101], v[68:69]
	v_pk_mul_f32 v[72:73], v[98:99], v[66:67]
	global_store_dwordx4 v[76:77], v[66:69], off
	v_cvt_pk_bf16_f32 v72, v72, v73
	v_cvt_pk_bf16_f32 v73, v70, v71
	global_store_dwordx2 v[74:75], v[72:73], off
	v_mul_f32_e32 v67, v67, v67
	v_mul_f32_e32 v69, v69, v69
	v_fmac_f32_e32 v67, v66, v66
	v_fmac_f32_e32 v69, v68, v68
	v_add_f32_e32 v66, v67, v69
	s_waitcnt vmcnt(4) lgkmcnt(0)
	v_pk_add_f32 v[64:65], v[64:65], v[184:185]
	v_pk_add_f32 v[62:63], v[62:63], v[182:183]
	v_pk_mul_f32 v[70:71], v[96:97], v[64:65]
	v_pk_mul_f32 v[72:73], v[94:95], v[62:63]
	global_store_dwordx4 v[76:77], v[62:65], off offset:64
	v_cvt_pk_bf16_f32 v72, v72, v73
	v_cvt_pk_bf16_f32 v73, v70, v71
	global_store_dwordx2 v[74:75], v[72:73], off offset:32
	v_mul_f32_e32 v63, v63, v63
	v_mul_f32_e32 v65, v65, v65
	v_fmac_f32_e32 v63, v62, v62
	v_fmac_f32_e32 v65, v64, v64
	v_add_f32_e32 v62, v63, v65
	v_add_f32_e32 v62, v66, v62
	s_waitcnt vmcnt(5) lgkmcnt(0)
	v_pk_add_f32 v[60:61], v[60:61], v[188:189]
	v_pk_add_f32 v[58:59], v[58:59], v[186:187]
	v_pk_mul_f32 v[70:71], v[92:93], v[60:61]
	v_pk_mul_f32 v[72:73], v[90:91], v[58:59]
	global_store_dwordx4 v[76:77], v[58:61], off offset:512
	v_cvt_pk_bf16_f32 v72, v72, v73
	v_cvt_pk_bf16_f32 v73, v70, v71
	global_store_dwordx2 v[74:75], v[72:73], off offset:256
	v_mul_f32_e32 v59, v59, v59
	v_mul_f32_e32 v61, v61, v61
	v_fmac_f32_e32 v59, v58, v58
	v_fmac_f32_e32 v61, v60, v60
	v_add_f32_e32 v58, v59, v61
	v_add_f32_e32 v60, v62, v58
	s_waitcnt vmcnt(6) lgkmcnt(0)
	v_pk_add_f32 v[58:59], v[56:57], v[192:193]
	v_pk_add_f32 v[56:57], v[54:55], v[190:191]
	v_mul_f32_e32 v55, v59, v59
	v_mul_f32_e32 v54, v57, v57
	v_fmac_f32_e32 v54, v56, v56
	v_fmac_f32_e32 v55, v58, v58
	v_add_f32_e32 v54, v54, v55
	v_add_f32_e32 v54, v60, v54
	ds_bpermute_b32 v55, v136, v54
	global_store_dwordx4 v[76:77], v[56:59], off offset:576
	s_waitcnt lgkmcnt(0)
	v_add_f32_e32 v54, v54, v55
	ds_bpermute_b32 v55, v137, v54
	v_pk_mul_f32 v[58:59], v[80:81], v[58:59]
	v_pk_mul_f32 v[56:57], v[78:79], v[56:57]
	v_cvt_pk_bf16_f32 v56, v56, v57
	v_cvt_pk_bf16_f32 v57, v58, v59
	global_store_dwordx2 v[74:75], v[56:57], off offset:288
	s_and_saveexec_b64 s[24:25], s[6:7]
	s_cbranch_execz .LBB0_1641
	s_waitcnt lgkmcnt(0)
	v_add_f32_e32 v54, v54, v55
	v_mul_f32_e32 v54, 0x4b800000, v54
	v_trunc_f32_e32 v54, v54
	v_mul_f32_e32 v55, 0x2f800000, v54
	v_floor_f32_e32 v55, v55
	v_fmac_f32_e32 v54, 0xcf800000, v55
	v_cvt_u32_f32_e32 v54, v54
	v_cvt_u32_f32_e32 v55, v55
	global_atomic_add_x2 v[134:135], v[54:55], off offset:1024
;     __device__ __forceinline__ void operator()(const f32x4 (&acc)[2][2][4][2], const Unit& u, int wr, int wc, int fr, int fq) const {
;     ...
;             for (int m = 0; m < 4; ++m) { const size_t off = (size_t)(row0 + ai * HALF + m * 16) * ldc + col0; float ss = 0.f;
; #pragma unroll
;                 for (int bj = 0; bj < 2; ++bj)
; #pragma unroll
;                     for (int n = 0; n < 2; ++n) { const f32x4 bs = *(const f32x4*)(base + off + bj * HALF + n * 16); const f32x4 o = bs + acc[ai][bj][m][n] * scale;
;                         *(f32x4*)(out + off + bj * HALF + n * 16) = o;
;                         if (xg) { ss += (o[0] * o[0] + o[1] * o[1]) + (o[2] * o[2] + o[3] * o[3]); const f32x4 og = o * gv[bj][n];
;                             typedef unsigned u32x2v __attribute__((ext_vector_type(2))); u32x2v w; w.x = cvt_pk_bf16(og[0], og[1]); w.y = cvt_pk_bf16(og[2], og[3]); *(u32x2v*)(xg + off + bj * HALF + n * 16) = w; } }
;                 if (xg) { ss += __shfl_xor(ss, 16); ss += __shfl_xor(ss, 32); if (fq == 0) atomicAdd(rowss + row0 + ai * HALF + m * 16, (rowss_t)(ss * 16777216.0f)); } }
.LBB0_1641:
	s_or_b64 exec, exec, s[24:25]
	s_mov_b64 s[24:25], 0x48000
	v_lshl_add_u64 v[58:59], v[166:167], 0, s[24:25]
	v_lshl_add_u64 v[60:61], v[58:59], 2, s[10:11]
	s_waitcnt lgkmcnt(0)
	global_load_dwordx4 v[54:57], v[60:61], off
	global_load_dwordx4 v[182:185], v[60:61], off offset:64
	global_load_dwordx4 v[186:189], v[60:61], off offset:512
	global_load_dwordx4 v[190:193], v[60:61], off offset:576
	v_lshl_add_u64 v[58:59], v[58:59], 1, s[12:13]
	s_waitcnt vmcnt(3) lgkmcnt(0)
	v_pk_add_f32 v[52:53], v[52:53], v[56:57]
	v_pk_add_f32 v[50:51], v[50:51], v[54:55]
	v_pk_mul_f32 v[54:55], v[100:101], v[52:53]
	v_pk_mul_f32 v[56:57], v[98:99], v[50:51]
	global_store_dwordx4 v[60:61], v[50:53], off
	v_cvt_pk_bf16_f32 v56, v56, v57
	v_cvt_pk_bf16_f32 v57, v54, v55
	global_store_dwordx2 v[58:59], v[56:57], off
	v_mul_f32_e32 v51, v51, v51
	v_mul_f32_e32 v53, v53, v53
	v_fmac_f32_e32 v51, v50, v50
	v_fmac_f32_e32 v53, v52, v52
	v_add_f32_e32 v50, v51, v53
	s_waitcnt vmcnt(4) lgkmcnt(0)
	v_pk_add_f32 v[48:49], v[48:49], v[184:185]
	v_pk_add_f32 v[46:47], v[46:47], v[182:183]
	v_pk_mul_f32 v[54:55], v[96:97], v[48:49]
	v_pk_mul_f32 v[56:57], v[94:95], v[46:47]
	global_store_dwordx4 v[60:61], v[46:49], off offset:64
	v_cvt_pk_bf16_f32 v56, v56, v57
	v_cvt_pk_bf16_f32 v57, v54, v55
	global_store_dwordx2 v[58:59], v[56:57], off offset:32
	v_mul_f32_e32 v47, v47, v47
	v_mul_f32_e32 v49, v49, v49
	v_fmac_f32_e32 v47, v46, v46
	v_fmac_f32_e32 v49, v48, v48
	v_add_f32_e32 v46, v47, v49
	v_add_f32_e32 v46, v50, v46
	s_waitcnt vmcnt(5) lgkmcnt(0)
	v_pk_add_f32 v[44:45], v[44:45], v[188:189]
	v_pk_add_f32 v[42:43], v[42:43], v[186:187]
	v_pk_mul_f32 v[54:55], v[92:93], v[44:45]
	v_pk_mul_f32 v[56:57], v[90:91], v[42:43]
	global_store_dwordx4 v[60:61], v[42:45], off offset:512
	v_cvt_pk_bf16_f32 v56, v56, v57
	v_cvt_pk_bf16_f32 v57, v54, v55
	global_store_dwordx2 v[58:59], v[56:57], off offset:256
	v_mul_f32_e32 v43, v43, v43
	v_mul_f32_e32 v45, v45, v45
	v_fmac_f32_e32 v43, v42, v42
	v_fmac_f32_e32 v45, v44, v44
	v_add_f32_e32 v42, v43, v45
	v_add_f32_e32 v44, v46, v42
	s_waitcnt vmcnt(6) lgkmcnt(0)
	v_pk_add_f32 v[42:43], v[40:41], v[192:193]
	v_pk_add_f32 v[40:41], v[38:39], v[190:191]
	v_mul_f32_e32 v39, v43, v43
	v_mul_f32_e32 v38, v41, v41
	v_fmac_f32_e32 v38, v40, v40
	v_fmac_f32_e32 v39, v42, v42
	v_add_f32_e32 v38, v38, v39
	v_add_f32_e32 v38, v44, v38
	ds_bpermute_b32 v39, v136, v38
	global_store_dwordx4 v[60:61], v[40:43], off offset:576
	s_waitcnt lgkmcnt(0)
	v_add_f32_e32 v38, v38, v39
	ds_bpermute_b32 v39, v137, v38
	v_pk_mul_f32 v[42:43], v[80:81], v[42:43]
	v_pk_mul_f32 v[40:41], v[78:79], v[40:41]
	v_cvt_pk_bf16_f32 v40, v40, v41
	v_cvt_pk_bf16_f32 v41, v42, v43
	global_store_dwordx2 v[58:59], v[40:41], off offset:288
	s_and_saveexec_b64 s[24:25], s[6:7]
	s_cbranch_execz .LBB0_1643
	s_waitcnt lgkmcnt(0)
	v_add_f32_e32 v38, v38, v39
	v_mul_f32_e32 v38, 0x4b800000, v38
	v_trunc_f32_e32 v38, v38
	v_mul_f32_e32 v39, 0x2f800000, v38
	v_floor_f32_e32 v39, v39
	v_fmac_f32_e32 v38, 0xcf800000, v39
	v_cvt_u32_f32_e32 v38, v38
	v_cvt_u32_f32_e32 v39, v39
	global_atomic_add_x2 v[134:135], v[38:39], off offset:1152
;     __device__ __forceinline__ void operator()(const f32x4 (&acc)[2][2][4][2], const Unit& u, int wr, int wc, int fr, int fq) const {
;     ...
;             for (int m = 0; m < 4; ++m) { const size_t off = (size_t)(row0 + ai * HALF + m * 16) * ldc + col0; float ss = 0.f;
; #pragma unroll
;                 for (int bj = 0; bj < 2; ++bj)
; #pragma unroll
;                     for (int n = 0; n < 2; ++n) { const f32x4 bs = *(const f32x4*)(base + off + bj * HALF + n * 16); const f32x4 o = bs + acc[ai][bj][m][n] * scale;
;                         *(f32x4*)(out + off + bj * HALF + n * 16) = o;
;                         if (xg) { ss += (o[0] * o[0] + o[1] * o[1]) + (o[2] * o[2] + o[3] * o[3]); const f32x4 og = o * gv[bj][n];
;                             typedef unsigned u32x2v __attribute__((ext_vector_type(2))); u32x2v w; w.x = cvt_pk_bf16(og[0], og[1]); w.y = cvt_pk_bf16(og[2], og[3]); *(u32x2v*)(xg + off + bj * HALF + n * 16) = w; } }
;                 if (xg) { ss += __shfl_xor(ss, 16); ss += __shfl_xor(ss, 32); if (fq == 0) atomicAdd(rowss + row0 + ai * HALF + m * 16, (rowss_t)(ss * 16777216.0f)); } }
.LBB0_1643:
	s_or_b64 exec, exec, s[24:25]
	s_mov_b64 s[24:25], 0x50000
	v_lshl_add_u64 v[42:43], v[166:167], 0, s[24:25]
	v_lshl_add_u64 v[44:45], v[42:43], 2, s[10:11]
	s_waitcnt lgkmcnt(0)
	global_load_dwordx4 v[38:41], v[44:45], off
	global_load_dwordx4 v[182:185], v[44:45], off offset:64
	global_load_dwordx4 v[186:189], v[44:45], off offset:512
	global_load_dwordx4 v[190:193], v[44:45], off offset:576
	v_lshl_add_u64 v[42:43], v[42:43], 1, s[12:13]
	s_waitcnt vmcnt(3) lgkmcnt(0)
	v_pk_add_f32 v[36:37], v[36:37], v[40:41]
	v_pk_add_f32 v[34:35], v[34:35], v[38:39]
	v_pk_mul_f32 v[38:39], v[100:101], v[36:37]
	v_pk_mul_f32 v[40:41], v[98:99], v[34:35]
	global_store_dwordx4 v[44:45], v[34:37], off
	v_cvt_pk_bf16_f32 v40, v40, v41
	v_cvt_pk_bf16_f32 v41, v38, v39
	global_store_dwordx2 v[42:43], v[40:41], off
	v_mul_f32_e32 v35, v35, v35
	v_mul_f32_e32 v37, v37, v37
	v_fmac_f32_e32 v35, v34, v34
	v_fmac_f32_e32 v37, v36, v36
	v_add_f32_e32 v34, v35, v37
	s_waitcnt vmcnt(4) lgkmcnt(0)
	v_pk_add_f32 v[32:33], v[32:33], v[184:185]
	v_pk_add_f32 v[30:31], v[30:31], v[182:183]
	v_pk_mul_f32 v[38:39], v[96:97], v[32:33]
	v_pk_mul_f32 v[40:41], v[94:95], v[30:31]
	global_store_dwordx4 v[44:45], v[30:33], off offset:64
	v_cvt_pk_bf16_f32 v40, v40, v41
	v_cvt_pk_bf16_f32 v41, v38, v39
	global_store_dwordx2 v[42:43], v[40:41], off offset:32
	v_mul_f32_e32 v31, v31, v31
	v_mul_f32_e32 v33, v33, v33
	v_fmac_f32_e32 v31, v30, v30
	v_fmac_f32_e32 v33, v32, v32
	v_add_f32_e32 v30, v31, v33
	v_add_f32_e32 v30, v34, v30
	s_waitcnt vmcnt(5) lgkmcnt(0)
	v_pk_add_f32 v[28:29], v[28:29], v[188:189]
	v_pk_add_f32 v[26:27], v[26:27], v[186:187]
	v_pk_mul_f32 v[38:39], v[92:93], v[28:29]
	v_pk_mul_f32 v[40:41], v[90:91], v[26:27]
	global_store_dwordx4 v[44:45], v[26:29], off offset:512
	v_cvt_pk_bf16_f32 v40, v40, v41
	v_cvt_pk_bf16_f32 v41, v38, v39
	global_store_dwordx2 v[42:43], v[40:41], off offset:256
	v_mul_f32_e32 v27, v27, v27
	v_mul_f32_e32 v29, v29, v29
	v_fmac_f32_e32 v27, v26, v26
	v_fmac_f32_e32 v29, v28, v28
	v_add_f32_e32 v26, v27, v29
	v_add_f32_e32 v28, v30, v26
	s_waitcnt vmcnt(6) lgkmcnt(0)
	v_pk_add_f32 v[26:27], v[24:25], v[192:193]
	v_pk_add_f32 v[24:25], v[22:23], v[190:191]
	v_mul_f32_e32 v23, v27, v27
	v_mul_f32_e32 v22, v25, v25
	v_fmac_f32_e32 v22, v24, v24
	v_fmac_f32_e32 v23, v26, v26
	v_add_f32_e32 v22, v22, v23
	v_add_f32_e32 v22, v28, v22
	ds_bpermute_b32 v23, v136, v22
	global_store_dwordx4 v[44:45], v[24:27], off offset:576
	s_waitcnt lgkmcnt(0)
	v_add_f32_e32 v22, v22, v23
	ds_bpermute_b32 v23, v137, v22
	v_pk_mul_f32 v[26:27], v[80:81], v[26:27]
	v_pk_mul_f32 v[24:25], v[78:79], v[24:25]
	v_cvt_pk_bf16_f32 v24, v24, v25
	v_cvt_pk_bf16_f32 v25, v26, v27
	global_store_dwordx2 v[42:43], v[24:25], off offset:288
	s_and_saveexec_b64 s[24:25], s[6:7]
	s_cbranch_execz .LBB0_1645
	s_waitcnt lgkmcnt(0)
	v_add_f32_e32 v22, v22, v23
	v_mul_f32_e32 v22, 0x4b800000, v22
	v_trunc_f32_e32 v22, v22
	v_mul_f32_e32 v23, 0x2f800000, v22
	v_floor_f32_e32 v23, v23
	v_fmac_f32_e32 v22, 0xcf800000, v23
	v_cvt_u32_f32_e32 v22, v22
	v_cvt_u32_f32_e32 v23, v23
	global_atomic_add_x2 v[134:135], v[22:23], off offset:1280
.LBB0_1645:
	s_or_b64 exec, exec, s[24:25]
	s_mov_b64 s[24:25], 0x58000
	v_lshl_add_u64 v[26:27], v[166:167], 0, s[24:25]
	v_lshl_add_u64 v[28:29], v[26:27], 2, s[10:11]
	s_waitcnt lgkmcnt(0)
	global_load_dwordx4 v[22:25], v[28:29], off
	global_load_dwordx4 v[182:185], v[28:29], off offset:64
	global_load_dwordx4 v[186:189], v[28:29], off offset:512
	global_load_dwordx4 v[190:193], v[28:29], off offset:576
	v_lshl_add_u64 v[26:27], v[26:27], 1, s[12:13]
	s_waitcnt vmcnt(3) lgkmcnt(0)
	v_pk_add_f32 v[20:21], v[20:21], v[24:25]
	v_pk_add_f32 v[18:19], v[18:19], v[22:23]
	v_pk_mul_f32 v[22:23], v[100:101], v[20:21]
	v_pk_mul_f32 v[24:25], v[98:99], v[18:19]
	global_store_dwordx4 v[28:29], v[18:21], off
	v_cvt_pk_bf16_f32 v24, v24, v25
	v_cvt_pk_bf16_f32 v25, v22, v23
	global_store_dwordx2 v[26:27], v[24:25], off
	v_mul_f32_e32 v19, v19, v19
	v_mul_f32_e32 v21, v21, v21
	v_fmac_f32_e32 v19, v18, v18
	v_fmac_f32_e32 v21, v20, v20
	v_add_f32_e32 v18, v19, v21
	s_waitcnt vmcnt(4) lgkmcnt(0)
	v_pk_add_f32 v[16:17], v[16:17], v[184:185]
	v_pk_add_f32 v[14:15], v[14:15], v[182:183]
	v_pk_mul_f32 v[22:23], v[96:97], v[16:17]
	v_pk_mul_f32 v[24:25], v[94:95], v[14:15]
	global_store_dwordx4 v[28:29], v[14:17], off offset:64
	v_cvt_pk_bf16_f32 v24, v24, v25
	v_cvt_pk_bf16_f32 v25, v22, v23
	global_store_dwordx2 v[26:27], v[24:25], off offset:32
	v_mul_f32_e32 v15, v15, v15
	v_mul_f32_e32 v17, v17, v17
	v_fmac_f32_e32 v15, v14, v14
	v_fmac_f32_e32 v17, v16, v16
	v_add_f32_e32 v14, v15, v17
	v_add_f32_e32 v14, v18, v14
	s_waitcnt vmcnt(5) lgkmcnt(0)
	v_pk_add_f32 v[12:13], v[12:13], v[188:189]
	v_pk_add_f32 v[10:11], v[10:11], v[186:187]
	v_pk_mul_f32 v[22:23], v[92:93], v[12:13]
	v_pk_mul_f32 v[24:25], v[90:91], v[10:11]
	global_store_dwordx4 v[28:29], v[10:13], off offset:512
	v_cvt_pk_bf16_f32 v24, v24, v25
	v_cvt_pk_bf16_f32 v25, v22, v23
	global_store_dwordx2 v[26:27], v[24:25], off offset:256
	v_mul_f32_e32 v11, v11, v11
	v_mul_f32_e32 v13, v13, v13
	v_fmac_f32_e32 v11, v10, v10
	v_fmac_f32_e32 v13, v12, v12
	v_add_f32_e32 v10, v11, v13
	v_add_f32_e32 v12, v14, v10
	s_waitcnt vmcnt(6) lgkmcnt(0)
	v_pk_add_f32 v[10:11], v[8:9], v[192:193]
	v_pk_add_f32 v[8:9], v[6:7], v[190:191]
	v_mul_f32_e32 v7, v11, v11
	v_mul_f32_e32 v6, v9, v9
	v_fmac_f32_e32 v6, v8, v8
	v_fmac_f32_e32 v7, v10, v10
	v_add_f32_e32 v6, v6, v7
	v_add_f32_e32 v6, v12, v6
	ds_bpermute_b32 v7, v136, v6
	global_store_dwordx4 v[28:29], v[8:11], off offset:576
	s_waitcnt lgkmcnt(0)
	v_add_f32_e32 v6, v6, v7
	ds_bpermute_b32 v7, v137, v6
	v_pk_mul_f32 v[10:11], v[80:81], v[10:11]
	v_pk_mul_f32 v[8:9], v[78:79], v[8:9]
	v_cvt_pk_bf16_f32 v8, v8, v9
	v_cvt_pk_bf16_f32 v9, v10, v11
	global_store_dwordx2 v[26:27], v[8:9], off offset:288
	s_and_saveexec_b64 s[24:25], s[6:7]
	s_cbranch_execz .LBB0_1622
	s_waitcnt lgkmcnt(0)
	v_add_f32_e32 v6, v6, v7
	v_mul_f32_e32 v6, 0x4b800000, v6
	v_trunc_f32_e32 v6, v6
	v_mul_f32_e32 v7, 0x2f800000, v6
	v_floor_f32_e32 v7, v7
	v_fmac_f32_e32 v6, 0xcf800000, v7
	v_cvt_u32_f32_e32 v6, v6
	v_cvt_u32_f32_e32 v7, v7
	global_atomic_add_x2 v[134:135], v[6:7], off offset:1408
	s_branch .LBB0_1622

; DI void rms_rows_f32(const Ctx& C, float* x, const float* g) {
;     for (int m = C.gw; m < T; m += C.ngw) {
;         f32x4* xr = (f32x4*)(x + (size_t)m * D) + C.lane; f32x4 v[8]; float s = 0.f;
; #pragma unroll
;         for (int j = 0; j < 8; ++j) { v[j] = xr[64 * j]; s += (v[j].x * v[j].x + v[j].y * v[j].y) + (v[j].z * v[j].z + v[j].w * v[j].w); }
;         const float rstd = 1.0f / sqrtf(wave_sum(s) * (1.0f / D) + EPS);
;         const f32x4* gr = (const f32x4*)g + C.lane;
; #pragma unroll
;         for (int j = 0; j < 8; ++j) { const f32x4 gv = gr[64 * j]; xr[64 * j] = v[j] * rstd * gv; }
;     }
; }
.LBB0_1722:
	global_load_dwordx4 v[34:37], v[22:23], off
	global_load_dwordx4 v[4:7], v[22:23], off offset:1024
	global_load_dwordx4 v[38:41], v[22:23], off offset:2048
	global_load_dwordx4 v[42:45], v[22:23], off offset:3072
	v_add_co_u32_e32 v24, vcc, s7, v22
	s_add_i32 s6, s6, s24
	s_nop 0
	v_addc_co_u32_e32 v25, vcc, 0, v23, vcc
	global_load_dwordx4 v[8:11], v[24:25], off
	global_load_dwordx4 v[46:49], v[24:25], off offset:1024
	global_load_dwordx4 v[50:53], v[24:25], off offset:2048
	global_load_dwordx4 v[0:3], v[24:25], off offset:3072
	global_load_dwordx4 v[54:57], v[12:13], off
	s_cmpk_lt_i32 s6, 0x4000
	s_waitcnt vmcnt(0) lgkmcnt(0)
	v_mov_b32_e32 v60, v35
	v_mov_b32_e32 v61, v5
	v_mov_b32_e32 v64, v37
	v_mov_b32_e32 v65, v7
	v_mov_b32_e32 v58, v34
	v_mov_b32_e32 v59, v4
	v_mov_b32_e32 v62, v36
	v_mov_b32_e32 v63, v6
	v_pk_mul_f32 v[66:67], v[40:41], v[40:41]
	v_pk_mul_f32 v[68:69], v[38:39], v[38:39]
	v_pk_mul_f32 v[60:61], v[60:61], v[60:61]
	v_pk_mul_f32 v[64:65], v[64:65], v[64:65]
	v_pk_mov_b32 v[74:75], v[68:69], v[66:67] op_sel:[1,0]
	v_mov_b32_e32 v69, v67
	v_pk_fma_f32 v[58:59], v[58:59], v[58:59], v[60:61]
	v_pk_fma_f32 v[60:61], v[62:63], v[62:63], v[64:65]
	v_mul_f32_e32 v70, v43, v43
	v_mul_f32_e32 v72, v45, v45
	v_pk_add_f32 v[62:63], v[74:75], v[68:69]
	v_pk_add_f32 v[58:59], v[58:59], v[60:61]
	v_mul_f32_e32 v79, v8, v8
	v_mul_f32_e32 v81, v9, v9
	v_mul_f32_e32 v82, v10, v10
	v_mul_f32_e32 v83, v11, v11
	v_pk_fma_f32 v[66:67], v[42:43], v[42:43], v[70:71] op_sel_hi:[1,1,0]
	v_pk_fma_f32 v[70:71], v[44:45], v[44:45], v[72:73] op_sel_hi:[1,1,0]
	v_pk_add_f32 v[60:61], v[62:63], v[62:63] op_sel:[0,1] op_sel_hi:[1,0]
	v_pk_add_f32 v[58:59], v[58:59], v[58:59] op_sel:[0,1] op_sel_hi:[1,0]
	v_pk_mul_f32 v[72:73], v[48:49], v[48:49]
	v_pk_mul_f32 v[76:77], v[46:47], v[46:47]
	v_mov_b32_e32 v67, v82
	v_mov_b32_e32 v71, v83
	v_mov_b32_e32 v61, v81
	v_mov_b32_e32 v59, v79
	v_pk_mov_b32 v[64:65], v[76:77], v[72:73] op_sel:[1,0]
	v_mov_b32_e32 v77, v73
	v_pk_add_f32 v[62:63], v[66:67], v[70:71]
	v_pk_add_f32 v[58:59], v[58:59], v[60:61]
	v_mul_f32_e32 v78, v51, v51
	v_mul_f32_e32 v80, v53, v53
	v_pk_add_f32 v[64:65], v[64:65], v[76:77]
	v_pk_add_f32 v[58:59], v[58:59], v[62:63]
	v_mul_f32_e32 v84, v0, v0
	v_mul_f32_e32 v85, v1, v1
	v_mul_f32_e32 v86, v2, v2
	v_mul_f32_e32 v87, v3, v3
	v_pk_fma_f32 v[68:69], v[50:51], v[50:51], v[78:79] op_sel_hi:[1,1,0]
	v_pk_fma_f32 v[72:73], v[52:53], v[52:53], v[80:81] op_sel_hi:[1,1,0]
	v_pk_add_f32 v[64:65], v[64:65], v[64:65] op_sel:[0,1] op_sel_hi:[1,0]
	v_pk_add_f32 v[58:59], v[58:59], v[58:59] op_sel:[0,1] op_sel_hi:[1,0]
	v_mov_b32_e32 v69, v86
	v_mov_b32_e32 v73, v87
	v_mov_b32_e32 v65, v85
	v_mov_b32_e32 v59, v84
	v_pk_add_f32 v[66:67], v[68:69], v[72:73]
	v_pk_add_f32 v[58:59], v[58:59], v[64:65]
	v_pk_add_f32 v[58:59], v[58:59], v[66:67]
	v_add_f32_e32 v58, v58, v59
	ds_bpermute_b32 v59, v26, v58
	s_waitcnt lgkmcnt(0)
	v_add_f32_e32 v58, v58, v59
	ds_bpermute_b32 v59, v27, v58
	s_waitcnt lgkmcnt(0)
	v_add_f32_e32 v58, v58, v59
	ds_bpermute_b32 v59, v28, v58
	s_waitcnt lgkmcnt(0)
	v_add_f32_e32 v58, v58, v59
	ds_bpermute_b32 v59, v29, v58
	s_waitcnt lgkmcnt(0)
	v_add_f32_e32 v58, v58, v59
	ds_bpermute_b32 v59, v30, v58
	s_waitcnt lgkmcnt(0)
	v_add_f32_e32 v58, v58, v59
	ds_bpermute_b32 v59, v31, v58
	s_waitcnt lgkmcnt(0)
	v_add_f32_e32 v58, v58, v59
	v_fmamk_f32 v58, v58, 0x3a000000, v32
	v_mul_f32_e32 v59, 0x4f800000, v58
	v_cmp_gt_f32_e32 vcc, s8, v58
	s_nop 1
	v_cndmask_b32_e32 v58, v58, v59, vcc
	v_sqrt_f32_e32 v59, v58
	s_nop 0
	v_add_u32_e32 v60, -1, v59
	v_add_u32_e32 v61, 1, v59
	v_fma_f32 v62, -v60, v59, v58
	v_fma_f32 v63, -v61, v59, v58
	v_cmp_ge_f32_e64 s[0:1], 0, v62
	s_nop 1
	v_cndmask_b32_e64 v59, v59, v60, s[0:1]
	v_cmp_lt_f32_e64 s[0:1], 0, v63
	s_nop 1
	v_cndmask_b32_e64 v59, v59, v61, s[0:1]
	v_mul_f32_e32 v60, 0x37800000, v59
	v_cndmask_b32_e32 v59, v59, v60, vcc
	v_cmp_class_f32_e32 vcc, v58, v33
	s_nop 1
	v_cndmask_b32_e32 v58, v59, v58, vcc
	v_div_scale_f32 v59, s[0:1], v58, v58, 1.0
	v_rcp_f32_e32 v61, v59
	v_div_scale_f32 v60, vcc, 1.0, v58, 1.0
	v_fma_f32 v62, -v59, v61, 1.0
	v_fmac_f32_e32 v61, v62, v61
	v_mul_f32_e32 v62, v60, v61
	v_fma_f32 v63, -v59, v62, v60
	v_fmac_f32_e32 v62, v63, v61
	v_fma_f32 v59, -v59, v62, v60
	v_div_fmas_f32 v59, v59, v61, v62
	v_div_fixup_f32 v58, v59, v58, 1.0
	v_pk_mul_f32 v[34:35], v[34:35], v[58:59] op_sel_hi:[1,0]
	v_pk_mul_f32 v[36:37], v[36:37], v[58:59] op_sel_hi:[1,0]
	v_pk_mul_f32 v[34:35], v[54:55], v[34:35]
	v_pk_mul_f32 v[36:37], v[56:57], v[36:37]
	global_load_dwordx4 v[100:103], v[12:13], off offset:1024
	global_load_dwordx4 v[104:107], v[12:13], off offset:2048
	global_load_dwordx4 v[108:111], v[12:13], off offset:3072
	global_load_dwordx4 v[112:115], v[14:15], off
	global_load_dwordx4 v[116:119], v[16:17], off
	global_load_dwordx4 v[120:123], v[18:19], off
	global_load_dwordx4 v[124:127], v[20:21], off
	global_store_dwordx4 v[22:23], v[34:37], off
	v_pk_mul_f32 v[6:7], v[6:7], v[58:59] op_sel_hi:[1,0]
	v_pk_mul_f32 v[4:5], v[4:5], v[58:59] op_sel_hi:[1,0]
	v_pk_mul_f32 v[10:11], v[10:11], v[58:59] op_sel_hi:[1,0]
	v_pk_mul_f32 v[8:9], v[8:9], v[58:59] op_sel_hi:[1,0]
	v_pk_mul_f32 v[2:3], v[2:3], v[58:59] op_sel_hi:[1,0]
	v_pk_mul_f32 v[0:1], v[0:1], v[58:59] op_sel_hi:[1,0]
	s_waitcnt vmcnt(7)
	v_pk_mul_f32 v[4:5], v[100:101], v[4:5]
	v_pk_mul_f32 v[6:7], v[102:103], v[6:7]
	global_store_dwordx4 v[22:23], v[4:7], off offset:1024
	v_pk_mul_f32 v[34:35], v[40:41], v[58:59] op_sel_hi:[1,0]
	v_pk_mul_f32 v[36:37], v[38:39], v[58:59] op_sel_hi:[1,0]
	s_waitcnt vmcnt(7)
	v_pk_mul_f32 v[6:7], v[106:107], v[34:35]
	v_pk_mul_f32 v[4:5], v[104:105], v[36:37]
	global_store_dwordx4 v[22:23], v[4:7], off offset:2048
	v_pk_mul_f32 v[34:35], v[44:45], v[58:59] op_sel_hi:[1,0]
	v_pk_mul_f32 v[36:37], v[42:43], v[58:59] op_sel_hi:[1,0]
	s_waitcnt vmcnt(7)
	v_pk_mul_f32 v[6:7], v[110:111], v[34:35]
	v_pk_mul_f32 v[4:5], v[108:109], v[36:37]
	global_store_dwordx4 v[22:23], v[4:7], off offset:3072
	v_lshl_add_u64 v[22:23], v[22:23], 0, s[4:5]
	s_waitcnt vmcnt(7)
	v_pk_mul_f32 v[4:5], v[112:113], v[8:9]
	v_pk_mul_f32 v[6:7], v[114:115], v[10:11]
	global_store_dwordx4 v[24:25], v[4:7], off
	v_pk_mul_f32 v[8:9], v[48:49], v[58:59] op_sel_hi:[1,0]
	v_pk_mul_f32 v[10:11], v[46:47], v[58:59] op_sel_hi:[1,0]
	s_waitcnt vmcnt(7)
	v_pk_mul_f32 v[6:7], v[118:119], v[8:9]
	v_pk_mul_f32 v[4:5], v[116:117], v[10:11]
	global_store_dwordx4 v[24:25], v[4:7], off offset:1024
	v_pk_mul_f32 v[8:9], v[52:53], v[58:59] op_sel_hi:[1,0]
	v_pk_mul_f32 v[10:11], v[50:51], v[58:59] op_sel_hi:[1,0]
	s_waitcnt vmcnt(7)
	v_pk_mul_f32 v[6:7], v[8:9], v[122:123]
	v_pk_mul_f32 v[4:5], v[10:11], v[120:121]
	global_store_dwordx4 v[24:25], v[4:7], off offset:2048
	s_waitcnt vmcnt(7)
	v_pk_mul_f32 v[0:1], v[0:1], v[124:125]
	v_pk_mul_f32 v[2:3], v[2:3], v[126:127]
	global_store_dwordx4 v[24:25], v[0:3], off offset:3072
	s_cbranch_scc1 .LBB0_1722
